# experiment: no s_setprio around the MFMA blocks at all
# speedup vs baseline: 1.0032x; 1.0032x over previous
; #define PG8_STAGE(bufoff, gbase, voff, p64) do { _Pragma("unroll") for (int _i = 0; _i < 2; ++_i) { \
;         const char* _gb = (const char*)(gbase) + (size_t)_i * (p64); const unsigned _la = ldsbase + (unsigned)(bufoff) + (unsigned)_i * 8192u; \
;         asm volatile("s_mov_b32 m0, %0\n\ts_nop 0\n\tglobal_load_lds_dwordx4 %1, %2" :: "s"(_la), "v"(voff), "s"(_gb) : "memory"); } } while (0)
; #define PG8_LDA(dst, b, h) do { _Pragma("unroll") for (int m = 0; m < 4; ++m) _Pragma("unroll") for (int k = 0; k < 2; ++k) dst[m][k] = *(const LAS bf16x8*)(lds + PG8_SA(b, h) + aoff + m * 2048 + k * 1024); } while (0)
; #define PG8_LDB(dst, b, h) do { _Pragma("unroll") for (int n = 0; n < 2; ++n) _Pragma("unroll") for (int k = 0; k < 2; ++k) dst[n][k] = *(const LAS bf16x8*)(lds + PG8_SB(b, h) + boff + n * 2048 + k * 1024); } while (0)
; #define PG8_MMA(ai, bj, At, Bt) do { __builtin_amdgcn_s_setprio(1); _Pragma("unroll") for (int m = 0; m < 4; ++m) _Pragma("unroll") for (int n = 0; n < 2; ++n) _Pragma("unroll") for (int k = 0; k < 2; ++k) \
;         acc[ai][bj][m][n] = __builtin_amdgcn_mfma_f32_16x16x32_bf16(Bt[n][k], At[m][k], acc[ai][bj][m][n], 0, 0, 0); __builtin_amdgcn_s_setprio(0); } while (0)
; #define PG8_WAIT_V(n) asm volatile("s_waitcnt vmcnt(" #n ")" ::: "memory")
; template <class Epi, class Sched>
; __device__ __forceinline__ void gemm_phase(LAS unsigned char* lds, const Sched& S, const Epi& E) {
;     ...
;         for (int t = 0; t < nt; t += 2) {
;             const bool last = (t == nt - 2);
;             const char* a1 = cA + (size_t)(t + 1) * kstep;
;             const char* a2 = last ? nA : cA + (size_t)(t + 2) * kstep; const char* b2 = last ? nB : cB + (size_t)(t + 2) * kstep;
;             const char* a3 = a2 + kstep; const char* b3 = b2 + kstep;
;             const unsigned vA2 = voffA, vB2 = voffB, hA2 = hA, hB2 = hB;
;             PG8_LDB(B0, 0, 0); PG8_LDB(B1, 0, 1); PG8_SCHED; PG8_LDA(At, 0, 0); PG8_STAGE(PG8_SA(1, 1), a1 + hA, voffA, hA / 2);
;             PG8_WAIT_V(8); PG8_WAIT_L(0); PG8_BAR; PG8_MMA(0, 0, At, B0); PG8_MMA(0, 1, At, B1); PG8_BAR; PG8_SCHED;
;             PG8_LDA(At, 0, 1); PG8_STAGE(PG8_SB(0, 0), b2, vB2, hB2 / 2); PG8_STAGE(PG8_SB(0, 1), b2 + hB2, vB2, hB2 / 2); PG8_STAGE(PG8_SA(0, 0), a2, vA2, hA2 / 2);
;             PG8_WAIT_V(8); PG8_WAIT_L(0); PG8_BAR; PG8_MMA(1, 0, At, B0); PG8_MMA(1, 1, At, B1); PG8_BAR; PG8_SCHED;
.LBB0_303:
	s_add_u32 s38, s38, 0x40080
	s_addc_u32 s39, s39, 0
	s_add_u32 s62, s40, 0x100
	s_addc_u32 s63, s41, 0
	s_mov_b32 s64, -2
	ds_read_b128 v[144:147], v138
	ds_read_b128 v[148:151], v138 offset:1024
	ds_read_b128 v[152:155], v138 offset:2048
	ds_read_b128 v[156:159], v138 offset:3072
	ds_read_b128 v[160:163], v139
	ds_read_b128 v[164:167], v139 offset:1024
	ds_read_b128 v[168:171], v139 offset:2048
	ds_read_b128 v[172:175], v139 offset:3072
	s_add_u32 s30, s38, 0xfffc0080
	s_addc_u32 s31, s39, -1
	s_cmp_eq_u32 s64, 12
	s_cselect_b32 s40, s24, s30
	s_cselect_b32 s41, s25, s31
	s_cselect_b32 s44, s26, s62
	s_cselect_b32 s45, s27, s63
	s_add_u32 s42, s40, 0x80
	s_addc_u32 s43, s41, 0
	ds_read_b128 v[178:181], v140
	ds_read_b128 v[182:185], v140 offset:1024
	ds_read_b128 v[186:189], v140 offset:2048
	ds_read_b128 v[190:193], v140 offset:3072
	ds_read_b128 v[194:197], v140 offset:4096
	ds_read_b128 v[198:201], v140 offset:5120
	ds_read_b128 v[202:205], v140 offset:6144
	ds_read_b128 v[206:209], v140 offset:7168
	s_mov_b32 m0, s55
	s_nop 0
	global_load_lds_dwordx4 v134, s[38:39]
	s_add_u32 s66, s38, 0x20000
	s_mov_b32 m0, s56
	s_addc_u32 s67, s39, 0
	global_load_lds_dwordx4 v134, s[66:67]
	s_waitcnt vmcnt(8) lgkmcnt(0)
	s_barrier
	v_mfma_f32_16x16x32_bf16 v[124:127], v[144:147], v[178:181], 0
	v_mfma_f32_16x16x32_bf16 v[120:123], v[152:155], v[178:181], 0
	v_mfma_f32_16x16x32_bf16 v[108:111], v[144:147], v[186:189], 0
	v_mfma_f32_16x16x32_bf16 v[104:107], v[152:155], v[186:189], 0
	v_mfma_f32_16x16x32_bf16 v[92:95], v[144:147], v[194:197], 0
	v_mfma_f32_16x16x32_bf16 v[88:91], v[152:155], v[194:197], 0
	v_mfma_f32_16x16x32_bf16 v[76:79], v[144:147], v[202:205], 0
	v_mfma_f32_16x16x32_bf16 v[72:75], v[152:155], v[202:205], 0
	v_mfma_f32_16x16x32_bf16 v[124:127], v[148:151], v[182:185], v[124:127]
	v_mfma_f32_16x16x32_bf16 v[120:123], v[156:159], v[182:185], v[120:123]
	v_mfma_f32_16x16x32_bf16 v[108:111], v[148:151], v[190:193], v[108:111]
	v_mfma_f32_16x16x32_bf16 v[104:107], v[156:159], v[190:193], v[104:107]
	v_mfma_f32_16x16x32_bf16 v[92:95], v[148:151], v[198:201], v[92:95]
	v_mfma_f32_16x16x32_bf16 v[88:91], v[156:159], v[198:201], v[88:91]
	v_mfma_f32_16x16x32_bf16 v[76:79], v[148:151], v[206:209], v[76:79]
	v_mfma_f32_16x16x32_bf16 v[72:75], v[156:159], v[206:209], v[72:75]
	v_mfma_f32_16x16x32_bf16 v[116:119], v[160:163], v[178:181], 0
	v_mfma_f32_16x16x32_bf16 v[112:115], v[168:171], v[178:181], 0
	v_mfma_f32_16x16x32_bf16 v[100:103], v[160:163], v[186:189], 0
	v_mfma_f32_16x16x32_bf16 v[96:99], v[168:171], v[186:189], 0
	v_mfma_f32_16x16x32_bf16 v[84:87], v[160:163], v[194:197], 0
	v_mfma_f32_16x16x32_bf16 v[80:83], v[168:171], v[194:197], 0
	v_mfma_f32_16x16x32_bf16 v[68:71], v[160:163], v[202:205], 0
	v_mfma_f32_16x16x32_bf16 v[64:67], v[168:171], v[202:205], 0
	v_mfma_f32_16x16x32_bf16 v[116:119], v[164:167], v[182:185], v[116:119]
	v_mfma_f32_16x16x32_bf16 v[112:115], v[172:175], v[182:185], v[112:115]
	v_mfma_f32_16x16x32_bf16 v[100:103], v[164:167], v[190:193], v[100:103]
	v_mfma_f32_16x16x32_bf16 v[96:99], v[172:175], v[190:193], v[96:99]
	v_mfma_f32_16x16x32_bf16 v[84:87], v[164:167], v[198:201], v[84:87]
	v_mfma_f32_16x16x32_bf16 v[80:83], v[172:175], v[198:201], v[80:83]
	v_mfma_f32_16x16x32_bf16 v[68:71], v[164:167], v[206:209], v[68:71]
	v_mfma_f32_16x16x32_bf16 v[64:67], v[172:175], v[206:209], v[64:67]
	s_add_i32 s64, s64, 2
	s_add_u32 s38, s38, 0x100
	s_addc_u32 s39, s39, 0
	s_add_u32 s62, s62, 0x100
	s_addc_u32 s63, s63, 0
	s_barrier
	s_add_u32 s66, s44, 0x20000
	ds_read_b128 v[178:181], v140 offset:16384
	ds_read_b128 v[182:185], v140 offset:17408
	ds_read_b128 v[186:189], v140 offset:18432
	ds_read_b128 v[190:193], v140 offset:19456
	ds_read_b128 v[194:197], v140 offset:20480
	ds_read_b128 v[198:201], v140 offset:21504
	ds_read_b128 v[202:205], v140 offset:22528
	ds_read_b128 v[206:209], v140 offset:23552
	s_mov_b32 m0, s33
	s_nop 0
	global_load_lds_dwordx4 v135, s[44:45]
	s_mov_b32 m0, s34
	s_addc_u32 s67, s45, 0
	global_load_lds_dwordx4 v135, s[66:67]
	s_add_u32 s66, s44, 0x40000
	s_mov_b32 m0, s35
	s_addc_u32 s67, s45, 0
	global_load_lds_dwordx4 v135, s[66:67]
	s_add_u32 s66, s44, 0x60000
	s_mov_b32 m0, s36
	s_addc_u32 s67, s45, 0
	global_load_lds_dwordx4 v135, s[66:67]
	s_mov_b32 m0, s12
	s_nop 0
	global_load_lds_dwordx4 v134, s[40:41]
	s_add_u32 s66, s40, 0x20000
	s_mov_b32 m0, s37
	s_addc_u32 s67, s41, 0
	global_load_lds_dwordx4 v134, s[66:67]
	s_waitcnt vmcnt(8) lgkmcnt(0)
	s_barrier
	v_mfma_f32_16x16x32_bf16 v[60:63], v[144:147], v[178:181], 0
	v_mfma_f32_16x16x32_bf16 v[56:59], v[152:155], v[178:181], 0
	v_mfma_f32_16x16x32_bf16 v[44:47], v[144:147], v[186:189], 0
	v_mfma_f32_16x16x32_bf16 v[40:43], v[152:155], v[186:189], 0
	v_mfma_f32_16x16x32_bf16 v[28:31], v[144:147], v[194:197], 0
	v_mfma_f32_16x16x32_bf16 v[24:27], v[152:155], v[194:197], 0
	v_mfma_f32_16x16x32_bf16 v[12:15], v[144:147], v[202:205], 0
	v_mfma_f32_16x16x32_bf16 v[8:11], v[152:155], v[202:205], 0
	v_mfma_f32_16x16x32_bf16 v[60:63], v[148:151], v[182:185], v[60:63]
	v_mfma_f32_16x16x32_bf16 v[56:59], v[156:159], v[182:185], v[56:59]
	v_mfma_f32_16x16x32_bf16 v[44:47], v[148:151], v[190:193], v[44:47]
	v_mfma_f32_16x16x32_bf16 v[40:43], v[156:159], v[190:193], v[40:43]
	v_mfma_f32_16x16x32_bf16 v[28:31], v[148:151], v[198:201], v[28:31]
	v_mfma_f32_16x16x32_bf16 v[24:27], v[156:159], v[198:201], v[24:27]
	v_mfma_f32_16x16x32_bf16 v[12:15], v[148:151], v[206:209], v[12:15]
	v_mfma_f32_16x16x32_bf16 v[8:11], v[156:159], v[206:209], v[8:11]
	v_mfma_f32_16x16x32_bf16 v[52:55], v[160:163], v[178:181], 0
	v_mfma_f32_16x16x32_bf16 v[48:51], v[168:171], v[178:181], 0
	v_mfma_f32_16x16x32_bf16 v[36:39], v[160:163], v[186:189], 0
	v_mfma_f32_16x16x32_bf16 v[32:35], v[168:171], v[186:189], 0
	v_mfma_f32_16x16x32_bf16 v[20:23], v[160:163], v[194:197], 0
	v_mfma_f32_16x16x32_bf16 v[16:19], v[168:171], v[194:197], 0
	v_mfma_f32_16x16x32_bf16 v[4:7], v[160:163], v[202:205], 0
	v_mfma_f32_16x16x32_bf16 v[0:3], v[168:171], v[202:205], 0
	v_mfma_f32_16x16x32_bf16 v[52:55], v[164:167], v[182:185], v[52:55]
	v_mfma_f32_16x16x32_bf16 v[48:51], v[172:175], v[182:185], v[48:51]
	v_mfma_f32_16x16x32_bf16 v[36:39], v[164:167], v[190:193], v[36:39]
	v_mfma_f32_16x16x32_bf16 v[32:35], v[172:175], v[190:193], v[32:35]
	v_mfma_f32_16x16x32_bf16 v[20:23], v[164:167], v[198:201], v[20:23]
	v_mfma_f32_16x16x32_bf16 v[16:19], v[172:175], v[198:201], v[16:19]
	v_mfma_f32_16x16x32_bf16 v[4:7], v[164:167], v[206:209], v[4:7]
	v_mfma_f32_16x16x32_bf16 v[0:3], v[172:175], v[206:209], v[0:3]
	s_barrier
	s_branch .Lpeel_mid_5680
; #define PG8_STAGE(bufoff, gbase, voff, p64) do { _Pragma("unroll") for (int _i = 0; _i < 2; ++_i) { \
;         const char* _gb = (const char*)(gbase) + (size_t)_i * (p64); const unsigned _la = ldsbase + (unsigned)(bufoff) + (unsigned)_i * 8192u; \
;         asm volatile("s_mov_b32 m0, %0\n\ts_nop 0\n\tglobal_load_lds_dwordx4 %1, %2" :: "s"(_la), "v"(voff), "s"(_gb) : "memory"); } } while (0)
; #define PG8_LDA(dst, b, h) do { _Pragma("unroll") for (int m = 0; m < 4; ++m) _Pragma("unroll") for (int k = 0; k < 2; ++k) dst[m][k] = *(const LAS bf16x8*)(lds + PG8_SA(b, h) + aoff + m * 2048 + k * 1024); } while (0)
; #define PG8_LDB(dst, b, h) do { _Pragma("unroll") for (int n = 0; n < 2; ++n) _Pragma("unroll") for (int k = 0; k < 2; ++k) dst[n][k] = *(const LAS bf16x8*)(lds + PG8_SB(b, h) + boff + n * 2048 + k * 1024); } while (0)
; #define PG8_MMA(ai, bj, At, Bt) do { __builtin_amdgcn_s_setprio(1); _Pragma("unroll") for (int m = 0; m < 4; ++m) _Pragma("unroll") for (int n = 0; n < 2; ++n) _Pragma("unroll") for (int k = 0; k < 2; ++k) \
;         acc[ai][bj][m][n] = __builtin_amdgcn_mfma_f32_16x16x32_bf16(Bt[n][k], At[m][k], acc[ai][bj][m][n], 0, 0, 0); __builtin_amdgcn_s_setprio(0); } while (0)
; #define PG8_WAIT_V(n) asm volatile("s_waitcnt vmcnt(" #n ")" ::: "memory")
; #define PG8_BAR __builtin_amdgcn_s_barrier()
; template <class Epi, class Sched>
; __device__ __forceinline__ void gemm_phase(LAS unsigned char* lds, const Sched& S, const Epi& E) {
;     ...
;             const bool last = (t == nt - 2);
;             const char* a1 = cA + (size_t)(t + 1) * kstep;
;             const char* a2 = last ? nA : cA + (size_t)(t + 2) * kstep; const char* b2 = last ? nB : cB + (size_t)(t + 2) * kstep;
;             const char* a3 = a2 + kstep; const char* b3 = b2 + kstep;
;             const unsigned vA2 = voffA, vB2 = voffB, hA2 = hA, hB2 = hB;
;             PG8_LDB(B0, 0, 0); PG8_LDB(B1, 0, 1); PG8_SCHED; PG8_LDA(At, 0, 0); PG8_STAGE(PG8_SA(1, 1), a1 + hA, voffA, hA / 2);
;             PG8_WAIT_V(8); PG8_WAIT_L(0); PG8_BAR; PG8_MMA(0, 0, At, B0); PG8_MMA(0, 1, At, B1); PG8_BAR; PG8_SCHED;
;             PG8_LDA(At, 0, 1); PG8_STAGE(PG8_SB(0, 0), b2, vB2, hB2 / 2); PG8_STAGE(PG8_SB(0, 1), b2 + hB2, vB2, hB2 / 2); PG8_STAGE(PG8_SA(0, 0), a2, vA2, hA2 / 2);
;             PG8_WAIT_V(8); PG8_WAIT_L(0); PG8_BAR; PG8_MMA(1, 0, At, B0); PG8_MMA(1, 1, At, B1); PG8_BAR; PG8_SCHED;
.LBB0_304:
	ds_read_b128 v[144:147], v138
	ds_read_b128 v[148:151], v138 offset:1024
	ds_read_b128 v[152:155], v138 offset:2048
	ds_read_b128 v[156:159], v138 offset:3072
	ds_read_b128 v[160:163], v139
	ds_read_b128 v[164:167], v139 offset:1024
	ds_read_b128 v[168:171], v139 offset:2048
	ds_read_b128 v[172:175], v139 offset:3072
	s_add_u32 s30, s38, 0xfffc0080
	s_addc_u32 s31, s39, -1
	s_cmp_eq_u32 s64, 12
	s_cselect_b32 s40, s24, s30
	s_cselect_b32 s41, s25, s31
	s_cselect_b32 s44, s26, s62
	s_cselect_b32 s45, s27, s63
	s_add_u32 s42, s40, 0x80
	s_addc_u32 s43, s41, 0
	ds_read_b128 v[178:181], v140
	ds_read_b128 v[182:185], v140 offset:1024
	ds_read_b128 v[186:189], v140 offset:2048
	ds_read_b128 v[190:193], v140 offset:3072
	ds_read_b128 v[194:197], v140 offset:4096
	ds_read_b128 v[198:201], v140 offset:5120
	ds_read_b128 v[202:205], v140 offset:6144
	ds_read_b128 v[206:209], v140 offset:7168
	s_mov_b32 m0, s55
	s_nop 0
	global_load_lds_dwordx4 v134, s[38:39]
	s_add_u32 s66, s38, 0x20000
	s_mov_b32 m0, s56
	s_addc_u32 s67, s39, 0
	global_load_lds_dwordx4 v134, s[66:67]
	s_waitcnt vmcnt(8) lgkmcnt(0)
	s_barrier
	v_mfma_f32_16x16x32_bf16 v[124:127], v[144:147], v[178:181], v[124:127]
	v_mfma_f32_16x16x32_bf16 v[120:123], v[152:155], v[178:181], v[120:123]
	v_mfma_f32_16x16x32_bf16 v[108:111], v[144:147], v[186:189], v[108:111]
	v_mfma_f32_16x16x32_bf16 v[104:107], v[152:155], v[186:189], v[104:107]
	v_mfma_f32_16x16x32_bf16 v[92:95], v[144:147], v[194:197], v[92:95]
	v_mfma_f32_16x16x32_bf16 v[88:91], v[152:155], v[194:197], v[88:91]
	v_mfma_f32_16x16x32_bf16 v[76:79], v[144:147], v[202:205], v[76:79]
	v_mfma_f32_16x16x32_bf16 v[72:75], v[152:155], v[202:205], v[72:75]
	v_mfma_f32_16x16x32_bf16 v[124:127], v[148:151], v[182:185], v[124:127]
	v_mfma_f32_16x16x32_bf16 v[120:123], v[156:159], v[182:185], v[120:123]
	v_mfma_f32_16x16x32_bf16 v[108:111], v[148:151], v[190:193], v[108:111]
	v_mfma_f32_16x16x32_bf16 v[104:107], v[156:159], v[190:193], v[104:107]
	v_mfma_f32_16x16x32_bf16 v[92:95], v[148:151], v[198:201], v[92:95]
	v_mfma_f32_16x16x32_bf16 v[88:91], v[156:159], v[198:201], v[88:91]
	v_mfma_f32_16x16x32_bf16 v[76:79], v[148:151], v[206:209], v[76:79]
	v_mfma_f32_16x16x32_bf16 v[72:75], v[156:159], v[206:209], v[72:75]
	v_mfma_f32_16x16x32_bf16 v[116:119], v[160:163], v[178:181], v[116:119]
	v_mfma_f32_16x16x32_bf16 v[112:115], v[168:171], v[178:181], v[112:115]
	v_mfma_f32_16x16x32_bf16 v[100:103], v[160:163], v[186:189], v[100:103]
	v_mfma_f32_16x16x32_bf16 v[96:99], v[168:171], v[186:189], v[96:99]
	v_mfma_f32_16x16x32_bf16 v[84:87], v[160:163], v[194:197], v[84:87]
	v_mfma_f32_16x16x32_bf16 v[80:83], v[168:171], v[194:197], v[80:83]
	v_mfma_f32_16x16x32_bf16 v[68:71], v[160:163], v[202:205], v[68:71]
	v_mfma_f32_16x16x32_bf16 v[64:67], v[168:171], v[202:205], v[64:67]
	v_mfma_f32_16x16x32_bf16 v[116:119], v[164:167], v[182:185], v[116:119]
	v_mfma_f32_16x16x32_bf16 v[112:115], v[172:175], v[182:185], v[112:115]
	v_mfma_f32_16x16x32_bf16 v[100:103], v[164:167], v[190:193], v[100:103]
	v_mfma_f32_16x16x32_bf16 v[96:99], v[172:175], v[190:193], v[96:99]
	v_mfma_f32_16x16x32_bf16 v[84:87], v[164:167], v[198:201], v[84:87]
	v_mfma_f32_16x16x32_bf16 v[80:83], v[172:175], v[198:201], v[80:83]
	v_mfma_f32_16x16x32_bf16 v[68:71], v[164:167], v[206:209], v[68:71]
	v_mfma_f32_16x16x32_bf16 v[64:67], v[172:175], v[206:209], v[64:67]
	s_add_i32 s64, s64, 2
	s_add_u32 s38, s38, 0x100
	s_addc_u32 s39, s39, 0
	s_add_u32 s62, s62, 0x100
	s_addc_u32 s63, s63, 0
	s_barrier
	s_add_u32 s66, s44, 0x20000
	ds_read_b128 v[178:181], v140 offset:16384
	ds_read_b128 v[182:185], v140 offset:17408
	ds_read_b128 v[186:189], v140 offset:18432
	ds_read_b128 v[190:193], v140 offset:19456
	ds_read_b128 v[194:197], v140 offset:20480
	ds_read_b128 v[198:201], v140 offset:21504
	ds_read_b128 v[202:205], v140 offset:22528
	ds_read_b128 v[206:209], v140 offset:23552
	s_mov_b32 m0, s33
	s_nop 0
	global_load_lds_dwordx4 v135, s[44:45]
	s_mov_b32 m0, s34
	s_addc_u32 s67, s45, 0
	global_load_lds_dwordx4 v135, s[66:67]
	s_add_u32 s66, s44, 0x40000
	s_mov_b32 m0, s35
	s_addc_u32 s67, s45, 0
	global_load_lds_dwordx4 v135, s[66:67]
	s_add_u32 s66, s44, 0x60000
	s_mov_b32 m0, s36
	s_addc_u32 s67, s45, 0
	global_load_lds_dwordx4 v135, s[66:67]
	s_mov_b32 m0, s12
	s_nop 0
	global_load_lds_dwordx4 v134, s[40:41]
	s_add_u32 s66, s40, 0x20000
	s_mov_b32 m0, s37
	s_addc_u32 s67, s41, 0
	global_load_lds_dwordx4 v134, s[66:67]
	s_waitcnt vmcnt(8) lgkmcnt(0)
	s_barrier
	v_mfma_f32_16x16x32_bf16 v[60:63], v[144:147], v[178:181], v[60:63]
	v_mfma_f32_16x16x32_bf16 v[56:59], v[152:155], v[178:181], v[56:59]
	v_mfma_f32_16x16x32_bf16 v[44:47], v[144:147], v[186:189], v[44:47]
	v_mfma_f32_16x16x32_bf16 v[40:43], v[152:155], v[186:189], v[40:43]
	v_mfma_f32_16x16x32_bf16 v[28:31], v[144:147], v[194:197], v[28:31]
	v_mfma_f32_16x16x32_bf16 v[24:27], v[152:155], v[194:197], v[24:27]
	v_mfma_f32_16x16x32_bf16 v[12:15], v[144:147], v[202:205], v[12:15]
	v_mfma_f32_16x16x32_bf16 v[8:11], v[152:155], v[202:205], v[8:11]
	v_mfma_f32_16x16x32_bf16 v[60:63], v[148:151], v[182:185], v[60:63]
	v_mfma_f32_16x16x32_bf16 v[56:59], v[156:159], v[182:185], v[56:59]
	v_mfma_f32_16x16x32_bf16 v[44:47], v[148:151], v[190:193], v[44:47]
	v_mfma_f32_16x16x32_bf16 v[40:43], v[156:159], v[190:193], v[40:43]
	v_mfma_f32_16x16x32_bf16 v[28:31], v[148:151], v[198:201], v[28:31]
	v_mfma_f32_16x16x32_bf16 v[24:27], v[156:159], v[198:201], v[24:27]
	v_mfma_f32_16x16x32_bf16 v[12:15], v[148:151], v[206:209], v[12:15]
	v_mfma_f32_16x16x32_bf16 v[8:11], v[156:159], v[206:209], v[8:11]
	v_mfma_f32_16x16x32_bf16 v[52:55], v[160:163], v[178:181], v[52:55]
	v_mfma_f32_16x16x32_bf16 v[48:51], v[168:171], v[178:181], v[48:51]
	v_mfma_f32_16x16x32_bf16 v[36:39], v[160:163], v[186:189], v[36:39]
	v_mfma_f32_16x16x32_bf16 v[32:35], v[168:171], v[186:189], v[32:35]
	v_mfma_f32_16x16x32_bf16 v[20:23], v[160:163], v[194:197], v[20:23]
	v_mfma_f32_16x16x32_bf16 v[16:19], v[168:171], v[194:197], v[16:19]
	v_mfma_f32_16x16x32_bf16 v[4:7], v[160:163], v[202:205], v[4:7]
	v_mfma_f32_16x16x32_bf16 v[0:3], v[168:171], v[202:205], v[0:3]
	v_mfma_f32_16x16x32_bf16 v[52:55], v[164:167], v[182:185], v[52:55]
	v_mfma_f32_16x16x32_bf16 v[48:51], v[172:175], v[182:185], v[48:51]
	v_mfma_f32_16x16x32_bf16 v[36:39], v[164:167], v[190:193], v[36:39]
	v_mfma_f32_16x16x32_bf16 v[32:35], v[172:175], v[190:193], v[32:35]
	v_mfma_f32_16x16x32_bf16 v[20:23], v[164:167], v[198:201], v[20:23]
	v_mfma_f32_16x16x32_bf16 v[16:19], v[172:175], v[198:201], v[16:19]
	v_mfma_f32_16x16x32_bf16 v[4:7], v[164:167], v[206:209], v[4:7]
	v_mfma_f32_16x16x32_bf16 v[0:3], v[172:175], v[206:209], v[0:3]
	s_barrier
; #define PG8_STAGE(bufoff, gbase, voff, p64) do { _Pragma("unroll") for (int _i = 0; _i < 2; ++_i) { \
;         const char* _gb = (const char*)(gbase) + (size_t)_i * (p64); const unsigned _la = ldsbase + (unsigned)(bufoff) + (unsigned)_i * 8192u; \
;         asm volatile("s_mov_b32 m0, %0\n\ts_nop 0\n\tglobal_load_lds_dwordx4 %1, %2" :: "s"(_la), "v"(voff), "s"(_gb) : "memory"); } } while (0)
; #define PG8_LDA(dst, b, h) do { _Pragma("unroll") for (int m = 0; m < 4; ++m) _Pragma("unroll") for (int k = 0; k < 2; ++k) dst[m][k] = *(const LAS bf16x8*)(lds + PG8_SA(b, h) + aoff + m * 2048 + k * 1024); } while (0)
; #define PG8_LDB(dst, b, h) do { _Pragma("unroll") for (int n = 0; n < 2; ++n) _Pragma("unroll") for (int k = 0; k < 2; ++k) dst[n][k] = *(const LAS bf16x8*)(lds + PG8_SB(b, h) + boff + n * 2048 + k * 1024); } while (0)
; #define PG8_MMA(ai, bj, At, Bt) do { __builtin_amdgcn_s_setprio(1); _Pragma("unroll") for (int m = 0; m < 4; ++m) _Pragma("unroll") for (int n = 0; n < 2; ++n) _Pragma("unroll") for (int k = 0; k < 2; ++k) \
;         acc[ai][bj][m][n] = __builtin_amdgcn_mfma_f32_16x16x32_bf16(Bt[n][k], At[m][k], acc[ai][bj][m][n], 0, 0, 0); __builtin_amdgcn_s_setprio(0); } while (0)
; #define PG8_WAIT_V(n) asm volatile("s_waitcnt vmcnt(" #n ")" ::: "memory")
; #define PG8_WAIT_L(n) asm volatile("s_waitcnt lgkmcnt(" #n ")" ::: "memory")
; #define PG8_BAR __builtin_amdgcn_s_barrier()
; #define PG8_SCHED __builtin_amdgcn_sched_barrier(0)
; template <class Epi, class Sched>
; __device__ __forceinline__ void gemm_phase(LAS unsigned char* lds, const Sched& S, const Epi& E) {
;     ...
;             PG8_LDB(B0, 1, 0); PG8_LDB(B1, 1, 1); PG8_SCHED; PG8_LDA(At, 1, 0); PG8_STAGE(PG8_SA(0, 1), a2 + hA2, vA2, hA2 / 2);
;             PG8_WAIT_V(8); PG8_WAIT_L(0); PG8_BAR; PG8_MMA(0, 0, At, B0); PG8_MMA(0, 1, At, B1); PG8_BAR; PG8_SCHED;
;             PG8_LDA(At, 1, 1); PG8_STAGE(PG8_SB(1, 0), b3, vB2, hB2 / 2); PG8_STAGE(PG8_SB(1, 1), b3 + hB2, vB2, hB2 / 2); PG8_STAGE(PG8_SA(1, 0), a3, vA2, hA2 / 2);
;             PG8_WAIT_V(8); PG8_WAIT_L(0); PG8_BAR; PG8_MMA(1, 0, At, B0); PG8_MMA(1, 1, At, B1); PG8_BAR; PG8_SCHED;
;         }
;         if (wr == 0) PG8_BAR;
.Lpeel_mid_5680:
	ds_read_b128 v[144:147], v141
	ds_read_b128 v[148:151], v141 offset:1024
	ds_read_b128 v[152:155], v141 offset:2048
	ds_read_b128 v[156:159], v141 offset:3072
	ds_read_b128 v[160:163], v142
	ds_read_b128 v[164:167], v142 offset:1024
	ds_read_b128 v[168:171], v142 offset:2048
	ds_read_b128 v[172:175], v142 offset:3072
	ds_read_b128 v[178:181], v140 offset:32768
	ds_read_b128 v[182:185], v140 offset:33792
	ds_read_b128 v[186:189], v140 offset:34816
	ds_read_b128 v[190:193], v140 offset:35840
	ds_read_b128 v[194:197], v140 offset:36864
	ds_read_b128 v[198:201], v140 offset:37888
	ds_read_b128 v[202:205], v140 offset:38912
	ds_read_b128 v[206:209], v140 offset:39936
	s_add_u32 s66, s40, 0x40000
	s_mov_b32 m0, s46
	s_addc_u32 s67, s41, 0
	global_load_lds_dwordx4 v134, s[66:67]
	s_add_u32 s66, s40, 0x60000
	s_mov_b32 m0, s47
	s_addc_u32 s67, s41, 0
	global_load_lds_dwordx4 v134, s[66:67]
	s_waitcnt vmcnt(8) lgkmcnt(0)
	s_barrier
	v_mfma_f32_16x16x32_bf16 v[124:127], v[144:147], v[178:181], v[124:127]
	v_mfma_f32_16x16x32_bf16 v[120:123], v[152:155], v[178:181], v[120:123]
	v_mfma_f32_16x16x32_bf16 v[108:111], v[144:147], v[186:189], v[108:111]
	v_mfma_f32_16x16x32_bf16 v[104:107], v[152:155], v[186:189], v[104:107]
	v_mfma_f32_16x16x32_bf16 v[92:95], v[144:147], v[194:197], v[92:95]
	v_mfma_f32_16x16x32_bf16 v[88:91], v[152:155], v[194:197], v[88:91]
	v_mfma_f32_16x16x32_bf16 v[76:79], v[144:147], v[202:205], v[76:79]
	v_mfma_f32_16x16x32_bf16 v[72:75], v[152:155], v[202:205], v[72:75]
	v_mfma_f32_16x16x32_bf16 v[124:127], v[148:151], v[182:185], v[124:127]
	v_mfma_f32_16x16x32_bf16 v[120:123], v[156:159], v[182:185], v[120:123]
	v_mfma_f32_16x16x32_bf16 v[108:111], v[148:151], v[190:193], v[108:111]
	v_mfma_f32_16x16x32_bf16 v[104:107], v[156:159], v[190:193], v[104:107]
	v_mfma_f32_16x16x32_bf16 v[92:95], v[148:151], v[198:201], v[92:95]
	v_mfma_f32_16x16x32_bf16 v[88:91], v[156:159], v[198:201], v[88:91]
	v_mfma_f32_16x16x32_bf16 v[76:79], v[148:151], v[206:209], v[76:79]
	v_mfma_f32_16x16x32_bf16 v[72:75], v[156:159], v[206:209], v[72:75]
	v_mfma_f32_16x16x32_bf16 v[116:119], v[160:163], v[178:181], v[116:119]
	v_mfma_f32_16x16x32_bf16 v[112:115], v[168:171], v[178:181], v[112:115]
	v_mfma_f32_16x16x32_bf16 v[100:103], v[160:163], v[186:189], v[100:103]
	v_mfma_f32_16x16x32_bf16 v[96:99], v[168:171], v[186:189], v[96:99]
	v_mfma_f32_16x16x32_bf16 v[84:87], v[160:163], v[194:197], v[84:87]
	v_mfma_f32_16x16x32_bf16 v[80:83], v[168:171], v[194:197], v[80:83]
	v_mfma_f32_16x16x32_bf16 v[68:71], v[160:163], v[202:205], v[68:71]
	v_mfma_f32_16x16x32_bf16 v[64:67], v[168:171], v[202:205], v[64:67]
	v_mfma_f32_16x16x32_bf16 v[116:119], v[164:167], v[182:185], v[116:119]
	v_mfma_f32_16x16x32_bf16 v[112:115], v[172:175], v[182:185], v[112:115]
	v_mfma_f32_16x16x32_bf16 v[100:103], v[164:167], v[190:193], v[100:103]
	v_mfma_f32_16x16x32_bf16 v[96:99], v[172:175], v[190:193], v[96:99]
	v_mfma_f32_16x16x32_bf16 v[84:87], v[164:167], v[198:201], v[84:87]
	v_mfma_f32_16x16x32_bf16 v[80:83], v[172:175], v[198:201], v[80:83]
	v_mfma_f32_16x16x32_bf16 v[68:71], v[164:167], v[206:209], v[68:71]
	v_mfma_f32_16x16x32_bf16 v[64:67], v[172:175], v[206:209], v[64:67]
	s_barrier
	s_add_u32 s66, s44, 0x80
	s_addc_u32 s67, s45, 0
	ds_read_b128 v[178:181], v140 offset:49152
	ds_read_b128 v[182:185], v140 offset:50176
	ds_read_b128 v[186:189], v140 offset:51200
	ds_read_b128 v[190:193], v140 offset:52224
	ds_read_b128 v[194:197], v140 offset:53248
	ds_read_b128 v[198:201], v140 offset:54272
	ds_read_b128 v[202:205], v140 offset:55296
	ds_read_b128 v[206:209], v140 offset:56320
	s_mov_b32 m0, s49
	s_nop 0
	global_load_lds_dwordx4 v135, s[66:67]
	s_add_u32 s66, s44, 0x20080
	s_mov_b32 m0, s50
	s_addc_u32 s67, s45, 0
	global_load_lds_dwordx4 v135, s[66:67]
	s_add_u32 s66, s44, 0x40080
	s_mov_b32 m0, s53
	s_addc_u32 s67, s45, 0
	global_load_lds_dwordx4 v135, s[66:67]
	s_add_u32 s44, s44, 0x60080
	s_mov_b32 m0, s54
	s_addc_u32 s45, s45, 0
	global_load_lds_dwordx4 v135, s[44:45]
	s_mov_b32 m0, s51
	s_nop 0
	global_load_lds_dwordx4 v134, s[42:43]
	s_add_u32 s40, s40, 0x20080
	s_mov_b32 m0, s52
	s_addc_u32 s41, s41, 0
	global_load_lds_dwordx4 v134, s[40:41]
	s_waitcnt vmcnt(8) lgkmcnt(0)
	s_barrier
	v_mfma_f32_16x16x32_bf16 v[60:63], v[144:147], v[178:181], v[60:63]
	v_mfma_f32_16x16x32_bf16 v[56:59], v[152:155], v[178:181], v[56:59]
	v_mfma_f32_16x16x32_bf16 v[44:47], v[144:147], v[186:189], v[44:47]
	v_mfma_f32_16x16x32_bf16 v[40:43], v[152:155], v[186:189], v[40:43]
	v_mfma_f32_16x16x32_bf16 v[28:31], v[144:147], v[194:197], v[28:31]
	v_mfma_f32_16x16x32_bf16 v[24:27], v[152:155], v[194:197], v[24:27]
	v_mfma_f32_16x16x32_bf16 v[12:15], v[144:147], v[202:205], v[12:15]
	v_mfma_f32_16x16x32_bf16 v[8:11], v[152:155], v[202:205], v[8:11]
	v_mfma_f32_16x16x32_bf16 v[60:63], v[148:151], v[182:185], v[60:63]
	v_mfma_f32_16x16x32_bf16 v[56:59], v[156:159], v[182:185], v[56:59]
	v_mfma_f32_16x16x32_bf16 v[44:47], v[148:151], v[190:193], v[44:47]
	v_mfma_f32_16x16x32_bf16 v[40:43], v[156:159], v[190:193], v[40:43]
	v_mfma_f32_16x16x32_bf16 v[28:31], v[148:151], v[198:201], v[28:31]
	v_mfma_f32_16x16x32_bf16 v[24:27], v[156:159], v[198:201], v[24:27]
	v_mfma_f32_16x16x32_bf16 v[12:15], v[148:151], v[206:209], v[12:15]
	v_mfma_f32_16x16x32_bf16 v[8:11], v[156:159], v[206:209], v[8:11]
	v_mfma_f32_16x16x32_bf16 v[52:55], v[160:163], v[178:181], v[52:55]
	v_mfma_f32_16x16x32_bf16 v[48:51], v[168:171], v[178:181], v[48:51]
	v_mfma_f32_16x16x32_bf16 v[36:39], v[160:163], v[186:189], v[36:39]
	v_mfma_f32_16x16x32_bf16 v[32:35], v[168:171], v[186:189], v[32:35]
	v_mfma_f32_16x16x32_bf16 v[20:23], v[160:163], v[194:197], v[20:23]
	v_mfma_f32_16x16x32_bf16 v[16:19], v[168:171], v[194:197], v[16:19]
	v_mfma_f32_16x16x32_bf16 v[4:7], v[160:163], v[202:205], v[4:7]
	v_mfma_f32_16x16x32_bf16 v[0:3], v[168:171], v[202:205], v[0:3]
	v_mfma_f32_16x16x32_bf16 v[52:55], v[164:167], v[182:185], v[52:55]
	v_mfma_f32_16x16x32_bf16 v[48:51], v[172:175], v[182:185], v[48:51]
	v_mfma_f32_16x16x32_bf16 v[36:39], v[164:167], v[190:193], v[36:39]
	v_mfma_f32_16x16x32_bf16 v[32:35], v[172:175], v[190:193], v[32:35]
	v_mfma_f32_16x16x32_bf16 v[20:23], v[164:167], v[198:201], v[20:23]
	v_mfma_f32_16x16x32_bf16 v[16:19], v[172:175], v[198:201], v[16:19]
	v_mfma_f32_16x16x32_bf16 v[4:7], v[164:167], v[206:209], v[4:7]
	v_mfma_f32_16x16x32_bf16 v[0:3], v[172:175], v[206:209], v[0:3]
	s_barrier
	s_cmp_gt_u32 s64, 13
	s_cbranch_scc0 .LBB0_304
	s_and_b64 vcc, exec, s[18:19]
	s_cbranch_vccz .LBB0_307
	s_barrier

; #define PG8_STAGE(bufoff, gbase, voff, p64) do { _Pragma("unroll") for (int _i = 0; _i < 2; ++_i) { \
;         const char* _gb = (const char*)(gbase) + (size_t)_i * (p64); const unsigned _la = ldsbase + (unsigned)(bufoff) + (unsigned)_i * 8192u; \
;         asm volatile("s_mov_b32 m0, %0\n\ts_nop 0\n\tglobal_load_lds_dwordx4 %1, %2" :: "s"(_la), "v"(voff), "s"(_gb) : "memory"); } } while (0)
; #define PG8_LDA(dst, b, h) do { _Pragma("unroll") for (int m = 0; m < 4; ++m) _Pragma("unroll") for (int k = 0; k < 2; ++k) dst[m][k] = *(const LAS bf16x8*)(lds + PG8_SA(b, h) + aoff + m * 2048 + k * 1024); } while (0)
; #define PG8_LDB(dst, b, h) do { _Pragma("unroll") for (int n = 0; n < 2; ++n) _Pragma("unroll") for (int k = 0; k < 2; ++k) dst[n][k] = *(const LAS bf16x8*)(lds + PG8_SB(b, h) + boff + n * 2048 + k * 1024); } while (0)
; #define PG8_MMA(ai, bj, At, Bt) do { __builtin_amdgcn_s_setprio(1); _Pragma("unroll") for (int m = 0; m < 4; ++m) _Pragma("unroll") for (int n = 0; n < 2; ++n) _Pragma("unroll") for (int k = 0; k < 2; ++k) \
;         acc[ai][bj][m][n] = __builtin_amdgcn_mfma_f32_16x16x32_bf16(Bt[n][k], At[m][k], acc[ai][bj][m][n], 0, 0, 0); __builtin_amdgcn_s_setprio(0); } while (0)
; #define PG8_WAIT_V(n) asm volatile("s_waitcnt vmcnt(" #n ")" ::: "memory")
; template <class Epi, class Sched>
; __device__ __forceinline__ void gemm_phase(LAS unsigned char* lds, const Sched& S, const Epi& E) {
;     ...
;         for (int t = 0; t < nt; t += 2) {
;             const bool last = (t == nt - 2);
;             const char* a1 = cA + (size_t)(t + 1) * kstep;
;             const char* a2 = last ? nA : cA + (size_t)(t + 2) * kstep; const char* b2 = last ? nB : cB + (size_t)(t + 2) * kstep;
;             const char* a3 = a2 + kstep; const char* b3 = b2 + kstep;
;             const unsigned vA2 = voffA, vB2 = voffB, hA2 = hA, hB2 = hB;
;             PG8_LDB(B0, 0, 0); PG8_LDB(B1, 0, 1); PG8_SCHED; PG8_LDA(At, 0, 0); PG8_STAGE(PG8_SA(1, 1), a1 + hA, voffA, hA / 2);
;             PG8_WAIT_V(8); PG8_WAIT_L(0); PG8_BAR; PG8_MMA(0, 0, At, B0); PG8_MMA(0, 1, At, B1); PG8_BAR; PG8_SCHED;
;             PG8_LDA(At, 0, 1); PG8_STAGE(PG8_SB(0, 0), b2, vB2, hB2 / 2); PG8_STAGE(PG8_SB(0, 1), b2 + hB2, vB2, hB2 / 2); PG8_STAGE(PG8_SA(0, 0), a2, vA2, hA2 / 2);
;             PG8_WAIT_V(8); PG8_WAIT_L(0); PG8_BAR; PG8_MMA(1, 0, At, B0); PG8_MMA(1, 1, At, B1); PG8_BAR; PG8_SCHED;
.LBB0_397:
	s_and_b64 s[42:43], s[26:27], exec
	s_cselect_b32 s44, s25, s41
	s_cselect_b32 s45, s24, s40
	s_cselect_b32 s66, s23, s39
	s_cselect_b32 s67, s22, s38
	s_add_i32 s68, s21, -2
	s_add_u32 s69, s38, 0x100
	s_addc_u32 s70, s39, 0
	s_add_u32 s71, s40, 0x100
	s_addc_u32 s72, s41, 0
	s_mov_b32 s38, 0
	ds_read_b128 v[130:133], v164
	ds_read_b128 v[134:137], v164 offset:1024
	ds_read_b128 v[138:141], v164 offset:2048
	ds_read_b128 v[142:145], v164 offset:3072
	ds_read_b128 v[146:149], v165
	ds_read_b128 v[150:153], v165 offset:1024
	ds_read_b128 v[154:157], v165 offset:2048
	ds_read_b128 v[158:161], v165 offset:3072
	s_add_i32 s73, s38, 2
	s_cmp_eq_u32 s68, s38
	s_cselect_b32 s38, s67, s69
	s_cselect_b32 s39, s66, s70
	s_cselect_b32 s42, s45, s71
	s_cselect_b32 s43, s44, s72
	s_add_u32 s40, s38, 0x80
	s_addc_u32 s41, s39, 0
	ds_read_b128 v[170:173], v166
	ds_read_b128 v[178:181], v166 offset:1024
	ds_read_b128 v[182:185], v166 offset:2048
	ds_read_b128 v[186:189], v166 offset:3072
	ds_read_b128 v[190:193], v166 offset:4096
	ds_read_b128 v[194:197], v166 offset:5120
	ds_read_b128 v[198:201], v166 offset:6144
	ds_read_b128 v[202:205], v166 offset:7168
	s_add_u32 s74, s69, 0xaff80
	s_mov_b32 m0, s59
	s_addc_u32 s75, s70, 0
	global_load_lds_dwordx4 v128, s[74:75]
	s_add_u32 s74, s69, 0x107f80
	s_mov_b32 m0, s60
	s_addc_u32 s75, s70, 0
	global_load_lds_dwordx4 v128, s[74:75]
	s_waitcnt vmcnt(8) lgkmcnt(0)
	s_barrier
	v_mfma_f32_16x16x32_bf16 v[124:127], v[130:133], v[170:173], 0
	v_mfma_f32_16x16x32_bf16 v[120:123], v[138:141], v[170:173], 0
	v_mfma_f32_16x16x32_bf16 v[116:119], v[130:133], v[182:185], 0
	v_mfma_f32_16x16x32_bf16 v[112:115], v[138:141], v[182:185], 0
	v_mfma_f32_16x16x32_bf16 v[108:111], v[130:133], v[190:193], 0
	v_mfma_f32_16x16x32_bf16 v[104:107], v[138:141], v[190:193], 0
	v_mfma_f32_16x16x32_bf16 v[100:103], v[130:133], v[198:201], 0
	v_mfma_f32_16x16x32_bf16 v[96:99], v[138:141], v[198:201], 0
	v_mfma_f32_16x16x32_bf16 v[124:127], v[134:137], v[178:181], v[124:127]
	v_mfma_f32_16x16x32_bf16 v[120:123], v[142:145], v[178:181], v[120:123]
	v_mfma_f32_16x16x32_bf16 v[116:119], v[134:137], v[186:189], v[116:119]
	v_mfma_f32_16x16x32_bf16 v[112:115], v[142:145], v[186:189], v[112:115]
	v_mfma_f32_16x16x32_bf16 v[108:111], v[134:137], v[194:197], v[108:111]
	v_mfma_f32_16x16x32_bf16 v[104:107], v[142:145], v[194:197], v[104:107]
	v_mfma_f32_16x16x32_bf16 v[100:103], v[134:137], v[202:205], v[100:103]
	v_mfma_f32_16x16x32_bf16 v[96:99], v[142:145], v[202:205], v[96:99]
	v_mfma_f32_16x16x32_bf16 v[60:63], v[146:149], v[170:173], 0
	v_mfma_f32_16x16x32_bf16 v[56:59], v[154:157], v[170:173], 0
	v_mfma_f32_16x16x32_bf16 v[52:55], v[146:149], v[182:185], 0
	v_mfma_f32_16x16x32_bf16 v[48:51], v[154:157], v[182:185], 0
	v_mfma_f32_16x16x32_bf16 v[44:47], v[146:149], v[190:193], 0
	v_mfma_f32_16x16x32_bf16 v[40:43], v[154:157], v[190:193], 0
	v_mfma_f32_16x16x32_bf16 v[36:39], v[146:149], v[198:201], 0
	v_mfma_f32_16x16x32_bf16 v[32:35], v[154:157], v[198:201], 0
	v_mfma_f32_16x16x32_bf16 v[60:63], v[150:153], v[178:181], v[60:63]
	v_mfma_f32_16x16x32_bf16 v[56:59], v[158:161], v[178:181], v[56:59]
	v_mfma_f32_16x16x32_bf16 v[52:55], v[150:153], v[186:189], v[52:55]
	v_mfma_f32_16x16x32_bf16 v[48:51], v[158:161], v[186:189], v[48:51]
	v_mfma_f32_16x16x32_bf16 v[44:47], v[150:153], v[194:197], v[44:47]
	v_mfma_f32_16x16x32_bf16 v[40:43], v[158:161], v[194:197], v[40:43]
	v_mfma_f32_16x16x32_bf16 v[36:39], v[150:153], v[202:205], v[36:39]
	v_mfma_f32_16x16x32_bf16 v[32:35], v[158:161], v[202:205], v[32:35]
	s_add_u32 s69, s69, 0x100
	s_addc_u32 s70, s70, 0
	s_add_u32 s71, s71, 0x100
	s_addc_u32 s72, s72, 0
	s_barrier
	s_add_u32 s74, s42, 0x58000
	ds_read_b128 v[170:173], v166 offset:16384
	ds_read_b128 v[178:181], v166 offset:17408
	ds_read_b128 v[182:185], v166 offset:18432
	ds_read_b128 v[186:189], v166 offset:19456
	ds_read_b128 v[190:193], v166 offset:20480
	ds_read_b128 v[194:197], v166 offset:21504
	ds_read_b128 v[198:201], v166 offset:22528
	ds_read_b128 v[202:205], v166 offset:23552
	s_mov_b32 m0, s15
	s_nop 0
	global_load_lds_dwordx4 v129, s[42:43]
	s_mov_b32 m0, s33
	s_addc_u32 s75, s43, 0
	global_load_lds_dwordx4 v129, s[74:75]
	s_add_u32 s74, s42, 0xb0000
	s_mov_b32 m0, s34
	s_addc_u32 s75, s43, 0
	global_load_lds_dwordx4 v129, s[74:75]
	s_add_u32 s74, s42, 0x108000
	s_mov_b32 m0, s35
	s_addc_u32 s75, s43, 0
	global_load_lds_dwordx4 v129, s[74:75]
	s_mov_b32 m0, s14
	s_nop 0
	global_load_lds_dwordx4 v128, s[38:39]
	s_add_u32 s74, s38, 0x58000
	s_mov_b32 m0, s36
	s_addc_u32 s75, s39, 0
	global_load_lds_dwordx4 v128, s[74:75]
	s_waitcnt vmcnt(8) lgkmcnt(0)
	s_barrier
	v_mfma_f32_16x16x32_bf16 v[92:95], v[130:133], v[170:173], 0
	v_mfma_f32_16x16x32_bf16 v[88:91], v[138:141], v[170:173], 0
	v_mfma_f32_16x16x32_bf16 v[84:87], v[130:133], v[182:185], 0
	v_mfma_f32_16x16x32_bf16 v[80:83], v[138:141], v[182:185], 0
	v_mfma_f32_16x16x32_bf16 v[76:79], v[130:133], v[190:193], 0
	v_mfma_f32_16x16x32_bf16 v[72:75], v[138:141], v[190:193], 0
	v_mfma_f32_16x16x32_bf16 v[68:71], v[130:133], v[198:201], 0
	v_mfma_f32_16x16x32_bf16 v[64:67], v[138:141], v[198:201], 0
	v_mfma_f32_16x16x32_bf16 v[92:95], v[134:137], v[178:181], v[92:95]
	v_mfma_f32_16x16x32_bf16 v[88:91], v[142:145], v[178:181], v[88:91]
	v_mfma_f32_16x16x32_bf16 v[84:87], v[134:137], v[186:189], v[84:87]
	v_mfma_f32_16x16x32_bf16 v[80:83], v[142:145], v[186:189], v[80:83]
	v_mfma_f32_16x16x32_bf16 v[76:79], v[134:137], v[194:197], v[76:79]
	v_mfma_f32_16x16x32_bf16 v[72:75], v[142:145], v[194:197], v[72:75]
	v_mfma_f32_16x16x32_bf16 v[68:71], v[134:137], v[202:205], v[68:71]
	v_mfma_f32_16x16x32_bf16 v[64:67], v[142:145], v[202:205], v[64:67]
	v_mfma_f32_16x16x32_bf16 v[28:31], v[146:149], v[170:173], 0
	v_mfma_f32_16x16x32_bf16 v[24:27], v[154:157], v[170:173], 0
	v_mfma_f32_16x16x32_bf16 v[20:23], v[146:149], v[182:185], 0
	v_mfma_f32_16x16x32_bf16 v[16:19], v[154:157], v[182:185], 0
	v_mfma_f32_16x16x32_bf16 v[12:15], v[146:149], v[190:193], 0
	v_mfma_f32_16x16x32_bf16 v[8:11], v[154:157], v[190:193], 0
	v_mfma_f32_16x16x32_bf16 v[4:7], v[146:149], v[198:201], 0
	v_mfma_f32_16x16x32_bf16 v[0:3], v[154:157], v[198:201], 0
	v_mfma_f32_16x16x32_bf16 v[28:31], v[150:153], v[178:181], v[28:31]
	v_mfma_f32_16x16x32_bf16 v[24:27], v[158:161], v[178:181], v[24:27]
	v_mfma_f32_16x16x32_bf16 v[20:23], v[150:153], v[186:189], v[20:23]
	v_mfma_f32_16x16x32_bf16 v[16:19], v[158:161], v[186:189], v[16:19]
	v_mfma_f32_16x16x32_bf16 v[12:15], v[150:153], v[194:197], v[12:15]
	v_mfma_f32_16x16x32_bf16 v[8:11], v[158:161], v[194:197], v[8:11]
	v_mfma_f32_16x16x32_bf16 v[4:7], v[150:153], v[202:205], v[4:7]
	v_mfma_f32_16x16x32_bf16 v[0:3], v[158:161], v[202:205], v[0:3]
	s_barrier
	s_branch .Lpeel_mid_7711
; #define PG8_STAGE(bufoff, gbase, voff, p64) do { _Pragma("unroll") for (int _i = 0; _i < 2; ++_i) { \
;         const char* _gb = (const char*)(gbase) + (size_t)_i * (p64); const unsigned _la = ldsbase + (unsigned)(bufoff) + (unsigned)_i * 8192u; \
;         asm volatile("s_mov_b32 m0, %0\n\ts_nop 0\n\tglobal_load_lds_dwordx4 %1, %2" :: "s"(_la), "v"(voff), "s"(_gb) : "memory"); } } while (0)
; #define PG8_LDA(dst, b, h) do { _Pragma("unroll") for (int m = 0; m < 4; ++m) _Pragma("unroll") for (int k = 0; k < 2; ++k) dst[m][k] = *(const LAS bf16x8*)(lds + PG8_SA(b, h) + aoff + m * 2048 + k * 1024); } while (0)
; #define PG8_LDB(dst, b, h) do { _Pragma("unroll") for (int n = 0; n < 2; ++n) _Pragma("unroll") for (int k = 0; k < 2; ++k) dst[n][k] = *(const LAS bf16x8*)(lds + PG8_SB(b, h) + boff + n * 2048 + k * 1024); } while (0)
; #define PG8_MMA(ai, bj, At, Bt) do { __builtin_amdgcn_s_setprio(1); _Pragma("unroll") for (int m = 0; m < 4; ++m) _Pragma("unroll") for (int n = 0; n < 2; ++n) _Pragma("unroll") for (int k = 0; k < 2; ++k) \
;         acc[ai][bj][m][n] = __builtin_amdgcn_mfma_f32_16x16x32_bf16(Bt[n][k], At[m][k], acc[ai][bj][m][n], 0, 0, 0); __builtin_amdgcn_s_setprio(0); } while (0)
; #define PG8_WAIT_V(n) asm volatile("s_waitcnt vmcnt(" #n ")" ::: "memory")
; #define PG8_BAR __builtin_amdgcn_s_barrier()
; template <class Epi, class Sched>
; __device__ __forceinline__ void gemm_phase(LAS unsigned char* lds, const Sched& S, const Epi& E) {
;     ...
;             const bool last = (t == nt - 2);
;             const char* a1 = cA + (size_t)(t + 1) * kstep;
;             const char* a2 = last ? nA : cA + (size_t)(t + 2) * kstep; const char* b2 = last ? nB : cB + (size_t)(t + 2) * kstep;
;             const char* a3 = a2 + kstep; const char* b3 = b2 + kstep;
;             const unsigned vA2 = voffA, vB2 = voffB, hA2 = hA, hB2 = hB;
;             PG8_LDB(B0, 0, 0); PG8_LDB(B1, 0, 1); PG8_SCHED; PG8_LDA(At, 0, 0); PG8_STAGE(PG8_SA(1, 1), a1 + hA, voffA, hA / 2);
;             PG8_WAIT_V(8); PG8_WAIT_L(0); PG8_BAR; PG8_MMA(0, 0, At, B0); PG8_MMA(0, 1, At, B1); PG8_BAR; PG8_SCHED;
;             PG8_LDA(At, 0, 1); PG8_STAGE(PG8_SB(0, 0), b2, vB2, hB2 / 2); PG8_STAGE(PG8_SB(0, 1), b2 + hB2, vB2, hB2 / 2); PG8_STAGE(PG8_SA(0, 0), a2, vA2, hA2 / 2);
;             PG8_WAIT_V(8); PG8_WAIT_L(0); PG8_BAR; PG8_MMA(1, 0, At, B0); PG8_MMA(1, 1, At, B1); PG8_BAR; PG8_SCHED;
.LBB0_398:
	ds_read_b128 v[130:133], v164
	ds_read_b128 v[134:137], v164 offset:1024
	ds_read_b128 v[138:141], v164 offset:2048
	ds_read_b128 v[142:145], v164 offset:3072
	ds_read_b128 v[146:149], v165
	ds_read_b128 v[150:153], v165 offset:1024
	ds_read_b128 v[154:157], v165 offset:2048
	ds_read_b128 v[158:161], v165 offset:3072
	s_add_i32 s73, s38, 2
	s_cmp_eq_u32 s68, s38
	s_cselect_b32 s38, s67, s69
	s_cselect_b32 s39, s66, s70
	s_cselect_b32 s42, s45, s71
	s_cselect_b32 s43, s44, s72
	s_add_u32 s40, s38, 0x80
	s_addc_u32 s41, s39, 0
	ds_read_b128 v[170:173], v166
	ds_read_b128 v[178:181], v166 offset:1024
	ds_read_b128 v[182:185], v166 offset:2048
	ds_read_b128 v[186:189], v166 offset:3072
	ds_read_b128 v[190:193], v166 offset:4096
	ds_read_b128 v[194:197], v166 offset:5120
	ds_read_b128 v[198:201], v166 offset:6144
	ds_read_b128 v[202:205], v166 offset:7168
	s_add_u32 s74, s69, 0xaff80
	s_mov_b32 m0, s59
	s_addc_u32 s75, s70, 0
	global_load_lds_dwordx4 v128, s[74:75]
	s_add_u32 s74, s69, 0x107f80
	s_mov_b32 m0, s60
	s_addc_u32 s75, s70, 0
	global_load_lds_dwordx4 v128, s[74:75]
	s_waitcnt vmcnt(8) lgkmcnt(0)
	s_barrier
	v_mfma_f32_16x16x32_bf16 v[124:127], v[130:133], v[170:173], v[124:127]
	v_mfma_f32_16x16x32_bf16 v[120:123], v[138:141], v[170:173], v[120:123]
	v_mfma_f32_16x16x32_bf16 v[116:119], v[130:133], v[182:185], v[116:119]
	v_mfma_f32_16x16x32_bf16 v[112:115], v[138:141], v[182:185], v[112:115]
	v_mfma_f32_16x16x32_bf16 v[108:111], v[130:133], v[190:193], v[108:111]
	v_mfma_f32_16x16x32_bf16 v[104:107], v[138:141], v[190:193], v[104:107]
	v_mfma_f32_16x16x32_bf16 v[100:103], v[130:133], v[198:201], v[100:103]
	v_mfma_f32_16x16x32_bf16 v[96:99], v[138:141], v[198:201], v[96:99]
	v_mfma_f32_16x16x32_bf16 v[124:127], v[134:137], v[178:181], v[124:127]
	v_mfma_f32_16x16x32_bf16 v[120:123], v[142:145], v[178:181], v[120:123]
	v_mfma_f32_16x16x32_bf16 v[116:119], v[134:137], v[186:189], v[116:119]
	v_mfma_f32_16x16x32_bf16 v[112:115], v[142:145], v[186:189], v[112:115]
	v_mfma_f32_16x16x32_bf16 v[108:111], v[134:137], v[194:197], v[108:111]
	v_mfma_f32_16x16x32_bf16 v[104:107], v[142:145], v[194:197], v[104:107]
	v_mfma_f32_16x16x32_bf16 v[100:103], v[134:137], v[202:205], v[100:103]
	v_mfma_f32_16x16x32_bf16 v[96:99], v[142:145], v[202:205], v[96:99]
	v_mfma_f32_16x16x32_bf16 v[60:63], v[146:149], v[170:173], v[60:63]
	v_mfma_f32_16x16x32_bf16 v[56:59], v[154:157], v[170:173], v[56:59]
	v_mfma_f32_16x16x32_bf16 v[52:55], v[146:149], v[182:185], v[52:55]
	v_mfma_f32_16x16x32_bf16 v[48:51], v[154:157], v[182:185], v[48:51]
	v_mfma_f32_16x16x32_bf16 v[44:47], v[146:149], v[190:193], v[44:47]
	v_mfma_f32_16x16x32_bf16 v[40:43], v[154:157], v[190:193], v[40:43]
	v_mfma_f32_16x16x32_bf16 v[36:39], v[146:149], v[198:201], v[36:39]
	v_mfma_f32_16x16x32_bf16 v[32:35], v[154:157], v[198:201], v[32:35]
	v_mfma_f32_16x16x32_bf16 v[60:63], v[150:153], v[178:181], v[60:63]
	v_mfma_f32_16x16x32_bf16 v[56:59], v[158:161], v[178:181], v[56:59]
	v_mfma_f32_16x16x32_bf16 v[52:55], v[150:153], v[186:189], v[52:55]
	v_mfma_f32_16x16x32_bf16 v[48:51], v[158:161], v[186:189], v[48:51]
	v_mfma_f32_16x16x32_bf16 v[44:47], v[150:153], v[194:197], v[44:47]
	v_mfma_f32_16x16x32_bf16 v[40:43], v[158:161], v[194:197], v[40:43]
	v_mfma_f32_16x16x32_bf16 v[36:39], v[150:153], v[202:205], v[36:39]
	v_mfma_f32_16x16x32_bf16 v[32:35], v[158:161], v[202:205], v[32:35]
	s_add_u32 s69, s69, 0x100
	s_addc_u32 s70, s70, 0
	s_add_u32 s71, s71, 0x100
	s_addc_u32 s72, s72, 0
	s_barrier
	s_add_u32 s74, s42, 0x58000
	ds_read_b128 v[170:173], v166 offset:16384
	ds_read_b128 v[178:181], v166 offset:17408
	ds_read_b128 v[182:185], v166 offset:18432
	ds_read_b128 v[186:189], v166 offset:19456
	ds_read_b128 v[190:193], v166 offset:20480
	ds_read_b128 v[194:197], v166 offset:21504
	ds_read_b128 v[198:201], v166 offset:22528
	ds_read_b128 v[202:205], v166 offset:23552
	s_mov_b32 m0, s15
	s_nop 0
	global_load_lds_dwordx4 v129, s[42:43]
	s_mov_b32 m0, s33
	s_addc_u32 s75, s43, 0
	global_load_lds_dwordx4 v129, s[74:75]
	s_add_u32 s74, s42, 0xb0000
	s_mov_b32 m0, s34
	s_addc_u32 s75, s43, 0
	global_load_lds_dwordx4 v129, s[74:75]
	s_add_u32 s74, s42, 0x108000
	s_mov_b32 m0, s35
	s_addc_u32 s75, s43, 0
	global_load_lds_dwordx4 v129, s[74:75]
	s_mov_b32 m0, s14
	s_nop 0
	global_load_lds_dwordx4 v128, s[38:39]
	s_add_u32 s74, s38, 0x58000
	s_mov_b32 m0, s36
	s_addc_u32 s75, s39, 0
	global_load_lds_dwordx4 v128, s[74:75]
	s_waitcnt vmcnt(8) lgkmcnt(0)
	s_barrier
	v_mfma_f32_16x16x32_bf16 v[92:95], v[130:133], v[170:173], v[92:95]
	v_mfma_f32_16x16x32_bf16 v[88:91], v[138:141], v[170:173], v[88:91]
	v_mfma_f32_16x16x32_bf16 v[84:87], v[130:133], v[182:185], v[84:87]
	v_mfma_f32_16x16x32_bf16 v[80:83], v[138:141], v[182:185], v[80:83]
	v_mfma_f32_16x16x32_bf16 v[76:79], v[130:133], v[190:193], v[76:79]
	v_mfma_f32_16x16x32_bf16 v[72:75], v[138:141], v[190:193], v[72:75]
	v_mfma_f32_16x16x32_bf16 v[68:71], v[130:133], v[198:201], v[68:71]
	v_mfma_f32_16x16x32_bf16 v[64:67], v[138:141], v[198:201], v[64:67]
	v_mfma_f32_16x16x32_bf16 v[92:95], v[134:137], v[178:181], v[92:95]
	v_mfma_f32_16x16x32_bf16 v[88:91], v[142:145], v[178:181], v[88:91]
	v_mfma_f32_16x16x32_bf16 v[84:87], v[134:137], v[186:189], v[84:87]
	v_mfma_f32_16x16x32_bf16 v[80:83], v[142:145], v[186:189], v[80:83]
	v_mfma_f32_16x16x32_bf16 v[76:79], v[134:137], v[194:197], v[76:79]
	v_mfma_f32_16x16x32_bf16 v[72:75], v[142:145], v[194:197], v[72:75]
	v_mfma_f32_16x16x32_bf16 v[68:71], v[134:137], v[202:205], v[68:71]
	v_mfma_f32_16x16x32_bf16 v[64:67], v[142:145], v[202:205], v[64:67]
	v_mfma_f32_16x16x32_bf16 v[28:31], v[146:149], v[170:173], v[28:31]
	v_mfma_f32_16x16x32_bf16 v[24:27], v[154:157], v[170:173], v[24:27]
	v_mfma_f32_16x16x32_bf16 v[20:23], v[146:149], v[182:185], v[20:23]
	v_mfma_f32_16x16x32_bf16 v[16:19], v[154:157], v[182:185], v[16:19]
	v_mfma_f32_16x16x32_bf16 v[12:15], v[146:149], v[190:193], v[12:15]
	v_mfma_f32_16x16x32_bf16 v[8:11], v[154:157], v[190:193], v[8:11]
	v_mfma_f32_16x16x32_bf16 v[4:7], v[146:149], v[198:201], v[4:7]
	v_mfma_f32_16x16x32_bf16 v[0:3], v[154:157], v[198:201], v[0:3]
	v_mfma_f32_16x16x32_bf16 v[28:31], v[150:153], v[178:181], v[28:31]
	v_mfma_f32_16x16x32_bf16 v[24:27], v[158:161], v[178:181], v[24:27]
	v_mfma_f32_16x16x32_bf16 v[20:23], v[150:153], v[186:189], v[20:23]
	v_mfma_f32_16x16x32_bf16 v[16:19], v[158:161], v[186:189], v[16:19]
	v_mfma_f32_16x16x32_bf16 v[12:15], v[150:153], v[194:197], v[12:15]
	v_mfma_f32_16x16x32_bf16 v[8:11], v[158:161], v[194:197], v[8:11]
	v_mfma_f32_16x16x32_bf16 v[4:7], v[150:153], v[202:205], v[4:7]
	v_mfma_f32_16x16x32_bf16 v[0:3], v[158:161], v[202:205], v[0:3]
	s_barrier
; #define PG8_STAGE(bufoff, gbase, voff, p64) do { _Pragma("unroll") for (int _i = 0; _i < 2; ++_i) { \
;         const char* _gb = (const char*)(gbase) + (size_t)_i * (p64); const unsigned _la = ldsbase + (unsigned)(bufoff) + (unsigned)_i * 8192u; \
;         asm volatile("s_mov_b32 m0, %0\n\ts_nop 0\n\tglobal_load_lds_dwordx4 %1, %2" :: "s"(_la), "v"(voff), "s"(_gb) : "memory"); } } while (0)
; #define PG8_LDA(dst, b, h) do { _Pragma("unroll") for (int m = 0; m < 4; ++m) _Pragma("unroll") for (int k = 0; k < 2; ++k) dst[m][k] = *(const LAS bf16x8*)(lds + PG8_SA(b, h) + aoff + m * 2048 + k * 1024); } while (0)
; #define PG8_LDB(dst, b, h) do { _Pragma("unroll") for (int n = 0; n < 2; ++n) _Pragma("unroll") for (int k = 0; k < 2; ++k) dst[n][k] = *(const LAS bf16x8*)(lds + PG8_SB(b, h) + boff + n * 2048 + k * 1024); } while (0)
; #define PG8_MMA(ai, bj, At, Bt) do { __builtin_amdgcn_s_setprio(1); _Pragma("unroll") for (int m = 0; m < 4; ++m) _Pragma("unroll") for (int n = 0; n < 2; ++n) _Pragma("unroll") for (int k = 0; k < 2; ++k) \
;         acc[ai][bj][m][n] = __builtin_amdgcn_mfma_f32_16x16x32_bf16(Bt[n][k], At[m][k], acc[ai][bj][m][n], 0, 0, 0); __builtin_amdgcn_s_setprio(0); } while (0)
; #define PG8_WAIT_V(n) asm volatile("s_waitcnt vmcnt(" #n ")" ::: "memory")
; #define PG8_WAIT_L(n) asm volatile("s_waitcnt lgkmcnt(" #n ")" ::: "memory")
; #define PG8_BAR __builtin_amdgcn_s_barrier()
; #define PG8_SCHED __builtin_amdgcn_sched_barrier(0)
; template <class Epi, class Sched>
; __device__ __forceinline__ void gemm_phase(LAS unsigned char* lds, const Sched& S, const Epi& E) {
;     ...
;             PG8_LDB(B0, 1, 0); PG8_LDB(B1, 1, 1); PG8_SCHED; PG8_LDA(At, 1, 0); PG8_STAGE(PG8_SA(0, 1), a2 + hA2, vA2, hA2 / 2);
;             PG8_WAIT_V(8); PG8_WAIT_L(0); PG8_BAR; PG8_MMA(0, 0, At, B0); PG8_MMA(0, 1, At, B1); PG8_BAR; PG8_SCHED;
;             PG8_LDA(At, 1, 1); PG8_STAGE(PG8_SB(1, 0), b3, vB2, hB2 / 2); PG8_STAGE(PG8_SB(1, 1), b3 + hB2, vB2, hB2 / 2); PG8_STAGE(PG8_SA(1, 0), a3, vA2, hA2 / 2);
;             PG8_WAIT_V(8); PG8_WAIT_L(0); PG8_BAR; PG8_MMA(1, 0, At, B0); PG8_MMA(1, 1, At, B1); PG8_BAR; PG8_SCHED;
;         }
;         if (wr == 0) PG8_BAR;
.Lpeel_mid_7711:
	ds_read_b128 v[130:133], v167
	ds_read_b128 v[134:137], v167 offset:1024
	ds_read_b128 v[138:141], v167 offset:2048
	ds_read_b128 v[142:145], v167 offset:3072
	ds_read_b128 v[146:149], v168
	ds_read_b128 v[150:153], v168 offset:1024
	ds_read_b128 v[154:157], v168 offset:2048
	ds_read_b128 v[158:161], v168 offset:3072
	ds_read_b128 v[170:173], v166 offset:32768
	ds_read_b128 v[178:181], v166 offset:33792
	ds_read_b128 v[182:185], v166 offset:34816
	ds_read_b128 v[186:189], v166 offset:35840
	ds_read_b128 v[190:193], v166 offset:36864
	ds_read_b128 v[194:197], v166 offset:37888
	ds_read_b128 v[198:201], v166 offset:38912
	ds_read_b128 v[202:205], v166 offset:39936
	s_add_u32 s74, s38, 0xb0000
	s_mov_b32 m0, s37
	s_addc_u32 s75, s39, 0
	global_load_lds_dwordx4 v128, s[74:75]
	s_add_u32 s74, s38, 0x108000
	s_mov_b32 m0, s46
	s_addc_u32 s75, s39, 0
	global_load_lds_dwordx4 v128, s[74:75]
	s_waitcnt vmcnt(8) lgkmcnt(0)
	s_barrier
	v_mfma_f32_16x16x32_bf16 v[124:127], v[130:133], v[170:173], v[124:127]
	v_mfma_f32_16x16x32_bf16 v[120:123], v[138:141], v[170:173], v[120:123]
	v_mfma_f32_16x16x32_bf16 v[116:119], v[130:133], v[182:185], v[116:119]
	v_mfma_f32_16x16x32_bf16 v[112:115], v[138:141], v[182:185], v[112:115]
	v_mfma_f32_16x16x32_bf16 v[108:111], v[130:133], v[190:193], v[108:111]
	v_mfma_f32_16x16x32_bf16 v[104:107], v[138:141], v[190:193], v[104:107]
	v_mfma_f32_16x16x32_bf16 v[100:103], v[130:133], v[198:201], v[100:103]
	v_mfma_f32_16x16x32_bf16 v[96:99], v[138:141], v[198:201], v[96:99]
	v_mfma_f32_16x16x32_bf16 v[124:127], v[134:137], v[178:181], v[124:127]
	v_mfma_f32_16x16x32_bf16 v[120:123], v[142:145], v[178:181], v[120:123]
	v_mfma_f32_16x16x32_bf16 v[116:119], v[134:137], v[186:189], v[116:119]
	v_mfma_f32_16x16x32_bf16 v[112:115], v[142:145], v[186:189], v[112:115]
	v_mfma_f32_16x16x32_bf16 v[108:111], v[134:137], v[194:197], v[108:111]
	v_mfma_f32_16x16x32_bf16 v[104:107], v[142:145], v[194:197], v[104:107]
	v_mfma_f32_16x16x32_bf16 v[100:103], v[134:137], v[202:205], v[100:103]
	v_mfma_f32_16x16x32_bf16 v[96:99], v[142:145], v[202:205], v[96:99]
	v_mfma_f32_16x16x32_bf16 v[60:63], v[146:149], v[170:173], v[60:63]
	v_mfma_f32_16x16x32_bf16 v[56:59], v[154:157], v[170:173], v[56:59]
	v_mfma_f32_16x16x32_bf16 v[52:55], v[146:149], v[182:185], v[52:55]
	v_mfma_f32_16x16x32_bf16 v[48:51], v[154:157], v[182:185], v[48:51]
	v_mfma_f32_16x16x32_bf16 v[44:47], v[146:149], v[190:193], v[44:47]
	v_mfma_f32_16x16x32_bf16 v[40:43], v[154:157], v[190:193], v[40:43]
	v_mfma_f32_16x16x32_bf16 v[36:39], v[146:149], v[198:201], v[36:39]
	v_mfma_f32_16x16x32_bf16 v[32:35], v[154:157], v[198:201], v[32:35]
	v_mfma_f32_16x16x32_bf16 v[60:63], v[150:153], v[178:181], v[60:63]
	v_mfma_f32_16x16x32_bf16 v[56:59], v[158:161], v[178:181], v[56:59]
	v_mfma_f32_16x16x32_bf16 v[52:55], v[150:153], v[186:189], v[52:55]
	v_mfma_f32_16x16x32_bf16 v[48:51], v[158:161], v[186:189], v[48:51]
	v_mfma_f32_16x16x32_bf16 v[44:47], v[150:153], v[194:197], v[44:47]
	v_mfma_f32_16x16x32_bf16 v[40:43], v[158:161], v[194:197], v[40:43]
	v_mfma_f32_16x16x32_bf16 v[36:39], v[150:153], v[202:205], v[36:39]
	v_mfma_f32_16x16x32_bf16 v[32:35], v[158:161], v[202:205], v[32:35]
	s_barrier
	s_add_u32 s74, s42, 0x80
	s_addc_u32 s75, s43, 0
	ds_read_b128 v[170:173], v166 offset:49152
	ds_read_b128 v[178:181], v166 offset:50176
	ds_read_b128 v[182:185], v166 offset:51200
	ds_read_b128 v[186:189], v166 offset:52224
	ds_read_b128 v[190:193], v166 offset:53248
	ds_read_b128 v[194:197], v166 offset:54272
	ds_read_b128 v[198:201], v166 offset:55296
	ds_read_b128 v[202:205], v166 offset:56320
	s_mov_b32 m0, s53
	s_nop 0
	global_load_lds_dwordx4 v129, s[74:75]
	s_add_u32 s74, s42, 0x58080
	s_mov_b32 m0, s54
	s_addc_u32 s75, s43, 0
	global_load_lds_dwordx4 v129, s[74:75]
	s_add_u32 s74, s42, 0xb0080
	s_mov_b32 m0, s57
	s_addc_u32 s75, s43, 0
	global_load_lds_dwordx4 v129, s[74:75]
	s_add_u32 s42, s42, 0x108080
	s_mov_b32 m0, s58
	s_addc_u32 s43, s43, 0
	global_load_lds_dwordx4 v129, s[42:43]
	s_mov_b32 m0, s55
	s_nop 0
	global_load_lds_dwordx4 v128, s[40:41]
	s_add_u32 s38, s38, 0x58080
	s_mov_b32 m0, s56
	s_addc_u32 s39, s39, 0
	global_load_lds_dwordx4 v128, s[38:39]
	s_waitcnt vmcnt(8) lgkmcnt(0)
	s_barrier
	v_mfma_f32_16x16x32_bf16 v[92:95], v[130:133], v[170:173], v[92:95]
	v_mfma_f32_16x16x32_bf16 v[88:91], v[138:141], v[170:173], v[88:91]
	v_mfma_f32_16x16x32_bf16 v[84:87], v[130:133], v[182:185], v[84:87]
	v_mfma_f32_16x16x32_bf16 v[80:83], v[138:141], v[182:185], v[80:83]
	v_mfma_f32_16x16x32_bf16 v[76:79], v[130:133], v[190:193], v[76:79]
	v_mfma_f32_16x16x32_bf16 v[72:75], v[138:141], v[190:193], v[72:75]
	v_mfma_f32_16x16x32_bf16 v[68:71], v[130:133], v[198:201], v[68:71]
	v_mfma_f32_16x16x32_bf16 v[64:67], v[138:141], v[198:201], v[64:67]
	v_mfma_f32_16x16x32_bf16 v[92:95], v[134:137], v[178:181], v[92:95]
	v_mfma_f32_16x16x32_bf16 v[88:91], v[142:145], v[178:181], v[88:91]
	v_mfma_f32_16x16x32_bf16 v[84:87], v[134:137], v[186:189], v[84:87]
	v_mfma_f32_16x16x32_bf16 v[80:83], v[142:145], v[186:189], v[80:83]
	v_mfma_f32_16x16x32_bf16 v[76:79], v[134:137], v[194:197], v[76:79]
	v_mfma_f32_16x16x32_bf16 v[72:75], v[142:145], v[194:197], v[72:75]
	v_mfma_f32_16x16x32_bf16 v[68:71], v[134:137], v[202:205], v[68:71]
	v_mfma_f32_16x16x32_bf16 v[64:67], v[142:145], v[202:205], v[64:67]
	v_mfma_f32_16x16x32_bf16 v[28:31], v[146:149], v[170:173], v[28:31]
	v_mfma_f32_16x16x32_bf16 v[24:27], v[154:157], v[170:173], v[24:27]
	v_mfma_f32_16x16x32_bf16 v[20:23], v[146:149], v[182:185], v[20:23]
	v_mfma_f32_16x16x32_bf16 v[16:19], v[154:157], v[182:185], v[16:19]
	v_mfma_f32_16x16x32_bf16 v[12:15], v[146:149], v[190:193], v[12:15]
	v_mfma_f32_16x16x32_bf16 v[8:11], v[154:157], v[190:193], v[8:11]
	v_mfma_f32_16x16x32_bf16 v[4:7], v[146:149], v[198:201], v[4:7]
	v_mfma_f32_16x16x32_bf16 v[0:3], v[154:157], v[198:201], v[0:3]
	v_mfma_f32_16x16x32_bf16 v[28:31], v[150:153], v[178:181], v[28:31]
	v_mfma_f32_16x16x32_bf16 v[24:27], v[158:161], v[178:181], v[24:27]
	v_mfma_f32_16x16x32_bf16 v[20:23], v[150:153], v[186:189], v[20:23]
	v_mfma_f32_16x16x32_bf16 v[16:19], v[158:161], v[186:189], v[16:19]
	v_mfma_f32_16x16x32_bf16 v[12:15], v[150:153], v[194:197], v[12:15]
	v_mfma_f32_16x16x32_bf16 v[8:11], v[158:161], v[194:197], v[8:11]
	v_mfma_f32_16x16x32_bf16 v[4:7], v[150:153], v[202:205], v[4:7]
	v_mfma_f32_16x16x32_bf16 v[0:3], v[158:161], v[202:205], v[0:3]
	s_barrier
	s_cmp_ge_i32 s73, s21
	s_mov_b32 s38, s73
	s_cbranch_scc0 .LBB0_398
	s_and_b64 vcc, exec, s[18:19]
	s_cbranch_vccz .LBB0_401
	s_barrier

; #define PG8_STAGE(bufoff, gbase, voff, p64) do { _Pragma("unroll") for (int _i = 0; _i < 2; ++_i) { \
;         const char* _gb = (const char*)(gbase) + (size_t)_i * (p64); const unsigned _la = ldsbase + (unsigned)(bufoff) + (unsigned)_i * 8192u; \
;         asm volatile("s_mov_b32 m0, %0\n\ts_nop 0\n\tglobal_load_lds_dwordx4 %1, %2" :: "s"(_la), "v"(voff), "s"(_gb) : "memory"); } } while (0)
; #define PG8_LDA(dst, b, h) do { _Pragma("unroll") for (int m = 0; m < 4; ++m) _Pragma("unroll") for (int k = 0; k < 2; ++k) dst[m][k] = *(const LAS bf16x8*)(lds + PG8_SA(b, h) + aoff + m * 2048 + k * 1024); } while (0)
; #define PG8_LDB(dst, b, h) do { _Pragma("unroll") for (int n = 0; n < 2; ++n) _Pragma("unroll") for (int k = 0; k < 2; ++k) dst[n][k] = *(const LAS bf16x8*)(lds + PG8_SB(b, h) + boff + n * 2048 + k * 1024); } while (0)
; #define PG8_MMA(ai, bj, At, Bt) do { __builtin_amdgcn_s_setprio(1); _Pragma("unroll") for (int m = 0; m < 4; ++m) _Pragma("unroll") for (int n = 0; n < 2; ++n) _Pragma("unroll") for (int k = 0; k < 2; ++k) \
;         acc[ai][bj][m][n] = __builtin_amdgcn_mfma_f32_16x16x32_bf16(Bt[n][k], At[m][k], acc[ai][bj][m][n], 0, 0, 0); __builtin_amdgcn_s_setprio(0); } while (0)
; #define PG8_WAIT_V(n) asm volatile("s_waitcnt vmcnt(" #n ")" ::: "memory")
; template <class Epi, class Sched>
; __device__ __forceinline__ void gemm_phase(LAS unsigned char* lds, const Sched& S, const Epi& E) {
;     ...
;         for (int t = 0; t < nt; t += 2) {
;             const bool last = (t == nt - 2);
;             const char* a1 = cA + (size_t)(t + 1) * kstep;
;             const char* a2 = last ? nA : cA + (size_t)(t + 2) * kstep; const char* b2 = last ? nB : cB + (size_t)(t + 2) * kstep;
;             const char* a3 = a2 + kstep; const char* b3 = b2 + kstep;
;             const unsigned vA2 = voffA, vB2 = voffB, hA2 = hA, hB2 = hB;
;             PG8_LDB(B0, 0, 0); PG8_LDB(B1, 0, 1); PG8_SCHED; PG8_LDA(At, 0, 0); PG8_STAGE(PG8_SA(1, 1), a1 + hA, voffA, hA / 2);
;             PG8_WAIT_V(8); PG8_WAIT_L(0); PG8_BAR; PG8_MMA(0, 0, At, B0); PG8_MMA(0, 1, At, B1); PG8_BAR; PG8_SCHED;
;             PG8_LDA(At, 0, 1); PG8_STAGE(PG8_SB(0, 0), b2, vB2, hB2 / 2); PG8_STAGE(PG8_SB(0, 1), b2 + hB2, vB2, hB2 / 2); PG8_STAGE(PG8_SA(0, 0), a2, vA2, hA2 / 2);
;             PG8_WAIT_V(8); PG8_WAIT_L(0); PG8_BAR; PG8_MMA(1, 0, At, B0); PG8_MMA(1, 1, At, B1); PG8_BAR; PG8_SCHED;
.LBB0_552:
	s_add_u32 s74, s22, 0x40080
	s_addc_u32 s75, s23, 0
	s_add_u32 s57, s16, 0x100
	s_addc_u32 s80, s17, 0
	s_mov_b32 s81, -2
	s_waitcnt vmcnt(2)
	s_waitcnt vmcnt(0)
	v_add_u32_e32 v128, 0x10000, v154
	ds_read_b128 v[138:141], v128
	ds_read_b128 v[142:145], v128 offset:1024
	ds_read_b128 v[146:149], v128 offset:2048
	ds_read_b128 v[172:175], v128 offset:3072
	v_add_u32_e32 v128, 0x14000, v154
	ds_read_b128 v[178:181], v128
	ds_read_b128 v[182:185], v128 offset:1024
	ds_read_b128 v[186:189], v128 offset:2048
	ds_read_b128 v[190:193], v128 offset:3072
	s_add_u32 s16, s74, 0xfffc0080
	s_addc_u32 s17, s75, -1
	s_cmp_eq_u32 s81, 12
	s_cselect_b32 s16, s58, s16
	s_cselect_b32 s17, s59, s17
	s_cselect_b32 s76, s62, s57
	s_cselect_b32 s77, s63, s80
	s_add_u32 s22, s16, 0x80
	s_addc_u32 s23, s17, 0
	ds_read_b128 v[194:197], v155
	ds_read_b128 v[198:201], v155 offset:1024
	ds_read_b128 v[202:205], v155 offset:2048
	ds_read_b128 v[206:209], v155 offset:3072
	ds_read_b128 v[210:213], v155 offset:4096
	ds_read_b128 v[214:217], v155 offset:5120
	ds_read_b128 v[218:221], v155 offset:6144
	ds_read_b128 v[222:225], v155 offset:7168
	s_mov_b32 m0, s67
	s_nop 0
	global_load_lds_dwordx4 v150, s[74:75]
	s_add_u32 s82, s74, 0x20000
	s_mov_b32 m0, s69
	s_addc_u32 s83, s75, 0
	global_load_lds_dwordx4 v150, s[82:83]
	s_waitcnt vmcnt(8) lgkmcnt(0)
	s_barrier
	v_mfma_f32_16x16x32_bf16 v[124:127], v[138:141], v[194:197], 0
	v_mfma_f32_16x16x32_bf16 v[120:123], v[146:149], v[194:197], 0
	v_mfma_f32_16x16x32_bf16 v[112:115], v[138:141], v[202:205], 0
	v_mfma_f32_16x16x32_bf16 v[104:107], v[146:149], v[202:205], 0
	v_mfma_f32_16x16x32_bf16 v[96:99], v[138:141], v[210:213], 0
	v_mfma_f32_16x16x32_bf16 v[88:91], v[146:149], v[210:213], 0
	v_mfma_f32_16x16x32_bf16 v[80:83], v[138:141], v[218:221], 0
	v_mfma_f32_16x16x32_bf16 v[72:75], v[146:149], v[218:221], 0
	v_mfma_f32_16x16x32_bf16 v[124:127], v[142:145], v[198:201], v[124:127]
	v_mfma_f32_16x16x32_bf16 v[120:123], v[172:175], v[198:201], v[120:123]
	v_mfma_f32_16x16x32_bf16 v[112:115], v[142:145], v[206:209], v[112:115]
	v_mfma_f32_16x16x32_bf16 v[104:107], v[172:175], v[206:209], v[104:107]
	v_mfma_f32_16x16x32_bf16 v[96:99], v[142:145], v[214:217], v[96:99]
	v_mfma_f32_16x16x32_bf16 v[88:91], v[172:175], v[214:217], v[88:91]
	v_mfma_f32_16x16x32_bf16 v[80:83], v[142:145], v[222:225], v[80:83]
	v_mfma_f32_16x16x32_bf16 v[72:75], v[172:175], v[222:225], v[72:75]
	v_mfma_f32_16x16x32_bf16 v[116:119], v[178:181], v[194:197], 0
	v_mfma_f32_16x16x32_bf16 v[108:111], v[186:189], v[194:197], 0
	v_mfma_f32_16x16x32_bf16 v[100:103], v[178:181], v[202:205], 0
	v_mfma_f32_16x16x32_bf16 v[92:95], v[186:189], v[202:205], 0
	v_mfma_f32_16x16x32_bf16 v[84:87], v[178:181], v[210:213], 0
	v_mfma_f32_16x16x32_bf16 v[76:79], v[186:189], v[210:213], 0
	v_mfma_f32_16x16x32_bf16 v[68:71], v[178:181], v[218:221], 0
	v_mfma_f32_16x16x32_bf16 v[64:67], v[186:189], v[218:221], 0
	v_mfma_f32_16x16x32_bf16 v[116:119], v[182:185], v[198:201], v[116:119]
	v_mfma_f32_16x16x32_bf16 v[108:111], v[190:193], v[198:201], v[108:111]
	v_mfma_f32_16x16x32_bf16 v[100:103], v[182:185], v[206:209], v[100:103]
	v_mfma_f32_16x16x32_bf16 v[92:95], v[190:193], v[206:209], v[92:95]
	v_mfma_f32_16x16x32_bf16 v[84:87], v[182:185], v[214:217], v[84:87]
	v_mfma_f32_16x16x32_bf16 v[76:79], v[190:193], v[214:217], v[76:79]
	v_mfma_f32_16x16x32_bf16 v[68:71], v[182:185], v[222:225], v[68:71]
	v_mfma_f32_16x16x32_bf16 v[64:67], v[190:193], v[222:225], v[64:67]
	s_add_i32 s81, s81, 2
	s_add_u32 s74, s74, 0x100
	s_addc_u32 s75, s75, 0
	s_add_u32 s57, s57, 0x100
	s_addc_u32 s80, s80, 0
	s_barrier
	s_add_u32 s82, s76, 0x20000
	ds_read_b128 v[194:197], v155 offset:16384
	ds_read_b128 v[198:201], v155 offset:17408
	ds_read_b128 v[202:205], v155 offset:18432
	ds_read_b128 v[206:209], v155 offset:19456
	ds_read_b128 v[210:213], v155 offset:20480
	ds_read_b128 v[214:217], v155 offset:21504
	ds_read_b128 v[218:221], v155 offset:22528
	ds_read_b128 v[222:225], v155 offset:23552
	s_mov_b32 m0, s24
	s_nop 0
	global_load_lds_dwordx4 v151, s[76:77]
	s_mov_b32 m0, s33
	s_addc_u32 s83, s77, 0
	global_load_lds_dwordx4 v151, s[82:83]
	s_add_u32 s82, s76, 0x40000
	s_mov_b32 m0, s34
	s_addc_u32 s83, s77, 0
	global_load_lds_dwordx4 v151, s[82:83]
	s_add_u32 s82, s76, 0x60000
	s_mov_b32 m0, s35
	s_addc_u32 s83, s77, 0
	global_load_lds_dwordx4 v151, s[82:83]
	s_mov_b32 m0, s15
	s_nop 0
	global_load_lds_dwordx4 v150, s[16:17]
	s_add_u32 s82, s16, 0x20000
	s_mov_b32 m0, s36
	s_addc_u32 s83, s17, 0
	global_load_lds_dwordx4 v150, s[82:83]
	s_waitcnt vmcnt(8) lgkmcnt(0)
	s_barrier
	v_mfma_f32_16x16x32_bf16 v[60:63], v[138:141], v[194:197], 0
	v_mfma_f32_16x16x32_bf16 v[56:59], v[146:149], v[194:197], 0
	v_mfma_f32_16x16x32_bf16 v[48:51], v[138:141], v[202:205], 0
	v_mfma_f32_16x16x32_bf16 v[40:43], v[146:149], v[202:205], 0
	v_mfma_f32_16x16x32_bf16 v[32:35], v[138:141], v[210:213], 0
	v_mfma_f32_16x16x32_bf16 v[24:27], v[146:149], v[210:213], 0
	v_mfma_f32_16x16x32_bf16 v[16:19], v[138:141], v[218:221], 0
	v_mfma_f32_16x16x32_bf16 v[8:11], v[146:149], v[218:221], 0
	v_mfma_f32_16x16x32_bf16 v[60:63], v[142:145], v[198:201], v[60:63]
	v_mfma_f32_16x16x32_bf16 v[56:59], v[172:175], v[198:201], v[56:59]
	v_mfma_f32_16x16x32_bf16 v[48:51], v[142:145], v[206:209], v[48:51]
	v_mfma_f32_16x16x32_bf16 v[40:43], v[172:175], v[206:209], v[40:43]
	v_mfma_f32_16x16x32_bf16 v[32:35], v[142:145], v[214:217], v[32:35]
	v_mfma_f32_16x16x32_bf16 v[24:27], v[172:175], v[214:217], v[24:27]
	v_mfma_f32_16x16x32_bf16 v[16:19], v[142:145], v[222:225], v[16:19]
	v_mfma_f32_16x16x32_bf16 v[8:11], v[172:175], v[222:225], v[8:11]
	v_mfma_f32_16x16x32_bf16 v[52:55], v[178:181], v[194:197], 0
	v_mfma_f32_16x16x32_bf16 v[44:47], v[186:189], v[194:197], 0
	v_mfma_f32_16x16x32_bf16 v[36:39], v[178:181], v[202:205], 0
	v_mfma_f32_16x16x32_bf16 v[28:31], v[186:189], v[202:205], 0
	v_mfma_f32_16x16x32_bf16 v[20:23], v[178:181], v[210:213], 0
	v_mfma_f32_16x16x32_bf16 v[12:15], v[186:189], v[210:213], 0
	v_mfma_f32_16x16x32_bf16 v[4:7], v[178:181], v[218:221], 0
	v_mfma_f32_16x16x32_bf16 v[0:3], v[186:189], v[218:221], 0
	v_mfma_f32_16x16x32_bf16 v[52:55], v[182:185], v[198:201], v[52:55]
	v_mfma_f32_16x16x32_bf16 v[44:47], v[190:193], v[198:201], v[44:47]
	v_mfma_f32_16x16x32_bf16 v[36:39], v[182:185], v[206:209], v[36:39]
	v_mfma_f32_16x16x32_bf16 v[28:31], v[190:193], v[206:209], v[28:31]
	v_mfma_f32_16x16x32_bf16 v[20:23], v[182:185], v[214:217], v[20:23]
	v_mfma_f32_16x16x32_bf16 v[12:15], v[190:193], v[214:217], v[12:15]
	v_mfma_f32_16x16x32_bf16 v[4:7], v[182:185], v[222:225], v[4:7]
	v_mfma_f32_16x16x32_bf16 v[0:3], v[190:193], v[222:225], v[0:3]
	s_barrier
	s_branch .Lpeel_mid_11724
; #define PG8_STAGE(bufoff, gbase, voff, p64) do { _Pragma("unroll") for (int _i = 0; _i < 2; ++_i) { \
;         const char* _gb = (const char*)(gbase) + (size_t)_i * (p64); const unsigned _la = ldsbase + (unsigned)(bufoff) + (unsigned)_i * 8192u; \
;         asm volatile("s_mov_b32 m0, %0\n\ts_nop 0\n\tglobal_load_lds_dwordx4 %1, %2" :: "s"(_la), "v"(voff), "s"(_gb) : "memory"); } } while (0)
; #define PG8_LDA(dst, b, h) do { _Pragma("unroll") for (int m = 0; m < 4; ++m) _Pragma("unroll") for (int k = 0; k < 2; ++k) dst[m][k] = *(const LAS bf16x8*)(lds + PG8_SA(b, h) + aoff + m * 2048 + k * 1024); } while (0)
; #define PG8_LDB(dst, b, h) do { _Pragma("unroll") for (int n = 0; n < 2; ++n) _Pragma("unroll") for (int k = 0; k < 2; ++k) dst[n][k] = *(const LAS bf16x8*)(lds + PG8_SB(b, h) + boff + n * 2048 + k * 1024); } while (0)
; #define PG8_MMA(ai, bj, At, Bt) do { __builtin_amdgcn_s_setprio(1); _Pragma("unroll") for (int m = 0; m < 4; ++m) _Pragma("unroll") for (int n = 0; n < 2; ++n) _Pragma("unroll") for (int k = 0; k < 2; ++k) \
;         acc[ai][bj][m][n] = __builtin_amdgcn_mfma_f32_16x16x32_bf16(Bt[n][k], At[m][k], acc[ai][bj][m][n], 0, 0, 0); __builtin_amdgcn_s_setprio(0); } while (0)
; #define PG8_WAIT_V(n) asm volatile("s_waitcnt vmcnt(" #n ")" ::: "memory")
; #define PG8_BAR __builtin_amdgcn_s_barrier()
; template <class Epi, class Sched>
; __device__ __forceinline__ void gemm_phase(LAS unsigned char* lds, const Sched& S, const Epi& E) {
;     ...
;             const bool last = (t == nt - 2);
;             const char* a1 = cA + (size_t)(t + 1) * kstep;
;             const char* a2 = last ? nA : cA + (size_t)(t + 2) * kstep; const char* b2 = last ? nB : cB + (size_t)(t + 2) * kstep;
;             const char* a3 = a2 + kstep; const char* b3 = b2 + kstep;
;             const unsigned vA2 = voffA, vB2 = voffB, hA2 = hA, hB2 = hB;
;             PG8_LDB(B0, 0, 0); PG8_LDB(B1, 0, 1); PG8_SCHED; PG8_LDA(At, 0, 0); PG8_STAGE(PG8_SA(1, 1), a1 + hA, voffA, hA / 2);
;             PG8_WAIT_V(8); PG8_WAIT_L(0); PG8_BAR; PG8_MMA(0, 0, At, B0); PG8_MMA(0, 1, At, B1); PG8_BAR; PG8_SCHED;
;             PG8_LDA(At, 0, 1); PG8_STAGE(PG8_SB(0, 0), b2, vB2, hB2 / 2); PG8_STAGE(PG8_SB(0, 1), b2 + hB2, vB2, hB2 / 2); PG8_STAGE(PG8_SA(0, 0), a2, vA2, hA2 / 2);
;             PG8_WAIT_V(8); PG8_WAIT_L(0); PG8_BAR; PG8_MMA(1, 0, At, B0); PG8_MMA(1, 1, At, B1); PG8_BAR; PG8_SCHED;
.LBB0_553:
	v_add_u32_e32 v128, 0x10000, v154
	ds_read_b128 v[138:141], v128
	ds_read_b128 v[142:145], v128 offset:1024
	ds_read_b128 v[146:149], v128 offset:2048
	ds_read_b128 v[172:175], v128 offset:3072
	v_add_u32_e32 v128, 0x14000, v154
	ds_read_b128 v[178:181], v128
	ds_read_b128 v[182:185], v128 offset:1024
	ds_read_b128 v[186:189], v128 offset:2048
	ds_read_b128 v[190:193], v128 offset:3072
	s_add_u32 s16, s74, 0xfffc0080
	s_addc_u32 s17, s75, -1
	s_cmp_eq_u32 s81, 12
	s_cselect_b32 s16, s58, s16
	s_cselect_b32 s17, s59, s17
	s_cselect_b32 s76, s62, s57
	s_cselect_b32 s77, s63, s80
	s_add_u32 s22, s16, 0x80
	s_addc_u32 s23, s17, 0
	ds_read_b128 v[194:197], v155
	ds_read_b128 v[198:201], v155 offset:1024
	ds_read_b128 v[202:205], v155 offset:2048
	ds_read_b128 v[206:209], v155 offset:3072
	ds_read_b128 v[210:213], v155 offset:4096
	ds_read_b128 v[214:217], v155 offset:5120
	ds_read_b128 v[218:221], v155 offset:6144
	ds_read_b128 v[222:225], v155 offset:7168
	s_mov_b32 m0, s67
	s_nop 0
	global_load_lds_dwordx4 v150, s[74:75]
	s_add_u32 s82, s74, 0x20000
	s_mov_b32 m0, s69
	s_addc_u32 s83, s75, 0
	global_load_lds_dwordx4 v150, s[82:83]
	s_waitcnt vmcnt(8) lgkmcnt(0)
	s_barrier
	v_mfma_f32_16x16x32_bf16 v[124:127], v[138:141], v[194:197], v[124:127]
	v_mfma_f32_16x16x32_bf16 v[120:123], v[146:149], v[194:197], v[120:123]
	v_mfma_f32_16x16x32_bf16 v[112:115], v[138:141], v[202:205], v[112:115]
	v_mfma_f32_16x16x32_bf16 v[104:107], v[146:149], v[202:205], v[104:107]
	v_mfma_f32_16x16x32_bf16 v[96:99], v[138:141], v[210:213], v[96:99]
	v_mfma_f32_16x16x32_bf16 v[88:91], v[146:149], v[210:213], v[88:91]
	v_mfma_f32_16x16x32_bf16 v[80:83], v[138:141], v[218:221], v[80:83]
	v_mfma_f32_16x16x32_bf16 v[72:75], v[146:149], v[218:221], v[72:75]
	v_mfma_f32_16x16x32_bf16 v[124:127], v[142:145], v[198:201], v[124:127]
	v_mfma_f32_16x16x32_bf16 v[120:123], v[172:175], v[198:201], v[120:123]
	v_mfma_f32_16x16x32_bf16 v[112:115], v[142:145], v[206:209], v[112:115]
	v_mfma_f32_16x16x32_bf16 v[104:107], v[172:175], v[206:209], v[104:107]
	v_mfma_f32_16x16x32_bf16 v[96:99], v[142:145], v[214:217], v[96:99]
	v_mfma_f32_16x16x32_bf16 v[88:91], v[172:175], v[214:217], v[88:91]
	v_mfma_f32_16x16x32_bf16 v[80:83], v[142:145], v[222:225], v[80:83]
	v_mfma_f32_16x16x32_bf16 v[72:75], v[172:175], v[222:225], v[72:75]
	v_mfma_f32_16x16x32_bf16 v[116:119], v[178:181], v[194:197], v[116:119]
	v_mfma_f32_16x16x32_bf16 v[108:111], v[186:189], v[194:197], v[108:111]
	v_mfma_f32_16x16x32_bf16 v[100:103], v[178:181], v[202:205], v[100:103]
	v_mfma_f32_16x16x32_bf16 v[92:95], v[186:189], v[202:205], v[92:95]
	v_mfma_f32_16x16x32_bf16 v[84:87], v[178:181], v[210:213], v[84:87]
	v_mfma_f32_16x16x32_bf16 v[76:79], v[186:189], v[210:213], v[76:79]
	v_mfma_f32_16x16x32_bf16 v[68:71], v[178:181], v[218:221], v[68:71]
	v_mfma_f32_16x16x32_bf16 v[64:67], v[186:189], v[218:221], v[64:67]
	v_mfma_f32_16x16x32_bf16 v[116:119], v[182:185], v[198:201], v[116:119]
	v_mfma_f32_16x16x32_bf16 v[108:111], v[190:193], v[198:201], v[108:111]
	v_mfma_f32_16x16x32_bf16 v[100:103], v[182:185], v[206:209], v[100:103]
	v_mfma_f32_16x16x32_bf16 v[92:95], v[190:193], v[206:209], v[92:95]
	v_mfma_f32_16x16x32_bf16 v[84:87], v[182:185], v[214:217], v[84:87]
	v_mfma_f32_16x16x32_bf16 v[76:79], v[190:193], v[214:217], v[76:79]
	v_mfma_f32_16x16x32_bf16 v[68:71], v[182:185], v[222:225], v[68:71]
	v_mfma_f32_16x16x32_bf16 v[64:67], v[190:193], v[222:225], v[64:67]
	s_add_i32 s81, s81, 2
	s_add_u32 s74, s74, 0x100
	s_addc_u32 s75, s75, 0
	s_add_u32 s57, s57, 0x100
	s_addc_u32 s80, s80, 0
	s_barrier
	s_add_u32 s82, s76, 0x20000
	ds_read_b128 v[194:197], v155 offset:16384
	ds_read_b128 v[198:201], v155 offset:17408
	ds_read_b128 v[202:205], v155 offset:18432
	ds_read_b128 v[206:209], v155 offset:19456
	ds_read_b128 v[210:213], v155 offset:20480
	ds_read_b128 v[214:217], v155 offset:21504
	ds_read_b128 v[218:221], v155 offset:22528
	ds_read_b128 v[222:225], v155 offset:23552
	s_mov_b32 m0, s24
	s_nop 0
	global_load_lds_dwordx4 v151, s[76:77]
	s_mov_b32 m0, s33
	s_addc_u32 s83, s77, 0
	global_load_lds_dwordx4 v151, s[82:83]
	s_add_u32 s82, s76, 0x40000
	s_mov_b32 m0, s34
	s_addc_u32 s83, s77, 0
	global_load_lds_dwordx4 v151, s[82:83]
	s_add_u32 s82, s76, 0x60000
	s_mov_b32 m0, s35
	s_addc_u32 s83, s77, 0
	global_load_lds_dwordx4 v151, s[82:83]
	s_mov_b32 m0, s15
	s_nop 0
	global_load_lds_dwordx4 v150, s[16:17]
	s_add_u32 s82, s16, 0x20000
	s_mov_b32 m0, s36
	s_addc_u32 s83, s17, 0
	global_load_lds_dwordx4 v150, s[82:83]
	s_waitcnt vmcnt(8) lgkmcnt(0)
	s_barrier
	v_mfma_f32_16x16x32_bf16 v[60:63], v[138:141], v[194:197], v[60:63]
	v_mfma_f32_16x16x32_bf16 v[56:59], v[146:149], v[194:197], v[56:59]
	v_mfma_f32_16x16x32_bf16 v[48:51], v[138:141], v[202:205], v[48:51]
	v_mfma_f32_16x16x32_bf16 v[40:43], v[146:149], v[202:205], v[40:43]
	v_mfma_f32_16x16x32_bf16 v[32:35], v[138:141], v[210:213], v[32:35]
	v_mfma_f32_16x16x32_bf16 v[24:27], v[146:149], v[210:213], v[24:27]
	v_mfma_f32_16x16x32_bf16 v[16:19], v[138:141], v[218:221], v[16:19]
	v_mfma_f32_16x16x32_bf16 v[8:11], v[146:149], v[218:221], v[8:11]
	v_mfma_f32_16x16x32_bf16 v[60:63], v[142:145], v[198:201], v[60:63]
	v_mfma_f32_16x16x32_bf16 v[56:59], v[172:175], v[198:201], v[56:59]
	v_mfma_f32_16x16x32_bf16 v[48:51], v[142:145], v[206:209], v[48:51]
	v_mfma_f32_16x16x32_bf16 v[40:43], v[172:175], v[206:209], v[40:43]
	v_mfma_f32_16x16x32_bf16 v[32:35], v[142:145], v[214:217], v[32:35]
	v_mfma_f32_16x16x32_bf16 v[24:27], v[172:175], v[214:217], v[24:27]
	v_mfma_f32_16x16x32_bf16 v[16:19], v[142:145], v[222:225], v[16:19]
	v_mfma_f32_16x16x32_bf16 v[8:11], v[172:175], v[222:225], v[8:11]
	v_mfma_f32_16x16x32_bf16 v[52:55], v[178:181], v[194:197], v[52:55]
	v_mfma_f32_16x16x32_bf16 v[44:47], v[186:189], v[194:197], v[44:47]
	v_mfma_f32_16x16x32_bf16 v[36:39], v[178:181], v[202:205], v[36:39]
	v_mfma_f32_16x16x32_bf16 v[28:31], v[186:189], v[202:205], v[28:31]
	v_mfma_f32_16x16x32_bf16 v[20:23], v[178:181], v[210:213], v[20:23]
	v_mfma_f32_16x16x32_bf16 v[12:15], v[186:189], v[210:213], v[12:15]
	v_mfma_f32_16x16x32_bf16 v[4:7], v[178:181], v[218:221], v[4:7]
	v_mfma_f32_16x16x32_bf16 v[0:3], v[186:189], v[218:221], v[0:3]
	v_mfma_f32_16x16x32_bf16 v[52:55], v[182:185], v[198:201], v[52:55]
	v_mfma_f32_16x16x32_bf16 v[44:47], v[190:193], v[198:201], v[44:47]
	v_mfma_f32_16x16x32_bf16 v[36:39], v[182:185], v[206:209], v[36:39]
	v_mfma_f32_16x16x32_bf16 v[28:31], v[190:193], v[206:209], v[28:31]
	v_mfma_f32_16x16x32_bf16 v[20:23], v[182:185], v[214:217], v[20:23]
	v_mfma_f32_16x16x32_bf16 v[12:15], v[190:193], v[214:217], v[12:15]
	v_mfma_f32_16x16x32_bf16 v[4:7], v[182:185], v[222:225], v[4:7]
	v_mfma_f32_16x16x32_bf16 v[0:3], v[190:193], v[222:225], v[0:3]
	s_barrier
; #define PG8_STAGE(bufoff, gbase, voff, p64) do { _Pragma("unroll") for (int _i = 0; _i < 2; ++_i) { \
;         const char* _gb = (const char*)(gbase) + (size_t)_i * (p64); const unsigned _la = ldsbase + (unsigned)(bufoff) + (unsigned)_i * 8192u; \
;         asm volatile("s_mov_b32 m0, %0\n\ts_nop 0\n\tglobal_load_lds_dwordx4 %1, %2" :: "s"(_la), "v"(voff), "s"(_gb) : "memory"); } } while (0)
; #define PG8_LDA(dst, b, h) do { _Pragma("unroll") for (int m = 0; m < 4; ++m) _Pragma("unroll") for (int k = 0; k < 2; ++k) dst[m][k] = *(const LAS bf16x8*)(lds + PG8_SA(b, h) + aoff + m * 2048 + k * 1024); } while (0)
; #define PG8_LDB(dst, b, h) do { _Pragma("unroll") for (int n = 0; n < 2; ++n) _Pragma("unroll") for (int k = 0; k < 2; ++k) dst[n][k] = *(const LAS bf16x8*)(lds + PG8_SB(b, h) + boff + n * 2048 + k * 1024); } while (0)
; #define PG8_MMA(ai, bj, At, Bt) do { __builtin_amdgcn_s_setprio(1); _Pragma("unroll") for (int m = 0; m < 4; ++m) _Pragma("unroll") for (int n = 0; n < 2; ++n) _Pragma("unroll") for (int k = 0; k < 2; ++k) \
;         acc[ai][bj][m][n] = __builtin_amdgcn_mfma_f32_16x16x32_bf16(Bt[n][k], At[m][k], acc[ai][bj][m][n], 0, 0, 0); __builtin_amdgcn_s_setprio(0); } while (0)
; #define PG8_WAIT_V(n) asm volatile("s_waitcnt vmcnt(" #n ")" ::: "memory")
; #define PG8_WAIT_L(n) asm volatile("s_waitcnt lgkmcnt(" #n ")" ::: "memory")
; #define PG8_BAR __builtin_amdgcn_s_barrier()
; #define PG8_SCHED __builtin_amdgcn_sched_barrier(0)
; template <class Epi, class Sched>
; __device__ __forceinline__ void gemm_phase(LAS unsigned char* lds, const Sched& S, const Epi& E) {
;     ...
;             PG8_LDB(B0, 1, 0); PG8_LDB(B1, 1, 1); PG8_SCHED; PG8_LDA(At, 1, 0); PG8_STAGE(PG8_SA(0, 1), a2 + hA2, vA2, hA2 / 2);
;             PG8_WAIT_V(8); PG8_WAIT_L(0); PG8_BAR; PG8_MMA(0, 0, At, B0); PG8_MMA(0, 1, At, B1); PG8_BAR; PG8_SCHED;
;             PG8_LDA(At, 1, 1); PG8_STAGE(PG8_SB(1, 0), b3, vB2, hB2 / 2); PG8_STAGE(PG8_SB(1, 1), b3 + hB2, vB2, hB2 / 2); PG8_STAGE(PG8_SA(1, 0), a3, vA2, hA2 / 2);
;             PG8_WAIT_V(8); PG8_WAIT_L(0); PG8_BAR; PG8_MMA(1, 0, At, B0); PG8_MMA(1, 1, At, B1); PG8_BAR; PG8_SCHED;
;         }
;         if (wr == 0) PG8_BAR;
.Lpeel_mid_11724:
	v_add_u32_e32 v128, 0x18000, v154
	ds_read_b128 v[138:141], v128
	ds_read_b128 v[142:145], v128 offset:1024
	ds_read_b128 v[146:149], v128 offset:2048
	ds_read_b128 v[172:175], v128 offset:3072
	v_add_u32_e32 v128, 0x1c000, v154
	ds_read_b128 v[178:181], v128
	ds_read_b128 v[182:185], v128 offset:1024
	ds_read_b128 v[186:189], v128 offset:2048
	ds_read_b128 v[190:193], v128 offset:3072
	ds_read_b128 v[194:197], v155 offset:32768
	ds_read_b128 v[198:201], v155 offset:33792
	ds_read_b128 v[202:205], v155 offset:34816
	ds_read_b128 v[206:209], v155 offset:35840
	ds_read_b128 v[210:213], v155 offset:36864
	ds_read_b128 v[214:217], v155 offset:37888
	ds_read_b128 v[218:221], v155 offset:38912
	ds_read_b128 v[222:225], v155 offset:39936
	s_add_u32 s82, s16, 0x40000
	s_mov_b32 m0, s37
	s_addc_u32 s83, s17, 0
	global_load_lds_dwordx4 v150, s[82:83]
	s_add_u32 s82, s16, 0x60000
	s_mov_b32 m0, s42
	s_addc_u32 s83, s17, 0
	global_load_lds_dwordx4 v150, s[82:83]
	s_waitcnt vmcnt(8) lgkmcnt(0)
	s_barrier
	v_mfma_f32_16x16x32_bf16 v[124:127], v[138:141], v[194:197], v[124:127]
	v_mfma_f32_16x16x32_bf16 v[120:123], v[146:149], v[194:197], v[120:123]
	v_mfma_f32_16x16x32_bf16 v[112:115], v[138:141], v[202:205], v[112:115]
	v_mfma_f32_16x16x32_bf16 v[104:107], v[146:149], v[202:205], v[104:107]
	v_mfma_f32_16x16x32_bf16 v[96:99], v[138:141], v[210:213], v[96:99]
	v_mfma_f32_16x16x32_bf16 v[88:91], v[146:149], v[210:213], v[88:91]
	v_mfma_f32_16x16x32_bf16 v[80:83], v[138:141], v[218:221], v[80:83]
	v_mfma_f32_16x16x32_bf16 v[72:75], v[146:149], v[218:221], v[72:75]
	v_mfma_f32_16x16x32_bf16 v[124:127], v[142:145], v[198:201], v[124:127]
	v_mfma_f32_16x16x32_bf16 v[120:123], v[172:175], v[198:201], v[120:123]
	v_mfma_f32_16x16x32_bf16 v[112:115], v[142:145], v[206:209], v[112:115]
	v_mfma_f32_16x16x32_bf16 v[104:107], v[172:175], v[206:209], v[104:107]
	v_mfma_f32_16x16x32_bf16 v[96:99], v[142:145], v[214:217], v[96:99]
	v_mfma_f32_16x16x32_bf16 v[88:91], v[172:175], v[214:217], v[88:91]
	v_mfma_f32_16x16x32_bf16 v[80:83], v[142:145], v[222:225], v[80:83]
	v_mfma_f32_16x16x32_bf16 v[72:75], v[172:175], v[222:225], v[72:75]
	v_mfma_f32_16x16x32_bf16 v[116:119], v[178:181], v[194:197], v[116:119]
	v_mfma_f32_16x16x32_bf16 v[108:111], v[186:189], v[194:197], v[108:111]
	v_mfma_f32_16x16x32_bf16 v[100:103], v[178:181], v[202:205], v[100:103]
	v_mfma_f32_16x16x32_bf16 v[92:95], v[186:189], v[202:205], v[92:95]
	v_mfma_f32_16x16x32_bf16 v[84:87], v[178:181], v[210:213], v[84:87]
	v_mfma_f32_16x16x32_bf16 v[76:79], v[186:189], v[210:213], v[76:79]
	v_mfma_f32_16x16x32_bf16 v[68:71], v[178:181], v[218:221], v[68:71]
	v_mfma_f32_16x16x32_bf16 v[64:67], v[186:189], v[218:221], v[64:67]
	v_mfma_f32_16x16x32_bf16 v[116:119], v[182:185], v[198:201], v[116:119]
	v_mfma_f32_16x16x32_bf16 v[108:111], v[190:193], v[198:201], v[108:111]
	v_mfma_f32_16x16x32_bf16 v[100:103], v[182:185], v[206:209], v[100:103]
	v_mfma_f32_16x16x32_bf16 v[92:95], v[190:193], v[206:209], v[92:95]
	v_mfma_f32_16x16x32_bf16 v[84:87], v[182:185], v[214:217], v[84:87]
	v_mfma_f32_16x16x32_bf16 v[76:79], v[190:193], v[214:217], v[76:79]
	v_mfma_f32_16x16x32_bf16 v[68:71], v[182:185], v[222:225], v[68:71]
	v_mfma_f32_16x16x32_bf16 v[64:67], v[190:193], v[222:225], v[64:67]
	s_barrier
	s_add_u32 s82, s76, 0x80
	s_addc_u32 s83, s77, 0
	ds_read_b128 v[194:197], v155 offset:49152
	ds_read_b128 v[198:201], v155 offset:50176
	ds_read_b128 v[202:205], v155 offset:51200
	ds_read_b128 v[206:209], v155 offset:52224
	ds_read_b128 v[210:213], v155 offset:53248
	ds_read_b128 v[214:217], v155 offset:54272
	ds_read_b128 v[218:221], v155 offset:55296
	ds_read_b128 v[222:225], v155 offset:56320
	s_mov_b32 m0, s50
	s_nop 0
	global_load_lds_dwordx4 v151, s[82:83]
	s_add_u32 s82, s76, 0x20080
	s_mov_b32 m0, s51
	s_addc_u32 s83, s77, 0
	global_load_lds_dwordx4 v151, s[82:83]
	s_add_u32 s82, s76, 0x40080
	s_mov_b32 m0, s65
	s_addc_u32 s83, s77, 0
	global_load_lds_dwordx4 v151, s[82:83]
	s_add_u32 s76, s76, 0x60080
	s_mov_b32 m0, s66
	s_addc_u32 s77, s77, 0
	global_load_lds_dwordx4 v151, s[76:77]
	s_mov_b32 m0, s61
	s_nop 0
	global_load_lds_dwordx4 v150, s[22:23]
	s_add_u32 s16, s16, 0x20080
	s_mov_b32 m0, s64
	s_addc_u32 s17, s17, 0
	global_load_lds_dwordx4 v150, s[16:17]
	s_waitcnt vmcnt(8) lgkmcnt(0)
	s_barrier
	v_mfma_f32_16x16x32_bf16 v[60:63], v[138:141], v[194:197], v[60:63]
	v_mfma_f32_16x16x32_bf16 v[56:59], v[146:149], v[194:197], v[56:59]
	v_mfma_f32_16x16x32_bf16 v[48:51], v[138:141], v[202:205], v[48:51]
	v_mfma_f32_16x16x32_bf16 v[40:43], v[146:149], v[202:205], v[40:43]
	v_mfma_f32_16x16x32_bf16 v[32:35], v[138:141], v[210:213], v[32:35]
	v_mfma_f32_16x16x32_bf16 v[24:27], v[146:149], v[210:213], v[24:27]
	v_mfma_f32_16x16x32_bf16 v[16:19], v[138:141], v[218:221], v[16:19]
	v_mfma_f32_16x16x32_bf16 v[8:11], v[146:149], v[218:221], v[8:11]
	v_mfma_f32_16x16x32_bf16 v[60:63], v[142:145], v[198:201], v[60:63]
	v_mfma_f32_16x16x32_bf16 v[56:59], v[172:175], v[198:201], v[56:59]
	v_mfma_f32_16x16x32_bf16 v[48:51], v[142:145], v[206:209], v[48:51]
	v_mfma_f32_16x16x32_bf16 v[40:43], v[172:175], v[206:209], v[40:43]
	v_mfma_f32_16x16x32_bf16 v[32:35], v[142:145], v[214:217], v[32:35]
	v_mfma_f32_16x16x32_bf16 v[24:27], v[172:175], v[214:217], v[24:27]
	v_mfma_f32_16x16x32_bf16 v[16:19], v[142:145], v[222:225], v[16:19]
	v_mfma_f32_16x16x32_bf16 v[8:11], v[172:175], v[222:225], v[8:11]
	v_mfma_f32_16x16x32_bf16 v[52:55], v[178:181], v[194:197], v[52:55]
	v_mfma_f32_16x16x32_bf16 v[44:47], v[186:189], v[194:197], v[44:47]
	v_mfma_f32_16x16x32_bf16 v[36:39], v[178:181], v[202:205], v[36:39]
	v_mfma_f32_16x16x32_bf16 v[28:31], v[186:189], v[202:205], v[28:31]
	v_mfma_f32_16x16x32_bf16 v[20:23], v[178:181], v[210:213], v[20:23]
	v_mfma_f32_16x16x32_bf16 v[12:15], v[186:189], v[210:213], v[12:15]
	v_mfma_f32_16x16x32_bf16 v[4:7], v[178:181], v[218:221], v[4:7]
	v_mfma_f32_16x16x32_bf16 v[0:3], v[186:189], v[218:221], v[0:3]
	v_mfma_f32_16x16x32_bf16 v[52:55], v[182:185], v[198:201], v[52:55]
	v_mfma_f32_16x16x32_bf16 v[44:47], v[190:193], v[198:201], v[44:47]
	v_mfma_f32_16x16x32_bf16 v[36:39], v[182:185], v[206:209], v[36:39]
	v_mfma_f32_16x16x32_bf16 v[28:31], v[190:193], v[206:209], v[28:31]
	v_mfma_f32_16x16x32_bf16 v[20:23], v[182:185], v[214:217], v[20:23]
	v_mfma_f32_16x16x32_bf16 v[12:15], v[190:193], v[214:217], v[12:15]
	v_mfma_f32_16x16x32_bf16 v[4:7], v[182:185], v[222:225], v[4:7]
	v_mfma_f32_16x16x32_bf16 v[0:3], v[190:193], v[222:225], v[0:3]
	s_barrier
	s_cmp_gt_u32 s81, 13
	s_cbranch_scc0 .LBB0_553
	s_and_b64 vcc, exec, s[6:7]
	s_cbranch_vccz .LBB0_556
	s_barrier

; #define PG8_STAGE(bufoff, gbase, voff, p64) do { _Pragma("unroll") for (int _i = 0; _i < 2; ++_i) { \
;         const char* _gb = (const char*)(gbase) + (size_t)_i * (p64); const unsigned _la = ldsbase + (unsigned)(bufoff) + (unsigned)_i * 8192u; \
;         asm volatile("s_mov_b32 m0, %0\n\ts_nop 0\n\tglobal_load_lds_dwordx4 %1, %2" :: "s"(_la), "v"(voff), "s"(_gb) : "memory"); } } while (0)
; #define PG8_LDA(dst, b, h) do { _Pragma("unroll") for (int m = 0; m < 4; ++m) _Pragma("unroll") for (int k = 0; k < 2; ++k) dst[m][k] = *(const LAS bf16x8*)(lds + PG8_SA(b, h) + aoff + m * 2048 + k * 1024); } while (0)
; #define PG8_LDB(dst, b, h) do { _Pragma("unroll") for (int n = 0; n < 2; ++n) _Pragma("unroll") for (int k = 0; k < 2; ++k) dst[n][k] = *(const LAS bf16x8*)(lds + PG8_SB(b, h) + boff + n * 2048 + k * 1024); } while (0)
; #define PG8_MMA(ai, bj, At, Bt) do { __builtin_amdgcn_s_setprio(1); _Pragma("unroll") for (int m = 0; m < 4; ++m) _Pragma("unroll") for (int n = 0; n < 2; ++n) _Pragma("unroll") for (int k = 0; k < 2; ++k) \
;         acc[ai][bj][m][n] = __builtin_amdgcn_mfma_f32_16x16x32_bf16(Bt[n][k], At[m][k], acc[ai][bj][m][n], 0, 0, 0); __builtin_amdgcn_s_setprio(0); } while (0)
; #define PG8_WAIT_V(n) asm volatile("s_waitcnt vmcnt(" #n ")" ::: "memory")
; template <class Epi, class Sched>
; __device__ __forceinline__ void gemm_phase(LAS unsigned char* lds, const Sched& S, const Epi& E) {
;     ...
;         for (int t = 0; t < nt; t += 2) {
;             const bool last = (t == nt - 2);
;             const char* a1 = cA + (size_t)(t + 1) * kstep;
;             const char* a2 = last ? nA : cA + (size_t)(t + 2) * kstep; const char* b2 = last ? nB : cB + (size_t)(t + 2) * kstep;
;             const char* a3 = a2 + kstep; const char* b3 = b2 + kstep;
;             const unsigned vA2 = voffA, vB2 = voffB, hA2 = hA, hB2 = hB;
;             PG8_LDB(B0, 0, 0); PG8_LDB(B1, 0, 1); PG8_SCHED; PG8_LDA(At, 0, 0); PG8_STAGE(PG8_SA(1, 1), a1 + hA, voffA, hA / 2);
;             PG8_WAIT_V(8); PG8_WAIT_L(0); PG8_BAR; PG8_MMA(0, 0, At, B0); PG8_MMA(0, 1, At, B1); PG8_BAR; PG8_SCHED;
;             PG8_LDA(At, 0, 1); PG8_STAGE(PG8_SB(0, 0), b2, vB2, hB2 / 2); PG8_STAGE(PG8_SB(0, 1), b2 + hB2, vB2, hB2 / 2); PG8_STAGE(PG8_SA(0, 0), a2, vA2, hA2 / 2);
;             PG8_WAIT_V(8); PG8_WAIT_L(0); PG8_BAR; PG8_MMA(1, 0, At, B0); PG8_MMA(1, 1, At, B1); PG8_BAR; PG8_SCHED;
.LBB0_581:
	s_add_u32 s62, s16, 0x40080
	s_addc_u32 s63, s17, 0
	s_add_u32 s55, s22, 0x100
	s_addc_u32 s74, s23, 0
	s_mov_b32 s75, -2
	s_waitcnt vmcnt(1)
	s_waitcnt vmcnt(0)
	v_add_u32_e32 v130, 0x10000, v153
	ds_read_b128 v[138:141], v130
	ds_read_b128 v[142:145], v130 offset:1024
	ds_read_b128 v[146:149], v130 offset:2048
	ds_read_b128 v[172:175], v130 offset:3072
	v_add_u32_e32 v130, 0x14000, v153
	ds_read_b128 v[178:181], v130
	ds_read_b128 v[182:185], v130 offset:1024
	ds_read_b128 v[186:189], v130 offset:2048
	ds_read_b128 v[190:193], v130 offset:3072
	s_add_u32 s16, s62, 0xfffc0080
	s_addc_u32 s17, s63, -1
	s_cmp_eq_u32 s75, 12
	s_cselect_b32 s16, s56, s16
	s_cselect_b32 s17, s57, s17
	s_cselect_b32 s72, s58, s55
	s_cselect_b32 s73, s59, s74
	s_add_u32 s22, s16, 0x80
	s_addc_u32 s23, s17, 0
	ds_read_b128 v[194:197], v154
	ds_read_b128 v[198:201], v154 offset:1024
	ds_read_b128 v[202:205], v154 offset:2048
	ds_read_b128 v[206:209], v154 offset:3072
	ds_read_b128 v[210:213], v154 offset:4096
	ds_read_b128 v[214:217], v154 offset:5120
	ds_read_b128 v[218:221], v154 offset:6144
	ds_read_b128 v[222:225], v154 offset:7168
	s_mov_b32 m0, s78
	s_nop 0
	global_load_lds_dwordx4 v128, s[62:63]
	s_add_u32 s82, s62, 0x20000
	s_mov_b32 m0, s80
	s_addc_u32 s83, s63, 0
	global_load_lds_dwordx4 v128, s[82:83]
	s_waitcnt vmcnt(8) lgkmcnt(0)
	s_barrier
	v_mfma_f32_16x16x32_bf16 v[124:127], v[138:141], v[194:197], 0
	v_mfma_f32_16x16x32_bf16 v[120:123], v[146:149], v[194:197], 0
	v_mfma_f32_16x16x32_bf16 v[116:119], v[138:141], v[202:205], 0
	v_mfma_f32_16x16x32_bf16 v[108:111], v[146:149], v[202:205], 0
	v_mfma_f32_16x16x32_bf16 v[100:103], v[138:141], v[210:213], 0
	v_mfma_f32_16x16x32_bf16 v[92:95], v[146:149], v[210:213], 0
	v_mfma_f32_16x16x32_bf16 v[84:87], v[138:141], v[218:221], 0
	v_mfma_f32_16x16x32_bf16 v[76:79], v[146:149], v[218:221], 0
	v_mfma_f32_16x16x32_bf16 v[124:127], v[142:145], v[198:201], v[124:127]
	v_mfma_f32_16x16x32_bf16 v[120:123], v[172:175], v[198:201], v[120:123]
	v_mfma_f32_16x16x32_bf16 v[116:119], v[142:145], v[206:209], v[116:119]
	v_mfma_f32_16x16x32_bf16 v[108:111], v[172:175], v[206:209], v[108:111]
	v_mfma_f32_16x16x32_bf16 v[100:103], v[142:145], v[214:217], v[100:103]
	v_mfma_f32_16x16x32_bf16 v[92:95], v[172:175], v[214:217], v[92:95]
	v_mfma_f32_16x16x32_bf16 v[84:87], v[142:145], v[222:225], v[84:87]
	v_mfma_f32_16x16x32_bf16 v[76:79], v[172:175], v[222:225], v[76:79]
	v_mfma_f32_16x16x32_bf16 v[112:115], v[178:181], v[194:197], 0
	v_mfma_f32_16x16x32_bf16 v[104:107], v[186:189], v[194:197], 0
	v_mfma_f32_16x16x32_bf16 v[96:99], v[178:181], v[202:205], 0
	v_mfma_f32_16x16x32_bf16 v[88:91], v[186:189], v[202:205], 0
	v_mfma_f32_16x16x32_bf16 v[80:83], v[178:181], v[210:213], 0
	v_mfma_f32_16x16x32_bf16 v[72:75], v[186:189], v[210:213], 0
	v_mfma_f32_16x16x32_bf16 v[68:71], v[178:181], v[218:221], 0
	v_mfma_f32_16x16x32_bf16 v[64:67], v[186:189], v[218:221], 0
	v_mfma_f32_16x16x32_bf16 v[112:115], v[182:185], v[198:201], v[112:115]
	v_mfma_f32_16x16x32_bf16 v[104:107], v[190:193], v[198:201], v[104:107]
	v_mfma_f32_16x16x32_bf16 v[96:99], v[182:185], v[206:209], v[96:99]
	v_mfma_f32_16x16x32_bf16 v[88:91], v[190:193], v[206:209], v[88:91]
	v_mfma_f32_16x16x32_bf16 v[80:83], v[182:185], v[214:217], v[80:83]
	v_mfma_f32_16x16x32_bf16 v[72:75], v[190:193], v[214:217], v[72:75]
	v_mfma_f32_16x16x32_bf16 v[68:71], v[182:185], v[222:225], v[68:71]
	v_mfma_f32_16x16x32_bf16 v[64:67], v[190:193], v[222:225], v[64:67]
	s_add_i32 s75, s75, 2
	s_add_u32 s62, s62, 0x100
	s_addc_u32 s63, s63, 0
	s_add_u32 s55, s55, 0x100
	s_addc_u32 s74, s74, 0
	s_barrier
	s_add_u32 s82, s72, 0x20000
	ds_read_b128 v[194:197], v154 offset:16384
	ds_read_b128 v[198:201], v154 offset:17408
	ds_read_b128 v[202:205], v154 offset:18432
	ds_read_b128 v[206:209], v154 offset:19456
	ds_read_b128 v[210:213], v154 offset:20480
	ds_read_b128 v[214:217], v154 offset:21504
	ds_read_b128 v[218:221], v154 offset:22528
	ds_read_b128 v[222:225], v154 offset:23552
	s_mov_b32 m0, s20
	s_nop 0
	global_load_lds_dwordx4 v150, s[72:73]
	s_mov_b32 m0, s24
	s_addc_u32 s83, s73, 0
	global_load_lds_dwordx4 v150, s[82:83]
	s_add_u32 s82, s72, 0x40000
	s_mov_b32 m0, s33
	s_addc_u32 s83, s73, 0
	global_load_lds_dwordx4 v150, s[82:83]
	s_add_u32 s82, s72, 0x60000
	s_mov_b32 m0, s34
	s_addc_u32 s83, s73, 0
	global_load_lds_dwordx4 v150, s[82:83]
	s_mov_b32 m0, s15
	s_nop 0
	global_load_lds_dwordx4 v128, s[16:17]
	s_add_u32 s82, s16, 0x20000
	s_mov_b32 m0, s35
	s_addc_u32 s83, s17, 0
	global_load_lds_dwordx4 v128, s[82:83]
	s_waitcnt vmcnt(8) lgkmcnt(0)
	s_barrier
	v_mfma_f32_16x16x32_bf16 v[60:63], v[138:141], v[194:197], 0
	v_mfma_f32_16x16x32_bf16 v[56:59], v[146:149], v[194:197], 0
	v_mfma_f32_16x16x32_bf16 v[52:55], v[138:141], v[202:205], 0
	v_mfma_f32_16x16x32_bf16 v[44:47], v[146:149], v[202:205], 0
	v_mfma_f32_16x16x32_bf16 v[36:39], v[138:141], v[210:213], 0
	v_mfma_f32_16x16x32_bf16 v[28:31], v[146:149], v[210:213], 0
	v_mfma_f32_16x16x32_bf16 v[20:23], v[138:141], v[218:221], 0
	v_mfma_f32_16x16x32_bf16 v[12:15], v[146:149], v[218:221], 0
	v_mfma_f32_16x16x32_bf16 v[60:63], v[142:145], v[198:201], v[60:63]
	v_mfma_f32_16x16x32_bf16 v[56:59], v[172:175], v[198:201], v[56:59]
	v_mfma_f32_16x16x32_bf16 v[52:55], v[142:145], v[206:209], v[52:55]
	v_mfma_f32_16x16x32_bf16 v[44:47], v[172:175], v[206:209], v[44:47]
	v_mfma_f32_16x16x32_bf16 v[36:39], v[142:145], v[214:217], v[36:39]
	v_mfma_f32_16x16x32_bf16 v[28:31], v[172:175], v[214:217], v[28:31]
	v_mfma_f32_16x16x32_bf16 v[20:23], v[142:145], v[222:225], v[20:23]
	v_mfma_f32_16x16x32_bf16 v[12:15], v[172:175], v[222:225], v[12:15]
	v_mfma_f32_16x16x32_bf16 v[48:51], v[178:181], v[194:197], 0
	v_mfma_f32_16x16x32_bf16 v[40:43], v[186:189], v[194:197], 0
	v_mfma_f32_16x16x32_bf16 v[32:35], v[178:181], v[202:205], 0
	v_mfma_f32_16x16x32_bf16 v[24:27], v[186:189], v[202:205], 0
	v_mfma_f32_16x16x32_bf16 v[16:19], v[178:181], v[210:213], 0
	v_mfma_f32_16x16x32_bf16 v[8:11], v[186:189], v[210:213], 0
	v_mfma_f32_16x16x32_bf16 v[4:7], v[178:181], v[218:221], 0
	v_mfma_f32_16x16x32_bf16 v[0:3], v[186:189], v[218:221], 0
	v_mfma_f32_16x16x32_bf16 v[48:51], v[182:185], v[198:201], v[48:51]
	v_mfma_f32_16x16x32_bf16 v[40:43], v[190:193], v[198:201], v[40:43]
	v_mfma_f32_16x16x32_bf16 v[32:35], v[182:185], v[206:209], v[32:35]
	v_mfma_f32_16x16x32_bf16 v[24:27], v[190:193], v[206:209], v[24:27]
	v_mfma_f32_16x16x32_bf16 v[16:19], v[182:185], v[214:217], v[16:19]
	v_mfma_f32_16x16x32_bf16 v[8:11], v[190:193], v[214:217], v[8:11]
	v_mfma_f32_16x16x32_bf16 v[4:7], v[182:185], v[222:225], v[4:7]
	v_mfma_f32_16x16x32_bf16 v[0:3], v[190:193], v[222:225], v[0:3]
	s_barrier
	s_branch .Lpeel_mid_14726
; #define PG8_STAGE(bufoff, gbase, voff, p64) do { _Pragma("unroll") for (int _i = 0; _i < 2; ++_i) { \
;         const char* _gb = (const char*)(gbase) + (size_t)_i * (p64); const unsigned _la = ldsbase + (unsigned)(bufoff) + (unsigned)_i * 8192u; \
;         asm volatile("s_mov_b32 m0, %0\n\ts_nop 0\n\tglobal_load_lds_dwordx4 %1, %2" :: "s"(_la), "v"(voff), "s"(_gb) : "memory"); } } while (0)
; #define PG8_LDA(dst, b, h) do { _Pragma("unroll") for (int m = 0; m < 4; ++m) _Pragma("unroll") for (int k = 0; k < 2; ++k) dst[m][k] = *(const LAS bf16x8*)(lds + PG8_SA(b, h) + aoff + m * 2048 + k * 1024); } while (0)
; #define PG8_LDB(dst, b, h) do { _Pragma("unroll") for (int n = 0; n < 2; ++n) _Pragma("unroll") for (int k = 0; k < 2; ++k) dst[n][k] = *(const LAS bf16x8*)(lds + PG8_SB(b, h) + boff + n * 2048 + k * 1024); } while (0)
; #define PG8_MMA(ai, bj, At, Bt) do { __builtin_amdgcn_s_setprio(1); _Pragma("unroll") for (int m = 0; m < 4; ++m) _Pragma("unroll") for (int n = 0; n < 2; ++n) _Pragma("unroll") for (int k = 0; k < 2; ++k) \
;         acc[ai][bj][m][n] = __builtin_amdgcn_mfma_f32_16x16x32_bf16(Bt[n][k], At[m][k], acc[ai][bj][m][n], 0, 0, 0); __builtin_amdgcn_s_setprio(0); } while (0)
; #define PG8_WAIT_V(n) asm volatile("s_waitcnt vmcnt(" #n ")" ::: "memory")
; #define PG8_BAR __builtin_amdgcn_s_barrier()
; template <class Epi, class Sched>
; __device__ __forceinline__ void gemm_phase(LAS unsigned char* lds, const Sched& S, const Epi& E) {
;     ...
;             const bool last = (t == nt - 2);
;             const char* a1 = cA + (size_t)(t + 1) * kstep;
;             const char* a2 = last ? nA : cA + (size_t)(t + 2) * kstep; const char* b2 = last ? nB : cB + (size_t)(t + 2) * kstep;
;             const char* a3 = a2 + kstep; const char* b3 = b2 + kstep;
;             const unsigned vA2 = voffA, vB2 = voffB, hA2 = hA, hB2 = hB;
;             PG8_LDB(B0, 0, 0); PG8_LDB(B1, 0, 1); PG8_SCHED; PG8_LDA(At, 0, 0); PG8_STAGE(PG8_SA(1, 1), a1 + hA, voffA, hA / 2);
;             PG8_WAIT_V(8); PG8_WAIT_L(0); PG8_BAR; PG8_MMA(0, 0, At, B0); PG8_MMA(0, 1, At, B1); PG8_BAR; PG8_SCHED;
;             PG8_LDA(At, 0, 1); PG8_STAGE(PG8_SB(0, 0), b2, vB2, hB2 / 2); PG8_STAGE(PG8_SB(0, 1), b2 + hB2, vB2, hB2 / 2); PG8_STAGE(PG8_SA(0, 0), a2, vA2, hA2 / 2);
;             PG8_WAIT_V(8); PG8_WAIT_L(0); PG8_BAR; PG8_MMA(1, 0, At, B0); PG8_MMA(1, 1, At, B1); PG8_BAR; PG8_SCHED;
.LBB0_582:
	v_add_u32_e32 v130, 0x10000, v153
	ds_read_b128 v[138:141], v130
	ds_read_b128 v[142:145], v130 offset:1024
	ds_read_b128 v[146:149], v130 offset:2048
	ds_read_b128 v[172:175], v130 offset:3072
	v_add_u32_e32 v130, 0x14000, v153
	ds_read_b128 v[178:181], v130
	ds_read_b128 v[182:185], v130 offset:1024
	ds_read_b128 v[186:189], v130 offset:2048
	ds_read_b128 v[190:193], v130 offset:3072
	s_add_u32 s16, s62, 0xfffc0080
	s_addc_u32 s17, s63, -1
	s_cmp_eq_u32 s75, 12
	s_cselect_b32 s16, s56, s16
	s_cselect_b32 s17, s57, s17
	s_cselect_b32 s72, s58, s55
	s_cselect_b32 s73, s59, s74
	s_add_u32 s22, s16, 0x80
	s_addc_u32 s23, s17, 0
	ds_read_b128 v[194:197], v154
	ds_read_b128 v[198:201], v154 offset:1024
	ds_read_b128 v[202:205], v154 offset:2048
	ds_read_b128 v[206:209], v154 offset:3072
	ds_read_b128 v[210:213], v154 offset:4096
	ds_read_b128 v[214:217], v154 offset:5120
	ds_read_b128 v[218:221], v154 offset:6144
	ds_read_b128 v[222:225], v154 offset:7168
	s_mov_b32 m0, s78
	s_nop 0
	global_load_lds_dwordx4 v128, s[62:63]
	s_add_u32 s82, s62, 0x20000
	s_mov_b32 m0, s80
	s_addc_u32 s83, s63, 0
	global_load_lds_dwordx4 v128, s[82:83]
	s_waitcnt vmcnt(8) lgkmcnt(0)
	s_barrier
	v_mfma_f32_16x16x32_bf16 v[124:127], v[138:141], v[194:197], v[124:127]
	v_mfma_f32_16x16x32_bf16 v[120:123], v[146:149], v[194:197], v[120:123]
	v_mfma_f32_16x16x32_bf16 v[116:119], v[138:141], v[202:205], v[116:119]
	v_mfma_f32_16x16x32_bf16 v[108:111], v[146:149], v[202:205], v[108:111]
	v_mfma_f32_16x16x32_bf16 v[100:103], v[138:141], v[210:213], v[100:103]
	v_mfma_f32_16x16x32_bf16 v[92:95], v[146:149], v[210:213], v[92:95]
	v_mfma_f32_16x16x32_bf16 v[84:87], v[138:141], v[218:221], v[84:87]
	v_mfma_f32_16x16x32_bf16 v[76:79], v[146:149], v[218:221], v[76:79]
	v_mfma_f32_16x16x32_bf16 v[124:127], v[142:145], v[198:201], v[124:127]
	v_mfma_f32_16x16x32_bf16 v[120:123], v[172:175], v[198:201], v[120:123]
	v_mfma_f32_16x16x32_bf16 v[116:119], v[142:145], v[206:209], v[116:119]
	v_mfma_f32_16x16x32_bf16 v[108:111], v[172:175], v[206:209], v[108:111]
	v_mfma_f32_16x16x32_bf16 v[100:103], v[142:145], v[214:217], v[100:103]
	v_mfma_f32_16x16x32_bf16 v[92:95], v[172:175], v[214:217], v[92:95]
	v_mfma_f32_16x16x32_bf16 v[84:87], v[142:145], v[222:225], v[84:87]
	v_mfma_f32_16x16x32_bf16 v[76:79], v[172:175], v[222:225], v[76:79]
	v_mfma_f32_16x16x32_bf16 v[112:115], v[178:181], v[194:197], v[112:115]
	v_mfma_f32_16x16x32_bf16 v[104:107], v[186:189], v[194:197], v[104:107]
	v_mfma_f32_16x16x32_bf16 v[96:99], v[178:181], v[202:205], v[96:99]
	v_mfma_f32_16x16x32_bf16 v[88:91], v[186:189], v[202:205], v[88:91]
	v_mfma_f32_16x16x32_bf16 v[80:83], v[178:181], v[210:213], v[80:83]
	v_mfma_f32_16x16x32_bf16 v[72:75], v[186:189], v[210:213], v[72:75]
	v_mfma_f32_16x16x32_bf16 v[68:71], v[178:181], v[218:221], v[68:71]
	v_mfma_f32_16x16x32_bf16 v[64:67], v[186:189], v[218:221], v[64:67]
	v_mfma_f32_16x16x32_bf16 v[112:115], v[182:185], v[198:201], v[112:115]
	v_mfma_f32_16x16x32_bf16 v[104:107], v[190:193], v[198:201], v[104:107]
	v_mfma_f32_16x16x32_bf16 v[96:99], v[182:185], v[206:209], v[96:99]
	v_mfma_f32_16x16x32_bf16 v[88:91], v[190:193], v[206:209], v[88:91]
	v_mfma_f32_16x16x32_bf16 v[80:83], v[182:185], v[214:217], v[80:83]
	v_mfma_f32_16x16x32_bf16 v[72:75], v[190:193], v[214:217], v[72:75]
	v_mfma_f32_16x16x32_bf16 v[68:71], v[182:185], v[222:225], v[68:71]
	v_mfma_f32_16x16x32_bf16 v[64:67], v[190:193], v[222:225], v[64:67]
	s_add_i32 s75, s75, 2
	s_add_u32 s62, s62, 0x100
	s_addc_u32 s63, s63, 0
	s_add_u32 s55, s55, 0x100
	s_addc_u32 s74, s74, 0
	s_barrier
	s_add_u32 s82, s72, 0x20000
	ds_read_b128 v[194:197], v154 offset:16384
	ds_read_b128 v[198:201], v154 offset:17408
	ds_read_b128 v[202:205], v154 offset:18432
	ds_read_b128 v[206:209], v154 offset:19456
	ds_read_b128 v[210:213], v154 offset:20480
	ds_read_b128 v[214:217], v154 offset:21504
	ds_read_b128 v[218:221], v154 offset:22528
	ds_read_b128 v[222:225], v154 offset:23552
	s_mov_b32 m0, s20
	s_nop 0
	global_load_lds_dwordx4 v150, s[72:73]
	s_mov_b32 m0, s24
	s_addc_u32 s83, s73, 0
	global_load_lds_dwordx4 v150, s[82:83]
	s_add_u32 s82, s72, 0x40000
	s_mov_b32 m0, s33
	s_addc_u32 s83, s73, 0
	global_load_lds_dwordx4 v150, s[82:83]
	s_add_u32 s82, s72, 0x60000
	s_mov_b32 m0, s34
	s_addc_u32 s83, s73, 0
	global_load_lds_dwordx4 v150, s[82:83]
	s_mov_b32 m0, s15
	s_nop 0
	global_load_lds_dwordx4 v128, s[16:17]
	s_add_u32 s82, s16, 0x20000
	s_mov_b32 m0, s35
	s_addc_u32 s83, s17, 0
	global_load_lds_dwordx4 v128, s[82:83]
	s_waitcnt vmcnt(8) lgkmcnt(0)
	s_barrier
	v_mfma_f32_16x16x32_bf16 v[60:63], v[138:141], v[194:197], v[60:63]
	v_mfma_f32_16x16x32_bf16 v[56:59], v[146:149], v[194:197], v[56:59]
	v_mfma_f32_16x16x32_bf16 v[52:55], v[138:141], v[202:205], v[52:55]
	v_mfma_f32_16x16x32_bf16 v[44:47], v[146:149], v[202:205], v[44:47]
	v_mfma_f32_16x16x32_bf16 v[36:39], v[138:141], v[210:213], v[36:39]
	v_mfma_f32_16x16x32_bf16 v[28:31], v[146:149], v[210:213], v[28:31]
	v_mfma_f32_16x16x32_bf16 v[20:23], v[138:141], v[218:221], v[20:23]
	v_mfma_f32_16x16x32_bf16 v[12:15], v[146:149], v[218:221], v[12:15]
	v_mfma_f32_16x16x32_bf16 v[60:63], v[142:145], v[198:201], v[60:63]
	v_mfma_f32_16x16x32_bf16 v[56:59], v[172:175], v[198:201], v[56:59]
	v_mfma_f32_16x16x32_bf16 v[52:55], v[142:145], v[206:209], v[52:55]
	v_mfma_f32_16x16x32_bf16 v[44:47], v[172:175], v[206:209], v[44:47]
	v_mfma_f32_16x16x32_bf16 v[36:39], v[142:145], v[214:217], v[36:39]
	v_mfma_f32_16x16x32_bf16 v[28:31], v[172:175], v[214:217], v[28:31]
	v_mfma_f32_16x16x32_bf16 v[20:23], v[142:145], v[222:225], v[20:23]
	v_mfma_f32_16x16x32_bf16 v[12:15], v[172:175], v[222:225], v[12:15]
	v_mfma_f32_16x16x32_bf16 v[48:51], v[178:181], v[194:197], v[48:51]
	v_mfma_f32_16x16x32_bf16 v[40:43], v[186:189], v[194:197], v[40:43]
	v_mfma_f32_16x16x32_bf16 v[32:35], v[178:181], v[202:205], v[32:35]
	v_mfma_f32_16x16x32_bf16 v[24:27], v[186:189], v[202:205], v[24:27]
	v_mfma_f32_16x16x32_bf16 v[16:19], v[178:181], v[210:213], v[16:19]
	v_mfma_f32_16x16x32_bf16 v[8:11], v[186:189], v[210:213], v[8:11]
	v_mfma_f32_16x16x32_bf16 v[4:7], v[178:181], v[218:221], v[4:7]
	v_mfma_f32_16x16x32_bf16 v[0:3], v[186:189], v[218:221], v[0:3]
	v_mfma_f32_16x16x32_bf16 v[48:51], v[182:185], v[198:201], v[48:51]
	v_mfma_f32_16x16x32_bf16 v[40:43], v[190:193], v[198:201], v[40:43]
	v_mfma_f32_16x16x32_bf16 v[32:35], v[182:185], v[206:209], v[32:35]
	v_mfma_f32_16x16x32_bf16 v[24:27], v[190:193], v[206:209], v[24:27]
	v_mfma_f32_16x16x32_bf16 v[16:19], v[182:185], v[214:217], v[16:19]
	v_mfma_f32_16x16x32_bf16 v[8:11], v[190:193], v[214:217], v[8:11]
	v_mfma_f32_16x16x32_bf16 v[4:7], v[182:185], v[222:225], v[4:7]
	v_mfma_f32_16x16x32_bf16 v[0:3], v[190:193], v[222:225], v[0:3]
	s_barrier
; #define PG8_STAGE(bufoff, gbase, voff, p64) do { _Pragma("unroll") for (int _i = 0; _i < 2; ++_i) { \
;         const char* _gb = (const char*)(gbase) + (size_t)_i * (p64); const unsigned _la = ldsbase + (unsigned)(bufoff) + (unsigned)_i * 8192u; \
;         asm volatile("s_mov_b32 m0, %0\n\ts_nop 0\n\tglobal_load_lds_dwordx4 %1, %2" :: "s"(_la), "v"(voff), "s"(_gb) : "memory"); } } while (0)
; #define PG8_LDA(dst, b, h) do { _Pragma("unroll") for (int m = 0; m < 4; ++m) _Pragma("unroll") for (int k = 0; k < 2; ++k) dst[m][k] = *(const LAS bf16x8*)(lds + PG8_SA(b, h) + aoff + m * 2048 + k * 1024); } while (0)
; #define PG8_LDB(dst, b, h) do { _Pragma("unroll") for (int n = 0; n < 2; ++n) _Pragma("unroll") for (int k = 0; k < 2; ++k) dst[n][k] = *(const LAS bf16x8*)(lds + PG8_SB(b, h) + boff + n * 2048 + k * 1024); } while (0)
; #define PG8_MMA(ai, bj, At, Bt) do { __builtin_amdgcn_s_setprio(1); _Pragma("unroll") for (int m = 0; m < 4; ++m) _Pragma("unroll") for (int n = 0; n < 2; ++n) _Pragma("unroll") for (int k = 0; k < 2; ++k) \
;         acc[ai][bj][m][n] = __builtin_amdgcn_mfma_f32_16x16x32_bf16(Bt[n][k], At[m][k], acc[ai][bj][m][n], 0, 0, 0); __builtin_amdgcn_s_setprio(0); } while (0)
; #define PG8_WAIT_V(n) asm volatile("s_waitcnt vmcnt(" #n ")" ::: "memory")
; #define PG8_WAIT_L(n) asm volatile("s_waitcnt lgkmcnt(" #n ")" ::: "memory")
; #define PG8_BAR __builtin_amdgcn_s_barrier()
; #define PG8_SCHED __builtin_amdgcn_sched_barrier(0)
; template <class Epi, class Sched>
; __device__ __forceinline__ void gemm_phase(LAS unsigned char* lds, const Sched& S, const Epi& E) {
;     ...
;             PG8_LDB(B0, 1, 0); PG8_LDB(B1, 1, 1); PG8_SCHED; PG8_LDA(At, 1, 0); PG8_STAGE(PG8_SA(0, 1), a2 + hA2, vA2, hA2 / 2);
;             PG8_WAIT_V(8); PG8_WAIT_L(0); PG8_BAR; PG8_MMA(0, 0, At, B0); PG8_MMA(0, 1, At, B1); PG8_BAR; PG8_SCHED;
;             PG8_LDA(At, 1, 1); PG8_STAGE(PG8_SB(1, 0), b3, vB2, hB2 / 2); PG8_STAGE(PG8_SB(1, 1), b3 + hB2, vB2, hB2 / 2); PG8_STAGE(PG8_SA(1, 0), a3, vA2, hA2 / 2);
;             PG8_WAIT_V(8); PG8_WAIT_L(0); PG8_BAR; PG8_MMA(1, 0, At, B0); PG8_MMA(1, 1, At, B1); PG8_BAR; PG8_SCHED;
;         }
;         if (wr == 0) PG8_BAR;
.Lpeel_mid_14726:
	v_add_u32_e32 v130, 0x18000, v153
	ds_read_b128 v[138:141], v130
	ds_read_b128 v[142:145], v130 offset:1024
	ds_read_b128 v[146:149], v130 offset:2048
	ds_read_b128 v[172:175], v130 offset:3072
	v_add_u32_e32 v130, 0x1c000, v153
	ds_read_b128 v[178:181], v130
	ds_read_b128 v[182:185], v130 offset:1024
	ds_read_b128 v[186:189], v130 offset:2048
	ds_read_b128 v[190:193], v130 offset:3072
	ds_read_b128 v[194:197], v154 offset:32768
	ds_read_b128 v[198:201], v154 offset:33792
	ds_read_b128 v[202:205], v154 offset:34816
	ds_read_b128 v[206:209], v154 offset:35840
	ds_read_b128 v[210:213], v154 offset:36864
	ds_read_b128 v[214:217], v154 offset:37888
	ds_read_b128 v[218:221], v154 offset:38912
	ds_read_b128 v[222:225], v154 offset:39936
	s_add_u32 s82, s16, 0x40000
	s_mov_b32 m0, s36
	s_addc_u32 s83, s17, 0
	global_load_lds_dwordx4 v128, s[82:83]
	s_add_u32 s82, s16, 0x60000
	s_mov_b32 m0, s37
	s_addc_u32 s83, s17, 0
	global_load_lds_dwordx4 v128, s[82:83]
	s_waitcnt vmcnt(8) lgkmcnt(0)
	s_barrier
	v_mfma_f32_16x16x32_bf16 v[124:127], v[138:141], v[194:197], v[124:127]
	v_mfma_f32_16x16x32_bf16 v[120:123], v[146:149], v[194:197], v[120:123]
	v_mfma_f32_16x16x32_bf16 v[116:119], v[138:141], v[202:205], v[116:119]
	v_mfma_f32_16x16x32_bf16 v[108:111], v[146:149], v[202:205], v[108:111]
	v_mfma_f32_16x16x32_bf16 v[100:103], v[138:141], v[210:213], v[100:103]
	v_mfma_f32_16x16x32_bf16 v[92:95], v[146:149], v[210:213], v[92:95]
	v_mfma_f32_16x16x32_bf16 v[84:87], v[138:141], v[218:221], v[84:87]
	v_mfma_f32_16x16x32_bf16 v[76:79], v[146:149], v[218:221], v[76:79]
	v_mfma_f32_16x16x32_bf16 v[124:127], v[142:145], v[198:201], v[124:127]
	v_mfma_f32_16x16x32_bf16 v[120:123], v[172:175], v[198:201], v[120:123]
	v_mfma_f32_16x16x32_bf16 v[116:119], v[142:145], v[206:209], v[116:119]
	v_mfma_f32_16x16x32_bf16 v[108:111], v[172:175], v[206:209], v[108:111]
	v_mfma_f32_16x16x32_bf16 v[100:103], v[142:145], v[214:217], v[100:103]
	v_mfma_f32_16x16x32_bf16 v[92:95], v[172:175], v[214:217], v[92:95]
	v_mfma_f32_16x16x32_bf16 v[84:87], v[142:145], v[222:225], v[84:87]
	v_mfma_f32_16x16x32_bf16 v[76:79], v[172:175], v[222:225], v[76:79]
	v_mfma_f32_16x16x32_bf16 v[112:115], v[178:181], v[194:197], v[112:115]
	v_mfma_f32_16x16x32_bf16 v[104:107], v[186:189], v[194:197], v[104:107]
	v_mfma_f32_16x16x32_bf16 v[96:99], v[178:181], v[202:205], v[96:99]
	v_mfma_f32_16x16x32_bf16 v[88:91], v[186:189], v[202:205], v[88:91]
	v_mfma_f32_16x16x32_bf16 v[80:83], v[178:181], v[210:213], v[80:83]
	v_mfma_f32_16x16x32_bf16 v[72:75], v[186:189], v[210:213], v[72:75]
	v_mfma_f32_16x16x32_bf16 v[68:71], v[178:181], v[218:221], v[68:71]
	v_mfma_f32_16x16x32_bf16 v[64:67], v[186:189], v[218:221], v[64:67]
	v_mfma_f32_16x16x32_bf16 v[112:115], v[182:185], v[198:201], v[112:115]
	v_mfma_f32_16x16x32_bf16 v[104:107], v[190:193], v[198:201], v[104:107]
	v_mfma_f32_16x16x32_bf16 v[96:99], v[182:185], v[206:209], v[96:99]
	v_mfma_f32_16x16x32_bf16 v[88:91], v[190:193], v[206:209], v[88:91]
	v_mfma_f32_16x16x32_bf16 v[80:83], v[182:185], v[214:217], v[80:83]
	v_mfma_f32_16x16x32_bf16 v[72:75], v[190:193], v[214:217], v[72:75]
	v_mfma_f32_16x16x32_bf16 v[68:71], v[182:185], v[222:225], v[68:71]
	v_mfma_f32_16x16x32_bf16 v[64:67], v[190:193], v[222:225], v[64:67]
	s_barrier
	s_add_u32 s82, s72, 0x80
	s_addc_u32 s83, s73, 0
	ds_read_b128 v[194:197], v154 offset:49152
	ds_read_b128 v[198:201], v154 offset:50176
	ds_read_b128 v[202:205], v154 offset:51200
	ds_read_b128 v[206:209], v154 offset:52224
	ds_read_b128 v[210:213], v154 offset:53248
	ds_read_b128 v[214:217], v154 offset:54272
	ds_read_b128 v[218:221], v154 offset:55296
	ds_read_b128 v[222:225], v154 offset:56320
	s_mov_b32 m0, s66
	s_nop 0
	global_load_lds_dwordx4 v150, s[82:83]
	s_add_u32 s82, s72, 0x20080
	s_mov_b32 m0, s67
	s_addc_u32 s83, s73, 0
	global_load_lds_dwordx4 v150, s[82:83]
	s_add_u32 s82, s72, 0x40080
	s_mov_b32 m0, s76
	s_addc_u32 s83, s73, 0
	global_load_lds_dwordx4 v150, s[82:83]
	s_add_u32 s72, s72, 0x60080
	s_mov_b32 m0, s77
	s_addc_u32 s73, s73, 0
	global_load_lds_dwordx4 v150, s[72:73]
	s_mov_b32 m0, s68
	s_nop 0
	global_load_lds_dwordx4 v128, s[22:23]
	s_add_u32 s16, s16, 0x20080
	s_mov_b32 m0, s69
	s_addc_u32 s17, s17, 0
	global_load_lds_dwordx4 v128, s[16:17]
	s_waitcnt vmcnt(8) lgkmcnt(0)
	s_barrier
	v_mfma_f32_16x16x32_bf16 v[60:63], v[138:141], v[194:197], v[60:63]
	v_mfma_f32_16x16x32_bf16 v[56:59], v[146:149], v[194:197], v[56:59]
	v_mfma_f32_16x16x32_bf16 v[52:55], v[138:141], v[202:205], v[52:55]
	v_mfma_f32_16x16x32_bf16 v[44:47], v[146:149], v[202:205], v[44:47]
	v_mfma_f32_16x16x32_bf16 v[36:39], v[138:141], v[210:213], v[36:39]
	v_mfma_f32_16x16x32_bf16 v[28:31], v[146:149], v[210:213], v[28:31]
	v_mfma_f32_16x16x32_bf16 v[20:23], v[138:141], v[218:221], v[20:23]
	v_mfma_f32_16x16x32_bf16 v[12:15], v[146:149], v[218:221], v[12:15]
	v_mfma_f32_16x16x32_bf16 v[60:63], v[142:145], v[198:201], v[60:63]
	v_mfma_f32_16x16x32_bf16 v[56:59], v[172:175], v[198:201], v[56:59]
	v_mfma_f32_16x16x32_bf16 v[52:55], v[142:145], v[206:209], v[52:55]
	v_mfma_f32_16x16x32_bf16 v[44:47], v[172:175], v[206:209], v[44:47]
	v_mfma_f32_16x16x32_bf16 v[36:39], v[142:145], v[214:217], v[36:39]
	v_mfma_f32_16x16x32_bf16 v[28:31], v[172:175], v[214:217], v[28:31]
	v_mfma_f32_16x16x32_bf16 v[20:23], v[142:145], v[222:225], v[20:23]
	v_mfma_f32_16x16x32_bf16 v[12:15], v[172:175], v[222:225], v[12:15]
	v_mfma_f32_16x16x32_bf16 v[48:51], v[178:181], v[194:197], v[48:51]
	v_mfma_f32_16x16x32_bf16 v[40:43], v[186:189], v[194:197], v[40:43]
	v_mfma_f32_16x16x32_bf16 v[32:35], v[178:181], v[202:205], v[32:35]
	v_mfma_f32_16x16x32_bf16 v[24:27], v[186:189], v[202:205], v[24:27]
	v_mfma_f32_16x16x32_bf16 v[16:19], v[178:181], v[210:213], v[16:19]
	v_mfma_f32_16x16x32_bf16 v[8:11], v[186:189], v[210:213], v[8:11]
	v_mfma_f32_16x16x32_bf16 v[4:7], v[178:181], v[218:221], v[4:7]
	v_mfma_f32_16x16x32_bf16 v[0:3], v[186:189], v[218:221], v[0:3]
	v_mfma_f32_16x16x32_bf16 v[48:51], v[182:185], v[198:201], v[48:51]
	v_mfma_f32_16x16x32_bf16 v[40:43], v[190:193], v[198:201], v[40:43]
	v_mfma_f32_16x16x32_bf16 v[32:35], v[182:185], v[206:209], v[32:35]
	v_mfma_f32_16x16x32_bf16 v[24:27], v[190:193], v[206:209], v[24:27]
	v_mfma_f32_16x16x32_bf16 v[16:19], v[182:185], v[214:217], v[16:19]
	v_mfma_f32_16x16x32_bf16 v[8:11], v[190:193], v[214:217], v[8:11]
	v_mfma_f32_16x16x32_bf16 v[4:7], v[182:185], v[222:225], v[4:7]
	v_mfma_f32_16x16x32_bf16 v[0:3], v[190:193], v[222:225], v[0:3]
	s_barrier
	s_cmp_gt_u32 s75, 13
	s_cbranch_scc0 .LBB0_582
	s_and_b64 vcc, exec, s[26:27]
	s_cbranch_vccz .LBB0_585
	s_barrier

; #define PG8_STAGE(bufoff, gbase, voff, p64) do { _Pragma("unroll") for (int _i = 0; _i < 2; ++_i) { \
;         const char* _gb = (const char*)(gbase) + (size_t)_i * (p64); const unsigned _la = ldsbase + (unsigned)(bufoff) + (unsigned)_i * 8192u; \
;         asm volatile("s_mov_b32 m0, %0\n\ts_nop 0\n\tglobal_load_lds_dwordx4 %1, %2" :: "s"(_la), "v"(voff), "s"(_gb) : "memory"); } } while (0)
; #define PG8_LDA(dst, b, h) do { _Pragma("unroll") for (int m = 0; m < 4; ++m) _Pragma("unroll") for (int k = 0; k < 2; ++k) dst[m][k] = *(const LAS bf16x8*)(lds + PG8_SA(b, h) + aoff + m * 2048 + k * 1024); } while (0)
; #define PG8_LDB(dst, b, h) do { _Pragma("unroll") for (int n = 0; n < 2; ++n) _Pragma("unroll") for (int k = 0; k < 2; ++k) dst[n][k] = *(const LAS bf16x8*)(lds + PG8_SB(b, h) + boff + n * 2048 + k * 1024); } while (0)
; #define PG8_MMA(ai, bj, At, Bt) do { __builtin_amdgcn_s_setprio(1); _Pragma("unroll") for (int m = 0; m < 4; ++m) _Pragma("unroll") for (int n = 0; n < 2; ++n) _Pragma("unroll") for (int k = 0; k < 2; ++k) \
;         acc[ai][bj][m][n] = __builtin_amdgcn_mfma_f32_16x16x32_bf16(Bt[n][k], At[m][k], acc[ai][bj][m][n], 0, 0, 0); __builtin_amdgcn_s_setprio(0); } while (0)
; #define PG8_WAIT_V(n) asm volatile("s_waitcnt vmcnt(" #n ")" ::: "memory")
; #define PG8_BAR __builtin_amdgcn_s_barrier()
; template <class Epi, class Sched>
; __device__ __forceinline__ void gemm_phase(LAS unsigned char* lds, const Sched& S, const Epi& E) {
;     ...
;             const bool last = (t == nt - 2);
;             const char* a1 = cA + (size_t)(t + 1) * kstep;
;             const char* a2 = last ? nA : cA + (size_t)(t + 2) * kstep; const char* b2 = last ? nB : cB + (size_t)(t + 2) * kstep;
;             const char* a3 = a2 + kstep; const char* b3 = b2 + kstep;
;             const unsigned vA2 = voffA, vB2 = voffB, hA2 = hA, hB2 = hB;
;             PG8_LDB(B0, 0, 0); PG8_LDB(B1, 0, 1); PG8_SCHED; PG8_LDA(At, 0, 0); PG8_STAGE(PG8_SA(1, 1), a1 + hA, voffA, hA / 2);
;             PG8_WAIT_V(8); PG8_WAIT_L(0); PG8_BAR; PG8_MMA(0, 0, At, B0); PG8_MMA(0, 1, At, B1); PG8_BAR; PG8_SCHED;
;             PG8_LDA(At, 0, 1); PG8_STAGE(PG8_SB(0, 0), b2, vB2, hB2 / 2); PG8_STAGE(PG8_SB(0, 1), b2 + hB2, vB2, hB2 / 2); PG8_STAGE(PG8_SA(0, 0), a2, vA2, hA2 / 2);
;             PG8_WAIT_V(8); PG8_WAIT_L(0); PG8_BAR; PG8_MMA(1, 0, At, B0); PG8_MMA(1, 1, At, B1); PG8_BAR; PG8_SCHED;
.LBB0_659:
	s_add_u32 s78, s16, 0x100
	s_addc_u32 s79, s17, 0
	s_mov_b32 s80, -2
	v_add_u32_e32 v130, 0x10000, v143
	ds_read_b128 v[146:149], v130
	ds_read_b128 v[150:153], v130 offset:1024
	ds_read_b128 v[172:175], v130 offset:2048
	ds_read_b128 v[178:181], v130 offset:3072
	v_add_u32_e32 v130, 0x14000, v143
	ds_read_b128 v[182:185], v130
	ds_read_b128 v[186:189], v130 offset:1024
	ds_read_b128 v[190:193], v130 offset:2048
	ds_read_b128 v[194:197], v130 offset:3072
	s_add_u32 s16, s58, 0x100
	s_addc_u32 s17, s59, 0
	s_cmp_eq_u32 s80, 4
	s_cselect_b32 s22, s40, s16
	s_cselect_b32 s23, s41, s17
	s_cselect_b32 s72, s54, s78
	s_cselect_b32 s73, s55, s79
	s_add_u32 s62, s22, 0x80
	s_addc_u32 s63, s23, 0
	ds_read_b128 v[198:201], v144
	ds_read_b128 v[202:205], v144 offset:1024
	ds_read_b128 v[206:209], v144 offset:2048
	ds_read_b128 v[210:213], v144 offset:3072
	ds_read_b128 v[214:217], v144 offset:4096
	ds_read_b128 v[218:221], v144 offset:5120
	ds_read_b128 v[222:225], v144 offset:6144
	ds_read_b128 v[226:229], v144 offset:7168
	s_add_u32 s82, s58, 0x20080
	s_mov_b32 m0, s66
	s_addc_u32 s83, s59, 0
	global_load_lds_dwordx4 v128, s[82:83]
	s_add_u32 s58, s58, 0x30080
	s_mov_b32 m0, s67
	s_addc_u32 s59, s59, 0
	global_load_lds_dwordx4 v128, s[58:59]
	s_waitcnt vmcnt(8) lgkmcnt(0)
	s_barrier
	v_mfma_f32_16x16x32_bf16 v[124:127], v[146:149], v[198:201], 0
	v_mfma_f32_16x16x32_bf16 v[120:123], v[172:175], v[198:201], 0
	v_mfma_f32_16x16x32_bf16 v[116:119], v[146:149], v[206:209], 0
	v_mfma_f32_16x16x32_bf16 v[108:111], v[172:175], v[206:209], 0
	v_mfma_f32_16x16x32_bf16 v[100:103], v[146:149], v[214:217], 0
	v_mfma_f32_16x16x32_bf16 v[92:95], v[172:175], v[214:217], 0
	v_mfma_f32_16x16x32_bf16 v[84:87], v[146:149], v[222:225], 0
	v_mfma_f32_16x16x32_bf16 v[76:79], v[172:175], v[222:225], 0
	v_mfma_f32_16x16x32_bf16 v[124:127], v[150:153], v[202:205], v[124:127]
	v_mfma_f32_16x16x32_bf16 v[120:123], v[178:181], v[202:205], v[120:123]
	v_mfma_f32_16x16x32_bf16 v[116:119], v[150:153], v[210:213], v[116:119]
	v_mfma_f32_16x16x32_bf16 v[108:111], v[178:181], v[210:213], v[108:111]
	v_mfma_f32_16x16x32_bf16 v[100:103], v[150:153], v[218:221], v[100:103]
	v_mfma_f32_16x16x32_bf16 v[92:95], v[178:181], v[218:221], v[92:95]
	v_mfma_f32_16x16x32_bf16 v[84:87], v[150:153], v[226:229], v[84:87]
	v_mfma_f32_16x16x32_bf16 v[76:79], v[178:181], v[226:229], v[76:79]
	v_mfma_f32_16x16x32_bf16 v[112:115], v[182:185], v[198:201], 0
	v_mfma_f32_16x16x32_bf16 v[104:107], v[190:193], v[198:201], 0
	v_mfma_f32_16x16x32_bf16 v[96:99], v[182:185], v[206:209], 0
	v_mfma_f32_16x16x32_bf16 v[88:91], v[190:193], v[206:209], 0
	v_mfma_f32_16x16x32_bf16 v[80:83], v[182:185], v[214:217], 0
	v_mfma_f32_16x16x32_bf16 v[72:75], v[190:193], v[214:217], 0
	v_mfma_f32_16x16x32_bf16 v[68:71], v[182:185], v[222:225], 0
	v_mfma_f32_16x16x32_bf16 v[64:67], v[190:193], v[222:225], 0
	v_mfma_f32_16x16x32_bf16 v[112:115], v[186:189], v[202:205], v[112:115]
	v_mfma_f32_16x16x32_bf16 v[104:107], v[194:197], v[202:205], v[104:107]
	v_mfma_f32_16x16x32_bf16 v[96:99], v[186:189], v[210:213], v[96:99]
	v_mfma_f32_16x16x32_bf16 v[88:91], v[194:197], v[210:213], v[88:91]
	v_mfma_f32_16x16x32_bf16 v[80:83], v[186:189], v[218:221], v[80:83]
	v_mfma_f32_16x16x32_bf16 v[72:75], v[194:197], v[218:221], v[72:75]
	v_mfma_f32_16x16x32_bf16 v[68:71], v[186:189], v[226:229], v[68:71]
	v_mfma_f32_16x16x32_bf16 v[64:67], v[194:197], v[226:229], v[64:67]
	s_add_i32 s80, s80, 2
	s_add_u32 s78, s78, 0x100
	s_addc_u32 s79, s79, 0
	s_barrier
	s_add_u32 s58, s72, 0x10000
	ds_read_b128 v[198:201], v144 offset:16384
	ds_read_b128 v[202:205], v144 offset:17408
	ds_read_b128 v[206:209], v144 offset:18432
	ds_read_b128 v[210:213], v144 offset:19456
	ds_read_b128 v[214:217], v144 offset:20480
	ds_read_b128 v[218:221], v144 offset:21504
	ds_read_b128 v[222:225], v144 offset:22528
	ds_read_b128 v[226:229], v144 offset:23552
	s_mov_b32 m0, s33
	s_nop 0
	global_load_lds_dwordx4 v140, s[72:73]
	s_mov_b32 m0, s34
	s_addc_u32 s59, s73, 0
	global_load_lds_dwordx4 v140, s[58:59]
	s_add_u32 s58, s72, 0x20000
	s_mov_b32 m0, s35
	s_addc_u32 s59, s73, 0
	global_load_lds_dwordx4 v140, s[58:59]
	s_add_u32 s58, s72, 0x30000
	s_mov_b32 m0, s36
	s_addc_u32 s59, s73, 0
	global_load_lds_dwordx4 v140, s[58:59]
	s_mov_b32 m0, s24
	s_nop 0
	global_load_lds_dwordx4 v128, s[22:23]
	s_add_u32 s58, s22, 0x10000
	s_mov_b32 m0, s37
	s_addc_u32 s59, s23, 0
	global_load_lds_dwordx4 v128, s[58:59]
	s_waitcnt vmcnt(8) lgkmcnt(0)
	s_barrier
	v_mfma_f32_16x16x32_bf16 v[60:63], v[146:149], v[198:201], 0
	v_mfma_f32_16x16x32_bf16 v[56:59], v[172:175], v[198:201], 0
	v_mfma_f32_16x16x32_bf16 v[52:55], v[146:149], v[206:209], 0
	v_mfma_f32_16x16x32_bf16 v[44:47], v[172:175], v[206:209], 0
	v_mfma_f32_16x16x32_bf16 v[36:39], v[146:149], v[214:217], 0
	v_mfma_f32_16x16x32_bf16 v[28:31], v[172:175], v[214:217], 0
	v_mfma_f32_16x16x32_bf16 v[20:23], v[146:149], v[222:225], 0
	v_mfma_f32_16x16x32_bf16 v[12:15], v[172:175], v[222:225], 0
	v_mfma_f32_16x16x32_bf16 v[60:63], v[150:153], v[202:205], v[60:63]
	v_mfma_f32_16x16x32_bf16 v[56:59], v[178:181], v[202:205], v[56:59]
	v_mfma_f32_16x16x32_bf16 v[52:55], v[150:153], v[210:213], v[52:55]
	v_mfma_f32_16x16x32_bf16 v[44:47], v[178:181], v[210:213], v[44:47]
	v_mfma_f32_16x16x32_bf16 v[36:39], v[150:153], v[218:221], v[36:39]
	v_mfma_f32_16x16x32_bf16 v[28:31], v[178:181], v[218:221], v[28:31]
	v_mfma_f32_16x16x32_bf16 v[20:23], v[150:153], v[226:229], v[20:23]
	v_mfma_f32_16x16x32_bf16 v[12:15], v[178:181], v[226:229], v[12:15]
	v_mfma_f32_16x16x32_bf16 v[48:51], v[182:185], v[198:201], 0
	v_mfma_f32_16x16x32_bf16 v[40:43], v[190:193], v[198:201], 0
	v_mfma_f32_16x16x32_bf16 v[32:35], v[182:185], v[206:209], 0
	v_mfma_f32_16x16x32_bf16 v[24:27], v[190:193], v[206:209], 0
	v_mfma_f32_16x16x32_bf16 v[16:19], v[182:185], v[214:217], 0
	v_mfma_f32_16x16x32_bf16 v[8:11], v[190:193], v[214:217], 0
	v_mfma_f32_16x16x32_bf16 v[4:7], v[182:185], v[222:225], 0
	v_mfma_f32_16x16x32_bf16 v[0:3], v[190:193], v[222:225], 0
	v_mfma_f32_16x16x32_bf16 v[48:51], v[186:189], v[202:205], v[48:51]
	v_mfma_f32_16x16x32_bf16 v[40:43], v[194:197], v[202:205], v[40:43]
	v_mfma_f32_16x16x32_bf16 v[32:35], v[186:189], v[210:213], v[32:35]
	v_mfma_f32_16x16x32_bf16 v[24:27], v[194:197], v[210:213], v[24:27]
	v_mfma_f32_16x16x32_bf16 v[16:19], v[186:189], v[218:221], v[16:19]
	v_mfma_f32_16x16x32_bf16 v[8:11], v[194:197], v[218:221], v[8:11]
	v_mfma_f32_16x16x32_bf16 v[4:7], v[186:189], v[226:229], v[4:7]
	v_mfma_f32_16x16x32_bf16 v[0:3], v[194:197], v[226:229], v[0:3]
	s_barrier
	s_branch .Lpeel_mid_17324
; #define PG8_STAGE(bufoff, gbase, voff, p64) do { _Pragma("unroll") for (int _i = 0; _i < 2; ++_i) { \
;         const char* _gb = (const char*)(gbase) + (size_t)_i * (p64); const unsigned _la = ldsbase + (unsigned)(bufoff) + (unsigned)_i * 8192u; \
;         asm volatile("s_mov_b32 m0, %0\n\ts_nop 0\n\tglobal_load_lds_dwordx4 %1, %2" :: "s"(_la), "v"(voff), "s"(_gb) : "memory"); } } while (0)
; #define PG8_LDA(dst, b, h) do { _Pragma("unroll") for (int m = 0; m < 4; ++m) _Pragma("unroll") for (int k = 0; k < 2; ++k) dst[m][k] = *(const LAS bf16x8*)(lds + PG8_SA(b, h) + aoff + m * 2048 + k * 1024); } while (0)
; #define PG8_LDB(dst, b, h) do { _Pragma("unroll") for (int n = 0; n < 2; ++n) _Pragma("unroll") for (int k = 0; k < 2; ++k) dst[n][k] = *(const LAS bf16x8*)(lds + PG8_SB(b, h) + boff + n * 2048 + k * 1024); } while (0)
; #define PG8_MMA(ai, bj, At, Bt) do { __builtin_amdgcn_s_setprio(1); _Pragma("unroll") for (int m = 0; m < 4; ++m) _Pragma("unroll") for (int n = 0; n < 2; ++n) _Pragma("unroll") for (int k = 0; k < 2; ++k) \
;         acc[ai][bj][m][n] = __builtin_amdgcn_mfma_f32_16x16x32_bf16(Bt[n][k], At[m][k], acc[ai][bj][m][n], 0, 0, 0); __builtin_amdgcn_s_setprio(0); } while (0)
; #define PG8_WAIT_V(n) asm volatile("s_waitcnt vmcnt(" #n ")" ::: "memory")
; #define PG8_WAIT_L(n) asm volatile("s_waitcnt lgkmcnt(" #n ")" ::: "memory")
; #define PG8_BAR __builtin_amdgcn_s_barrier()
; #define PG8_SCHED __builtin_amdgcn_sched_barrier(0)
; template <class Epi, class Sched>
; __device__ __forceinline__ void gemm_phase(LAS unsigned char* lds, const Sched& S, const Epi& E) {
;     ...
;             PG8_LDB(B0, 0, 0); PG8_LDB(B1, 0, 1); PG8_SCHED; PG8_LDA(At, 0, 0); PG8_STAGE(PG8_SA(1, 1), a1 + hA, voffA, hA / 2);
;             PG8_WAIT_V(8); PG8_WAIT_L(0); PG8_BAR; PG8_MMA(0, 0, At, B0); PG8_MMA(0, 1, At, B1); PG8_BAR; PG8_SCHED;
;             PG8_LDA(At, 0, 1); PG8_STAGE(PG8_SB(0, 0), b2, vB2, hB2 / 2); PG8_STAGE(PG8_SB(0, 1), b2 + hB2, vB2, hB2 / 2); PG8_STAGE(PG8_SA(0, 0), a2, vA2, hA2 / 2);
;             PG8_WAIT_V(8); PG8_WAIT_L(0); PG8_BAR; PG8_MMA(1, 0, At, B0); PG8_MMA(1, 1, At, B1); PG8_BAR; PG8_SCHED;
.LBB0_660:
	v_add_u32_e32 v130, 0x10000, v143
	ds_read_b128 v[146:149], v130
	ds_read_b128 v[150:153], v130 offset:1024
	ds_read_b128 v[172:175], v130 offset:2048
	ds_read_b128 v[178:181], v130 offset:3072
	v_add_u32_e32 v130, 0x14000, v143
	ds_read_b128 v[182:185], v130
	ds_read_b128 v[186:189], v130 offset:1024
	ds_read_b128 v[190:193], v130 offset:2048
	ds_read_b128 v[194:197], v130 offset:3072
	s_add_u32 s16, s58, 0x100
	s_addc_u32 s17, s59, 0
	s_cmp_eq_u32 s80, 4
	s_cselect_b32 s22, s40, s16
	s_cselect_b32 s23, s41, s17
	s_cselect_b32 s72, s54, s78
	s_cselect_b32 s73, s55, s79
	s_add_u32 s62, s22, 0x80
	s_addc_u32 s63, s23, 0
	ds_read_b128 v[198:201], v144
	ds_read_b128 v[202:205], v144 offset:1024
	ds_read_b128 v[206:209], v144 offset:2048
	ds_read_b128 v[210:213], v144 offset:3072
	ds_read_b128 v[214:217], v144 offset:4096
	ds_read_b128 v[218:221], v144 offset:5120
	ds_read_b128 v[222:225], v144 offset:6144
	ds_read_b128 v[226:229], v144 offset:7168
	s_add_u32 s82, s58, 0x20080
	s_mov_b32 m0, s66
	s_addc_u32 s83, s59, 0
	global_load_lds_dwordx4 v128, s[82:83]
	s_add_u32 s58, s58, 0x30080
	s_mov_b32 m0, s67
	s_addc_u32 s59, s59, 0
	global_load_lds_dwordx4 v128, s[58:59]
	s_waitcnt vmcnt(8) lgkmcnt(0)
	s_barrier
	v_mfma_f32_16x16x32_bf16 v[124:127], v[146:149], v[198:201], v[124:127]
	v_mfma_f32_16x16x32_bf16 v[120:123], v[172:175], v[198:201], v[120:123]
	v_mfma_f32_16x16x32_bf16 v[116:119], v[146:149], v[206:209], v[116:119]
	v_mfma_f32_16x16x32_bf16 v[108:111], v[172:175], v[206:209], v[108:111]
	v_mfma_f32_16x16x32_bf16 v[100:103], v[146:149], v[214:217], v[100:103]
	v_mfma_f32_16x16x32_bf16 v[92:95], v[172:175], v[214:217], v[92:95]
	v_mfma_f32_16x16x32_bf16 v[84:87], v[146:149], v[222:225], v[84:87]
	v_mfma_f32_16x16x32_bf16 v[76:79], v[172:175], v[222:225], v[76:79]
	v_mfma_f32_16x16x32_bf16 v[124:127], v[150:153], v[202:205], v[124:127]
	v_mfma_f32_16x16x32_bf16 v[120:123], v[178:181], v[202:205], v[120:123]
	v_mfma_f32_16x16x32_bf16 v[116:119], v[150:153], v[210:213], v[116:119]
	v_mfma_f32_16x16x32_bf16 v[108:111], v[178:181], v[210:213], v[108:111]
	v_mfma_f32_16x16x32_bf16 v[100:103], v[150:153], v[218:221], v[100:103]
	v_mfma_f32_16x16x32_bf16 v[92:95], v[178:181], v[218:221], v[92:95]
	v_mfma_f32_16x16x32_bf16 v[84:87], v[150:153], v[226:229], v[84:87]
	v_mfma_f32_16x16x32_bf16 v[76:79], v[178:181], v[226:229], v[76:79]
	v_mfma_f32_16x16x32_bf16 v[112:115], v[182:185], v[198:201], v[112:115]
	v_mfma_f32_16x16x32_bf16 v[104:107], v[190:193], v[198:201], v[104:107]
	v_mfma_f32_16x16x32_bf16 v[96:99], v[182:185], v[206:209], v[96:99]
	v_mfma_f32_16x16x32_bf16 v[88:91], v[190:193], v[206:209], v[88:91]
	v_mfma_f32_16x16x32_bf16 v[80:83], v[182:185], v[214:217], v[80:83]
	v_mfma_f32_16x16x32_bf16 v[72:75], v[190:193], v[214:217], v[72:75]
	v_mfma_f32_16x16x32_bf16 v[68:71], v[182:185], v[222:225], v[68:71]
	v_mfma_f32_16x16x32_bf16 v[64:67], v[190:193], v[222:225], v[64:67]
	v_mfma_f32_16x16x32_bf16 v[112:115], v[186:189], v[202:205], v[112:115]
	v_mfma_f32_16x16x32_bf16 v[104:107], v[194:197], v[202:205], v[104:107]
	v_mfma_f32_16x16x32_bf16 v[96:99], v[186:189], v[210:213], v[96:99]
	v_mfma_f32_16x16x32_bf16 v[88:91], v[194:197], v[210:213], v[88:91]
	v_mfma_f32_16x16x32_bf16 v[80:83], v[186:189], v[218:221], v[80:83]
	v_mfma_f32_16x16x32_bf16 v[72:75], v[194:197], v[218:221], v[72:75]
	v_mfma_f32_16x16x32_bf16 v[68:71], v[186:189], v[226:229], v[68:71]
	v_mfma_f32_16x16x32_bf16 v[64:67], v[194:197], v[226:229], v[64:67]
	s_add_i32 s80, s80, 2
	s_add_u32 s78, s78, 0x100
	s_addc_u32 s79, s79, 0
	s_barrier
	s_add_u32 s58, s72, 0x10000
	ds_read_b128 v[198:201], v144 offset:16384
	ds_read_b128 v[202:205], v144 offset:17408
	ds_read_b128 v[206:209], v144 offset:18432
	ds_read_b128 v[210:213], v144 offset:19456
	ds_read_b128 v[214:217], v144 offset:20480
	ds_read_b128 v[218:221], v144 offset:21504
	ds_read_b128 v[222:225], v144 offset:22528
	ds_read_b128 v[226:229], v144 offset:23552
	s_mov_b32 m0, s33
	s_nop 0
	global_load_lds_dwordx4 v140, s[72:73]
	s_mov_b32 m0, s34
	s_addc_u32 s59, s73, 0
	global_load_lds_dwordx4 v140, s[58:59]
	s_add_u32 s58, s72, 0x20000
	s_mov_b32 m0, s35
	s_addc_u32 s59, s73, 0
	global_load_lds_dwordx4 v140, s[58:59]
	s_add_u32 s58, s72, 0x30000
	s_mov_b32 m0, s36
	s_addc_u32 s59, s73, 0
	global_load_lds_dwordx4 v140, s[58:59]
	s_mov_b32 m0, s24
	s_nop 0
	global_load_lds_dwordx4 v128, s[22:23]
	s_add_u32 s58, s22, 0x10000
	s_mov_b32 m0, s37
	s_addc_u32 s59, s23, 0
	global_load_lds_dwordx4 v128, s[58:59]
	s_waitcnt vmcnt(8) lgkmcnt(0)
	s_barrier
	v_mfma_f32_16x16x32_bf16 v[60:63], v[146:149], v[198:201], v[60:63]
	v_mfma_f32_16x16x32_bf16 v[56:59], v[172:175], v[198:201], v[56:59]
	v_mfma_f32_16x16x32_bf16 v[52:55], v[146:149], v[206:209], v[52:55]
	v_mfma_f32_16x16x32_bf16 v[44:47], v[172:175], v[206:209], v[44:47]
	v_mfma_f32_16x16x32_bf16 v[36:39], v[146:149], v[214:217], v[36:39]
	v_mfma_f32_16x16x32_bf16 v[28:31], v[172:175], v[214:217], v[28:31]
	v_mfma_f32_16x16x32_bf16 v[20:23], v[146:149], v[222:225], v[20:23]
	v_mfma_f32_16x16x32_bf16 v[12:15], v[172:175], v[222:225], v[12:15]
	v_mfma_f32_16x16x32_bf16 v[60:63], v[150:153], v[202:205], v[60:63]
	v_mfma_f32_16x16x32_bf16 v[56:59], v[178:181], v[202:205], v[56:59]
	v_mfma_f32_16x16x32_bf16 v[52:55], v[150:153], v[210:213], v[52:55]
	v_mfma_f32_16x16x32_bf16 v[44:47], v[178:181], v[210:213], v[44:47]
	v_mfma_f32_16x16x32_bf16 v[36:39], v[150:153], v[218:221], v[36:39]
	v_mfma_f32_16x16x32_bf16 v[28:31], v[178:181], v[218:221], v[28:31]
	v_mfma_f32_16x16x32_bf16 v[20:23], v[150:153], v[226:229], v[20:23]
	v_mfma_f32_16x16x32_bf16 v[12:15], v[178:181], v[226:229], v[12:15]
	v_mfma_f32_16x16x32_bf16 v[48:51], v[182:185], v[198:201], v[48:51]
	v_mfma_f32_16x16x32_bf16 v[40:43], v[190:193], v[198:201], v[40:43]
	v_mfma_f32_16x16x32_bf16 v[32:35], v[182:185], v[206:209], v[32:35]
	v_mfma_f32_16x16x32_bf16 v[24:27], v[190:193], v[206:209], v[24:27]
	v_mfma_f32_16x16x32_bf16 v[16:19], v[182:185], v[214:217], v[16:19]
	v_mfma_f32_16x16x32_bf16 v[8:11], v[190:193], v[214:217], v[8:11]
	v_mfma_f32_16x16x32_bf16 v[4:7], v[182:185], v[222:225], v[4:7]
	v_mfma_f32_16x16x32_bf16 v[0:3], v[190:193], v[222:225], v[0:3]
	v_mfma_f32_16x16x32_bf16 v[48:51], v[186:189], v[202:205], v[48:51]
	v_mfma_f32_16x16x32_bf16 v[40:43], v[194:197], v[202:205], v[40:43]
	v_mfma_f32_16x16x32_bf16 v[32:35], v[186:189], v[210:213], v[32:35]
	v_mfma_f32_16x16x32_bf16 v[24:27], v[194:197], v[210:213], v[24:27]
	v_mfma_f32_16x16x32_bf16 v[16:19], v[186:189], v[218:221], v[16:19]
	v_mfma_f32_16x16x32_bf16 v[8:11], v[194:197], v[218:221], v[8:11]
	v_mfma_f32_16x16x32_bf16 v[4:7], v[186:189], v[226:229], v[4:7]
	v_mfma_f32_16x16x32_bf16 v[0:3], v[194:197], v[226:229], v[0:3]
	s_barrier
; #define PG8_STAGE(bufoff, gbase, voff, p64) do { _Pragma("unroll") for (int _i = 0; _i < 2; ++_i) { \
;         const char* _gb = (const char*)(gbase) + (size_t)_i * (p64); const unsigned _la = ldsbase + (unsigned)(bufoff) + (unsigned)_i * 8192u; \
;         asm volatile("s_mov_b32 m0, %0\n\ts_nop 0\n\tglobal_load_lds_dwordx4 %1, %2" :: "s"(_la), "v"(voff), "s"(_gb) : "memory"); } } while (0)
; #define PG8_LDA(dst, b, h) do { _Pragma("unroll") for (int m = 0; m < 4; ++m) _Pragma("unroll") for (int k = 0; k < 2; ++k) dst[m][k] = *(const LAS bf16x8*)(lds + PG8_SA(b, h) + aoff + m * 2048 + k * 1024); } while (0)
; #define PG8_LDB(dst, b, h) do { _Pragma("unroll") for (int n = 0; n < 2; ++n) _Pragma("unroll") for (int k = 0; k < 2; ++k) dst[n][k] = *(const LAS bf16x8*)(lds + PG8_SB(b, h) + boff + n * 2048 + k * 1024); } while (0)
; #define PG8_MMA(ai, bj, At, Bt) do { __builtin_amdgcn_s_setprio(1); _Pragma("unroll") for (int m = 0; m < 4; ++m) _Pragma("unroll") for (int n = 0; n < 2; ++n) _Pragma("unroll") for (int k = 0; k < 2; ++k) \
;         acc[ai][bj][m][n] = __builtin_amdgcn_mfma_f32_16x16x32_bf16(Bt[n][k], At[m][k], acc[ai][bj][m][n], 0, 0, 0); __builtin_amdgcn_s_setprio(0); } while (0)
; #define PG8_WAIT_V(n) asm volatile("s_waitcnt vmcnt(" #n ")" ::: "memory")
; #define PG8_WAIT_L(n) asm volatile("s_waitcnt lgkmcnt(" #n ")" ::: "memory")
; #define PG8_BAR __builtin_amdgcn_s_barrier()
; #define PG8_SCHED __builtin_amdgcn_sched_barrier(0)
; template <class Epi, class Sched>
; __device__ __forceinline__ void gemm_phase(LAS unsigned char* lds, const Sched& S, const Epi& E) {
;     ...
;             PG8_LDB(B0, 1, 0); PG8_LDB(B1, 1, 1); PG8_SCHED; PG8_LDA(At, 1, 0); PG8_STAGE(PG8_SA(0, 1), a2 + hA2, vA2, hA2 / 2);
;             PG8_WAIT_V(8); PG8_WAIT_L(0); PG8_BAR; PG8_MMA(0, 0, At, B0); PG8_MMA(0, 1, At, B1); PG8_BAR; PG8_SCHED;
;             PG8_LDA(At, 1, 1); PG8_STAGE(PG8_SB(1, 0), b3, vB2, hB2 / 2); PG8_STAGE(PG8_SB(1, 1), b3 + hB2, vB2, hB2 / 2); PG8_STAGE(PG8_SA(1, 0), a3, vA2, hA2 / 2);
;             PG8_WAIT_V(8); PG8_WAIT_L(0); PG8_BAR; PG8_MMA(1, 0, At, B0); PG8_MMA(1, 1, At, B1); PG8_BAR; PG8_SCHED;
.Lpeel_mid_17324:
	v_add_u32_e32 v130, 0x18000, v143
	ds_read_b128 v[146:149], v130
	ds_read_b128 v[150:153], v130 offset:1024
	ds_read_b128 v[172:175], v130 offset:2048
	ds_read_b128 v[178:181], v130 offset:3072
	v_add_u32_e32 v130, 0x1c000, v143
	ds_read_b128 v[182:185], v130
	ds_read_b128 v[186:189], v130 offset:1024
	ds_read_b128 v[190:193], v130 offset:2048
	ds_read_b128 v[194:197], v130 offset:3072
	ds_read_b128 v[198:201], v144 offset:32768
	ds_read_b128 v[202:205], v144 offset:33792
	ds_read_b128 v[206:209], v144 offset:34816
	ds_read_b128 v[210:213], v144 offset:35840
	ds_read_b128 v[214:217], v144 offset:36864
	ds_read_b128 v[218:221], v144 offset:37888
	ds_read_b128 v[222:225], v144 offset:38912
	ds_read_b128 v[226:229], v144 offset:39936
	s_add_u32 s58, s22, 0x20000
	s_mov_b32 m0, s42
	s_addc_u32 s59, s23, 0
	global_load_lds_dwordx4 v128, s[58:59]
	s_add_u32 s58, s22, 0x30000
	s_mov_b32 m0, s44
	s_addc_u32 s59, s23, 0
	global_load_lds_dwordx4 v128, s[58:59]
	s_waitcnt vmcnt(8) lgkmcnt(0)
	s_barrier
	v_mfma_f32_16x16x32_bf16 v[124:127], v[146:149], v[198:201], v[124:127]
	v_mfma_f32_16x16x32_bf16 v[120:123], v[172:175], v[198:201], v[120:123]
	v_mfma_f32_16x16x32_bf16 v[116:119], v[146:149], v[206:209], v[116:119]
	v_mfma_f32_16x16x32_bf16 v[108:111], v[172:175], v[206:209], v[108:111]
	v_mfma_f32_16x16x32_bf16 v[100:103], v[146:149], v[214:217], v[100:103]
	v_mfma_f32_16x16x32_bf16 v[92:95], v[172:175], v[214:217], v[92:95]
	v_mfma_f32_16x16x32_bf16 v[84:87], v[146:149], v[222:225], v[84:87]
	v_mfma_f32_16x16x32_bf16 v[76:79], v[172:175], v[222:225], v[76:79]
	v_mfma_f32_16x16x32_bf16 v[124:127], v[150:153], v[202:205], v[124:127]
	v_mfma_f32_16x16x32_bf16 v[120:123], v[178:181], v[202:205], v[120:123]
	v_mfma_f32_16x16x32_bf16 v[116:119], v[150:153], v[210:213], v[116:119]
	v_mfma_f32_16x16x32_bf16 v[108:111], v[178:181], v[210:213], v[108:111]
	v_mfma_f32_16x16x32_bf16 v[100:103], v[150:153], v[218:221], v[100:103]
	v_mfma_f32_16x16x32_bf16 v[92:95], v[178:181], v[218:221], v[92:95]
	v_mfma_f32_16x16x32_bf16 v[84:87], v[150:153], v[226:229], v[84:87]
	v_mfma_f32_16x16x32_bf16 v[76:79], v[178:181], v[226:229], v[76:79]
	v_mfma_f32_16x16x32_bf16 v[112:115], v[182:185], v[198:201], v[112:115]
	v_mfma_f32_16x16x32_bf16 v[104:107], v[190:193], v[198:201], v[104:107]
	v_mfma_f32_16x16x32_bf16 v[96:99], v[182:185], v[206:209], v[96:99]
	v_mfma_f32_16x16x32_bf16 v[88:91], v[190:193], v[206:209], v[88:91]
	v_mfma_f32_16x16x32_bf16 v[80:83], v[182:185], v[214:217], v[80:83]
	v_mfma_f32_16x16x32_bf16 v[72:75], v[190:193], v[214:217], v[72:75]
	v_mfma_f32_16x16x32_bf16 v[68:71], v[182:185], v[222:225], v[68:71]
	v_mfma_f32_16x16x32_bf16 v[64:67], v[190:193], v[222:225], v[64:67]
	v_mfma_f32_16x16x32_bf16 v[112:115], v[186:189], v[202:205], v[112:115]
	v_mfma_f32_16x16x32_bf16 v[104:107], v[194:197], v[202:205], v[104:107]
	v_mfma_f32_16x16x32_bf16 v[96:99], v[186:189], v[210:213], v[96:99]
	v_mfma_f32_16x16x32_bf16 v[88:91], v[194:197], v[210:213], v[88:91]
	v_mfma_f32_16x16x32_bf16 v[80:83], v[186:189], v[218:221], v[80:83]
	v_mfma_f32_16x16x32_bf16 v[72:75], v[194:197], v[218:221], v[72:75]
	v_mfma_f32_16x16x32_bf16 v[68:71], v[186:189], v[226:229], v[68:71]
	v_mfma_f32_16x16x32_bf16 v[64:67], v[194:197], v[226:229], v[64:67]
	s_barrier
	s_add_u32 s58, s72, 0x80
	s_addc_u32 s59, s73, 0
	ds_read_b128 v[198:201], v144 offset:49152
	ds_read_b128 v[202:205], v144 offset:50176
	ds_read_b128 v[206:209], v144 offset:51200
	ds_read_b128 v[210:213], v144 offset:52224
	ds_read_b128 v[214:217], v144 offset:53248
	ds_read_b128 v[218:221], v144 offset:54272
	ds_read_b128 v[222:225], v144 offset:55296
	ds_read_b128 v[226:229], v144 offset:56320
	s_mov_b32 m0, s48
	s_nop 0
	global_load_lds_dwordx4 v140, s[58:59]
	s_add_u32 s58, s72, 0x10080
	s_mov_b32 m0, s50
	s_addc_u32 s59, s73, 0
	global_load_lds_dwordx4 v140, s[58:59]
	s_add_u32 s58, s72, 0x20080
	s_mov_b32 m0, s64
	s_addc_u32 s59, s73, 0
	global_load_lds_dwordx4 v140, s[58:59]
	s_add_u32 s58, s72, 0x30080
	s_mov_b32 m0, s65
	s_addc_u32 s59, s73, 0
	global_load_lds_dwordx4 v140, s[58:59]
	s_mov_b32 m0, s51
	s_nop 0
	global_load_lds_dwordx4 v128, s[62:63]
	s_add_u32 s22, s22, 0x10080
	s_mov_b32 m0, s61
	s_addc_u32 s23, s23, 0
	global_load_lds_dwordx4 v128, s[22:23]
	s_waitcnt vmcnt(8) lgkmcnt(0)
	s_barrier
	v_mfma_f32_16x16x32_bf16 v[60:63], v[146:149], v[198:201], v[60:63]
	v_mfma_f32_16x16x32_bf16 v[56:59], v[172:175], v[198:201], v[56:59]
	v_mfma_f32_16x16x32_bf16 v[52:55], v[146:149], v[206:209], v[52:55]
	v_mfma_f32_16x16x32_bf16 v[44:47], v[172:175], v[206:209], v[44:47]
	v_mfma_f32_16x16x32_bf16 v[36:39], v[146:149], v[214:217], v[36:39]
	v_mfma_f32_16x16x32_bf16 v[28:31], v[172:175], v[214:217], v[28:31]
	v_mfma_f32_16x16x32_bf16 v[20:23], v[146:149], v[222:225], v[20:23]
	v_mfma_f32_16x16x32_bf16 v[12:15], v[172:175], v[222:225], v[12:15]
	v_mfma_f32_16x16x32_bf16 v[60:63], v[150:153], v[202:205], v[60:63]
	v_mfma_f32_16x16x32_bf16 v[56:59], v[178:181], v[202:205], v[56:59]
	v_mfma_f32_16x16x32_bf16 v[52:55], v[150:153], v[210:213], v[52:55]
	v_mfma_f32_16x16x32_bf16 v[44:47], v[178:181], v[210:213], v[44:47]
	v_mfma_f32_16x16x32_bf16 v[36:39], v[150:153], v[218:221], v[36:39]
	v_mfma_f32_16x16x32_bf16 v[28:31], v[178:181], v[218:221], v[28:31]
	v_mfma_f32_16x16x32_bf16 v[20:23], v[150:153], v[226:229], v[20:23]
	v_mfma_f32_16x16x32_bf16 v[12:15], v[178:181], v[226:229], v[12:15]
	v_mfma_f32_16x16x32_bf16 v[48:51], v[182:185], v[198:201], v[48:51]
	v_mfma_f32_16x16x32_bf16 v[40:43], v[190:193], v[198:201], v[40:43]
	v_mfma_f32_16x16x32_bf16 v[32:35], v[182:185], v[206:209], v[32:35]
	v_mfma_f32_16x16x32_bf16 v[24:27], v[190:193], v[206:209], v[24:27]
	v_mfma_f32_16x16x32_bf16 v[16:19], v[182:185], v[214:217], v[16:19]
	v_mfma_f32_16x16x32_bf16 v[8:11], v[190:193], v[214:217], v[8:11]
	v_mfma_f32_16x16x32_bf16 v[4:7], v[182:185], v[222:225], v[4:7]
	v_mfma_f32_16x16x32_bf16 v[0:3], v[190:193], v[222:225], v[0:3]
	v_mfma_f32_16x16x32_bf16 v[48:51], v[186:189], v[202:205], v[48:51]
	v_mfma_f32_16x16x32_bf16 v[40:43], v[194:197], v[202:205], v[40:43]
	v_mfma_f32_16x16x32_bf16 v[32:35], v[186:189], v[210:213], v[32:35]
	v_mfma_f32_16x16x32_bf16 v[24:27], v[194:197], v[210:213], v[24:27]
	v_mfma_f32_16x16x32_bf16 v[16:19], v[186:189], v[218:221], v[16:19]
	v_mfma_f32_16x16x32_bf16 v[8:11], v[194:197], v[218:221], v[8:11]
	v_mfma_f32_16x16x32_bf16 v[4:7], v[186:189], v[226:229], v[4:7]
	v_mfma_f32_16x16x32_bf16 v[0:3], v[194:197], v[226:229], v[0:3]
	s_barrier
	s_cmp_gt_u32 s80, 5
	s_mov_b64 s[58:59], s[16:17]
	s_cbranch_scc0 .LBB0_660
	s_and_b64 vcc, exec, s[38:39]
	s_cbranch_vccz .LBB0_663
	s_barrier

; #define PG8_STAGE(bufoff, gbase, voff, p64) do { _Pragma("unroll") for (int _i = 0; _i < 2; ++_i) { \
;         const char* _gb = (const char*)(gbase) + (size_t)_i * (p64); const unsigned _la = ldsbase + (unsigned)(bufoff) + (unsigned)_i * 8192u; \
;         asm volatile("s_mov_b32 m0, %0\n\ts_nop 0\n\tglobal_load_lds_dwordx4 %1, %2" :: "s"(_la), "v"(voff), "s"(_gb) : "memory"); } } while (0)
; #define PG8_LDA(dst, b, h) do { _Pragma("unroll") for (int m = 0; m < 4; ++m) _Pragma("unroll") for (int k = 0; k < 2; ++k) dst[m][k] = *(const LAS bf16x8*)(lds + PG8_SA(b, h) + aoff + m * 2048 + k * 1024); } while (0)
; #define PG8_LDB(dst, b, h) do { _Pragma("unroll") for (int n = 0; n < 2; ++n) _Pragma("unroll") for (int k = 0; k < 2; ++k) dst[n][k] = *(const LAS bf16x8*)(lds + PG8_SB(b, h) + boff + n * 2048 + k * 1024); } while (0)
; #define PG8_MMA(ai, bj, At, Bt) do { __builtin_amdgcn_s_setprio(1); _Pragma("unroll") for (int m = 0; m < 4; ++m) _Pragma("unroll") for (int n = 0; n < 2; ++n) _Pragma("unroll") for (int k = 0; k < 2; ++k) \
;         acc[ai][bj][m][n] = __builtin_amdgcn_mfma_f32_16x16x32_bf16(Bt[n][k], At[m][k], acc[ai][bj][m][n], 0, 0, 0); __builtin_amdgcn_s_setprio(0); } while (0)
; #define PG8_WAIT_V(n) asm volatile("s_waitcnt vmcnt(" #n ")" ::: "memory")
; #define PG8_WAIT_L(n) asm volatile("s_waitcnt lgkmcnt(" #n ")" ::: "memory")
; #define PG8_BAR __builtin_amdgcn_s_barrier()
; #define PG8_SCHED __builtin_amdgcn_sched_barrier(0)
; template <class Epi, class Sched>
; __device__ __forceinline__ void gemm_phase(LAS unsigned char* lds, const Sched& S, const Epi& E) {
;     ...
;             PG8_LDB(B0, 0, 0); PG8_LDB(B1, 0, 1); PG8_SCHED; PG8_LDA(At, 0, 0); PG8_STAGE(PG8_SA(1, 1), a1 + hA, voffA, hA / 2);
;             PG8_WAIT_V(8); PG8_WAIT_L(0); PG8_BAR; PG8_MMA(0, 0, At, B0); PG8_MMA(0, 1, At, B1); PG8_BAR; PG8_SCHED;
;             PG8_LDA(At, 0, 1); PG8_STAGE(PG8_SB(0, 0), b2, vB2, hB2 / 2); PG8_STAGE(PG8_SB(0, 1), b2 + hB2, vB2, hB2 / 2); PG8_STAGE(PG8_SA(0, 0), a2, vA2, hA2 / 2);
;             PG8_WAIT_V(8); PG8_WAIT_L(0); PG8_BAR; PG8_MMA(1, 0, At, B0); PG8_MMA(1, 1, At, B1); PG8_BAR; PG8_SCHED;
.LBB0_679:
	v_add_u32_e32 v130, 0x10000, v141
	v_add_u32_e32 v131, 0x14000, v141
	ds_read_b128 v[0:3], v130
	ds_read_b128 v[4:7], v130 offset:1024
	ds_read_b128 v[8:11], v130 offset:2048
	ds_read_b128 v[12:15], v130 offset:3072
	ds_read_b128 v[16:19], v131
	ds_read_b128 v[20:23], v131 offset:1024
	ds_read_b128 v[24:27], v131 offset:2048
	ds_read_b128 v[28:31], v131 offset:3072
	s_add_u32 s22, s56, 0x100
	s_addc_u32 s23, s57, 0
	s_add_u32 s76, s58, 0x100
	s_addc_u32 s77, s59, 0
	s_add_u32 s16, s56, 0x180
	s_addc_u32 s17, s57, 0
	ds_read_b128 v[32:35], v142
	ds_read_b128 v[36:39], v142 offset:1024
	ds_read_b128 v[40:43], v142 offset:2048
	ds_read_b128 v[44:47], v142 offset:3072
	ds_read_b128 v[48:51], v142 offset:4096
	ds_read_b128 v[52:55], v142 offset:5120
	ds_read_b128 v[56:59], v142 offset:6144
	ds_read_b128 v[60:63], v142 offset:7168
	s_add_u32 s78, s56, 0x10080
	s_mov_b32 m0, s66
	s_addc_u32 s79, s57, 0
	global_load_lds_dwordx4 v128, s[78:79]
	s_add_u32 s78, s56, 0x18080
	s_mov_b32 m0, s67
	s_addc_u32 s79, s57, 0
	global_load_lds_dwordx4 v128, s[78:79]
	s_waitcnt vmcnt(8) lgkmcnt(0)
	s_barrier
	v_mfma_f32_16x16x32_bf16 v[64:67], v[0:3], v[32:35], 0
	v_mfma_f32_16x16x32_bf16 v[68:71], v[8:11], v[32:35], 0
	v_mfma_f32_16x16x32_bf16 v[72:75], v[0:3], v[40:43], 0
	v_mfma_f32_16x16x32_bf16 v[76:79], v[8:11], v[40:43], 0
	v_mfma_f32_16x16x32_bf16 v[80:83], v[0:3], v[48:51], 0
	v_mfma_f32_16x16x32_bf16 v[84:87], v[8:11], v[48:51], 0
	v_mfma_f32_16x16x32_bf16 v[88:91], v[0:3], v[56:59], 0
	v_mfma_f32_16x16x32_bf16 v[92:95], v[8:11], v[56:59], 0
	v_mfma_f32_16x16x32_bf16 v[64:67], v[4:7], v[36:39], v[64:67]
	v_mfma_f32_16x16x32_bf16 v[68:71], v[12:15], v[36:39], v[68:71]
	v_mfma_f32_16x16x32_bf16 v[72:75], v[4:7], v[44:47], v[72:75]
	v_mfma_f32_16x16x32_bf16 v[76:79], v[12:15], v[44:47], v[76:79]
	v_mfma_f32_16x16x32_bf16 v[80:83], v[4:7], v[52:55], v[80:83]
	v_mfma_f32_16x16x32_bf16 v[84:87], v[12:15], v[52:55], v[84:87]
	v_mfma_f32_16x16x32_bf16 v[88:91], v[4:7], v[60:63], v[88:91]
	v_mfma_f32_16x16x32_bf16 v[92:95], v[12:15], v[60:63], v[92:95]
	v_mfma_f32_16x16x32_bf16 v[96:99], v[16:19], v[32:35], 0
	v_mfma_f32_16x16x32_bf16 v[32:35], v[24:27], v[32:35], 0
	v_mfma_f32_16x16x32_bf16 v[96:99], v[20:23], v[36:39], v[96:99]
	v_mfma_f32_16x16x32_bf16 v[32:35], v[28:31], v[36:39], v[32:35]
	v_mfma_f32_16x16x32_bf16 v[36:39], v[16:19], v[40:43], 0
	v_mfma_f32_16x16x32_bf16 v[40:43], v[24:27], v[40:43], 0
	v_mfma_f32_16x16x32_bf16 v[36:39], v[20:23], v[44:47], v[36:39]
	v_mfma_f32_16x16x32_bf16 v[40:43], v[28:31], v[44:47], v[40:43]
	v_mfma_f32_16x16x32_bf16 v[44:47], v[16:19], v[48:51], 0
	v_mfma_f32_16x16x32_bf16 v[48:51], v[24:27], v[48:51], 0
	v_mfma_f32_16x16x32_bf16 v[44:47], v[20:23], v[52:55], v[44:47]
	v_mfma_f32_16x16x32_bf16 v[48:51], v[28:31], v[52:55], v[48:51]
	v_mfma_f32_16x16x32_bf16 v[52:55], v[16:19], v[56:59], 0
	v_mfma_f32_16x16x32_bf16 v[56:59], v[24:27], v[56:59], 0
	v_mfma_f32_16x16x32_bf16 v[52:55], v[20:23], v[60:63], v[52:55]
	v_mfma_f32_16x16x32_bf16 v[56:59], v[28:31], v[60:63], v[56:59]
	s_barrier
	ds_read_b128 v[60:63], v142 offset:16384
	ds_read_b128 v[100:103], v142 offset:17408
	ds_read_b128 v[104:107], v142 offset:18432
	ds_read_b128 v[108:111], v142 offset:19456
	ds_read_b128 v[112:115], v142 offset:20480
	ds_read_b128 v[116:119], v142 offset:21504
	ds_read_b128 v[120:123], v142 offset:22528
	ds_read_b128 v[124:127], v142 offset:23552
	s_mov_b32 m0, s33
	s_nop 0
	global_load_lds_dwordx4 v138, s[76:77]
	s_add_u32 s76, s58, 0x8100
	s_mov_b32 m0, s34
	s_addc_u32 s77, s59, 0
	global_load_lds_dwordx4 v138, s[76:77]
	s_add_u32 s76, s58, 0x10100
	s_mov_b32 m0, s35
	s_addc_u32 s77, s59, 0
	global_load_lds_dwordx4 v138, s[76:77]
	s_add_u32 s76, s58, 0x18100
	s_mov_b32 m0, s36
	s_addc_u32 s77, s59, 0
	global_load_lds_dwordx4 v138, s[76:77]
	s_mov_b32 m0, s24
	s_nop 0
	global_load_lds_dwordx4 v128, s[22:23]
	s_add_u32 s22, s56, 0x8100
	s_mov_b32 m0, s37
	s_addc_u32 s23, s57, 0
	global_load_lds_dwordx4 v128, s[22:23]
	s_waitcnt vmcnt(8) lgkmcnt(0)
	s_barrier
	v_mfma_f32_16x16x32_bf16 v[144:147], v[0:3], v[60:63], 0
	v_mfma_f32_16x16x32_bf16 v[152:155], v[0:3], v[104:107], 0
	v_mfma_f32_16x16x32_bf16 v[178:181], v[0:3], v[112:115], 0
	v_mfma_f32_16x16x32_bf16 v[0:3], v[0:3], v[120:123], 0
	v_mfma_f32_16x16x32_bf16 v[144:147], v[4:7], v[100:103], v[144:147]
	v_mfma_f32_16x16x32_bf16 v[152:155], v[4:7], v[108:111], v[152:155]
	v_mfma_f32_16x16x32_bf16 v[178:181], v[4:7], v[116:119], v[178:181]
	v_mfma_f32_16x16x32_bf16 v[0:3], v[4:7], v[124:127], v[0:3]
	v_mfma_f32_16x16x32_bf16 v[4:7], v[8:11], v[120:123], 0
	v_mfma_f32_16x16x32_bf16 v[148:151], v[8:11], v[60:63], 0
	v_mfma_f32_16x16x32_bf16 v[172:175], v[8:11], v[104:107], 0
	v_mfma_f32_16x16x32_bf16 v[182:185], v[8:11], v[112:115], 0
	v_mfma_f32_16x16x32_bf16 v[4:7], v[12:15], v[124:127], v[4:7]
	v_mfma_f32_16x16x32_bf16 v[148:151], v[12:15], v[100:103], v[148:151]
	v_mfma_f32_16x16x32_bf16 v[172:175], v[12:15], v[108:111], v[172:175]
	v_mfma_f32_16x16x32_bf16 v[182:185], v[12:15], v[116:119], v[182:185]
	v_mfma_f32_16x16x32_bf16 v[8:11], v[16:19], v[60:63], 0
	v_mfma_f32_16x16x32_bf16 v[12:15], v[24:27], v[60:63], 0
	v_mfma_f32_16x16x32_bf16 v[8:11], v[20:23], v[100:103], v[8:11]
	v_mfma_f32_16x16x32_bf16 v[12:15], v[28:31], v[100:103], v[12:15]
	v_mfma_f32_16x16x32_bf16 v[60:63], v[16:19], v[104:107], 0
	v_mfma_f32_16x16x32_bf16 v[100:103], v[24:27], v[104:107], 0
	v_mfma_f32_16x16x32_bf16 v[104:107], v[16:19], v[112:115], 0
	v_mfma_f32_16x16x32_bf16 v[16:19], v[16:19], v[120:123], 0
	v_mfma_f32_16x16x32_bf16 v[60:63], v[20:23], v[108:111], v[60:63]
	v_mfma_f32_16x16x32_bf16 v[100:103], v[28:31], v[108:111], v[100:103]
	v_mfma_f32_16x16x32_bf16 v[104:107], v[20:23], v[116:119], v[104:107]
	v_mfma_f32_16x16x32_bf16 v[108:111], v[24:27], v[112:115], 0
	v_mfma_f32_16x16x32_bf16 v[16:19], v[20:23], v[124:127], v[16:19]
	v_mfma_f32_16x16x32_bf16 v[20:23], v[24:27], v[120:123], 0
	v_mfma_f32_16x16x32_bf16 v[108:111], v[28:31], v[116:119], v[108:111]
	v_mfma_f32_16x16x32_bf16 v[20:23], v[28:31], v[124:127], v[20:23]
	s_barrier
; #define PG8_STAGE(bufoff, gbase, voff, p64) do { _Pragma("unroll") for (int _i = 0; _i < 2; ++_i) { \
;         const char* _gb = (const char*)(gbase) + (size_t)_i * (p64); const unsigned _la = ldsbase + (unsigned)(bufoff) + (unsigned)_i * 8192u; \
;         asm volatile("s_mov_b32 m0, %0\n\ts_nop 0\n\tglobal_load_lds_dwordx4 %1, %2" :: "s"(_la), "v"(voff), "s"(_gb) : "memory"); } } while (0)
; #define PG8_LDA(dst, b, h) do { _Pragma("unroll") for (int m = 0; m < 4; ++m) _Pragma("unroll") for (int k = 0; k < 2; ++k) dst[m][k] = *(const LAS bf16x8*)(lds + PG8_SA(b, h) + aoff + m * 2048 + k * 1024); } while (0)
; #define PG8_LDB(dst, b, h) do { _Pragma("unroll") for (int n = 0; n < 2; ++n) _Pragma("unroll") for (int k = 0; k < 2; ++k) dst[n][k] = *(const LAS bf16x8*)(lds + PG8_SB(b, h) + boff + n * 2048 + k * 1024); } while (0)
; #define PG8_MMA(ai, bj, At, Bt) do { __builtin_amdgcn_s_setprio(1); _Pragma("unroll") for (int m = 0; m < 4; ++m) _Pragma("unroll") for (int n = 0; n < 2; ++n) _Pragma("unroll") for (int k = 0; k < 2; ++k) \
;         acc[ai][bj][m][n] = __builtin_amdgcn_mfma_f32_16x16x32_bf16(Bt[n][k], At[m][k], acc[ai][bj][m][n], 0, 0, 0); __builtin_amdgcn_s_setprio(0); } while (0)
; #define PG8_WAIT_V(n) asm volatile("s_waitcnt vmcnt(" #n ")" ::: "memory")
; #define PG8_WAIT_L(n) asm volatile("s_waitcnt lgkmcnt(" #n ")" ::: "memory")
; #define PG8_BAR __builtin_amdgcn_s_barrier()
; #define PG8_SCHED __builtin_amdgcn_sched_barrier(0)
; template <class Epi, class Sched>
; __device__ __forceinline__ void gemm_phase(LAS unsigned char* lds, const Sched& S, const Epi& E) {
;     ...
;             PG8_LDB(B0, 1, 0); PG8_LDB(B1, 1, 1); PG8_SCHED; PG8_LDA(At, 1, 0); PG8_STAGE(PG8_SA(0, 1), a2 + hA2, vA2, hA2 / 2);
;             PG8_WAIT_V(8); PG8_WAIT_L(0); PG8_BAR; PG8_MMA(0, 0, At, B0); PG8_MMA(0, 1, At, B1); PG8_BAR; PG8_SCHED;
;             PG8_LDA(At, 1, 1); PG8_STAGE(PG8_SB(1, 0), b3, vB2, hB2 / 2); PG8_STAGE(PG8_SB(1, 1), b3 + hB2, vB2, hB2 / 2); PG8_STAGE(PG8_SA(1, 0), a3, vA2, hA2 / 2);
;             PG8_WAIT_V(8); PG8_WAIT_L(0); PG8_BAR; PG8_MMA(1, 0, At, B0); PG8_MMA(1, 1, At, B1); PG8_BAR; PG8_SCHED;
	v_add_u32_e32 v132, 0x18000, v141
	v_add_u32_e32 v133, 0x1c000, v141
	ds_read_b128 v[24:27], v132
	ds_read_b128 v[28:31], v132 offset:1024
	ds_read_b128 v[112:115], v132 offset:2048
	ds_read_b128 v[116:119], v132 offset:3072
	ds_read_b128 v[120:123], v133
	ds_read_b128 v[124:127], v133 offset:1024
	ds_read_b128 v[186:189], v133 offset:2048
	ds_read_b128 v[190:193], v133 offset:3072
	ds_read_b128 v[194:197], v142 offset:32768
	ds_read_b128 v[198:201], v142 offset:33792
	ds_read_b128 v[202:205], v142 offset:34816
	ds_read_b128 v[206:209], v142 offset:35840
	ds_read_b128 v[210:213], v142 offset:36864
	ds_read_b128 v[214:217], v142 offset:37888
	ds_read_b128 v[218:221], v142 offset:38912
	ds_read_b128 v[222:225], v142 offset:39936
	s_add_u32 s22, s56, 0x10100
	s_mov_b32 m0, s42
	s_addc_u32 s23, s57, 0
	global_load_lds_dwordx4 v128, s[22:23]
	s_add_u32 s22, s56, 0x18100
	s_mov_b32 m0, s44
	s_addc_u32 s23, s57, 0
	global_load_lds_dwordx4 v128, s[22:23]
	s_waitcnt vmcnt(8) lgkmcnt(0)
	s_barrier
	v_mfma_f32_16x16x32_bf16 v[64:67], v[24:27], v[194:197], v[64:67]
	v_mfma_f32_16x16x32_bf16 v[68:71], v[112:115], v[194:197], v[68:71]
	v_mfma_f32_16x16x32_bf16 v[72:75], v[24:27], v[202:205], v[72:75]
	v_mfma_f32_16x16x32_bf16 v[76:79], v[112:115], v[202:205], v[76:79]
	v_mfma_f32_16x16x32_bf16 v[80:83], v[24:27], v[210:213], v[80:83]
	v_mfma_f32_16x16x32_bf16 v[84:87], v[112:115], v[210:213], v[84:87]
	v_mfma_f32_16x16x32_bf16 v[88:91], v[24:27], v[218:221], v[88:91]
	v_mfma_f32_16x16x32_bf16 v[92:95], v[112:115], v[218:221], v[92:95]
	v_mfma_f32_16x16x32_bf16 v[64:67], v[28:31], v[198:201], v[64:67]
	v_mfma_f32_16x16x32_bf16 v[68:71], v[116:119], v[198:201], v[68:71]
	v_mfma_f32_16x16x32_bf16 v[72:75], v[28:31], v[206:209], v[72:75]
	v_mfma_f32_16x16x32_bf16 v[76:79], v[116:119], v[206:209], v[76:79]
	v_mfma_f32_16x16x32_bf16 v[80:83], v[28:31], v[214:217], v[80:83]
	v_mfma_f32_16x16x32_bf16 v[84:87], v[116:119], v[214:217], v[84:87]
	v_mfma_f32_16x16x32_bf16 v[88:91], v[28:31], v[222:225], v[88:91]
	v_mfma_f32_16x16x32_bf16 v[92:95], v[116:119], v[222:225], v[92:95]
	v_mfma_f32_16x16x32_bf16 v[96:99], v[120:123], v[194:197], v[96:99]
	v_mfma_f32_16x16x32_bf16 v[32:35], v[186:189], v[194:197], v[32:35]
	v_mfma_f32_16x16x32_bf16 v[36:39], v[120:123], v[202:205], v[36:39]
	v_mfma_f32_16x16x32_bf16 v[40:43], v[186:189], v[202:205], v[40:43]
	v_mfma_f32_16x16x32_bf16 v[44:47], v[120:123], v[210:213], v[44:47]
	v_mfma_f32_16x16x32_bf16 v[48:51], v[186:189], v[210:213], v[48:51]
	v_mfma_f32_16x16x32_bf16 v[52:55], v[120:123], v[218:221], v[52:55]
	v_mfma_f32_16x16x32_bf16 v[56:59], v[186:189], v[218:221], v[56:59]
	v_mfma_f32_16x16x32_bf16 v[96:99], v[124:127], v[198:201], v[96:99]
	v_mfma_f32_16x16x32_bf16 v[32:35], v[190:193], v[198:201], v[32:35]
	v_mfma_f32_16x16x32_bf16 v[36:39], v[124:127], v[206:209], v[36:39]
	v_mfma_f32_16x16x32_bf16 v[40:43], v[190:193], v[206:209], v[40:43]
	v_mfma_f32_16x16x32_bf16 v[44:47], v[124:127], v[214:217], v[44:47]
	v_mfma_f32_16x16x32_bf16 v[48:51], v[190:193], v[214:217], v[48:51]
	v_mfma_f32_16x16x32_bf16 v[52:55], v[124:127], v[222:225], v[52:55]
	v_mfma_f32_16x16x32_bf16 v[56:59], v[190:193], v[222:225], v[56:59]
	s_barrier
	s_add_u32 s22, s58, 0x180
	s_addc_u32 s23, s59, 0
	ds_read_b128 v[194:197], v142 offset:49152
	ds_read_b128 v[198:201], v142 offset:50176
	ds_read_b128 v[202:205], v142 offset:51200
	ds_read_b128 v[206:209], v142 offset:52224
	ds_read_b128 v[210:213], v142 offset:53248
	ds_read_b128 v[214:217], v142 offset:54272
	ds_read_b128 v[218:221], v142 offset:55296
	ds_read_b128 v[222:225], v142 offset:56320
	s_mov_b32 m0, s51
	s_nop 0
	global_load_lds_dwordx4 v138, s[22:23]
	s_add_u32 s22, s58, 0x8180
	s_mov_b32 m0, s61
	s_addc_u32 s23, s59, 0
	global_load_lds_dwordx4 v138, s[22:23]
	s_add_u32 s22, s58, 0x10180
	s_mov_b32 m0, s64
	s_addc_u32 s23, s59, 0
	global_load_lds_dwordx4 v138, s[22:23]
	s_add_u32 s22, s58, 0x18180
	s_mov_b32 m0, s65
	s_addc_u32 s23, s59, 0
	global_load_lds_dwordx4 v138, s[22:23]
	s_mov_b32 m0, s62
	s_nop 0
	global_load_lds_dwordx4 v128, s[16:17]
	s_add_u32 s16, s56, 0x8180
	s_mov_b32 m0, s63
	s_addc_u32 s17, s57, 0
	global_load_lds_dwordx4 v128, s[16:17]
	s_waitcnt vmcnt(8) lgkmcnt(0)
	s_barrier
	v_mfma_f32_16x16x32_bf16 v[0:3], v[24:27], v[218:221], v[0:3]
	v_mfma_f32_16x16x32_bf16 v[4:7], v[112:115], v[218:221], v[4:7]
	v_mfma_f32_16x16x32_bf16 v[144:147], v[24:27], v[194:197], v[144:147]
	v_mfma_f32_16x16x32_bf16 v[148:151], v[112:115], v[194:197], v[148:151]
	v_mfma_f32_16x16x32_bf16 v[152:155], v[24:27], v[202:205], v[152:155]
	v_mfma_f32_16x16x32_bf16 v[172:175], v[112:115], v[202:205], v[172:175]
	v_mfma_f32_16x16x32_bf16 v[178:181], v[24:27], v[210:213], v[178:181]
	v_mfma_f32_16x16x32_bf16 v[182:185], v[112:115], v[210:213], v[182:185]
	v_mfma_f32_16x16x32_bf16 v[0:3], v[28:31], v[222:225], v[0:3]
	v_mfma_f32_16x16x32_bf16 v[4:7], v[116:119], v[222:225], v[4:7]
	v_mfma_f32_16x16x32_bf16 v[144:147], v[28:31], v[198:201], v[144:147]
	v_mfma_f32_16x16x32_bf16 v[148:151], v[116:119], v[198:201], v[148:151]
	v_mfma_f32_16x16x32_bf16 v[152:155], v[28:31], v[206:209], v[152:155]
	v_mfma_f32_16x16x32_bf16 v[172:175], v[116:119], v[206:209], v[172:175]
	v_mfma_f32_16x16x32_bf16 v[178:181], v[28:31], v[214:217], v[178:181]
	v_mfma_f32_16x16x32_bf16 v[182:185], v[116:119], v[214:217], v[182:185]
	v_mfma_f32_16x16x32_bf16 v[8:11], v[120:123], v[194:197], v[8:11]
	v_mfma_f32_16x16x32_bf16 v[12:15], v[186:189], v[194:197], v[12:15]
	v_mfma_f32_16x16x32_bf16 v[24:27], v[120:123], v[202:205], v[60:63]
	v_mfma_f32_16x16x32_bf16 v[28:31], v[186:189], v[202:205], v[100:103]
	v_mfma_f32_16x16x32_bf16 v[60:63], v[120:123], v[210:213], v[104:107]
	v_mfma_f32_16x16x32_bf16 v[100:103], v[186:189], v[210:213], v[108:111]
	v_mfma_f32_16x16x32_bf16 v[16:19], v[120:123], v[218:221], v[16:19]
	v_mfma_f32_16x16x32_bf16 v[20:23], v[186:189], v[218:221], v[20:23]
	v_mfma_f32_16x16x32_bf16 v[8:11], v[124:127], v[198:201], v[8:11]
	v_mfma_f32_16x16x32_bf16 v[12:15], v[190:193], v[198:201], v[12:15]
	v_mfma_f32_16x16x32_bf16 v[24:27], v[124:127], v[206:209], v[24:27]
	v_mfma_f32_16x16x32_bf16 v[28:31], v[190:193], v[206:209], v[28:31]
	v_mfma_f32_16x16x32_bf16 v[60:63], v[124:127], v[214:217], v[60:63]
	v_mfma_f32_16x16x32_bf16 v[100:103], v[190:193], v[214:217], v[100:103]
	v_mfma_f32_16x16x32_bf16 v[16:19], v[124:127], v[222:225], v[16:19]
	v_mfma_f32_16x16x32_bf16 v[20:23], v[190:193], v[222:225], v[20:23]
	s_barrier
; #define PG8_STAGE(bufoff, gbase, voff, p64) do { _Pragma("unroll") for (int _i = 0; _i < 2; ++_i) { \
;         const char* _gb = (const char*)(gbase) + (size_t)_i * (p64); const unsigned _la = ldsbase + (unsigned)(bufoff) + (unsigned)_i * 8192u; \
;         asm volatile("s_mov_b32 m0, %0\n\ts_nop 0\n\tglobal_load_lds_dwordx4 %1, %2" :: "s"(_la), "v"(voff), "s"(_gb) : "memory"); } } while (0)
; #define PG8_LDA(dst, b, h) do { _Pragma("unroll") for (int m = 0; m < 4; ++m) _Pragma("unroll") for (int k = 0; k < 2; ++k) dst[m][k] = *(const LAS bf16x8*)(lds + PG8_SA(b, h) + aoff + m * 2048 + k * 1024); } while (0)
; #define PG8_LDB(dst, b, h) do { _Pragma("unroll") for (int n = 0; n < 2; ++n) _Pragma("unroll") for (int k = 0; k < 2; ++k) dst[n][k] = *(const LAS bf16x8*)(lds + PG8_SB(b, h) + boff + n * 2048 + k * 1024); } while (0)
; #define PG8_MMA(ai, bj, At, Bt) do { __builtin_amdgcn_s_setprio(1); _Pragma("unroll") for (int m = 0; m < 4; ++m) _Pragma("unroll") for (int n = 0; n < 2; ++n) _Pragma("unroll") for (int k = 0; k < 2; ++k) \
;         acc[ai][bj][m][n] = __builtin_amdgcn_mfma_f32_16x16x32_bf16(Bt[n][k], At[m][k], acc[ai][bj][m][n], 0, 0, 0); __builtin_amdgcn_s_setprio(0); } while (0)
; #define PG8_WAIT_V(n) asm volatile("s_waitcnt vmcnt(" #n ")" ::: "memory")
; #define PG8_WAIT_L(n) asm volatile("s_waitcnt lgkmcnt(" #n ")" ::: "memory")
; #define PG8_BAR __builtin_amdgcn_s_barrier()
; #define PG8_SCHED __builtin_amdgcn_sched_barrier(0)
; template <class Epi, class Sched>
; __device__ __forceinline__ void gemm_phase(LAS unsigned char* lds, const Sched& S, const Epi& E) {
;     ...
;             PG8_LDB(B0, 0, 0); PG8_LDB(B1, 0, 1); PG8_SCHED; PG8_LDA(At, 0, 0); PG8_STAGE(PG8_SA(1, 1), a1 + hA, voffA, hA / 2);
;             PG8_WAIT_V(8); PG8_WAIT_L(0); PG8_BAR; PG8_MMA(0, 0, At, B0); PG8_MMA(0, 1, At, B1); PG8_BAR; PG8_SCHED;
;             PG8_LDA(At, 0, 1); PG8_STAGE(PG8_SB(0, 0), b2, vB2, hB2 / 2); PG8_STAGE(PG8_SB(0, 1), b2 + hB2, vB2, hB2 / 2); PG8_STAGE(PG8_SA(0, 0), a2, vA2, hA2 / 2);
;             PG8_WAIT_V(8); PG8_WAIT_L(0); PG8_BAR; PG8_MMA(1, 0, At, B0); PG8_MMA(1, 1, At, B1); PG8_BAR; PG8_SCHED;
	ds_read_b128 v[104:107], v130
	ds_read_b128 v[108:111], v130 offset:1024
	ds_read_b128 v[112:115], v130 offset:2048
	ds_read_b128 v[116:119], v130 offset:3072
	ds_read_b128 v[120:123], v131
	ds_read_b128 v[124:127], v131 offset:1024
	ds_read_b128 v[186:189], v131 offset:2048
	ds_read_b128 v[190:193], v131 offset:3072
	s_add_u32 s16, s38, 0x80
	s_addc_u32 s17, s39, 0
	ds_read_b128 v[194:197], v142
	ds_read_b128 v[198:201], v142 offset:1024
	ds_read_b128 v[202:205], v142 offset:2048
	ds_read_b128 v[206:209], v142 offset:3072
	ds_read_b128 v[210:213], v142 offset:4096
	ds_read_b128 v[214:217], v142 offset:5120
	ds_read_b128 v[218:221], v142 offset:6144
	ds_read_b128 v[222:225], v142 offset:7168
	s_add_u32 s22, s56, 0x10180
	s_mov_b32 m0, s66
	s_addc_u32 s23, s57, 0
	global_load_lds_dwordx4 v128, s[22:23]
	s_add_u32 s22, s56, 0x18180
	s_mov_b32 m0, s67
	s_addc_u32 s23, s57, 0
	global_load_lds_dwordx4 v128, s[22:23]
	s_waitcnt vmcnt(8) lgkmcnt(0)
	s_barrier
	v_mfma_f32_16x16x32_bf16 v[64:67], v[104:107], v[194:197], v[64:67]
	v_mfma_f32_16x16x32_bf16 v[68:71], v[112:115], v[194:197], v[68:71]
	v_mfma_f32_16x16x32_bf16 v[72:75], v[104:107], v[202:205], v[72:75]
	v_mfma_f32_16x16x32_bf16 v[76:79], v[112:115], v[202:205], v[76:79]
	v_mfma_f32_16x16x32_bf16 v[80:83], v[104:107], v[210:213], v[80:83]
	v_mfma_f32_16x16x32_bf16 v[84:87], v[112:115], v[210:213], v[84:87]
	v_mfma_f32_16x16x32_bf16 v[88:91], v[104:107], v[218:221], v[88:91]
	v_mfma_f32_16x16x32_bf16 v[92:95], v[112:115], v[218:221], v[92:95]
	v_mfma_f32_16x16x32_bf16 v[64:67], v[108:111], v[198:201], v[64:67]
	v_mfma_f32_16x16x32_bf16 v[68:71], v[116:119], v[198:201], v[68:71]
	v_mfma_f32_16x16x32_bf16 v[72:75], v[108:111], v[206:209], v[72:75]
	v_mfma_f32_16x16x32_bf16 v[76:79], v[116:119], v[206:209], v[76:79]
	v_mfma_f32_16x16x32_bf16 v[80:83], v[108:111], v[214:217], v[80:83]
	v_mfma_f32_16x16x32_bf16 v[84:87], v[116:119], v[214:217], v[84:87]
	v_mfma_f32_16x16x32_bf16 v[88:91], v[108:111], v[222:225], v[88:91]
	v_mfma_f32_16x16x32_bf16 v[92:95], v[116:119], v[222:225], v[92:95]
	v_mfma_f32_16x16x32_bf16 v[32:35], v[186:189], v[194:197], v[32:35]
	v_mfma_f32_16x16x32_bf16 v[96:99], v[120:123], v[194:197], v[96:99]
	v_mfma_f32_16x16x32_bf16 v[194:197], v[190:193], v[198:201], v[32:35]
	v_mfma_f32_16x16x32_bf16 v[32:35], v[120:123], v[202:205], v[36:39]
	v_mfma_f32_16x16x32_bf16 v[96:99], v[124:127], v[198:201], v[96:99]
	v_mfma_f32_16x16x32_bf16 v[198:201], v[124:127], v[206:209], v[32:35]
	v_mfma_f32_16x16x32_bf16 v[32:35], v[186:189], v[202:205], v[40:43]
	v_mfma_f32_16x16x32_bf16 v[40:43], v[190:193], v[206:209], v[32:35]
	v_mfma_f32_16x16x32_bf16 v[32:35], v[120:123], v[210:213], v[44:47]
	v_mfma_f32_16x16x32_bf16 v[44:47], v[124:127], v[214:217], v[32:35]
	v_mfma_f32_16x16x32_bf16 v[32:35], v[186:189], v[210:213], v[48:51]
	v_mfma_f32_16x16x32_bf16 v[202:205], v[190:193], v[214:217], v[32:35]
	v_mfma_f32_16x16x32_bf16 v[32:35], v[120:123], v[218:221], v[52:55]
	v_mfma_f32_16x16x32_bf16 v[206:209], v[124:127], v[222:225], v[32:35]
	v_mfma_f32_16x16x32_bf16 v[32:35], v[186:189], v[218:221], v[56:59]
	v_mfma_f32_16x16x32_bf16 v[210:213], v[190:193], v[222:225], v[32:35]
	s_barrier
	s_add_u32 s22, s40, 0x8000
	s_nop 3
	ds_read_b128 v[32:35], v142 offset:16384
	ds_read_b128 v[36:39], v142 offset:17408
	ds_read_b128 v[48:51], v142 offset:18432
	ds_read_b128 v[52:55], v142 offset:19456
	ds_read_b128 v[56:59], v142 offset:20480
	ds_read_b128 v[214:217], v142 offset:21504
	ds_read_b128 v[218:221], v142 offset:22528
	ds_read_b128 v[222:225], v142 offset:23552
	s_mov_b32 m0, s33
	s_nop 0
	global_load_lds_dwordx4 v138, s[40:41]
	s_mov_b32 m0, s34
	s_addc_u32 s23, s41, 0
	global_load_lds_dwordx4 v138, s[22:23]
	s_add_u32 s22, s40, 0x10000
	s_mov_b32 m0, s35
	s_addc_u32 s23, s41, 0
	global_load_lds_dwordx4 v138, s[22:23]
	s_add_u32 s22, s40, 0x18000
	s_mov_b32 m0, s36
	s_addc_u32 s23, s41, 0
	global_load_lds_dwordx4 v138, s[22:23]
	s_mov_b32 m0, s24
	s_nop 0
	global_load_lds_dwordx4 v128, s[38:39]
	s_add_u32 s22, s38, 0x8000
	s_mov_b32 m0, s37
	s_addc_u32 s23, s39, 0
	global_load_lds_dwordx4 v128, s[22:23]
	s_waitcnt vmcnt(8) lgkmcnt(0)
	s_barrier
	v_mfma_f32_16x16x32_bf16 v[0:3], v[104:107], v[218:221], v[0:3]
	v_mfma_f32_16x16x32_bf16 v[144:147], v[104:107], v[32:35], v[144:147]
	v_mfma_f32_16x16x32_bf16 v[152:155], v[104:107], v[48:51], v[152:155]
	v_mfma_f32_16x16x32_bf16 v[178:181], v[104:107], v[56:59], v[178:181]
	v_mfma_f32_16x16x32_bf16 v[104:107], v[108:111], v[222:225], v[0:3]
	v_mfma_f32_16x16x32_bf16 v[0:3], v[112:115], v[218:221], v[4:7]
	v_mfma_f32_16x16x32_bf16 v[144:147], v[108:111], v[36:39], v[144:147]
	v_mfma_f32_16x16x32_bf16 v[148:151], v[112:115], v[32:35], v[148:151]
	v_mfma_f32_16x16x32_bf16 v[152:155], v[108:111], v[52:55], v[152:155]
	v_mfma_f32_16x16x32_bf16 v[172:175], v[112:115], v[48:51], v[172:175]
	v_mfma_f32_16x16x32_bf16 v[178:181], v[108:111], v[214:217], v[178:181]
	v_mfma_f32_16x16x32_bf16 v[182:185], v[112:115], v[56:59], v[182:185]
	v_mfma_f32_16x16x32_bf16 v[108:111], v[116:119], v[222:225], v[0:3]
	v_mfma_f32_16x16x32_bf16 v[148:151], v[116:119], v[36:39], v[148:151]
	v_mfma_f32_16x16x32_bf16 v[172:175], v[116:119], v[52:55], v[172:175]
	v_mfma_f32_16x16x32_bf16 v[182:185], v[116:119], v[214:217], v[182:185]
	v_mfma_f32_16x16x32_bf16 v[0:3], v[120:123], v[32:35], v[8:11]
	v_mfma_f32_16x16x32_bf16 v[112:115], v[124:127], v[36:39], v[0:3]
	v_mfma_f32_16x16x32_bf16 v[0:3], v[186:189], v[32:35], v[12:15]
	v_mfma_f32_16x16x32_bf16 v[116:119], v[190:193], v[36:39], v[0:3]
	v_mfma_f32_16x16x32_bf16 v[0:3], v[120:123], v[48:51], v[24:27]
	v_mfma_f32_16x16x32_bf16 v[226:229], v[124:127], v[52:55], v[0:3]
	v_mfma_f32_16x16x32_bf16 v[0:3], v[186:189], v[48:51], v[28:31]
	v_mfma_f32_16x16x32_bf16 v[230:233], v[190:193], v[52:55], v[0:3]
	v_mfma_f32_16x16x32_bf16 v[0:3], v[120:123], v[56:59], v[60:63]
	v_mfma_f32_16x16x32_bf16 v[234:237], v[124:127], v[214:217], v[0:3]
	v_mfma_f32_16x16x32_bf16 v[0:3], v[186:189], v[56:59], v[100:103]
	v_mfma_f32_16x16x32_bf16 v[214:217], v[190:193], v[214:217], v[0:3]
	v_mfma_f32_16x16x32_bf16 v[0:3], v[120:123], v[218:221], v[16:19]
	v_mfma_f32_16x16x32_bf16 v[238:241], v[124:127], v[222:225], v[0:3]
	v_mfma_f32_16x16x32_bf16 v[0:3], v[186:189], v[218:221], v[20:23]
	v_mfma_f32_16x16x32_bf16 v[186:189], v[190:193], v[222:225], v[0:3]
	s_barrier
; #define PG8_STAGE(bufoff, gbase, voff, p64) do { _Pragma("unroll") for (int _i = 0; _i < 2; ++_i) { \
;         const char* _gb = (const char*)(gbase) + (size_t)_i * (p64); const unsigned _la = ldsbase + (unsigned)(bufoff) + (unsigned)_i * 8192u; \
;         asm volatile("s_mov_b32 m0, %0\n\ts_nop 0\n\tglobal_load_lds_dwordx4 %1, %2" :: "s"(_la), "v"(voff), "s"(_gb) : "memory"); } } while (0)
; #define PG8_LDA(dst, b, h) do { _Pragma("unroll") for (int m = 0; m < 4; ++m) _Pragma("unroll") for (int k = 0; k < 2; ++k) dst[m][k] = *(const LAS bf16x8*)(lds + PG8_SA(b, h) + aoff + m * 2048 + k * 1024); } while (0)
; #define PG8_LDB(dst, b, h) do { _Pragma("unroll") for (int n = 0; n < 2; ++n) _Pragma("unroll") for (int k = 0; k < 2; ++k) dst[n][k] = *(const LAS bf16x8*)(lds + PG8_SB(b, h) + boff + n * 2048 + k * 1024); } while (0)
; #define PG8_MMA(ai, bj, At, Bt) do { __builtin_amdgcn_s_setprio(1); _Pragma("unroll") for (int m = 0; m < 4; ++m) _Pragma("unroll") for (int n = 0; n < 2; ++n) _Pragma("unroll") for (int k = 0; k < 2; ++k) \
;         acc[ai][bj][m][n] = __builtin_amdgcn_mfma_f32_16x16x32_bf16(Bt[n][k], At[m][k], acc[ai][bj][m][n], 0, 0, 0); __builtin_amdgcn_s_setprio(0); } while (0)
; #define PG8_WAIT_V(n) asm volatile("s_waitcnt vmcnt(" #n ")" ::: "memory")
; #define PG8_WAIT_L(n) asm volatile("s_waitcnt lgkmcnt(" #n ")" ::: "memory")
; #define PG8_BAR __builtin_amdgcn_s_barrier()
; #define PG8_SCHED __builtin_amdgcn_sched_barrier(0)
; template <class Epi, class Sched>
; __device__ __forceinline__ void gemm_phase(LAS unsigned char* lds, const Sched& S, const Epi& E) {
;     ...
;             PG8_LDB(B0, 1, 0); PG8_LDB(B1, 1, 1); PG8_SCHED; PG8_LDA(At, 1, 0); PG8_STAGE(PG8_SA(0, 1), a2 + hA2, vA2, hA2 / 2);
;             PG8_WAIT_V(8); PG8_WAIT_L(0); PG8_BAR; PG8_MMA(0, 0, At, B0); PG8_MMA(0, 1, At, B1); PG8_BAR; PG8_SCHED;
;             PG8_LDA(At, 1, 1); PG8_STAGE(PG8_SB(1, 0), b3, vB2, hB2 / 2); PG8_STAGE(PG8_SB(1, 1), b3 + hB2, vB2, hB2 / 2); PG8_STAGE(PG8_SA(1, 0), a3, vA2, hA2 / 2);
;             PG8_WAIT_V(8); PG8_WAIT_L(0); PG8_BAR; PG8_MMA(1, 0, At, B0); PG8_MMA(1, 1, At, B1); PG8_BAR; PG8_SCHED;
;         }
;         if (wr == 0) PG8_BAR;
	ds_read_b128 v[120:123], v132
	ds_read_b128 v[124:127], v132 offset:1024
	ds_read_b128 v[190:193], v132 offset:2048
	ds_read_b128 v[218:221], v132 offset:3072
	ds_read_b128 v[222:225], v133
	ds_read_b128 v[242:245], v133 offset:1024
	ds_read_b128 v[246:249], v133 offset:2048
	ds_read_b128 v[250:253], v133 offset:3072
	ds_read_b128 v[24:27], v142 offset:32768
	ds_read_b128 v[28:31], v142 offset:33792
	ds_read_b128 v[52:55], v142 offset:34816
	ds_read_b128 v[100:103], v142 offset:35840
	ds_read_b128 v[130:133], v142 offset:36864
	ds_read_b128 v[162:165], v142 offset:37888
	ds_read_b128 v[134:137], v142 offset:38912
	ds_read_b128 v[158:161], v142 offset:39936
	s_add_u32 s22, s38, 0x10000
	s_mov_b32 m0, s42
	s_addc_u32 s23, s39, 0
	global_load_lds_dwordx4 v128, s[22:23]
	s_add_u32 s22, s38, 0x18000
	s_mov_b32 m0, s44
	s_addc_u32 s23, s39, 0
	global_load_lds_dwordx4 v128, s[22:23]
	s_waitcnt vmcnt(8) lgkmcnt(0)
	s_barrier
	v_mfma_f32_16x16x32_bf16 v[0:3], v[120:123], v[24:27], v[64:67]
	v_mfma_f32_16x16x32_bf16 v[32:35], v[124:127], v[28:31], v[0:3]
	v_mfma_f32_16x16x32_bf16 v[0:3], v[190:193], v[24:27], v[68:71]
	v_mfma_f32_16x16x32_bf16 v[36:39], v[218:221], v[28:31], v[0:3]
	v_mfma_f32_16x16x32_bf16 v[0:3], v[120:123], v[52:55], v[72:75]
	v_mfma_f32_16x16x32_bf16 v[16:19], v[124:127], v[100:103], v[0:3]
	v_mfma_f32_16x16x32_bf16 v[0:3], v[190:193], v[52:55], v[76:79]
	v_mfma_f32_16x16x32_bf16 v[20:23], v[218:221], v[100:103], v[0:3]
	v_mfma_f32_16x16x32_bf16 v[0:3], v[120:123], v[130:133], v[80:83]
	v_mfma_f32_16x16x32_bf16 v[8:11], v[124:127], v[162:165], v[0:3]
	v_mfma_f32_16x16x32_bf16 v[0:3], v[190:193], v[130:133], v[84:87]
	v_mfma_f32_16x16x32_bf16 v[12:15], v[218:221], v[162:165], v[0:3]
	v_mfma_f32_16x16x32_bf16 v[0:3], v[120:123], v[134:137], v[88:91]
	v_mfma_f32_16x16x32_bf16 v[4:7], v[190:193], v[134:137], v[92:95]
	v_mfma_f32_16x16x32_bf16 v[0:3], v[124:127], v[158:161], v[0:3]
	v_mfma_f32_16x16x32_bf16 v[4:7], v[218:221], v[158:161], v[4:7]
	v_mfma_f32_16x16x32_bf16 v[48:51], v[222:225], v[24:27], v[96:99]
	v_mfma_f32_16x16x32_bf16 v[24:27], v[246:249], v[24:27], v[194:197]
	v_mfma_f32_16x16x32_bf16 v[60:63], v[250:253], v[28:31], v[24:27]
	v_mfma_f32_16x16x32_bf16 v[24:27], v[222:225], v[52:55], v[198:201]
	v_mfma_f32_16x16x32_bf16 v[56:59], v[242:245], v[28:31], v[48:51]
	v_mfma_f32_16x16x32_bf16 v[48:51], v[242:245], v[100:103], v[24:27]
	v_mfma_f32_16x16x32_bf16 v[24:27], v[246:249], v[52:55], v[40:43]
	v_mfma_f32_16x16x32_bf16 v[52:55], v[250:253], v[100:103], v[24:27]
	v_mfma_f32_16x16x32_bf16 v[24:27], v[222:225], v[130:133], v[44:47]
	v_mfma_f32_16x16x32_bf16 v[40:43], v[242:245], v[162:165], v[24:27]
	v_mfma_f32_16x16x32_bf16 v[24:27], v[246:249], v[130:133], v[202:205]
	v_mfma_f32_16x16x32_bf16 v[44:47], v[250:253], v[162:165], v[24:27]
	v_mfma_f32_16x16x32_bf16 v[24:27], v[222:225], v[134:137], v[206:209]
	v_mfma_f32_16x16x32_bf16 v[28:31], v[246:249], v[134:137], v[210:213]
	v_mfma_f32_16x16x32_bf16 v[24:27], v[242:245], v[158:161], v[24:27]
	v_mfma_f32_16x16x32_bf16 v[28:31], v[250:253], v[158:161], v[28:31]
	s_barrier
	s_add_u32 s22, s40, 0x80
	s_addc_u32 s23, s41, 0
	ds_read_b128 v[88:91], v142 offset:49152
	ds_read_b128 v[92:95], v142 offset:50176
	ds_read_b128 v[130:133], v142 offset:51200
	ds_read_b128 v[134:137], v142 offset:52224
	ds_read_b128 v[158:161], v142 offset:53248
	ds_read_b128 v[162:165], v142 offset:54272
	ds_read_b128 v[194:197], v142 offset:55296
	ds_read_b128 v[198:201], v142 offset:56320
	s_mov_b32 m0, s51
	s_nop 0
	global_load_lds_dwordx4 v138, s[22:23]
	s_add_u32 s22, s40, 0x8080
	s_mov_b32 m0, s61
	s_addc_u32 s23, s41, 0
	global_load_lds_dwordx4 v138, s[22:23]
	s_add_u32 s22, s40, 0x10080
	s_mov_b32 m0, s64
	s_addc_u32 s23, s41, 0
	global_load_lds_dwordx4 v138, s[22:23]
	s_add_u32 s22, s40, 0x18080
	s_mov_b32 m0, s65
	s_addc_u32 s23, s41, 0
	global_load_lds_dwordx4 v138, s[22:23]
	s_mov_b32 m0, s62
	s_nop 0
	global_load_lds_dwordx4 v128, s[16:17]
	s_add_u32 s16, s38, 0x8080
	s_mov_b32 m0, s63
	s_addc_u32 s17, s39, 0
	global_load_lds_dwordx4 v128, s[16:17]
	s_waitcnt vmcnt(8) lgkmcnt(0)
	s_barrier
	v_mfma_f32_16x16x32_bf16 v[64:67], v[120:123], v[88:91], v[144:147]
	v_mfma_f32_16x16x32_bf16 v[96:99], v[124:127], v[92:95], v[64:67]
	v_mfma_f32_16x16x32_bf16 v[64:67], v[190:193], v[88:91], v[148:151]
	v_mfma_f32_16x16x32_bf16 v[100:103], v[218:221], v[92:95], v[64:67]
	v_mfma_f32_16x16x32_bf16 v[64:67], v[120:123], v[130:133], v[152:155]
	v_mfma_f32_16x16x32_bf16 v[80:83], v[124:127], v[134:137], v[64:67]
	v_mfma_f32_16x16x32_bf16 v[64:67], v[190:193], v[130:133], v[172:175]
	v_mfma_f32_16x16x32_bf16 v[84:87], v[218:221], v[134:137], v[64:67]
	v_mfma_f32_16x16x32_bf16 v[64:67], v[120:123], v[158:161], v[178:181]
	v_mfma_f32_16x16x32_bf16 v[72:75], v[124:127], v[162:165], v[64:67]
	v_mfma_f32_16x16x32_bf16 v[64:67], v[190:193], v[158:161], v[182:185]
	v_mfma_f32_16x16x32_bf16 v[76:79], v[218:221], v[162:165], v[64:67]
	v_mfma_f32_16x16x32_bf16 v[64:67], v[120:123], v[194:197], v[104:107]
	v_mfma_f32_16x16x32_bf16 v[68:71], v[190:193], v[194:197], v[108:111]
	v_mfma_f32_16x16x32_bf16 v[64:67], v[124:127], v[198:201], v[64:67]
	v_mfma_f32_16x16x32_bf16 v[68:71], v[218:221], v[198:201], v[68:71]
	v_mfma_f32_16x16x32_bf16 v[104:107], v[222:225], v[88:91], v[112:115]
	v_mfma_f32_16x16x32_bf16 v[88:91], v[246:249], v[88:91], v[116:119]
	v_mfma_f32_16x16x32_bf16 v[124:127], v[250:253], v[92:95], v[88:91]
	v_mfma_f32_16x16x32_bf16 v[88:91], v[222:225], v[130:133], v[226:229]
	v_mfma_f32_16x16x32_bf16 v[112:115], v[242:245], v[134:137], v[88:91]
	v_mfma_f32_16x16x32_bf16 v[88:91], v[246:249], v[130:133], v[230:233]
	v_mfma_f32_16x16x32_bf16 v[116:119], v[250:253], v[134:137], v[88:91]
	v_mfma_f32_16x16x32_bf16 v[88:91], v[222:225], v[158:161], v[234:237]
	v_mfma_f32_16x16x32_bf16 v[120:123], v[242:245], v[92:95], v[104:107]
	v_mfma_f32_16x16x32_bf16 v[104:107], v[242:245], v[162:165], v[88:91]
	v_mfma_f32_16x16x32_bf16 v[88:91], v[246:249], v[158:161], v[214:217]
	v_mfma_f32_16x16x32_bf16 v[108:111], v[250:253], v[162:165], v[88:91]
	v_mfma_f32_16x16x32_bf16 v[88:91], v[222:225], v[194:197], v[238:241]
	v_mfma_f32_16x16x32_bf16 v[92:95], v[246:249], v[194:197], v[186:189]
	v_mfma_f32_16x16x32_bf16 v[88:91], v[242:245], v[198:201], v[88:91]
	v_mfma_f32_16x16x32_bf16 v[92:95], v[250:253], v[198:201], v[92:95]
	s_barrier
	s_andn2_b64 vcc, exec, s[8:9]
	s_cbranch_vccnz .LBB0_681
	s_barrier

; #define PG8_STAGE(bufoff, gbase, voff, p64) do { _Pragma("unroll") for (int _i = 0; _i < 2; ++_i) { \
;         const char* _gb = (const char*)(gbase) + (size_t)_i * (p64); const unsigned _la = ldsbase + (unsigned)(bufoff) + (unsigned)_i * 8192u; \
;         asm volatile("s_mov_b32 m0, %0\n\ts_nop 0\n\tglobal_load_lds_dwordx4 %1, %2" :: "s"(_la), "v"(voff), "s"(_gb) : "memory"); } } while (0)
; #define PG8_LDA(dst, b, h) do { _Pragma("unroll") for (int m = 0; m < 4; ++m) _Pragma("unroll") for (int k = 0; k < 2; ++k) dst[m][k] = *(const LAS bf16x8*)(lds + PG8_SA(b, h) + aoff + m * 2048 + k * 1024); } while (0)
; #define PG8_LDB(dst, b, h) do { _Pragma("unroll") for (int n = 0; n < 2; ++n) _Pragma("unroll") for (int k = 0; k < 2; ++k) dst[n][k] = *(const LAS bf16x8*)(lds + PG8_SB(b, h) + boff + n * 2048 + k * 1024); } while (0)
; #define PG8_MMA(ai, bj, At, Bt) do { __builtin_amdgcn_s_setprio(1); _Pragma("unroll") for (int m = 0; m < 4; ++m) _Pragma("unroll") for (int n = 0; n < 2; ++n) _Pragma("unroll") for (int k = 0; k < 2; ++k) \
;         acc[ai][bj][m][n] = __builtin_amdgcn_mfma_f32_16x16x32_bf16(Bt[n][k], At[m][k], acc[ai][bj][m][n], 0, 0, 0); __builtin_amdgcn_s_setprio(0); } while (0)
; #define PG8_WAIT_V(n) asm volatile("s_waitcnt vmcnt(" #n ")" ::: "memory")
; #define PG8_BAR __builtin_amdgcn_s_barrier()
; template <class Epi, class Sched>
; __device__ __forceinline__ void gemm_phase(LAS unsigned char* lds, const Sched& S, const Epi& E) {
;     ...
;             const bool last = (t == nt - 2);
;             const char* a1 = cA + (size_t)(t + 1) * kstep;
;             const char* a2 = last ? nA : cA + (size_t)(t + 2) * kstep; const char* b2 = last ? nB : cB + (size_t)(t + 2) * kstep;
;             const char* a3 = a2 + kstep; const char* b3 = b2 + kstep;
;             const unsigned vA2 = voffA, vB2 = voffB, hA2 = hA, hB2 = hB;
;             PG8_LDB(B0, 0, 0); PG8_LDB(B1, 0, 1); PG8_SCHED; PG8_LDA(At, 0, 0); PG8_STAGE(PG8_SA(1, 1), a1 + hA, voffA, hA / 2);
;             PG8_WAIT_V(8); PG8_WAIT_L(0); PG8_BAR; PG8_MMA(0, 0, At, B0); PG8_MMA(0, 1, At, B1); PG8_BAR; PG8_SCHED;
;             PG8_LDA(At, 0, 1); PG8_STAGE(PG8_SB(0, 0), b2, vB2, hB2 / 2); PG8_STAGE(PG8_SB(0, 1), b2 + hB2, vB2, hB2 / 2); PG8_STAGE(PG8_SA(0, 0), a2, vA2, hA2 / 2);
;             PG8_WAIT_V(8); PG8_WAIT_L(0); PG8_BAR; PG8_MMA(1, 0, At, B0); PG8_MMA(1, 1, At, B1); PG8_BAR; PG8_SCHED;
.LBB0_756:
	s_add_u32 s56, s22, 0x40080
	s_addc_u32 s57, s23, 0
	s_add_u32 s69, s16, 0x100
	s_addc_u32 s72, s17, 0
	s_mov_b32 s73, -2
	v_add_u32_e32 v128, 0x10000, v146
	ds_read_b128 v[130:133], v128
	ds_read_b128 v[134:137], v128 offset:1024
	ds_read_b128 v[138:141], v128 offset:2048
	ds_read_b128 v[148:151], v128 offset:3072
	v_add_u32_e32 v128, 0x14000, v146
	ds_read_b128 v[152:155], v128
	ds_read_b128 v[158:161], v128 offset:1024
	ds_read_b128 v[162:165], v128 offset:2048
	ds_read_b128 v[172:175], v128 offset:3072
	s_add_u32 s16, s56, 0xfffc0080
	s_addc_u32 s17, s57, -1
	s_cmp_eq_u32 s73, 12
	s_cselect_b32 s16, s40, s16
	s_cselect_b32 s17, s41, s17
	s_cselect_b32 s58, s54, s69
	s_cselect_b32 s59, s55, s72
	s_add_u32 s22, s16, 0x80
	s_addc_u32 s23, s17, 0
	ds_read_b128 v[178:181], v147
	ds_read_b128 v[182:185], v147 offset:1024
	ds_read_b128 v[186:189], v147 offset:2048
	ds_read_b128 v[190:193], v147 offset:3072
	ds_read_b128 v[194:197], v147 offset:4096
	ds_read_b128 v[198:201], v147 offset:5120
	ds_read_b128 v[202:205], v147 offset:6144
	ds_read_b128 v[206:209], v147 offset:7168
	s_mov_b32 m0, s62
	s_nop 0
	global_load_lds_dwordx4 v142, s[56:57]
	s_add_u32 s74, s56, 0x20000
	s_mov_b32 m0, s63
	s_addc_u32 s75, s57, 0
	global_load_lds_dwordx4 v142, s[74:75]
	s_waitcnt vmcnt(8) lgkmcnt(0)
	s_barrier
	v_mfma_f32_16x16x32_bf16 v[124:127], v[130:133], v[178:181], 0
	v_mfma_f32_16x16x32_bf16 v[116:119], v[138:141], v[178:181], 0
	v_mfma_f32_16x16x32_bf16 v[108:111], v[130:133], v[186:189], 0
	v_mfma_f32_16x16x32_bf16 v[100:103], v[138:141], v[186:189], 0
	v_mfma_f32_16x16x32_bf16 v[92:95], v[130:133], v[194:197], 0
	v_mfma_f32_16x16x32_bf16 v[84:87], v[138:141], v[194:197], 0
	v_mfma_f32_16x16x32_bf16 v[76:79], v[130:133], v[202:205], 0
	v_mfma_f32_16x16x32_bf16 v[68:71], v[138:141], v[202:205], 0
	v_mfma_f32_16x16x32_bf16 v[124:127], v[134:137], v[182:185], v[124:127]
	v_mfma_f32_16x16x32_bf16 v[116:119], v[148:151], v[182:185], v[116:119]
	v_mfma_f32_16x16x32_bf16 v[108:111], v[134:137], v[190:193], v[108:111]
	v_mfma_f32_16x16x32_bf16 v[100:103], v[148:151], v[190:193], v[100:103]
	v_mfma_f32_16x16x32_bf16 v[92:95], v[134:137], v[198:201], v[92:95]
	v_mfma_f32_16x16x32_bf16 v[84:87], v[148:151], v[198:201], v[84:87]
	v_mfma_f32_16x16x32_bf16 v[76:79], v[134:137], v[206:209], v[76:79]
	v_mfma_f32_16x16x32_bf16 v[68:71], v[148:151], v[206:209], v[68:71]
	v_mfma_f32_16x16x32_bf16 v[120:123], v[152:155], v[178:181], 0
	v_mfma_f32_16x16x32_bf16 v[112:115], v[162:165], v[178:181], 0
	v_mfma_f32_16x16x32_bf16 v[104:107], v[152:155], v[186:189], 0
	v_mfma_f32_16x16x32_bf16 v[96:99], v[162:165], v[186:189], 0
	v_mfma_f32_16x16x32_bf16 v[88:91], v[152:155], v[194:197], 0
	v_mfma_f32_16x16x32_bf16 v[80:83], v[162:165], v[194:197], 0
	v_mfma_f32_16x16x32_bf16 v[72:75], v[152:155], v[202:205], 0
	v_mfma_f32_16x16x32_bf16 v[64:67], v[162:165], v[202:205], 0
	v_mfma_f32_16x16x32_bf16 v[120:123], v[158:161], v[182:185], v[120:123]
	v_mfma_f32_16x16x32_bf16 v[112:115], v[172:175], v[182:185], v[112:115]
	v_mfma_f32_16x16x32_bf16 v[104:107], v[158:161], v[190:193], v[104:107]
	v_mfma_f32_16x16x32_bf16 v[96:99], v[172:175], v[190:193], v[96:99]
	v_mfma_f32_16x16x32_bf16 v[88:91], v[158:161], v[198:201], v[88:91]
	v_mfma_f32_16x16x32_bf16 v[80:83], v[172:175], v[198:201], v[80:83]
	v_mfma_f32_16x16x32_bf16 v[72:75], v[158:161], v[206:209], v[72:75]
	v_mfma_f32_16x16x32_bf16 v[64:67], v[172:175], v[206:209], v[64:67]
	s_add_i32 s73, s73, 2
	s_add_u32 s56, s56, 0x100
	s_addc_u32 s57, s57, 0
	s_add_u32 s69, s69, 0x100
	s_addc_u32 s72, s72, 0
	s_barrier
	s_add_u32 s74, s58, 0x20000
	ds_read_b128 v[178:181], v147 offset:16384
	ds_read_b128 v[182:185], v147 offset:17408
	ds_read_b128 v[186:189], v147 offset:18432
	ds_read_b128 v[190:193], v147 offset:19456
	ds_read_b128 v[194:197], v147 offset:20480
	ds_read_b128 v[198:201], v147 offset:21504
	ds_read_b128 v[202:205], v147 offset:22528
	ds_read_b128 v[206:209], v147 offset:23552
	s_mov_b32 m0, s20
	s_nop 0
	global_load_lds_dwordx4 v143, s[58:59]
	s_mov_b32 m0, s24
	s_addc_u32 s75, s59, 0
	global_load_lds_dwordx4 v143, s[74:75]
	s_add_u32 s74, s58, 0x40000
	s_mov_b32 m0, s33
	s_addc_u32 s75, s59, 0
	global_load_lds_dwordx4 v143, s[74:75]
	s_add_u32 s74, s58, 0x60000
	s_mov_b32 m0, s34
	s_addc_u32 s75, s59, 0
	global_load_lds_dwordx4 v143, s[74:75]
	s_mov_b32 m0, s15
	s_nop 0
	global_load_lds_dwordx4 v142, s[16:17]
	s_add_u32 s74, s16, 0x20000
	s_mov_b32 m0, s35
	s_addc_u32 s75, s17, 0
	global_load_lds_dwordx4 v142, s[74:75]
	s_waitcnt vmcnt(8) lgkmcnt(0)
	s_barrier
	v_mfma_f32_16x16x32_bf16 v[60:63], v[130:133], v[178:181], 0
	v_mfma_f32_16x16x32_bf16 v[52:55], v[138:141], v[178:181], 0
	v_mfma_f32_16x16x32_bf16 v[44:47], v[130:133], v[186:189], 0
	v_mfma_f32_16x16x32_bf16 v[36:39], v[138:141], v[186:189], 0
	v_mfma_f32_16x16x32_bf16 v[28:31], v[130:133], v[194:197], 0
	v_mfma_f32_16x16x32_bf16 v[20:23], v[138:141], v[194:197], 0
	v_mfma_f32_16x16x32_bf16 v[12:15], v[130:133], v[202:205], 0
	v_mfma_f32_16x16x32_bf16 v[4:7], v[138:141], v[202:205], 0
	v_mfma_f32_16x16x32_bf16 v[60:63], v[134:137], v[182:185], v[60:63]
	v_mfma_f32_16x16x32_bf16 v[52:55], v[148:151], v[182:185], v[52:55]
	v_mfma_f32_16x16x32_bf16 v[44:47], v[134:137], v[190:193], v[44:47]
	v_mfma_f32_16x16x32_bf16 v[36:39], v[148:151], v[190:193], v[36:39]
	v_mfma_f32_16x16x32_bf16 v[28:31], v[134:137], v[198:201], v[28:31]
	v_mfma_f32_16x16x32_bf16 v[20:23], v[148:151], v[198:201], v[20:23]
	v_mfma_f32_16x16x32_bf16 v[12:15], v[134:137], v[206:209], v[12:15]
	v_mfma_f32_16x16x32_bf16 v[4:7], v[148:151], v[206:209], v[4:7]
	v_mfma_f32_16x16x32_bf16 v[56:59], v[152:155], v[178:181], 0
	v_mfma_f32_16x16x32_bf16 v[48:51], v[162:165], v[178:181], 0
	v_mfma_f32_16x16x32_bf16 v[40:43], v[152:155], v[186:189], 0
	v_mfma_f32_16x16x32_bf16 v[32:35], v[162:165], v[186:189], 0
	v_mfma_f32_16x16x32_bf16 v[24:27], v[152:155], v[194:197], 0
	v_mfma_f32_16x16x32_bf16 v[16:19], v[162:165], v[194:197], 0
	v_mfma_f32_16x16x32_bf16 v[8:11], v[152:155], v[202:205], 0
	v_mfma_f32_16x16x32_bf16 v[0:3], v[162:165], v[202:205], 0
	v_mfma_f32_16x16x32_bf16 v[56:59], v[158:161], v[182:185], v[56:59]
	v_mfma_f32_16x16x32_bf16 v[48:51], v[172:175], v[182:185], v[48:51]
	v_mfma_f32_16x16x32_bf16 v[40:43], v[158:161], v[190:193], v[40:43]
	v_mfma_f32_16x16x32_bf16 v[32:35], v[172:175], v[190:193], v[32:35]
	v_mfma_f32_16x16x32_bf16 v[24:27], v[158:161], v[198:201], v[24:27]
	v_mfma_f32_16x16x32_bf16 v[16:19], v[172:175], v[198:201], v[16:19]
	v_mfma_f32_16x16x32_bf16 v[8:11], v[158:161], v[206:209], v[8:11]
	v_mfma_f32_16x16x32_bf16 v[0:3], v[172:175], v[206:209], v[0:3]
	s_barrier
	s_branch .Lpeel_mid_20519
; #define PG8_STAGE(bufoff, gbase, voff, p64) do { _Pragma("unroll") for (int _i = 0; _i < 2; ++_i) { \
;         const char* _gb = (const char*)(gbase) + (size_t)_i * (p64); const unsigned _la = ldsbase + (unsigned)(bufoff) + (unsigned)_i * 8192u; \
;         asm volatile("s_mov_b32 m0, %0\n\ts_nop 0\n\tglobal_load_lds_dwordx4 %1, %2" :: "s"(_la), "v"(voff), "s"(_gb) : "memory"); } } while (0)
; #define PG8_LDA(dst, b, h) do { _Pragma("unroll") for (int m = 0; m < 4; ++m) _Pragma("unroll") for (int k = 0; k < 2; ++k) dst[m][k] = *(const LAS bf16x8*)(lds + PG8_SA(b, h) + aoff + m * 2048 + k * 1024); } while (0)
; #define PG8_LDB(dst, b, h) do { _Pragma("unroll") for (int n = 0; n < 2; ++n) _Pragma("unroll") for (int k = 0; k < 2; ++k) dst[n][k] = *(const LAS bf16x8*)(lds + PG8_SB(b, h) + boff + n * 2048 + k * 1024); } while (0)
; #define PG8_MMA(ai, bj, At, Bt) do { __builtin_amdgcn_s_setprio(1); _Pragma("unroll") for (int m = 0; m < 4; ++m) _Pragma("unroll") for (int n = 0; n < 2; ++n) _Pragma("unroll") for (int k = 0; k < 2; ++k) \
;         acc[ai][bj][m][n] = __builtin_amdgcn_mfma_f32_16x16x32_bf16(Bt[n][k], At[m][k], acc[ai][bj][m][n], 0, 0, 0); __builtin_amdgcn_s_setprio(0); } while (0)
; #define PG8_WAIT_V(n) asm volatile("s_waitcnt vmcnt(" #n ")" ::: "memory")
; #define PG8_WAIT_L(n) asm volatile("s_waitcnt lgkmcnt(" #n ")" ::: "memory")
; #define PG8_BAR __builtin_amdgcn_s_barrier()
; #define PG8_SCHED __builtin_amdgcn_sched_barrier(0)
; template <class Epi, class Sched>
; __device__ __forceinline__ void gemm_phase(LAS unsigned char* lds, const Sched& S, const Epi& E) {
;     ...
;             PG8_LDB(B0, 0, 0); PG8_LDB(B1, 0, 1); PG8_SCHED; PG8_LDA(At, 0, 0); PG8_STAGE(PG8_SA(1, 1), a1 + hA, voffA, hA / 2);
;             PG8_WAIT_V(8); PG8_WAIT_L(0); PG8_BAR; PG8_MMA(0, 0, At, B0); PG8_MMA(0, 1, At, B1); PG8_BAR; PG8_SCHED;
;             PG8_LDA(At, 0, 1); PG8_STAGE(PG8_SB(0, 0), b2, vB2, hB2 / 2); PG8_STAGE(PG8_SB(0, 1), b2 + hB2, vB2, hB2 / 2); PG8_STAGE(PG8_SA(0, 0), a2, vA2, hA2 / 2);
;             PG8_WAIT_V(8); PG8_WAIT_L(0); PG8_BAR; PG8_MMA(1, 0, At, B0); PG8_MMA(1, 1, At, B1); PG8_BAR; PG8_SCHED;
.LBB0_757:
	v_add_u32_e32 v128, 0x10000, v146
	ds_read_b128 v[130:133], v128
	ds_read_b128 v[134:137], v128 offset:1024
	ds_read_b128 v[138:141], v128 offset:2048
	ds_read_b128 v[148:151], v128 offset:3072
	v_add_u32_e32 v128, 0x14000, v146
	ds_read_b128 v[152:155], v128
	ds_read_b128 v[158:161], v128 offset:1024
	ds_read_b128 v[162:165], v128 offset:2048
	ds_read_b128 v[172:175], v128 offset:3072
	s_add_u32 s16, s56, 0xfffc0080
	s_addc_u32 s17, s57, -1
	s_cmp_eq_u32 s73, 12
	s_cselect_b32 s16, s40, s16
	s_cselect_b32 s17, s41, s17
	s_cselect_b32 s58, s54, s69
	s_cselect_b32 s59, s55, s72
	s_add_u32 s22, s16, 0x80
	s_addc_u32 s23, s17, 0
	ds_read_b128 v[178:181], v147
	ds_read_b128 v[182:185], v147 offset:1024
	ds_read_b128 v[186:189], v147 offset:2048
	ds_read_b128 v[190:193], v147 offset:3072
	ds_read_b128 v[194:197], v147 offset:4096
	ds_read_b128 v[198:201], v147 offset:5120
	ds_read_b128 v[202:205], v147 offset:6144
	ds_read_b128 v[206:209], v147 offset:7168
	s_mov_b32 m0, s62
	s_nop 0
	global_load_lds_dwordx4 v142, s[56:57]
	s_add_u32 s74, s56, 0x20000
	s_mov_b32 m0, s63
	s_addc_u32 s75, s57, 0
	global_load_lds_dwordx4 v142, s[74:75]
	s_waitcnt vmcnt(8) lgkmcnt(0)
	s_barrier
	v_mfma_f32_16x16x32_bf16 v[124:127], v[130:133], v[178:181], v[124:127]
	v_mfma_f32_16x16x32_bf16 v[116:119], v[138:141], v[178:181], v[116:119]
	v_mfma_f32_16x16x32_bf16 v[108:111], v[130:133], v[186:189], v[108:111]
	v_mfma_f32_16x16x32_bf16 v[100:103], v[138:141], v[186:189], v[100:103]
	v_mfma_f32_16x16x32_bf16 v[92:95], v[130:133], v[194:197], v[92:95]
	v_mfma_f32_16x16x32_bf16 v[84:87], v[138:141], v[194:197], v[84:87]
	v_mfma_f32_16x16x32_bf16 v[76:79], v[130:133], v[202:205], v[76:79]
	v_mfma_f32_16x16x32_bf16 v[68:71], v[138:141], v[202:205], v[68:71]
	v_mfma_f32_16x16x32_bf16 v[124:127], v[134:137], v[182:185], v[124:127]
	v_mfma_f32_16x16x32_bf16 v[116:119], v[148:151], v[182:185], v[116:119]
	v_mfma_f32_16x16x32_bf16 v[108:111], v[134:137], v[190:193], v[108:111]
	v_mfma_f32_16x16x32_bf16 v[100:103], v[148:151], v[190:193], v[100:103]
	v_mfma_f32_16x16x32_bf16 v[92:95], v[134:137], v[198:201], v[92:95]
	v_mfma_f32_16x16x32_bf16 v[84:87], v[148:151], v[198:201], v[84:87]
	v_mfma_f32_16x16x32_bf16 v[76:79], v[134:137], v[206:209], v[76:79]
	v_mfma_f32_16x16x32_bf16 v[68:71], v[148:151], v[206:209], v[68:71]
	v_mfma_f32_16x16x32_bf16 v[120:123], v[152:155], v[178:181], v[120:123]
	v_mfma_f32_16x16x32_bf16 v[112:115], v[162:165], v[178:181], v[112:115]
	v_mfma_f32_16x16x32_bf16 v[104:107], v[152:155], v[186:189], v[104:107]
	v_mfma_f32_16x16x32_bf16 v[96:99], v[162:165], v[186:189], v[96:99]
	v_mfma_f32_16x16x32_bf16 v[88:91], v[152:155], v[194:197], v[88:91]
	v_mfma_f32_16x16x32_bf16 v[80:83], v[162:165], v[194:197], v[80:83]
	v_mfma_f32_16x16x32_bf16 v[72:75], v[152:155], v[202:205], v[72:75]
	v_mfma_f32_16x16x32_bf16 v[64:67], v[162:165], v[202:205], v[64:67]
	v_mfma_f32_16x16x32_bf16 v[120:123], v[158:161], v[182:185], v[120:123]
	v_mfma_f32_16x16x32_bf16 v[112:115], v[172:175], v[182:185], v[112:115]
	v_mfma_f32_16x16x32_bf16 v[104:107], v[158:161], v[190:193], v[104:107]
	v_mfma_f32_16x16x32_bf16 v[96:99], v[172:175], v[190:193], v[96:99]
	v_mfma_f32_16x16x32_bf16 v[88:91], v[158:161], v[198:201], v[88:91]
	v_mfma_f32_16x16x32_bf16 v[80:83], v[172:175], v[198:201], v[80:83]
	v_mfma_f32_16x16x32_bf16 v[72:75], v[158:161], v[206:209], v[72:75]
	v_mfma_f32_16x16x32_bf16 v[64:67], v[172:175], v[206:209], v[64:67]
	s_add_i32 s73, s73, 2
	s_add_u32 s56, s56, 0x100
	s_addc_u32 s57, s57, 0
	s_add_u32 s69, s69, 0x100
	s_addc_u32 s72, s72, 0
	s_barrier
	s_add_u32 s74, s58, 0x20000
	ds_read_b128 v[178:181], v147 offset:16384
	ds_read_b128 v[182:185], v147 offset:17408
	ds_read_b128 v[186:189], v147 offset:18432
	ds_read_b128 v[190:193], v147 offset:19456
	ds_read_b128 v[194:197], v147 offset:20480
	ds_read_b128 v[198:201], v147 offset:21504
	ds_read_b128 v[202:205], v147 offset:22528
	ds_read_b128 v[206:209], v147 offset:23552
	s_mov_b32 m0, s20
	s_nop 0
	global_load_lds_dwordx4 v143, s[58:59]
	s_mov_b32 m0, s24
	s_addc_u32 s75, s59, 0
	global_load_lds_dwordx4 v143, s[74:75]
	s_add_u32 s74, s58, 0x40000
	s_mov_b32 m0, s33
	s_addc_u32 s75, s59, 0
	global_load_lds_dwordx4 v143, s[74:75]
	s_add_u32 s74, s58, 0x60000
	s_mov_b32 m0, s34
	s_addc_u32 s75, s59, 0
	global_load_lds_dwordx4 v143, s[74:75]
	s_mov_b32 m0, s15
	s_nop 0
	global_load_lds_dwordx4 v142, s[16:17]
	s_add_u32 s74, s16, 0x20000
	s_mov_b32 m0, s35
	s_addc_u32 s75, s17, 0
	global_load_lds_dwordx4 v142, s[74:75]
	s_waitcnt vmcnt(8) lgkmcnt(0)
	s_barrier
	v_mfma_f32_16x16x32_bf16 v[60:63], v[130:133], v[178:181], v[60:63]
	v_mfma_f32_16x16x32_bf16 v[52:55], v[138:141], v[178:181], v[52:55]
	v_mfma_f32_16x16x32_bf16 v[44:47], v[130:133], v[186:189], v[44:47]
	v_mfma_f32_16x16x32_bf16 v[36:39], v[138:141], v[186:189], v[36:39]
	v_mfma_f32_16x16x32_bf16 v[28:31], v[130:133], v[194:197], v[28:31]
	v_mfma_f32_16x16x32_bf16 v[20:23], v[138:141], v[194:197], v[20:23]
	v_mfma_f32_16x16x32_bf16 v[12:15], v[130:133], v[202:205], v[12:15]
	v_mfma_f32_16x16x32_bf16 v[4:7], v[138:141], v[202:205], v[4:7]
	v_mfma_f32_16x16x32_bf16 v[60:63], v[134:137], v[182:185], v[60:63]
	v_mfma_f32_16x16x32_bf16 v[52:55], v[148:151], v[182:185], v[52:55]
	v_mfma_f32_16x16x32_bf16 v[44:47], v[134:137], v[190:193], v[44:47]
	v_mfma_f32_16x16x32_bf16 v[36:39], v[148:151], v[190:193], v[36:39]
	v_mfma_f32_16x16x32_bf16 v[28:31], v[134:137], v[198:201], v[28:31]
	v_mfma_f32_16x16x32_bf16 v[20:23], v[148:151], v[198:201], v[20:23]
	v_mfma_f32_16x16x32_bf16 v[12:15], v[134:137], v[206:209], v[12:15]
	v_mfma_f32_16x16x32_bf16 v[4:7], v[148:151], v[206:209], v[4:7]
	v_mfma_f32_16x16x32_bf16 v[56:59], v[152:155], v[178:181], v[56:59]
	v_mfma_f32_16x16x32_bf16 v[48:51], v[162:165], v[178:181], v[48:51]
	v_mfma_f32_16x16x32_bf16 v[40:43], v[152:155], v[186:189], v[40:43]
	v_mfma_f32_16x16x32_bf16 v[32:35], v[162:165], v[186:189], v[32:35]
	v_mfma_f32_16x16x32_bf16 v[24:27], v[152:155], v[194:197], v[24:27]
	v_mfma_f32_16x16x32_bf16 v[16:19], v[162:165], v[194:197], v[16:19]
	v_mfma_f32_16x16x32_bf16 v[8:11], v[152:155], v[202:205], v[8:11]
	v_mfma_f32_16x16x32_bf16 v[0:3], v[162:165], v[202:205], v[0:3]
	v_mfma_f32_16x16x32_bf16 v[56:59], v[158:161], v[182:185], v[56:59]
	v_mfma_f32_16x16x32_bf16 v[48:51], v[172:175], v[182:185], v[48:51]
	v_mfma_f32_16x16x32_bf16 v[40:43], v[158:161], v[190:193], v[40:43]
	v_mfma_f32_16x16x32_bf16 v[32:35], v[172:175], v[190:193], v[32:35]
	v_mfma_f32_16x16x32_bf16 v[24:27], v[158:161], v[198:201], v[24:27]
	v_mfma_f32_16x16x32_bf16 v[16:19], v[172:175], v[198:201], v[16:19]
	v_mfma_f32_16x16x32_bf16 v[8:11], v[158:161], v[206:209], v[8:11]
	v_mfma_f32_16x16x32_bf16 v[0:3], v[172:175], v[206:209], v[0:3]
	s_barrier
; #define PG8_STAGE(bufoff, gbase, voff, p64) do { _Pragma("unroll") for (int _i = 0; _i < 2; ++_i) { \
;         const char* _gb = (const char*)(gbase) + (size_t)_i * (p64); const unsigned _la = ldsbase + (unsigned)(bufoff) + (unsigned)_i * 8192u; \
;         asm volatile("s_mov_b32 m0, %0\n\ts_nop 0\n\tglobal_load_lds_dwordx4 %1, %2" :: "s"(_la), "v"(voff), "s"(_gb) : "memory"); } } while (0)
; #define PG8_LDA(dst, b, h) do { _Pragma("unroll") for (int m = 0; m < 4; ++m) _Pragma("unroll") for (int k = 0; k < 2; ++k) dst[m][k] = *(const LAS bf16x8*)(lds + PG8_SA(b, h) + aoff + m * 2048 + k * 1024); } while (0)
; #define PG8_LDB(dst, b, h) do { _Pragma("unroll") for (int n = 0; n < 2; ++n) _Pragma("unroll") for (int k = 0; k < 2; ++k) dst[n][k] = *(const LAS bf16x8*)(lds + PG8_SB(b, h) + boff + n * 2048 + k * 1024); } while (0)
; #define PG8_MMA(ai, bj, At, Bt) do { __builtin_amdgcn_s_setprio(1); _Pragma("unroll") for (int m = 0; m < 4; ++m) _Pragma("unroll") for (int n = 0; n < 2; ++n) _Pragma("unroll") for (int k = 0; k < 2; ++k) \
;         acc[ai][bj][m][n] = __builtin_amdgcn_mfma_f32_16x16x32_bf16(Bt[n][k], At[m][k], acc[ai][bj][m][n], 0, 0, 0); __builtin_amdgcn_s_setprio(0); } while (0)
; #define PG8_WAIT_V(n) asm volatile("s_waitcnt vmcnt(" #n ")" ::: "memory")
; #define PG8_WAIT_L(n) asm volatile("s_waitcnt lgkmcnt(" #n ")" ::: "memory")
; #define PG8_BAR __builtin_amdgcn_s_barrier()
; #define PG8_SCHED __builtin_amdgcn_sched_barrier(0)
; template <class Epi, class Sched>
; __device__ __forceinline__ void gemm_phase(LAS unsigned char* lds, const Sched& S, const Epi& E) {
;     ...
;             PG8_LDB(B0, 1, 0); PG8_LDB(B1, 1, 1); PG8_SCHED; PG8_LDA(At, 1, 0); PG8_STAGE(PG8_SA(0, 1), a2 + hA2, vA2, hA2 / 2);
;             PG8_WAIT_V(8); PG8_WAIT_L(0); PG8_BAR; PG8_MMA(0, 0, At, B0); PG8_MMA(0, 1, At, B1); PG8_BAR; PG8_SCHED;
;             PG8_LDA(At, 1, 1); PG8_STAGE(PG8_SB(1, 0), b3, vB2, hB2 / 2); PG8_STAGE(PG8_SB(1, 1), b3 + hB2, vB2, hB2 / 2); PG8_STAGE(PG8_SA(1, 0), a3, vA2, hA2 / 2);
;             PG8_WAIT_V(8); PG8_WAIT_L(0); PG8_BAR; PG8_MMA(1, 0, At, B0); PG8_MMA(1, 1, At, B1); PG8_BAR; PG8_SCHED;
;         }
;         if (wr == 0) PG8_BAR;
.Lpeel_mid_20519:
	v_add_u32_e32 v128, 0x18000, v146
	ds_read_b128 v[130:133], v128
	ds_read_b128 v[134:137], v128 offset:1024
	ds_read_b128 v[138:141], v128 offset:2048
	ds_read_b128 v[148:151], v128 offset:3072
	v_add_u32_e32 v128, 0x1c000, v146
	ds_read_b128 v[152:155], v128
	ds_read_b128 v[158:161], v128 offset:1024
	ds_read_b128 v[162:165], v128 offset:2048
	ds_read_b128 v[172:175], v128 offset:3072
	ds_read_b128 v[178:181], v147 offset:32768
	ds_read_b128 v[182:185], v147 offset:33792
	ds_read_b128 v[186:189], v147 offset:34816
	ds_read_b128 v[190:193], v147 offset:35840
	ds_read_b128 v[194:197], v147 offset:36864
	ds_read_b128 v[198:201], v147 offset:37888
	ds_read_b128 v[202:205], v147 offset:38912
	ds_read_b128 v[206:209], v147 offset:39936
	s_add_u32 s74, s16, 0x40000
	s_mov_b32 m0, s36
	s_addc_u32 s75, s17, 0
	global_load_lds_dwordx4 v142, s[74:75]
	s_add_u32 s74, s16, 0x60000
	s_mov_b32 m0, s37
	s_addc_u32 s75, s17, 0
	global_load_lds_dwordx4 v142, s[74:75]
	s_waitcnt vmcnt(8) lgkmcnt(0)
	s_barrier
	v_mfma_f32_16x16x32_bf16 v[124:127], v[130:133], v[178:181], v[124:127]
	v_mfma_f32_16x16x32_bf16 v[116:119], v[138:141], v[178:181], v[116:119]
	v_mfma_f32_16x16x32_bf16 v[108:111], v[130:133], v[186:189], v[108:111]
	v_mfma_f32_16x16x32_bf16 v[100:103], v[138:141], v[186:189], v[100:103]
	v_mfma_f32_16x16x32_bf16 v[92:95], v[130:133], v[194:197], v[92:95]
	v_mfma_f32_16x16x32_bf16 v[84:87], v[138:141], v[194:197], v[84:87]
	v_mfma_f32_16x16x32_bf16 v[76:79], v[130:133], v[202:205], v[76:79]
	v_mfma_f32_16x16x32_bf16 v[68:71], v[138:141], v[202:205], v[68:71]
	v_mfma_f32_16x16x32_bf16 v[124:127], v[134:137], v[182:185], v[124:127]
	v_mfma_f32_16x16x32_bf16 v[116:119], v[148:151], v[182:185], v[116:119]
	v_mfma_f32_16x16x32_bf16 v[108:111], v[134:137], v[190:193], v[108:111]
	v_mfma_f32_16x16x32_bf16 v[100:103], v[148:151], v[190:193], v[100:103]
	v_mfma_f32_16x16x32_bf16 v[92:95], v[134:137], v[198:201], v[92:95]
	v_mfma_f32_16x16x32_bf16 v[84:87], v[148:151], v[198:201], v[84:87]
	v_mfma_f32_16x16x32_bf16 v[76:79], v[134:137], v[206:209], v[76:79]
	v_mfma_f32_16x16x32_bf16 v[68:71], v[148:151], v[206:209], v[68:71]
	v_mfma_f32_16x16x32_bf16 v[120:123], v[152:155], v[178:181], v[120:123]
	v_mfma_f32_16x16x32_bf16 v[112:115], v[162:165], v[178:181], v[112:115]
	v_mfma_f32_16x16x32_bf16 v[104:107], v[152:155], v[186:189], v[104:107]
	v_mfma_f32_16x16x32_bf16 v[96:99], v[162:165], v[186:189], v[96:99]
	v_mfma_f32_16x16x32_bf16 v[88:91], v[152:155], v[194:197], v[88:91]
	v_mfma_f32_16x16x32_bf16 v[80:83], v[162:165], v[194:197], v[80:83]
	v_mfma_f32_16x16x32_bf16 v[72:75], v[152:155], v[202:205], v[72:75]
	v_mfma_f32_16x16x32_bf16 v[64:67], v[162:165], v[202:205], v[64:67]
	v_mfma_f32_16x16x32_bf16 v[120:123], v[158:161], v[182:185], v[120:123]
	v_mfma_f32_16x16x32_bf16 v[112:115], v[172:175], v[182:185], v[112:115]
	v_mfma_f32_16x16x32_bf16 v[104:107], v[158:161], v[190:193], v[104:107]
	v_mfma_f32_16x16x32_bf16 v[96:99], v[172:175], v[190:193], v[96:99]
	v_mfma_f32_16x16x32_bf16 v[88:91], v[158:161], v[198:201], v[88:91]
	v_mfma_f32_16x16x32_bf16 v[80:83], v[172:175], v[198:201], v[80:83]
	v_mfma_f32_16x16x32_bf16 v[72:75], v[158:161], v[206:209], v[72:75]
	v_mfma_f32_16x16x32_bf16 v[64:67], v[172:175], v[206:209], v[64:67]
	s_barrier
	s_add_u32 s74, s58, 0x80
	s_addc_u32 s75, s59, 0
	ds_read_b128 v[178:181], v147 offset:49152
	ds_read_b128 v[182:185], v147 offset:50176
	ds_read_b128 v[186:189], v147 offset:51200
	ds_read_b128 v[190:193], v147 offset:52224
	ds_read_b128 v[194:197], v147 offset:53248
	ds_read_b128 v[198:201], v147 offset:54272
	ds_read_b128 v[202:205], v147 offset:55296
	ds_read_b128 v[206:209], v147 offset:56320
	s_mov_b32 m0, s45
	s_nop 0
	global_load_lds_dwordx4 v143, s[74:75]
	s_add_u32 s74, s58, 0x20080
	s_mov_b32 m0, s47
	s_addc_u32 s75, s59, 0
	global_load_lds_dwordx4 v143, s[74:75]
	s_add_u32 s74, s58, 0x40080
	s_mov_b32 m0, s51
	s_addc_u32 s75, s59, 0
	global_load_lds_dwordx4 v143, s[74:75]
	s_add_u32 s58, s58, 0x60080
	s_mov_b32 m0, s61
	s_addc_u32 s59, s59, 0
	global_load_lds_dwordx4 v143, s[58:59]
	s_mov_b32 m0, s48
	s_nop 0
	global_load_lds_dwordx4 v142, s[22:23]
	s_add_u32 s16, s16, 0x20080
	s_mov_b32 m0, s50
	s_addc_u32 s17, s17, 0
	global_load_lds_dwordx4 v142, s[16:17]
	s_waitcnt vmcnt(8) lgkmcnt(0)
	s_barrier
	v_mfma_f32_16x16x32_bf16 v[60:63], v[130:133], v[178:181], v[60:63]
	v_mfma_f32_16x16x32_bf16 v[52:55], v[138:141], v[178:181], v[52:55]
	v_mfma_f32_16x16x32_bf16 v[44:47], v[130:133], v[186:189], v[44:47]
	v_mfma_f32_16x16x32_bf16 v[36:39], v[138:141], v[186:189], v[36:39]
	v_mfma_f32_16x16x32_bf16 v[28:31], v[130:133], v[194:197], v[28:31]
	v_mfma_f32_16x16x32_bf16 v[20:23], v[138:141], v[194:197], v[20:23]
	v_mfma_f32_16x16x32_bf16 v[12:15], v[130:133], v[202:205], v[12:15]
	v_mfma_f32_16x16x32_bf16 v[4:7], v[138:141], v[202:205], v[4:7]
	v_mfma_f32_16x16x32_bf16 v[60:63], v[134:137], v[182:185], v[60:63]
	v_mfma_f32_16x16x32_bf16 v[52:55], v[148:151], v[182:185], v[52:55]
	v_mfma_f32_16x16x32_bf16 v[44:47], v[134:137], v[190:193], v[44:47]
	v_mfma_f32_16x16x32_bf16 v[36:39], v[148:151], v[190:193], v[36:39]
	v_mfma_f32_16x16x32_bf16 v[28:31], v[134:137], v[198:201], v[28:31]
	v_mfma_f32_16x16x32_bf16 v[20:23], v[148:151], v[198:201], v[20:23]
	v_mfma_f32_16x16x32_bf16 v[12:15], v[134:137], v[206:209], v[12:15]
	v_mfma_f32_16x16x32_bf16 v[4:7], v[148:151], v[206:209], v[4:7]
	v_mfma_f32_16x16x32_bf16 v[56:59], v[152:155], v[178:181], v[56:59]
	v_mfma_f32_16x16x32_bf16 v[48:51], v[162:165], v[178:181], v[48:51]
	v_mfma_f32_16x16x32_bf16 v[40:43], v[152:155], v[186:189], v[40:43]
	v_mfma_f32_16x16x32_bf16 v[32:35], v[162:165], v[186:189], v[32:35]
	v_mfma_f32_16x16x32_bf16 v[24:27], v[152:155], v[194:197], v[24:27]
	v_mfma_f32_16x16x32_bf16 v[16:19], v[162:165], v[194:197], v[16:19]
	v_mfma_f32_16x16x32_bf16 v[8:11], v[152:155], v[202:205], v[8:11]
	v_mfma_f32_16x16x32_bf16 v[0:3], v[162:165], v[202:205], v[0:3]
	v_mfma_f32_16x16x32_bf16 v[56:59], v[158:161], v[182:185], v[56:59]
	v_mfma_f32_16x16x32_bf16 v[48:51], v[172:175], v[182:185], v[48:51]
	v_mfma_f32_16x16x32_bf16 v[40:43], v[158:161], v[190:193], v[40:43]
	v_mfma_f32_16x16x32_bf16 v[32:35], v[172:175], v[190:193], v[32:35]
	v_mfma_f32_16x16x32_bf16 v[24:27], v[158:161], v[198:201], v[24:27]
	v_mfma_f32_16x16x32_bf16 v[16:19], v[172:175], v[198:201], v[16:19]
	v_mfma_f32_16x16x32_bf16 v[8:11], v[158:161], v[206:209], v[8:11]
	v_mfma_f32_16x16x32_bf16 v[0:3], v[172:175], v[206:209], v[0:3]
	s_barrier
	s_cmp_gt_u32 s73, 13
	s_cbranch_scc0 .LBB0_757
	s_and_b64 vcc, exec, s[38:39]
	s_cbranch_vccz .LBB0_760
	s_barrier

; #define PG8_STAGE(bufoff, gbase, voff, p64) do { _Pragma("unroll") for (int _i = 0; _i < 2; ++_i) { \
;         const char* _gb = (const char*)(gbase) + (size_t)_i * (p64); const unsigned _la = ldsbase + (unsigned)(bufoff) + (unsigned)_i * 8192u; \
;         asm volatile("s_mov_b32 m0, %0\n\ts_nop 0\n\tglobal_load_lds_dwordx4 %1, %2" :: "s"(_la), "v"(voff), "s"(_gb) : "memory"); } } while (0)
; #define PG8_LDA(dst, b, h) do { _Pragma("unroll") for (int m = 0; m < 4; ++m) _Pragma("unroll") for (int k = 0; k < 2; ++k) dst[m][k] = *(const LAS bf16x8*)(lds + PG8_SA(b, h) + aoff + m * 2048 + k * 1024); } while (0)
; #define PG8_LDB(dst, b, h) do { _Pragma("unroll") for (int n = 0; n < 2; ++n) _Pragma("unroll") for (int k = 0; k < 2; ++k) dst[n][k] = *(const LAS bf16x8*)(lds + PG8_SB(b, h) + boff + n * 2048 + k * 1024); } while (0)
; #define PG8_MMA(ai, bj, At, Bt) do { __builtin_amdgcn_s_setprio(1); _Pragma("unroll") for (int m = 0; m < 4; ++m) _Pragma("unroll") for (int n = 0; n < 2; ++n) _Pragma("unroll") for (int k = 0; k < 2; ++k) \
;         acc[ai][bj][m][n] = __builtin_amdgcn_mfma_f32_16x16x32_bf16(Bt[n][k], At[m][k], acc[ai][bj][m][n], 0, 0, 0); __builtin_amdgcn_s_setprio(0); } while (0)
; #define PG8_WAIT_V(n) asm volatile("s_waitcnt vmcnt(" #n ")" ::: "memory")
; #define PG8_WAIT_L(n) asm volatile("s_waitcnt lgkmcnt(" #n ")" ::: "memory")
; #define PG8_BAR __builtin_amdgcn_s_barrier()
; #define PG8_SCHED __builtin_amdgcn_sched_barrier(0)
; template <class Epi, class Sched>
; __device__ __forceinline__ void gemm_phase(LAS unsigned char* lds, const Sched& S, const Epi& E) {
;     ...
;             PG8_LDB(B0, 0, 0); PG8_LDB(B1, 0, 1); PG8_SCHED; PG8_LDA(At, 0, 0); PG8_STAGE(PG8_SA(1, 1), a1 + hA, voffA, hA / 2);
;             PG8_WAIT_V(8); PG8_WAIT_L(0); PG8_BAR; PG8_MMA(0, 0, At, B0); PG8_MMA(0, 1, At, B1); PG8_BAR; PG8_SCHED;
;             PG8_LDA(At, 0, 1); PG8_STAGE(PG8_SB(0, 0), b2, vB2, hB2 / 2); PG8_STAGE(PG8_SB(0, 1), b2 + hB2, vB2, hB2 / 2); PG8_STAGE(PG8_SA(0, 0), a2, vA2, hA2 / 2);
;             PG8_WAIT_V(8); PG8_WAIT_L(0); PG8_BAR; PG8_MMA(1, 0, At, B0); PG8_MMA(1, 1, At, B1); PG8_BAR; PG8_SCHED;
.LBB0_831:
	v_add_u32_e32 v142, 0x10000, v147
	v_add_u32_e32 v143, 0x14000, v147
	ds_read_b128 v[0:3], v142
	ds_read_b128 v[4:7], v142 offset:1024
	s_waitcnt vmcnt(3)
	ds_read_b128 v[8:11], v142 offset:2048
	s_waitcnt vmcnt(2)
	ds_read_b128 v[12:15], v142 offset:3072
	s_waitcnt vmcnt(1)
	ds_read_b128 v[16:19], v143
	s_waitcnt vmcnt(0)
	ds_read_b128 v[20:23], v143 offset:1024
	ds_read_b128 v[24:27], v143 offset:2048
	ds_read_b128 v[28:31], v143 offset:3072
	s_and_b64 s[16:17], s[6:7], exec
	s_cselect_b32 s17, s23, s89
	s_cselect_b32 s16, s22, s88
	s_add_u32 s30, s88, 0x100
	s_addc_u32 s31, s89, 0
	ds_read_b128 v[32:35], v148
	ds_read_b128 v[36:39], v148 offset:1024
	ds_read_b128 v[40:43], v148 offset:2048
	ds_read_b128 v[44:47], v148 offset:3072
	ds_read_b128 v[48:51], v148 offset:4096
	ds_read_b128 v[52:55], v148 offset:5120
	ds_read_b128 v[56:59], v148 offset:6144
	ds_read_b128 v[60:63], v148 offset:7168
	s_mov_b32 m0, s69
	s_nop 0
	global_load_lds_dwordx4 v144, s[94:95]
	s_mov_b32 m0, s24
	s_nop 0
	global_load_lds_dwordx4 v144, s[96:97]
	s_waitcnt vmcnt(8) lgkmcnt(0)
	s_barrier
	v_mfma_f32_16x16x32_bf16 v[64:67], v[0:3], v[32:35], 0
	v_mfma_f32_16x16x32_bf16 v[68:71], v[8:11], v[32:35], 0
	v_mfma_f32_16x16x32_bf16 v[72:75], v[0:3], v[40:43], 0
	v_mfma_f32_16x16x32_bf16 v[76:79], v[8:11], v[40:43], 0
	v_mfma_f32_16x16x32_bf16 v[80:83], v[0:3], v[48:51], 0
	v_mfma_f32_16x16x32_bf16 v[84:87], v[8:11], v[48:51], 0
	v_mfma_f32_16x16x32_bf16 v[88:91], v[0:3], v[56:59], 0
	v_mfma_f32_16x16x32_bf16 v[92:95], v[8:11], v[56:59], 0
	v_mfma_f32_16x16x32_bf16 v[64:67], v[4:7], v[36:39], v[64:67]
	v_mfma_f32_16x16x32_bf16 v[68:71], v[12:15], v[36:39], v[68:71]
	v_mfma_f32_16x16x32_bf16 v[72:75], v[4:7], v[44:47], v[72:75]
	v_mfma_f32_16x16x32_bf16 v[76:79], v[12:15], v[44:47], v[76:79]
	v_mfma_f32_16x16x32_bf16 v[80:83], v[4:7], v[52:55], v[80:83]
	v_mfma_f32_16x16x32_bf16 v[84:87], v[12:15], v[52:55], v[84:87]
	v_mfma_f32_16x16x32_bf16 v[88:91], v[4:7], v[60:63], v[88:91]
	v_mfma_f32_16x16x32_bf16 v[92:95], v[12:15], v[60:63], v[92:95]
	v_mfma_f32_16x16x32_bf16 v[96:99], v[16:19], v[32:35], 0
	v_mfma_f32_16x16x32_bf16 v[32:35], v[24:27], v[32:35], 0
	v_mfma_f32_16x16x32_bf16 v[96:99], v[20:23], v[36:39], v[96:99]
	v_mfma_f32_16x16x32_bf16 v[32:35], v[28:31], v[36:39], v[32:35]
	v_mfma_f32_16x16x32_bf16 v[36:39], v[16:19], v[40:43], 0
	v_mfma_f32_16x16x32_bf16 v[40:43], v[24:27], v[40:43], 0
	v_mfma_f32_16x16x32_bf16 v[36:39], v[20:23], v[44:47], v[36:39]
	v_mfma_f32_16x16x32_bf16 v[40:43], v[28:31], v[44:47], v[40:43]
	v_mfma_f32_16x16x32_bf16 v[44:47], v[16:19], v[48:51], 0
	v_mfma_f32_16x16x32_bf16 v[48:51], v[24:27], v[48:51], 0
	v_mfma_f32_16x16x32_bf16 v[44:47], v[20:23], v[52:55], v[44:47]
	v_mfma_f32_16x16x32_bf16 v[48:51], v[28:31], v[52:55], v[48:51]
	v_mfma_f32_16x16x32_bf16 v[52:55], v[16:19], v[56:59], 0
	v_mfma_f32_16x16x32_bf16 v[56:59], v[24:27], v[56:59], 0
	v_mfma_f32_16x16x32_bf16 v[52:55], v[20:23], v[60:63], v[52:55]
	v_mfma_f32_16x16x32_bf16 v[56:59], v[28:31], v[60:63], v[56:59]
	s_barrier
	ds_read_b128 v[60:63], v148 offset:16384
	ds_read_b128 v[100:103], v148 offset:17408
	ds_read_b128 v[104:107], v148 offset:18432
	ds_read_b128 v[108:111], v148 offset:19456
	ds_read_b128 v[112:115], v148 offset:20480
	ds_read_b128 v[116:119], v148 offset:21504
	ds_read_b128 v[120:123], v148 offset:22528
	ds_read_b128 v[124:127], v148 offset:23552
	s_mov_b32 m0, s12
	s_nop 0
	global_load_lds_dwordx4 v128, s[30:31]
	s_add_u32 s30, s88, 0x20100
	s_mov_b32 m0, s44
	s_addc_u32 s31, s89, 0
	global_load_lds_dwordx4 v128, s[30:31]
	s_add_u32 s30, s88, 0x40100
	s_mov_b32 m0, s42
	s_addc_u32 s31, s89, 0
	global_load_lds_dwordx4 v128, s[30:31]
	s_add_u32 s30, s88, 0x60100
	s_mov_b32 m0, s48
	s_addc_u32 s31, s89, 0
	global_load_lds_dwordx4 v128, s[30:31]
	s_mov_b32 m0, s47
	s_nop 0
	global_load_lds_dwordx4 v144, s[90:91]
	s_mov_b32 m0, s61
	s_nop 0
	global_load_lds_dwordx4 v144, s[38:39]
	s_waitcnt vmcnt(8) lgkmcnt(0)
	s_barrier
	v_mfma_f32_16x16x32_bf16 v[130:133], v[0:3], v[60:63], 0
	v_mfma_f32_16x16x32_bf16 v[138:141], v[0:3], v[104:107], 0
	v_mfma_f32_16x16x32_bf16 v[158:161], v[0:3], v[112:115], 0
	v_mfma_f32_16x16x32_bf16 v[0:3], v[0:3], v[120:123], 0
	v_mfma_f32_16x16x32_bf16 v[130:133], v[4:7], v[100:103], v[130:133]
	v_mfma_f32_16x16x32_bf16 v[138:141], v[4:7], v[108:111], v[138:141]
	v_mfma_f32_16x16x32_bf16 v[158:161], v[4:7], v[116:119], v[158:161]
	v_mfma_f32_16x16x32_bf16 v[0:3], v[4:7], v[124:127], v[0:3]
	v_mfma_f32_16x16x32_bf16 v[4:7], v[8:11], v[120:123], 0
	v_mfma_f32_16x16x32_bf16 v[134:137], v[8:11], v[60:63], 0
	v_mfma_f32_16x16x32_bf16 v[150:153], v[8:11], v[104:107], 0
	v_mfma_f32_16x16x32_bf16 v[162:165], v[8:11], v[112:115], 0
	v_mfma_f32_16x16x32_bf16 v[4:7], v[12:15], v[124:127], v[4:7]
	v_mfma_f32_16x16x32_bf16 v[134:137], v[12:15], v[100:103], v[134:137]
	v_mfma_f32_16x16x32_bf16 v[150:153], v[12:15], v[108:111], v[150:153]
	v_mfma_f32_16x16x32_bf16 v[162:165], v[12:15], v[116:119], v[162:165]
	v_mfma_f32_16x16x32_bf16 v[8:11], v[16:19], v[60:63], 0
	v_mfma_f32_16x16x32_bf16 v[12:15], v[24:27], v[60:63], 0
	v_mfma_f32_16x16x32_bf16 v[8:11], v[20:23], v[100:103], v[8:11]
	v_mfma_f32_16x16x32_bf16 v[12:15], v[28:31], v[100:103], v[12:15]
	v_mfma_f32_16x16x32_bf16 v[60:63], v[16:19], v[104:107], 0
	v_mfma_f32_16x16x32_bf16 v[100:103], v[24:27], v[104:107], 0
	v_mfma_f32_16x16x32_bf16 v[104:107], v[16:19], v[112:115], 0
	v_mfma_f32_16x16x32_bf16 v[16:19], v[16:19], v[120:123], 0
	v_mfma_f32_16x16x32_bf16 v[60:63], v[20:23], v[108:111], v[60:63]
	v_mfma_f32_16x16x32_bf16 v[100:103], v[28:31], v[108:111], v[100:103]
	v_mfma_f32_16x16x32_bf16 v[104:107], v[20:23], v[116:119], v[104:107]
	v_mfma_f32_16x16x32_bf16 v[108:111], v[24:27], v[112:115], 0
	v_mfma_f32_16x16x32_bf16 v[16:19], v[20:23], v[124:127], v[16:19]
	v_mfma_f32_16x16x32_bf16 v[20:23], v[24:27], v[120:123], 0
	v_mfma_f32_16x16x32_bf16 v[108:111], v[28:31], v[116:119], v[108:111]
	v_mfma_f32_16x16x32_bf16 v[20:23], v[28:31], v[124:127], v[20:23]
	s_barrier
; #define PG8_STAGE(bufoff, gbase, voff, p64) do { _Pragma("unroll") for (int _i = 0; _i < 2; ++_i) { \
;         const char* _gb = (const char*)(gbase) + (size_t)_i * (p64); const unsigned _la = ldsbase + (unsigned)(bufoff) + (unsigned)_i * 8192u; \
;         asm volatile("s_mov_b32 m0, %0\n\ts_nop 0\n\tglobal_load_lds_dwordx4 %1, %2" :: "s"(_la), "v"(voff), "s"(_gb) : "memory"); } } while (0)
; #define PG8_LDA(dst, b, h) do { _Pragma("unroll") for (int m = 0; m < 4; ++m) _Pragma("unroll") for (int k = 0; k < 2; ++k) dst[m][k] = *(const LAS bf16x8*)(lds + PG8_SA(b, h) + aoff + m * 2048 + k * 1024); } while (0)
; #define PG8_LDB(dst, b, h) do { _Pragma("unroll") for (int n = 0; n < 2; ++n) _Pragma("unroll") for (int k = 0; k < 2; ++k) dst[n][k] = *(const LAS bf16x8*)(lds + PG8_SB(b, h) + boff + n * 2048 + k * 1024); } while (0)
; #define PG8_MMA(ai, bj, At, Bt) do { __builtin_amdgcn_s_setprio(1); _Pragma("unroll") for (int m = 0; m < 4; ++m) _Pragma("unroll") for (int n = 0; n < 2; ++n) _Pragma("unroll") for (int k = 0; k < 2; ++k) \
;         acc[ai][bj][m][n] = __builtin_amdgcn_mfma_f32_16x16x32_bf16(Bt[n][k], At[m][k], acc[ai][bj][m][n], 0, 0, 0); __builtin_amdgcn_s_setprio(0); } while (0)
; #define PG8_WAIT_V(n) asm volatile("s_waitcnt vmcnt(" #n ")" ::: "memory")
; #define PG8_WAIT_L(n) asm volatile("s_waitcnt lgkmcnt(" #n ")" ::: "memory")
; #define PG8_BAR __builtin_amdgcn_s_barrier()
; #define PG8_SCHED __builtin_amdgcn_sched_barrier(0)
; template <class Epi, class Sched>
; __device__ __forceinline__ void gemm_phase(LAS unsigned char* lds, const Sched& S, const Epi& E) {
;     ...
;             PG8_LDB(B0, 1, 0); PG8_LDB(B1, 1, 1); PG8_SCHED; PG8_LDA(At, 1, 0); PG8_STAGE(PG8_SA(0, 1), a2 + hA2, vA2, hA2 / 2);
;             PG8_WAIT_V(8); PG8_WAIT_L(0); PG8_BAR; PG8_MMA(0, 0, At, B0); PG8_MMA(0, 1, At, B1); PG8_BAR; PG8_SCHED;
;             PG8_LDA(At, 1, 1); PG8_STAGE(PG8_SB(1, 0), b3, vB2, hB2 / 2); PG8_STAGE(PG8_SB(1, 1), b3 + hB2, vB2, hB2 / 2); PG8_STAGE(PG8_SA(1, 0), a3, vA2, hA2 / 2);
;             PG8_WAIT_V(8); PG8_WAIT_L(0); PG8_BAR; PG8_MMA(1, 0, At, B0); PG8_MMA(1, 1, At, B1); PG8_BAR; PG8_SCHED;
	v_add_u32_e32 v149, 0x18000, v147
	v_add_u32_e32 v154, 0x1c000, v147
	ds_read_b128 v[24:27], v149
	ds_read_b128 v[28:31], v149 offset:1024
	ds_read_b128 v[112:115], v149 offset:2048
	ds_read_b128 v[116:119], v149 offset:3072
	ds_read_b128 v[120:123], v154
	ds_read_b128 v[124:127], v154 offset:1024
	ds_read_b128 v[172:175], v154 offset:2048
	ds_read_b128 v[178:181], v154 offset:3072
	ds_read_b128 v[182:185], v148 offset:32768
	ds_read_b128 v[186:189], v148 offset:33792
	ds_read_b128 v[190:193], v148 offset:34816
	ds_read_b128 v[194:197], v148 offset:35840
	ds_read_b128 v[198:201], v148 offset:36864
	ds_read_b128 v[202:205], v148 offset:37888
	ds_read_b128 v[206:209], v148 offset:38912
	ds_read_b128 v[210:213], v148 offset:39936
	s_mov_b32 m0, s14
	s_nop 0
	global_load_lds_dwordx4 v144, s[40:41]
	s_mov_b32 m0, s15
	s_nop 0
	global_load_lds_dwordx4 v144, s[56:57]
	s_waitcnt vmcnt(8) lgkmcnt(0)
	s_barrier
	v_mfma_f32_16x16x32_bf16 v[64:67], v[24:27], v[182:185], v[64:67]
	v_mfma_f32_16x16x32_bf16 v[68:71], v[112:115], v[182:185], v[68:71]
	v_mfma_f32_16x16x32_bf16 v[72:75], v[24:27], v[190:193], v[72:75]
	v_mfma_f32_16x16x32_bf16 v[76:79], v[112:115], v[190:193], v[76:79]
	v_mfma_f32_16x16x32_bf16 v[80:83], v[24:27], v[198:201], v[80:83]
	v_mfma_f32_16x16x32_bf16 v[84:87], v[112:115], v[198:201], v[84:87]
	v_mfma_f32_16x16x32_bf16 v[88:91], v[24:27], v[206:209], v[88:91]
	v_mfma_f32_16x16x32_bf16 v[92:95], v[112:115], v[206:209], v[92:95]
	v_mfma_f32_16x16x32_bf16 v[64:67], v[28:31], v[186:189], v[64:67]
	v_mfma_f32_16x16x32_bf16 v[68:71], v[116:119], v[186:189], v[68:71]
	v_mfma_f32_16x16x32_bf16 v[72:75], v[28:31], v[194:197], v[72:75]
	v_mfma_f32_16x16x32_bf16 v[76:79], v[116:119], v[194:197], v[76:79]
	v_mfma_f32_16x16x32_bf16 v[80:83], v[28:31], v[202:205], v[80:83]
	v_mfma_f32_16x16x32_bf16 v[84:87], v[116:119], v[202:205], v[84:87]
	v_mfma_f32_16x16x32_bf16 v[88:91], v[28:31], v[210:213], v[88:91]
	v_mfma_f32_16x16x32_bf16 v[92:95], v[116:119], v[210:213], v[92:95]
	v_mfma_f32_16x16x32_bf16 v[96:99], v[120:123], v[182:185], v[96:99]
	v_mfma_f32_16x16x32_bf16 v[32:35], v[172:175], v[182:185], v[32:35]
	v_mfma_f32_16x16x32_bf16 v[36:39], v[120:123], v[190:193], v[36:39]
	v_mfma_f32_16x16x32_bf16 v[40:43], v[172:175], v[190:193], v[40:43]
	v_mfma_f32_16x16x32_bf16 v[44:47], v[120:123], v[198:201], v[44:47]
	v_mfma_f32_16x16x32_bf16 v[48:51], v[172:175], v[198:201], v[48:51]
	v_mfma_f32_16x16x32_bf16 v[52:55], v[120:123], v[206:209], v[52:55]
	v_mfma_f32_16x16x32_bf16 v[56:59], v[172:175], v[206:209], v[56:59]
	v_mfma_f32_16x16x32_bf16 v[96:99], v[124:127], v[186:189], v[96:99]
	v_mfma_f32_16x16x32_bf16 v[32:35], v[178:181], v[186:189], v[32:35]
	v_mfma_f32_16x16x32_bf16 v[36:39], v[124:127], v[194:197], v[36:39]
	v_mfma_f32_16x16x32_bf16 v[40:43], v[178:181], v[194:197], v[40:43]
	v_mfma_f32_16x16x32_bf16 v[44:47], v[124:127], v[202:205], v[44:47]
	v_mfma_f32_16x16x32_bf16 v[48:51], v[178:181], v[202:205], v[48:51]
	v_mfma_f32_16x16x32_bf16 v[52:55], v[124:127], v[210:213], v[52:55]
	v_mfma_f32_16x16x32_bf16 v[56:59], v[178:181], v[210:213], v[56:59]
	s_barrier
	s_add_u32 s30, s88, 0x180
	s_addc_u32 s31, s89, 0
	ds_read_b128 v[182:185], v148 offset:49152
	ds_read_b128 v[186:189], v148 offset:50176
	ds_read_b128 v[190:193], v148 offset:51200
	ds_read_b128 v[194:197], v148 offset:52224
	ds_read_b128 v[198:201], v148 offset:53248
	ds_read_b128 v[202:205], v148 offset:54272
	ds_read_b128 v[206:209], v148 offset:55296
	ds_read_b128 v[210:213], v148 offset:56320
	s_mov_b32 m0, s65
	s_nop 0
	global_load_lds_dwordx4 v128, s[30:31]
	s_add_u32 s30, s88, 0x20180
	s_mov_b32 m0, s66
	s_addc_u32 s31, s89, 0
	global_load_lds_dwordx4 v128, s[30:31]
	s_add_u32 s30, s88, 0x40180
	s_mov_b32 m0, s36
	s_addc_u32 s31, s89, 0
	global_load_lds_dwordx4 v128, s[30:31]
	s_add_u32 s30, s88, 0x60180
	s_mov_b32 m0, s37
	s_addc_u32 s31, s89, 0
	global_load_lds_dwordx4 v128, s[30:31]
	s_mov_b32 m0, s67
	s_nop 0
	global_load_lds_dwordx4 v144, s[92:93]
	s_mov_b32 m0, s45
	s_nop 0
	global_load_lds_dwordx4 v144, s[62:63]
	s_waitcnt vmcnt(8) lgkmcnt(0)
	s_barrier
	v_mfma_f32_16x16x32_bf16 v[0:3], v[24:27], v[206:209], v[0:3]
	v_mfma_f32_16x16x32_bf16 v[4:7], v[112:115], v[206:209], v[4:7]
	v_mfma_f32_16x16x32_bf16 v[130:133], v[24:27], v[182:185], v[130:133]
	v_mfma_f32_16x16x32_bf16 v[134:137], v[112:115], v[182:185], v[134:137]
	v_mfma_f32_16x16x32_bf16 v[138:141], v[24:27], v[190:193], v[138:141]
	v_mfma_f32_16x16x32_bf16 v[150:153], v[112:115], v[190:193], v[150:153]
	v_mfma_f32_16x16x32_bf16 v[158:161], v[24:27], v[198:201], v[158:161]
	v_mfma_f32_16x16x32_bf16 v[162:165], v[112:115], v[198:201], v[162:165]
	v_mfma_f32_16x16x32_bf16 v[0:3], v[28:31], v[210:213], v[0:3]
	v_mfma_f32_16x16x32_bf16 v[4:7], v[116:119], v[210:213], v[4:7]
	v_mfma_f32_16x16x32_bf16 v[130:133], v[28:31], v[186:189], v[130:133]
	v_mfma_f32_16x16x32_bf16 v[134:137], v[116:119], v[186:189], v[134:137]
	v_mfma_f32_16x16x32_bf16 v[138:141], v[28:31], v[194:197], v[138:141]
	v_mfma_f32_16x16x32_bf16 v[150:153], v[116:119], v[194:197], v[150:153]
	v_mfma_f32_16x16x32_bf16 v[158:161], v[28:31], v[202:205], v[158:161]
	v_mfma_f32_16x16x32_bf16 v[162:165], v[116:119], v[202:205], v[162:165]
	v_mfma_f32_16x16x32_bf16 v[8:11], v[120:123], v[182:185], v[8:11]
	v_mfma_f32_16x16x32_bf16 v[12:15], v[172:175], v[182:185], v[12:15]
	v_mfma_f32_16x16x32_bf16 v[24:27], v[120:123], v[190:193], v[60:63]
	v_mfma_f32_16x16x32_bf16 v[28:31], v[172:175], v[190:193], v[100:103]
	v_mfma_f32_16x16x32_bf16 v[60:63], v[120:123], v[198:201], v[104:107]
	v_mfma_f32_16x16x32_bf16 v[100:103], v[172:175], v[198:201], v[108:111]
	v_mfma_f32_16x16x32_bf16 v[16:19], v[120:123], v[206:209], v[16:19]
	v_mfma_f32_16x16x32_bf16 v[20:23], v[172:175], v[206:209], v[20:23]
	v_mfma_f32_16x16x32_bf16 v[8:11], v[124:127], v[186:189], v[8:11]
	v_mfma_f32_16x16x32_bf16 v[12:15], v[178:181], v[186:189], v[12:15]
	v_mfma_f32_16x16x32_bf16 v[24:27], v[124:127], v[194:197], v[24:27]
	v_mfma_f32_16x16x32_bf16 v[28:31], v[178:181], v[194:197], v[28:31]
	v_mfma_f32_16x16x32_bf16 v[60:63], v[124:127], v[202:205], v[60:63]
	v_mfma_f32_16x16x32_bf16 v[100:103], v[178:181], v[202:205], v[100:103]
	v_mfma_f32_16x16x32_bf16 v[16:19], v[124:127], v[210:213], v[16:19]
	v_mfma_f32_16x16x32_bf16 v[20:23], v[178:181], v[210:213], v[20:23]
	s_barrier
; #define PG8_STAGE(bufoff, gbase, voff, p64) do { _Pragma("unroll") for (int _i = 0; _i < 2; ++_i) { \
;         const char* _gb = (const char*)(gbase) + (size_t)_i * (p64); const unsigned _la = ldsbase + (unsigned)(bufoff) + (unsigned)_i * 8192u; \
;         asm volatile("s_mov_b32 m0, %0\n\ts_nop 0\n\tglobal_load_lds_dwordx4 %1, %2" :: "s"(_la), "v"(voff), "s"(_gb) : "memory"); } } while (0)
; #define PG8_LDA(dst, b, h) do { _Pragma("unroll") for (int m = 0; m < 4; ++m) _Pragma("unroll") for (int k = 0; k < 2; ++k) dst[m][k] = *(const LAS bf16x8*)(lds + PG8_SA(b, h) + aoff + m * 2048 + k * 1024); } while (0)
; #define PG8_LDB(dst, b, h) do { _Pragma("unroll") for (int n = 0; n < 2; ++n) _Pragma("unroll") for (int k = 0; k < 2; ++k) dst[n][k] = *(const LAS bf16x8*)(lds + PG8_SB(b, h) + boff + n * 2048 + k * 1024); } while (0)
; #define PG8_MMA(ai, bj, At, Bt) do { __builtin_amdgcn_s_setprio(1); _Pragma("unroll") for (int m = 0; m < 4; ++m) _Pragma("unroll") for (int n = 0; n < 2; ++n) _Pragma("unroll") for (int k = 0; k < 2; ++k) \
;         acc[ai][bj][m][n] = __builtin_amdgcn_mfma_f32_16x16x32_bf16(Bt[n][k], At[m][k], acc[ai][bj][m][n], 0, 0, 0); __builtin_amdgcn_s_setprio(0); } while (0)
; #define PG8_WAIT_V(n) asm volatile("s_waitcnt vmcnt(" #n ")" ::: "memory")
; #define PG8_WAIT_L(n) asm volatile("s_waitcnt lgkmcnt(" #n ")" ::: "memory")
; #define PG8_BAR __builtin_amdgcn_s_barrier()
; #define PG8_SCHED __builtin_amdgcn_sched_barrier(0)
; template <class Epi, class Sched>
; __device__ __forceinline__ void gemm_phase(LAS unsigned char* lds, const Sched& S, const Epi& E) {
;     ...
;             PG8_LDB(B0, 0, 0); PG8_LDB(B1, 0, 1); PG8_SCHED; PG8_LDA(At, 0, 0); PG8_STAGE(PG8_SA(1, 1), a1 + hA, voffA, hA / 2);
;             PG8_WAIT_V(8); PG8_WAIT_L(0); PG8_BAR; PG8_MMA(0, 0, At, B0); PG8_MMA(0, 1, At, B1); PG8_BAR; PG8_SCHED;
;             PG8_LDA(At, 0, 1); PG8_STAGE(PG8_SB(0, 0), b2, vB2, hB2 / 2); PG8_STAGE(PG8_SB(0, 1), b2 + hB2, vB2, hB2 / 2); PG8_STAGE(PG8_SA(0, 0), a2, vA2, hA2 / 2);
;             PG8_WAIT_V(8); PG8_WAIT_L(0); PG8_BAR; PG8_MMA(1, 0, At, B0); PG8_MMA(1, 1, At, B1); PG8_BAR; PG8_SCHED;
	ds_read_b128 v[104:107], v142
	ds_read_b128 v[108:111], v142 offset:1024
	ds_read_b128 v[112:115], v142 offset:2048
	ds_read_b128 v[116:119], v142 offset:3072
	ds_read_b128 v[120:123], v143
	ds_read_b128 v[124:127], v143 offset:1024
	ds_read_b128 v[172:175], v143 offset:2048
	ds_read_b128 v[178:181], v143 offset:3072
	ds_read_b128 v[182:185], v148
	ds_read_b128 v[186:189], v148 offset:1024
	ds_read_b128 v[190:193], v148 offset:2048
	ds_read_b128 v[194:197], v148 offset:3072
	ds_read_b128 v[198:201], v148 offset:4096
	ds_read_b128 v[202:205], v148 offset:5120
	ds_read_b128 v[206:209], v148 offset:6144
	ds_read_b128 v[210:213], v148 offset:7168
	s_mov_b32 m0, s69
	s_nop 0
	global_load_lds_dwordx4 v144, s[26:27]
	s_mov_b32 m0, s24
	s_nop 0
	global_load_lds_dwordx4 v144, s[54:55]
	s_waitcnt vmcnt(8) lgkmcnt(0)
	s_barrier
	v_mfma_f32_16x16x32_bf16 v[64:67], v[104:107], v[182:185], v[64:67]
	v_mfma_f32_16x16x32_bf16 v[68:71], v[112:115], v[182:185], v[68:71]
	v_mfma_f32_16x16x32_bf16 v[72:75], v[104:107], v[190:193], v[72:75]
	v_mfma_f32_16x16x32_bf16 v[76:79], v[112:115], v[190:193], v[76:79]
	v_mfma_f32_16x16x32_bf16 v[80:83], v[104:107], v[198:201], v[80:83]
	v_mfma_f32_16x16x32_bf16 v[84:87], v[112:115], v[198:201], v[84:87]
	v_mfma_f32_16x16x32_bf16 v[88:91], v[104:107], v[206:209], v[88:91]
	v_mfma_f32_16x16x32_bf16 v[64:67], v[108:111], v[186:189], v[64:67]
	v_mfma_f32_16x16x32_bf16 v[68:71], v[116:119], v[186:189], v[68:71]
	v_mfma_f32_16x16x32_bf16 v[72:75], v[108:111], v[194:197], v[72:75]
	v_mfma_f32_16x16x32_bf16 v[76:79], v[116:119], v[194:197], v[76:79]
	v_mfma_f32_16x16x32_bf16 v[80:83], v[108:111], v[202:205], v[80:83]
	v_mfma_f32_16x16x32_bf16 v[84:87], v[116:119], v[202:205], v[84:87]
	v_mfma_f32_16x16x32_bf16 v[214:217], v[108:111], v[210:213], v[88:91]
	v_mfma_f32_16x16x32_bf16 v[88:91], v[112:115], v[206:209], v[92:95]
	v_mfma_f32_16x16x32_bf16 v[218:221], v[116:119], v[210:213], v[88:91]
	v_mfma_f32_16x16x32_bf16 v[88:91], v[120:123], v[182:185], v[96:99]
	v_mfma_f32_16x16x32_bf16 v[32:35], v[172:175], v[182:185], v[32:35]
	v_mfma_f32_16x16x32_bf16 v[36:39], v[120:123], v[190:193], v[36:39]
	v_mfma_f32_16x16x32_bf16 v[40:43], v[172:175], v[190:193], v[40:43]
	v_mfma_f32_16x16x32_bf16 v[44:47], v[120:123], v[198:201], v[44:47]
	v_mfma_f32_16x16x32_bf16 v[48:51], v[172:175], v[198:201], v[48:51]
	v_mfma_f32_16x16x32_bf16 v[52:55], v[120:123], v[206:209], v[52:55]
	v_mfma_f32_16x16x32_bf16 v[56:59], v[172:175], v[206:209], v[56:59]
	v_mfma_f32_16x16x32_bf16 v[96:99], v[124:127], v[186:189], v[88:91]
	v_mfma_f32_16x16x32_bf16 v[32:35], v[178:181], v[186:189], v[32:35]
	v_mfma_f32_16x16x32_bf16 v[36:39], v[124:127], v[194:197], v[36:39]
	v_mfma_f32_16x16x32_bf16 v[40:43], v[178:181], v[194:197], v[40:43]
	v_mfma_f32_16x16x32_bf16 v[44:47], v[124:127], v[202:205], v[44:47]
	v_mfma_f32_16x16x32_bf16 v[48:51], v[178:181], v[202:205], v[48:51]
	v_mfma_f32_16x16x32_bf16 v[52:55], v[124:127], v[210:213], v[52:55]
	v_mfma_f32_16x16x32_bf16 v[56:59], v[178:181], v[210:213], v[56:59]
	s_barrier
	s_add_u32 s30, s16, 0x20000
	ds_read_b128 v[88:91], v148 offset:16384
	ds_read_b128 v[92:95], v148 offset:17408
	ds_read_b128 v[182:185], v148 offset:18432
	ds_read_b128 v[186:189], v148 offset:19456
	ds_read_b128 v[190:193], v148 offset:20480
	ds_read_b128 v[194:197], v148 offset:21504
	ds_read_b128 v[198:201], v148 offset:22528
	ds_read_b128 v[202:205], v148 offset:23552
	s_mov_b32 m0, s12
	s_nop 0
	global_load_lds_dwordx4 v128, s[16:17]
	s_mov_b32 m0, s44
	s_addc_u32 s31, s17, 0
	global_load_lds_dwordx4 v128, s[30:31]
	s_add_u32 s30, s16, 0x40000
	s_mov_b32 m0, s42
	s_addc_u32 s31, s17, 0
	global_load_lds_dwordx4 v128, s[30:31]
	s_add_u32 s30, s16, 0x60000
	s_mov_b32 m0, s48
	s_addc_u32 s31, s17, 0
	global_load_lds_dwordx4 v128, s[30:31]
	s_mov_b32 m0, s47
	s_nop 0
	global_load_lds_dwordx4 v144, s[8:9]
	s_mov_b32 m0, s61
	s_nop 0
	global_load_lds_dwordx4 v144, s[10:11]
	s_waitcnt vmcnt(8) lgkmcnt(0)
	s_barrier
	v_mfma_f32_16x16x32_bf16 v[0:3], v[104:107], v[198:201], v[0:3]
	v_mfma_f32_16x16x32_bf16 v[4:7], v[112:115], v[198:201], v[4:7]
	v_mfma_f32_16x16x32_bf16 v[130:133], v[104:107], v[88:91], v[130:133]
	v_mfma_f32_16x16x32_bf16 v[134:137], v[112:115], v[88:91], v[134:137]
	v_mfma_f32_16x16x32_bf16 v[138:141], v[104:107], v[182:185], v[138:141]
	v_mfma_f32_16x16x32_bf16 v[150:153], v[112:115], v[182:185], v[150:153]
	v_mfma_f32_16x16x32_bf16 v[158:161], v[104:107], v[190:193], v[158:161]
	v_mfma_f32_16x16x32_bf16 v[162:165], v[112:115], v[190:193], v[162:165]
	v_mfma_f32_16x16x32_bf16 v[0:3], v[108:111], v[202:205], v[0:3]
	v_mfma_f32_16x16x32_bf16 v[4:7], v[116:119], v[202:205], v[4:7]
	v_mfma_f32_16x16x32_bf16 v[130:133], v[108:111], v[92:95], v[130:133]
	v_mfma_f32_16x16x32_bf16 v[134:137], v[116:119], v[92:95], v[134:137]
	v_mfma_f32_16x16x32_bf16 v[138:141], v[108:111], v[186:189], v[138:141]
	v_mfma_f32_16x16x32_bf16 v[150:153], v[116:119], v[186:189], v[150:153]
	v_mfma_f32_16x16x32_bf16 v[158:161], v[108:111], v[194:197], v[158:161]
	v_mfma_f32_16x16x32_bf16 v[162:165], v[116:119], v[194:197], v[162:165]
	v_mfma_f32_16x16x32_bf16 v[8:11], v[120:123], v[88:91], v[8:11]
	v_mfma_f32_16x16x32_bf16 v[206:209], v[124:127], v[92:95], v[8:11]
	v_mfma_f32_16x16x32_bf16 v[8:11], v[172:175], v[88:91], v[12:15]
	v_mfma_f32_16x16x32_bf16 v[210:213], v[178:181], v[92:95], v[8:11]
	v_mfma_f32_16x16x32_bf16 v[8:11], v[120:123], v[182:185], v[24:27]
	v_mfma_f32_16x16x32_bf16 v[222:225], v[124:127], v[186:189], v[8:11]
	v_mfma_f32_16x16x32_bf16 v[8:11], v[172:175], v[182:185], v[28:31]
	v_mfma_f32_16x16x32_bf16 v[182:185], v[178:181], v[186:189], v[8:11]
	v_mfma_f32_16x16x32_bf16 v[8:11], v[120:123], v[190:193], v[60:63]
	v_mfma_f32_16x16x32_bf16 v[186:189], v[124:127], v[194:197], v[8:11]
	v_mfma_f32_16x16x32_bf16 v[8:11], v[172:175], v[190:193], v[100:103]
	v_mfma_f32_16x16x32_bf16 v[190:193], v[178:181], v[194:197], v[8:11]
	v_mfma_f32_16x16x32_bf16 v[8:11], v[120:123], v[198:201], v[16:19]
	v_mfma_f32_16x16x32_bf16 v[194:197], v[124:127], v[202:205], v[8:11]
	v_mfma_f32_16x16x32_bf16 v[8:11], v[172:175], v[198:201], v[20:23]
	v_mfma_f32_16x16x32_bf16 v[172:175], v[178:181], v[202:205], v[8:11]
	s_barrier
; #define PG8_STAGE(bufoff, gbase, voff, p64) do { _Pragma("unroll") for (int _i = 0; _i < 2; ++_i) { \
;         const char* _gb = (const char*)(gbase) + (size_t)_i * (p64); const unsigned _la = ldsbase + (unsigned)(bufoff) + (unsigned)_i * 8192u; \
;         asm volatile("s_mov_b32 m0, %0\n\ts_nop 0\n\tglobal_load_lds_dwordx4 %1, %2" :: "s"(_la), "v"(voff), "s"(_gb) : "memory"); } } while (0)
; #define PG8_LDA(dst, b, h) do { _Pragma("unroll") for (int m = 0; m < 4; ++m) _Pragma("unroll") for (int k = 0; k < 2; ++k) dst[m][k] = *(const LAS bf16x8*)(lds + PG8_SA(b, h) + aoff + m * 2048 + k * 1024); } while (0)
; #define PG8_LDB(dst, b, h) do { _Pragma("unroll") for (int n = 0; n < 2; ++n) _Pragma("unroll") for (int k = 0; k < 2; ++k) dst[n][k] = *(const LAS bf16x8*)(lds + PG8_SB(b, h) + boff + n * 2048 + k * 1024); } while (0)
; #define PG8_MMA(ai, bj, At, Bt) do { __builtin_amdgcn_s_setprio(1); _Pragma("unroll") for (int m = 0; m < 4; ++m) _Pragma("unroll") for (int n = 0; n < 2; ++n) _Pragma("unroll") for (int k = 0; k < 2; ++k) \
;         acc[ai][bj][m][n] = __builtin_amdgcn_mfma_f32_16x16x32_bf16(Bt[n][k], At[m][k], acc[ai][bj][m][n], 0, 0, 0); __builtin_amdgcn_s_setprio(0); } while (0)
; #define PG8_WAIT_V(n) asm volatile("s_waitcnt vmcnt(" #n ")" ::: "memory")
; #define PG8_WAIT_L(n) asm volatile("s_waitcnt lgkmcnt(" #n ")" ::: "memory")
; #define PG8_BAR __builtin_amdgcn_s_barrier()
; #define PG8_SCHED __builtin_amdgcn_sched_barrier(0)
; template <class Epi, class Sched>
; __device__ __forceinline__ void gemm_phase(LAS unsigned char* lds, const Sched& S, const Epi& E) {
;     ...
;             PG8_LDB(B0, 1, 0); PG8_LDB(B1, 1, 1); PG8_SCHED; PG8_LDA(At, 1, 0); PG8_STAGE(PG8_SA(0, 1), a2 + hA2, vA2, hA2 / 2);
;             PG8_WAIT_V(8); PG8_WAIT_L(0); PG8_BAR; PG8_MMA(0, 0, At, B0); PG8_MMA(0, 1, At, B1); PG8_BAR; PG8_SCHED;
;             PG8_LDA(At, 1, 1); PG8_STAGE(PG8_SB(1, 0), b3, vB2, hB2 / 2); PG8_STAGE(PG8_SB(1, 1), b3 + hB2, vB2, hB2 / 2); PG8_STAGE(PG8_SA(1, 0), a3, vA2, hA2 / 2);
;             PG8_WAIT_V(8); PG8_WAIT_L(0); PG8_BAR; PG8_MMA(1, 0, At, B0); PG8_MMA(1, 1, At, B1); PG8_BAR; PG8_SCHED;
;         }
;         if (wr == 0) PG8_BAR;
	s_nop 4
	ds_read_b128 v[8:11], v149
	ds_read_b128 v[12:15], v149 offset:1024
	ds_read_b128 v[16:19], v149 offset:2048
	ds_read_b128 v[20:23], v149 offset:3072
	ds_read_b128 v[178:181], v154
	ds_read_b128 v[198:201], v154 offset:1024
	ds_read_b128 v[202:205], v154 offset:2048
	ds_read_b128 v[226:229], v154 offset:3072
	ds_read_b128 v[24:27], v148 offset:32768
	ds_read_b128 v[28:31], v148 offset:33792
	ds_read_b128 v[60:63], v148 offset:34816
	ds_read_b128 v[230:233], v148 offset:35840
	ds_read_b128 v[234:237], v148 offset:36864
	ds_read_b128 v[238:241], v148 offset:37888
	ds_read_b128 v[242:245], v148 offset:38912
	ds_read_b128 v[246:249], v148 offset:39936
	s_mov_b32 m0, s14
	s_nop 0
	global_load_lds_dwordx4 v144, s[74:75]
	s_mov_b32 m0, s15
	s_nop 0
	global_load_lds_dwordx4 v144, s[76:77]
	s_waitcnt vmcnt(8) lgkmcnt(0)
	s_barrier
	v_mfma_f32_16x16x32_bf16 v[64:67], v[8:11], v[24:27], v[64:67]
	v_mfma_f32_16x16x32_bf16 v[124:127], v[12:15], v[28:31], v[64:67]
	v_mfma_f32_16x16x32_bf16 v[64:67], v[16:19], v[24:27], v[68:71]
	v_mfma_f32_16x16x32_bf16 v[120:123], v[20:23], v[28:31], v[64:67]
	v_mfma_f32_16x16x32_bf16 v[64:67], v[8:11], v[60:63], v[72:75]
	v_mfma_f32_16x16x32_bf16 v[108:111], v[12:15], v[230:233], v[64:67]
	v_mfma_f32_16x16x32_bf16 v[64:67], v[16:19], v[60:63], v[76:79]
	v_mfma_f32_16x16x32_bf16 v[104:107], v[20:23], v[230:233], v[64:67]
	v_mfma_f32_16x16x32_bf16 v[64:67], v[8:11], v[234:237], v[80:83]
	v_mfma_f32_16x16x32_bf16 v[92:95], v[12:15], v[238:241], v[64:67]
	v_mfma_f32_16x16x32_bf16 v[64:67], v[16:19], v[234:237], v[84:87]
	v_mfma_f32_16x16x32_bf16 v[88:91], v[20:23], v[238:241], v[64:67]
	v_mfma_f32_16x16x32_bf16 v[64:67], v[8:11], v[242:245], v[214:217]
	v_mfma_f32_16x16x32_bf16 v[76:79], v[12:15], v[246:249], v[64:67]
	v_mfma_f32_16x16x32_bf16 v[64:67], v[16:19], v[242:245], v[218:221]
	v_mfma_f32_16x16x32_bf16 v[72:75], v[20:23], v[246:249], v[64:67]
	v_mfma_f32_16x16x32_bf16 v[64:67], v[178:181], v[24:27], v[96:99]
	v_mfma_f32_16x16x32_bf16 v[24:27], v[202:205], v[24:27], v[32:35]
	v_mfma_f32_16x16x32_bf16 v[112:115], v[226:229], v[28:31], v[24:27]
	v_mfma_f32_16x16x32_bf16 v[24:27], v[178:181], v[60:63], v[36:39]
	v_mfma_f32_16x16x32_bf16 v[100:103], v[198:201], v[230:233], v[24:27]
	v_mfma_f32_16x16x32_bf16 v[24:27], v[202:205], v[60:63], v[40:43]
	v_mfma_f32_16x16x32_bf16 v[96:99], v[226:229], v[230:233], v[24:27]
	v_mfma_f32_16x16x32_bf16 v[24:27], v[178:181], v[234:237], v[44:47]
	v_mfma_f32_16x16x32_bf16 v[84:87], v[198:201], v[238:241], v[24:27]
	v_mfma_f32_16x16x32_bf16 v[24:27], v[202:205], v[234:237], v[48:51]
	v_mfma_f32_16x16x32_bf16 v[80:83], v[226:229], v[238:241], v[24:27]
	v_mfma_f32_16x16x32_bf16 v[24:27], v[178:181], v[242:245], v[52:55]
	v_mfma_f32_16x16x32_bf16 v[68:71], v[198:201], v[246:249], v[24:27]
	v_mfma_f32_16x16x32_bf16 v[24:27], v[202:205], v[242:245], v[56:59]
	v_mfma_f32_16x16x32_bf16 v[116:119], v[198:201], v[28:31], v[64:67]
	v_mfma_f32_16x16x32_bf16 v[64:67], v[226:229], v[246:249], v[24:27]
	s_barrier
	s_add_u32 s30, s16, 0x80
	s_addc_u32 s31, s17, 0
	ds_read_b128 v[32:35], v148 offset:49152
	ds_read_b128 v[36:39], v148 offset:50176
	ds_read_b128 v[214:217], v148 offset:51200
	ds_read_b128 v[218:221], v148 offset:52224
	ds_read_b128 v[230:233], v148 offset:53248
	ds_read_b128 v[234:237], v148 offset:54272
	ds_read_b128 v[238:241], v148 offset:55296
	ds_read_b128 v[242:245], v148 offset:56320
	s_mov_b32 m0, s65
	s_nop 0
	global_load_lds_dwordx4 v128, s[30:31]
	s_add_u32 s30, s16, 0x20080
	s_mov_b32 m0, s66
	s_addc_u32 s31, s17, 0
	global_load_lds_dwordx4 v128, s[30:31]
	s_add_u32 s30, s16, 0x40080
	s_mov_b32 m0, s36
	s_addc_u32 s31, s17, 0
	global_load_lds_dwordx4 v128, s[30:31]
	s_add_u32 s16, s16, 0x60080
	s_mov_b32 m0, s37
	s_addc_u32 s17, s17, 0
	global_load_lds_dwordx4 v128, s[16:17]
	s_mov_b32 m0, s67
	s_nop 0
	global_load_lds_dwordx4 v144, s[82:83]
	s_mov_b32 m0, s45
	s_nop 0
	global_load_lds_dwordx4 v144, s[84:85]
	s_waitcnt vmcnt(8) lgkmcnt(0)
	s_barrier
	v_mfma_f32_16x16x32_bf16 v[24:27], v[8:11], v[32:35], v[130:133]
	v_mfma_f32_16x16x32_bf16 v[60:63], v[12:15], v[36:39], v[24:27]
	v_mfma_f32_16x16x32_bf16 v[24:27], v[16:19], v[32:35], v[134:137]
	v_mfma_f32_16x16x32_bf16 v[56:59], v[20:23], v[36:39], v[24:27]
	v_mfma_f32_16x16x32_bf16 v[24:27], v[8:11], v[214:217], v[138:141]
	v_mfma_f32_16x16x32_bf16 v[44:47], v[12:15], v[218:221], v[24:27]
	v_mfma_f32_16x16x32_bf16 v[24:27], v[16:19], v[214:217], v[150:153]
	v_mfma_f32_16x16x32_bf16 v[40:43], v[20:23], v[218:221], v[24:27]
	v_mfma_f32_16x16x32_bf16 v[24:27], v[8:11], v[230:233], v[158:161]
	v_mfma_f32_16x16x32_bf16 v[0:3], v[8:11], v[238:241], v[0:3]
	v_mfma_f32_16x16x32_bf16 v[28:31], v[12:15], v[234:237], v[24:27]
	v_mfma_f32_16x16x32_bf16 v[24:27], v[16:19], v[230:233], v[162:165]
	v_mfma_f32_16x16x32_bf16 v[12:15], v[12:15], v[242:245], v[0:3]
	v_mfma_f32_16x16x32_bf16 v[0:3], v[16:19], v[238:241], v[4:7]
	v_mfma_f32_16x16x32_bf16 v[24:27], v[20:23], v[234:237], v[24:27]
	v_mfma_f32_16x16x32_bf16 v[8:11], v[20:23], v[242:245], v[0:3]
	v_mfma_f32_16x16x32_bf16 v[0:3], v[178:181], v[32:35], v[206:209]
	v_mfma_f32_16x16x32_bf16 v[52:55], v[198:201], v[36:39], v[0:3]
	v_mfma_f32_16x16x32_bf16 v[0:3], v[202:205], v[32:35], v[210:213]
	v_mfma_f32_16x16x32_bf16 v[48:51], v[226:229], v[36:39], v[0:3]
	v_mfma_f32_16x16x32_bf16 v[0:3], v[178:181], v[214:217], v[222:225]
	v_mfma_f32_16x16x32_bf16 v[36:39], v[198:201], v[218:221], v[0:3]
	v_mfma_f32_16x16x32_bf16 v[0:3], v[202:205], v[214:217], v[182:185]
	v_mfma_f32_16x16x32_bf16 v[32:35], v[226:229], v[218:221], v[0:3]
	v_mfma_f32_16x16x32_bf16 v[0:3], v[178:181], v[230:233], v[186:189]
	v_mfma_f32_16x16x32_bf16 v[20:23], v[198:201], v[234:237], v[0:3]
	v_mfma_f32_16x16x32_bf16 v[0:3], v[202:205], v[230:233], v[190:193]
	v_mfma_f32_16x16x32_bf16 v[16:19], v[226:229], v[234:237], v[0:3]
	v_mfma_f32_16x16x32_bf16 v[0:3], v[178:181], v[238:241], v[194:197]
	v_mfma_f32_16x16x32_bf16 v[4:7], v[198:201], v[242:245], v[0:3]
	v_mfma_f32_16x16x32_bf16 v[0:3], v[202:205], v[238:241], v[172:175]
	v_mfma_f32_16x16x32_bf16 v[0:3], v[226:229], v[242:245], v[0:3]
	s_barrier
	s_andn2_b64 vcc, exec, s[86:87]
	s_cbranch_vccnz .LBB0_833
	s_barrier

; #define PG8_STAGE(bufoff, gbase, voff, p64) do { _Pragma("unroll") for (int _i = 0; _i < 2; ++_i) { \
;         const char* _gb = (const char*)(gbase) + (size_t)_i * (p64); const unsigned _la = ldsbase + (unsigned)(bufoff) + (unsigned)_i * 8192u; \
;         asm volatile("s_mov_b32 m0, %0\n\ts_nop 0\n\tglobal_load_lds_dwordx4 %1, %2" :: "s"(_la), "v"(voff), "s"(_gb) : "memory"); } } while (0)
; #define PG8_LDA(dst, b, h) do { _Pragma("unroll") for (int m = 0; m < 4; ++m) _Pragma("unroll") for (int k = 0; k < 2; ++k) dst[m][k] = *(const LAS bf16x8*)(lds + PG8_SA(b, h) + aoff + m * 2048 + k * 1024); } while (0)
; #define PG8_LDB(dst, b, h) do { _Pragma("unroll") for (int n = 0; n < 2; ++n) _Pragma("unroll") for (int k = 0; k < 2; ++k) dst[n][k] = *(const LAS bf16x8*)(lds + PG8_SB(b, h) + boff + n * 2048 + k * 1024); } while (0)
; #define PG8_MMA(ai, bj, At, Bt) do { __builtin_amdgcn_s_setprio(1); _Pragma("unroll") for (int m = 0; m < 4; ++m) _Pragma("unroll") for (int n = 0; n < 2; ++n) _Pragma("unroll") for (int k = 0; k < 2; ++k) \
;         acc[ai][bj][m][n] = __builtin_amdgcn_mfma_f32_16x16x32_bf16(Bt[n][k], At[m][k], acc[ai][bj][m][n], 0, 0, 0); __builtin_amdgcn_s_setprio(0); } while (0)
; #define PG8_WAIT_V(n) asm volatile("s_waitcnt vmcnt(" #n ")" ::: "memory")
; #define PG8_WAIT_L(n) asm volatile("s_waitcnt lgkmcnt(" #n ")" ::: "memory")
; #define PG8_BAR __builtin_amdgcn_s_barrier()
; template <class Epi, class Sched>
; __device__ __forceinline__ void gemm_phase(LAS unsigned char* lds, const Sched& S, const Epi& E) {
;     ...
;             const bool last = (t == nt - 2);
;             const char* a1 = cA + (size_t)(t + 1) * kstep;
;             const char* a2 = last ? nA : cA + (size_t)(t + 2) * kstep; const char* b2 = last ? nB : cB + (size_t)(t + 2) * kstep;
;             const char* a3 = a2 + kstep; const char* b3 = b2 + kstep;
;             const unsigned vA2 = voffA, vB2 = voffB, hA2 = hA, hB2 = hB;
;             PG8_LDB(B0, 0, 0); PG8_LDB(B1, 0, 1); PG8_SCHED; PG8_LDA(At, 0, 0); PG8_STAGE(PG8_SA(1, 1), a1 + hA, voffA, hA / 2);
;             PG8_WAIT_V(8); PG8_WAIT_L(0); PG8_BAR; PG8_MMA(0, 0, At, B0); PG8_MMA(0, 1, At, B1); PG8_BAR; PG8_SCHED;
;             PG8_LDA(At, 0, 1); PG8_STAGE(PG8_SB(0, 0), b2, vB2, hB2 / 2); PG8_STAGE(PG8_SB(0, 1), b2 + hB2, vB2, hB2 / 2); PG8_STAGE(PG8_SA(0, 0), a2, vA2, hA2 / 2);
.LBB0_844:
	v_add_u32_e32 v142, 0x10000, v175
	v_add_u32_e32 v154, 0x14000, v175
	ds_read_b128 v[130:133], v142
	ds_read_b128 v[134:137], v142 offset:1024
	ds_read_b128 v[138:141], v142 offset:2048
	ds_read_b128 v[142:145], v142 offset:3072
	ds_read_b128 v[146:149], v154
	ds_read_b128 v[150:153], v154 offset:1024
	ds_read_b128 v[158:161], v154 offset:2048
	ds_read_b128 v[162:165], v154 offset:3072
	s_add_i32 s80, s8, 2
	s_cmp_eq_u32 s73, s8
	s_cselect_b32 s8, s56, s76
	s_cselect_b32 s9, s57, s77
	s_cselect_b32 s22, s58, s78
	s_cselect_b32 s23, s59, s79
	s_add_u32 s16, s8, 0x80
	s_addc_u32 s17, s9, 0
	ds_read_b128 v[180:183], v177
	ds_read_b128 v[184:187], v177 offset:1024
	ds_read_b128 v[188:191], v177 offset:2048
	ds_read_b128 v[192:195], v177 offset:3072
	ds_read_b128 v[196:199], v177 offset:4096
	ds_read_b128 v[200:203], v177 offset:5120
	ds_read_b128 v[204:207], v177 offset:6144
	ds_read_b128 v[208:211], v177 offset:7168
	s_add_u32 s30, s76, 0x3ff80
	s_mov_b32 m0, s66
	s_addc_u32 s31, s77, 0
	global_load_lds_dwordx4 v172, s[30:31]
	s_add_u32 s30, s76, 0x5ff80
	s_mov_b32 m0, s67
	s_addc_u32 s31, s77, 0
	global_load_lds_dwordx4 v172, s[30:31]
	s_waitcnt vmcnt(8) lgkmcnt(0)
	s_barrier
	v_mfma_f32_16x16x32_bf16 v[124:127], v[130:133], v[180:183], v[124:127]
	v_mfma_f32_16x16x32_bf16 v[120:123], v[138:141], v[180:183], v[120:123]
	v_mfma_f32_16x16x32_bf16 v[116:119], v[130:133], v[188:191], v[116:119]
	v_mfma_f32_16x16x32_bf16 v[112:115], v[138:141], v[188:191], v[112:115]
	v_mfma_f32_16x16x32_bf16 v[108:111], v[130:133], v[196:199], v[108:111]
	v_mfma_f32_16x16x32_bf16 v[104:107], v[138:141], v[196:199], v[104:107]
	v_mfma_f32_16x16x32_bf16 v[100:103], v[130:133], v[204:207], v[100:103]
	v_mfma_f32_16x16x32_bf16 v[96:99], v[138:141], v[204:207], v[96:99]
	v_mfma_f32_16x16x32_bf16 v[124:127], v[134:137], v[184:187], v[124:127]
	v_mfma_f32_16x16x32_bf16 v[120:123], v[142:145], v[184:187], v[120:123]
	v_mfma_f32_16x16x32_bf16 v[116:119], v[134:137], v[192:195], v[116:119]
	v_mfma_f32_16x16x32_bf16 v[112:115], v[142:145], v[192:195], v[112:115]
	v_mfma_f32_16x16x32_bf16 v[108:111], v[134:137], v[200:203], v[108:111]
	v_mfma_f32_16x16x32_bf16 v[104:107], v[142:145], v[200:203], v[104:107]
	v_mfma_f32_16x16x32_bf16 v[100:103], v[134:137], v[208:211], v[100:103]
	v_mfma_f32_16x16x32_bf16 v[96:99], v[142:145], v[208:211], v[96:99]
	v_mfma_f32_16x16x32_bf16 v[92:95], v[146:149], v[180:183], v[92:95]
	v_mfma_f32_16x16x32_bf16 v[88:91], v[158:161], v[180:183], v[88:91]
	v_mfma_f32_16x16x32_bf16 v[84:87], v[146:149], v[188:191], v[84:87]
	v_mfma_f32_16x16x32_bf16 v[80:83], v[158:161], v[188:191], v[80:83]
	v_mfma_f32_16x16x32_bf16 v[76:79], v[146:149], v[196:199], v[76:79]
	v_mfma_f32_16x16x32_bf16 v[72:75], v[158:161], v[196:199], v[72:75]
	v_mfma_f32_16x16x32_bf16 v[68:71], v[146:149], v[204:207], v[68:71]
	v_mfma_f32_16x16x32_bf16 v[64:67], v[158:161], v[204:207], v[64:67]
	v_mfma_f32_16x16x32_bf16 v[92:95], v[150:153], v[184:187], v[92:95]
	v_mfma_f32_16x16x32_bf16 v[88:91], v[162:165], v[184:187], v[88:91]
	v_mfma_f32_16x16x32_bf16 v[84:87], v[150:153], v[192:195], v[84:87]
	v_mfma_f32_16x16x32_bf16 v[80:83], v[162:165], v[192:195], v[80:83]
	v_mfma_f32_16x16x32_bf16 v[76:79], v[150:153], v[200:203], v[76:79]
	v_mfma_f32_16x16x32_bf16 v[72:75], v[162:165], v[200:203], v[72:75]
	v_mfma_f32_16x16x32_bf16 v[68:71], v[150:153], v[208:211], v[68:71]
	v_mfma_f32_16x16x32_bf16 v[64:67], v[162:165], v[208:211], v[64:67]
	s_add_u32 s76, s76, 0x100
	s_addc_u32 s77, s77, 0
	s_add_u32 s78, s78, 0x100
	s_addc_u32 s79, s79, 0
	s_barrier
	s_add_u32 s30, s22, 0x10000
	ds_read_b128 v[180:183], v177 offset:16384
	ds_read_b128 v[184:187], v177 offset:17408
	ds_read_b128 v[188:191], v177 offset:18432
	ds_read_b128 v[192:195], v177 offset:19456
	ds_read_b128 v[196:199], v177 offset:20480
	ds_read_b128 v[200:203], v177 offset:21504
	ds_read_b128 v[204:207], v177 offset:22528
	ds_read_b128 v[208:211], v177 offset:23552
	s_mov_b32 m0, s5
	s_nop 0
	global_load_lds_dwordx4 v128, s[22:23]
	s_mov_b32 m0, s12
	s_addc_u32 s31, s23, 0
	global_load_lds_dwordx4 v128, s[30:31]
	s_add_u32 s30, s22, 0x20000
	s_mov_b32 m0, s14
	s_addc_u32 s31, s23, 0
	global_load_lds_dwordx4 v128, s[30:31]
	s_add_u32 s30, s22, 0x30000
	s_mov_b32 m0, s15
	s_addc_u32 s31, s23, 0
	global_load_lds_dwordx4 v128, s[30:31]
	s_mov_b32 m0, s4
	s_nop 0
	global_load_lds_dwordx4 v172, s[8:9]
	s_add_u32 s30, s8, 0x20000
	s_mov_b32 m0, s24
	s_addc_u32 s31, s9, 0
	global_load_lds_dwordx4 v172, s[30:31]
	s_waitcnt vmcnt(8) lgkmcnt(0)
	s_barrier
; #define PG8_STAGE(bufoff, gbase, voff, p64) do { _Pragma("unroll") for (int _i = 0; _i < 2; ++_i) { \
;         const char* _gb = (const char*)(gbase) + (size_t)_i * (p64); const unsigned _la = ldsbase + (unsigned)(bufoff) + (unsigned)_i * 8192u; \
;         asm volatile("s_mov_b32 m0, %0\n\ts_nop 0\n\tglobal_load_lds_dwordx4 %1, %2" :: "s"(_la), "v"(voff), "s"(_gb) : "memory"); } } while (0)
; #define PG8_LDA(dst, b, h) do { _Pragma("unroll") for (int m = 0; m < 4; ++m) _Pragma("unroll") for (int k = 0; k < 2; ++k) dst[m][k] = *(const LAS bf16x8*)(lds + PG8_SA(b, h) + aoff + m * 2048 + k * 1024); } while (0)
; #define PG8_LDB(dst, b, h) do { _Pragma("unroll") for (int n = 0; n < 2; ++n) _Pragma("unroll") for (int k = 0; k < 2; ++k) dst[n][k] = *(const LAS bf16x8*)(lds + PG8_SB(b, h) + boff + n * 2048 + k * 1024); } while (0)
; #define PG8_MMA(ai, bj, At, Bt) do { __builtin_amdgcn_s_setprio(1); _Pragma("unroll") for (int m = 0; m < 4; ++m) _Pragma("unroll") for (int n = 0; n < 2; ++n) _Pragma("unroll") for (int k = 0; k < 2; ++k) \
;         acc[ai][bj][m][n] = __builtin_amdgcn_mfma_f32_16x16x32_bf16(Bt[n][k], At[m][k], acc[ai][bj][m][n], 0, 0, 0); __builtin_amdgcn_s_setprio(0); } while (0)
; #define PG8_WAIT_V(n) asm volatile("s_waitcnt vmcnt(" #n ")" ::: "memory")
; #define PG8_WAIT_L(n) asm volatile("s_waitcnt lgkmcnt(" #n ")" ::: "memory")
; #define PG8_BAR __builtin_amdgcn_s_barrier()
; #define PG8_SCHED __builtin_amdgcn_sched_barrier(0)
; template <class Epi, class Sched>
; __device__ __forceinline__ void gemm_phase(LAS unsigned char* lds, const Sched& S, const Epi& E) {
;     ...
;             PG8_WAIT_V(8); PG8_WAIT_L(0); PG8_BAR; PG8_MMA(1, 0, At, B0); PG8_MMA(1, 1, At, B1); PG8_BAR; PG8_SCHED;
;             PG8_LDB(B0, 1, 0); PG8_LDB(B1, 1, 1); PG8_SCHED; PG8_LDA(At, 1, 0); PG8_STAGE(PG8_SA(0, 1), a2 + hA2, vA2, hA2 / 2);
;             PG8_WAIT_V(8); PG8_WAIT_L(0); PG8_BAR; PG8_MMA(0, 0, At, B0); PG8_MMA(0, 1, At, B1); PG8_BAR; PG8_SCHED;
	v_mfma_f32_16x16x32_bf16 v[60:63], v[130:133], v[180:183], v[60:63]
	v_mfma_f32_16x16x32_bf16 v[56:59], v[138:141], v[180:183], v[56:59]
	v_mfma_f32_16x16x32_bf16 v[52:55], v[130:133], v[188:191], v[52:55]
	v_mfma_f32_16x16x32_bf16 v[48:51], v[138:141], v[188:191], v[48:51]
	v_mfma_f32_16x16x32_bf16 v[44:47], v[130:133], v[196:199], v[44:47]
	v_mfma_f32_16x16x32_bf16 v[40:43], v[138:141], v[196:199], v[40:43]
	v_mfma_f32_16x16x32_bf16 v[36:39], v[130:133], v[204:207], v[36:39]
	v_mfma_f32_16x16x32_bf16 v[32:35], v[138:141], v[204:207], v[32:35]
	v_mfma_f32_16x16x32_bf16 v[60:63], v[134:137], v[184:187], v[60:63]
	v_mfma_f32_16x16x32_bf16 v[56:59], v[142:145], v[184:187], v[56:59]
	v_mfma_f32_16x16x32_bf16 v[52:55], v[134:137], v[192:195], v[52:55]
	v_mfma_f32_16x16x32_bf16 v[48:51], v[142:145], v[192:195], v[48:51]
	v_mfma_f32_16x16x32_bf16 v[44:47], v[134:137], v[200:203], v[44:47]
	v_mfma_f32_16x16x32_bf16 v[40:43], v[142:145], v[200:203], v[40:43]
	v_mfma_f32_16x16x32_bf16 v[36:39], v[134:137], v[208:211], v[36:39]
	v_mfma_f32_16x16x32_bf16 v[32:35], v[142:145], v[208:211], v[32:35]
	v_mfma_f32_16x16x32_bf16 v[28:31], v[146:149], v[180:183], v[28:31]
	v_mfma_f32_16x16x32_bf16 v[24:27], v[158:161], v[180:183], v[24:27]
	v_mfma_f32_16x16x32_bf16 v[20:23], v[146:149], v[188:191], v[20:23]
	v_mfma_f32_16x16x32_bf16 v[16:19], v[158:161], v[188:191], v[16:19]
	v_mfma_f32_16x16x32_bf16 v[12:15], v[146:149], v[196:199], v[12:15]
	v_mfma_f32_16x16x32_bf16 v[8:11], v[158:161], v[196:199], v[8:11]
	v_mfma_f32_16x16x32_bf16 v[4:7], v[146:149], v[204:207], v[4:7]
	v_mfma_f32_16x16x32_bf16 v[0:3], v[158:161], v[204:207], v[0:3]
	v_mfma_f32_16x16x32_bf16 v[28:31], v[150:153], v[184:187], v[28:31]
	v_mfma_f32_16x16x32_bf16 v[24:27], v[162:165], v[184:187], v[24:27]
	v_mfma_f32_16x16x32_bf16 v[20:23], v[150:153], v[192:195], v[20:23]
	v_mfma_f32_16x16x32_bf16 v[16:19], v[162:165], v[192:195], v[16:19]
	v_mfma_f32_16x16x32_bf16 v[12:15], v[150:153], v[200:203], v[12:15]
	v_mfma_f32_16x16x32_bf16 v[8:11], v[162:165], v[200:203], v[8:11]
	v_mfma_f32_16x16x32_bf16 v[4:7], v[150:153], v[208:211], v[4:7]
	v_mfma_f32_16x16x32_bf16 v[0:3], v[162:165], v[208:211], v[0:3]
	s_barrier
	v_add_u32_e32 v142, 0x18000, v175
	v_add_u32_e32 v154, 0x1c000, v175
	ds_read_b128 v[130:133], v142
	ds_read_b128 v[134:137], v142 offset:1024
	ds_read_b128 v[138:141], v142 offset:2048
	ds_read_b128 v[142:145], v142 offset:3072
	ds_read_b128 v[146:149], v154
	ds_read_b128 v[150:153], v154 offset:1024
	ds_read_b128 v[158:161], v154 offset:2048
	ds_read_b128 v[162:165], v154 offset:3072
	ds_read_b128 v[180:183], v177 offset:32768
	ds_read_b128 v[184:187], v177 offset:33792
	ds_read_b128 v[188:191], v177 offset:34816
	ds_read_b128 v[192:195], v177 offset:35840
	ds_read_b128 v[196:199], v177 offset:36864
	ds_read_b128 v[200:203], v177 offset:37888
	ds_read_b128 v[204:207], v177 offset:38912
	ds_read_b128 v[208:211], v177 offset:39936
	s_add_u32 s30, s8, 0x40000
	s_mov_b32 m0, s33
	s_addc_u32 s31, s9, 0
	global_load_lds_dwordx4 v172, s[30:31]
	s_add_u32 s30, s8, 0x60000
	s_mov_b32 m0, s34
	s_addc_u32 s31, s9, 0
	global_load_lds_dwordx4 v172, s[30:31]
	s_waitcnt vmcnt(8) lgkmcnt(0)
	s_barrier
	v_mfma_f32_16x16x32_bf16 v[124:127], v[130:133], v[180:183], v[124:127]
	v_mfma_f32_16x16x32_bf16 v[120:123], v[138:141], v[180:183], v[120:123]
	v_mfma_f32_16x16x32_bf16 v[116:119], v[130:133], v[188:191], v[116:119]
	v_mfma_f32_16x16x32_bf16 v[112:115], v[138:141], v[188:191], v[112:115]
	v_mfma_f32_16x16x32_bf16 v[108:111], v[130:133], v[196:199], v[108:111]
	v_mfma_f32_16x16x32_bf16 v[104:107], v[138:141], v[196:199], v[104:107]
	v_mfma_f32_16x16x32_bf16 v[100:103], v[130:133], v[204:207], v[100:103]
	v_mfma_f32_16x16x32_bf16 v[96:99], v[138:141], v[204:207], v[96:99]
	v_mfma_f32_16x16x32_bf16 v[124:127], v[134:137], v[184:187], v[124:127]
	v_mfma_f32_16x16x32_bf16 v[120:123], v[142:145], v[184:187], v[120:123]
	v_mfma_f32_16x16x32_bf16 v[116:119], v[134:137], v[192:195], v[116:119]
	v_mfma_f32_16x16x32_bf16 v[112:115], v[142:145], v[192:195], v[112:115]
	v_mfma_f32_16x16x32_bf16 v[108:111], v[134:137], v[200:203], v[108:111]
	v_mfma_f32_16x16x32_bf16 v[104:107], v[142:145], v[200:203], v[104:107]
	v_mfma_f32_16x16x32_bf16 v[100:103], v[134:137], v[208:211], v[100:103]
	v_mfma_f32_16x16x32_bf16 v[96:99], v[142:145], v[208:211], v[96:99]
	v_mfma_f32_16x16x32_bf16 v[92:95], v[146:149], v[180:183], v[92:95]
	v_mfma_f32_16x16x32_bf16 v[88:91], v[158:161], v[180:183], v[88:91]
	v_mfma_f32_16x16x32_bf16 v[84:87], v[146:149], v[188:191], v[84:87]
	v_mfma_f32_16x16x32_bf16 v[80:83], v[158:161], v[188:191], v[80:83]
	v_mfma_f32_16x16x32_bf16 v[76:79], v[146:149], v[196:199], v[76:79]
	v_mfma_f32_16x16x32_bf16 v[72:75], v[158:161], v[196:199], v[72:75]
	v_mfma_f32_16x16x32_bf16 v[68:71], v[146:149], v[204:207], v[68:71]
	v_mfma_f32_16x16x32_bf16 v[64:67], v[158:161], v[204:207], v[64:67]
	v_mfma_f32_16x16x32_bf16 v[92:95], v[150:153], v[184:187], v[92:95]
	v_mfma_f32_16x16x32_bf16 v[88:91], v[162:165], v[184:187], v[88:91]
	v_mfma_f32_16x16x32_bf16 v[84:87], v[150:153], v[192:195], v[84:87]
	v_mfma_f32_16x16x32_bf16 v[80:83], v[162:165], v[192:195], v[80:83]
	v_mfma_f32_16x16x32_bf16 v[76:79], v[150:153], v[200:203], v[76:79]
	v_mfma_f32_16x16x32_bf16 v[72:75], v[162:165], v[200:203], v[72:75]
	v_mfma_f32_16x16x32_bf16 v[68:71], v[150:153], v[208:211], v[68:71]
	v_mfma_f32_16x16x32_bf16 v[64:67], v[162:165], v[208:211], v[64:67]
	s_barrier
; #define PG8_STAGE(bufoff, gbase, voff, p64) do { _Pragma("unroll") for (int _i = 0; _i < 2; ++_i) { \
;         const char* _gb = (const char*)(gbase) + (size_t)_i * (p64); const unsigned _la = ldsbase + (unsigned)(bufoff) + (unsigned)_i * 8192u; \
;         asm volatile("s_mov_b32 m0, %0\n\ts_nop 0\n\tglobal_load_lds_dwordx4 %1, %2" :: "s"(_la), "v"(voff), "s"(_gb) : "memory"); } } while (0)
; #define PG8_LDA(dst, b, h) do { _Pragma("unroll") for (int m = 0; m < 4; ++m) _Pragma("unroll") for (int k = 0; k < 2; ++k) dst[m][k] = *(const LAS bf16x8*)(lds + PG8_SA(b, h) + aoff + m * 2048 + k * 1024); } while (0)
; #define PG8_MMA(ai, bj, At, Bt) do { __builtin_amdgcn_s_setprio(1); _Pragma("unroll") for (int m = 0; m < 4; ++m) _Pragma("unroll") for (int n = 0; n < 2; ++n) _Pragma("unroll") for (int k = 0; k < 2; ++k) \
;         acc[ai][bj][m][n] = __builtin_amdgcn_mfma_f32_16x16x32_bf16(Bt[n][k], At[m][k], acc[ai][bj][m][n], 0, 0, 0); __builtin_amdgcn_s_setprio(0); } while (0)
; #define PG8_WAIT_V(n) asm volatile("s_waitcnt vmcnt(" #n ")" ::: "memory")
; #define PG8_WAIT_L(n) asm volatile("s_waitcnt lgkmcnt(" #n ")" ::: "memory")
; #define PG8_BAR __builtin_amdgcn_s_barrier()
; #define PG8_SCHED __builtin_amdgcn_sched_barrier(0)
; template <class Epi, class Sched>
; __device__ __forceinline__ void gemm_phase(LAS unsigned char* lds, const Sched& S, const Epi& E) {
;     ...
;             PG8_LDA(At, 1, 1); PG8_STAGE(PG8_SB(1, 0), b3, vB2, hB2 / 2); PG8_STAGE(PG8_SB(1, 1), b3 + hB2, vB2, hB2 / 2); PG8_STAGE(PG8_SA(1, 0), a3, vA2, hA2 / 2);
;             PG8_WAIT_V(8); PG8_WAIT_L(0); PG8_BAR; PG8_MMA(1, 0, At, B0); PG8_MMA(1, 1, At, B1); PG8_BAR; PG8_SCHED;
;         }
;         if (wr == 0) PG8_BAR;
	s_add_u32 s30, s22, 0x80
	s_addc_u32 s31, s23, 0
	ds_read_b128 v[180:183], v177 offset:49152
	ds_read_b128 v[184:187], v177 offset:50176
	ds_read_b128 v[188:191], v177 offset:51200
	ds_read_b128 v[192:195], v177 offset:52224
	ds_read_b128 v[196:199], v177 offset:53248
	ds_read_b128 v[200:203], v177 offset:54272
	ds_read_b128 v[204:207], v177 offset:55296
	ds_read_b128 v[208:211], v177 offset:56320
	s_mov_b32 m0, s51
	s_nop 0
	global_load_lds_dwordx4 v128, s[30:31]
	s_add_u32 s30, s22, 0x10080
	s_mov_b32 m0, s61
	s_addc_u32 s31, s23, 0
	global_load_lds_dwordx4 v128, s[30:31]
	s_add_u32 s30, s22, 0x20080
	s_mov_b32 m0, s64
	s_addc_u32 s31, s23, 0
	global_load_lds_dwordx4 v128, s[30:31]
	s_add_u32 s22, s22, 0x30080
	s_mov_b32 m0, s65
	s_addc_u32 s23, s23, 0
	global_load_lds_dwordx4 v128, s[22:23]
	s_mov_b32 m0, s62
	s_nop 0
	global_load_lds_dwordx4 v172, s[16:17]
	s_add_u32 s8, s8, 0x20080
	s_mov_b32 m0, s63
	s_addc_u32 s9, s9, 0
	global_load_lds_dwordx4 v172, s[8:9]
	s_waitcnt vmcnt(8) lgkmcnt(0)
	s_barrier
	v_mfma_f32_16x16x32_bf16 v[60:63], v[130:133], v[180:183], v[60:63]
	v_mfma_f32_16x16x32_bf16 v[56:59], v[138:141], v[180:183], v[56:59]
	v_mfma_f32_16x16x32_bf16 v[52:55], v[130:133], v[188:191], v[52:55]
	v_mfma_f32_16x16x32_bf16 v[48:51], v[138:141], v[188:191], v[48:51]
	v_mfma_f32_16x16x32_bf16 v[44:47], v[130:133], v[196:199], v[44:47]
	v_mfma_f32_16x16x32_bf16 v[40:43], v[138:141], v[196:199], v[40:43]
	v_mfma_f32_16x16x32_bf16 v[36:39], v[130:133], v[204:207], v[36:39]
	v_mfma_f32_16x16x32_bf16 v[32:35], v[138:141], v[204:207], v[32:35]
	v_mfma_f32_16x16x32_bf16 v[60:63], v[134:137], v[184:187], v[60:63]
	v_mfma_f32_16x16x32_bf16 v[56:59], v[142:145], v[184:187], v[56:59]
	v_mfma_f32_16x16x32_bf16 v[52:55], v[134:137], v[192:195], v[52:55]
	v_mfma_f32_16x16x32_bf16 v[48:51], v[142:145], v[192:195], v[48:51]
	v_mfma_f32_16x16x32_bf16 v[44:47], v[134:137], v[200:203], v[44:47]
	v_mfma_f32_16x16x32_bf16 v[40:43], v[142:145], v[200:203], v[40:43]
	v_mfma_f32_16x16x32_bf16 v[36:39], v[134:137], v[208:211], v[36:39]
	v_mfma_f32_16x16x32_bf16 v[32:35], v[142:145], v[208:211], v[32:35]
	v_mfma_f32_16x16x32_bf16 v[28:31], v[146:149], v[180:183], v[28:31]
	v_mfma_f32_16x16x32_bf16 v[24:27], v[158:161], v[180:183], v[24:27]
	v_mfma_f32_16x16x32_bf16 v[20:23], v[146:149], v[188:191], v[20:23]
	v_mfma_f32_16x16x32_bf16 v[16:19], v[158:161], v[188:191], v[16:19]
	v_mfma_f32_16x16x32_bf16 v[12:15], v[146:149], v[196:199], v[12:15]
	v_mfma_f32_16x16x32_bf16 v[8:11], v[158:161], v[196:199], v[8:11]
	v_mfma_f32_16x16x32_bf16 v[4:7], v[146:149], v[204:207], v[4:7]
	v_mfma_f32_16x16x32_bf16 v[0:3], v[158:161], v[204:207], v[0:3]
	v_mfma_f32_16x16x32_bf16 v[28:31], v[150:153], v[184:187], v[28:31]
	v_mfma_f32_16x16x32_bf16 v[24:27], v[162:165], v[184:187], v[24:27]
	v_mfma_f32_16x16x32_bf16 v[20:23], v[150:153], v[192:195], v[20:23]
	v_mfma_f32_16x16x32_bf16 v[16:19], v[162:165], v[192:195], v[16:19]
	v_mfma_f32_16x16x32_bf16 v[12:15], v[150:153], v[200:203], v[12:15]
	v_mfma_f32_16x16x32_bf16 v[8:11], v[162:165], v[200:203], v[8:11]
	v_mfma_f32_16x16x32_bf16 v[4:7], v[150:153], v[208:211], v[4:7]
	v_mfma_f32_16x16x32_bf16 v[0:3], v[162:165], v[208:211], v[0:3]
	s_barrier
	s_cmp_ge_u32 s80, s7
	s_mov_b32 s8, s80
	s_cbranch_scc0 .LBB0_844
	s_and_b64 vcc, exec, s[10:11]
	s_cbranch_vccz .LBB0_847
	s_barrier

; #define PG8_STAGE(bufoff, gbase, voff, p64) do { _Pragma("unroll") for (int _i = 0; _i < 2; ++_i) { \
;         const char* _gb = (const char*)(gbase) + (size_t)_i * (p64); const unsigned _la = ldsbase + (unsigned)(bufoff) + (unsigned)_i * 8192u; \
;         asm volatile("s_mov_b32 m0, %0\n\ts_nop 0\n\tglobal_load_lds_dwordx4 %1, %2" :: "s"(_la), "v"(voff), "s"(_gb) : "memory"); } } while (0)
; #define PG8_LDA(dst, b, h) do { _Pragma("unroll") for (int m = 0; m < 4; ++m) _Pragma("unroll") for (int k = 0; k < 2; ++k) dst[m][k] = *(const LAS bf16x8*)(lds + PG8_SA(b, h) + aoff + m * 2048 + k * 1024); } while (0)
; #define PG8_LDB(dst, b, h) do { _Pragma("unroll") for (int n = 0; n < 2; ++n) _Pragma("unroll") for (int k = 0; k < 2; ++k) dst[n][k] = *(const LAS bf16x8*)(lds + PG8_SB(b, h) + boff + n * 2048 + k * 1024); } while (0)
; #define PG8_MMA(ai, bj, At, Bt) do { __builtin_amdgcn_s_setprio(1); _Pragma("unroll") for (int m = 0; m < 4; ++m) _Pragma("unroll") for (int n = 0; n < 2; ++n) _Pragma("unroll") for (int k = 0; k < 2; ++k) \
;         acc[ai][bj][m][n] = __builtin_amdgcn_mfma_f32_16x16x32_bf16(Bt[n][k], At[m][k], acc[ai][bj][m][n], 0, 0, 0); __builtin_amdgcn_s_setprio(0); } while (0)
; #define PG8_WAIT_V(n) asm volatile("s_waitcnt vmcnt(" #n ")" ::: "memory")
; #define PG8_BAR __builtin_amdgcn_s_barrier()
; template <class Epi, class Sched>
; __device__ __forceinline__ void gemm_phase(LAS unsigned char* lds, const Sched& S, const Epi& E) {
;     ...
;             const bool last = (t == nt - 2);
;             const char* a1 = cA + (size_t)(t + 1) * kstep;
;             const char* a2 = last ? nA : cA + (size_t)(t + 2) * kstep; const char* b2 = last ? nB : cB + (size_t)(t + 2) * kstep;
;             const char* a3 = a2 + kstep; const char* b3 = b2 + kstep;
;             const unsigned vA2 = voffA, vB2 = voffB, hA2 = hA, hB2 = hB;
;             PG8_LDB(B0, 0, 0); PG8_LDB(B1, 0, 1); PG8_SCHED; PG8_LDA(At, 0, 0); PG8_STAGE(PG8_SA(1, 1), a1 + hA, voffA, hA / 2);
;             PG8_WAIT_V(8); PG8_WAIT_L(0); PG8_BAR; PG8_MMA(0, 0, At, B0); PG8_MMA(0, 1, At, B1); PG8_BAR; PG8_SCHED;
;             PG8_LDA(At, 0, 1); PG8_STAGE(PG8_SB(0, 0), b2, vB2, hB2 / 2); PG8_STAGE(PG8_SB(0, 1), b2 + hB2, vB2, hB2 / 2); PG8_STAGE(PG8_SA(0, 0), a2, vA2, hA2 / 2);
;             PG8_WAIT_V(8); PG8_WAIT_L(0); PG8_BAR; PG8_MMA(1, 0, At, B0); PG8_MMA(1, 1, At, B1); PG8_BAR; PG8_SCHED;
.LBB0_980:
	s_add_u32 s26, s26, 0x40080
	s_addc_u32 s27, s27, 0
	s_add_u32 s62, s38, 0x100
	s_addc_u32 s63, s39, 0
	s_mov_b32 s65, -2
	s_waitcnt vmcnt(3)
	s_waitcnt vmcnt(2)
	s_waitcnt vmcnt(1)
	s_waitcnt vmcnt(0)
	ds_read_b128 v[112:115], v162
	ds_read_b128 v[116:119], v162 offset:1024
	ds_read_b128 v[140:143], v162 offset:2048
	ds_read_b128 v[144:147], v162 offset:3072
	ds_read_b128 v[148:151], v163
	ds_read_b128 v[152:155], v163 offset:1024
	ds_read_b128 v[168:171], v163 offset:2048
	ds_read_b128 v[172:175], v163 offset:3072
	s_add_u32 s30, s26, 0xfffc0080
	s_addc_u32 s38, s27, -1
	s_cmp_eq_u32 s65, 12
	s_cselect_b32 s39, s23, s38
	s_cselect_b32 s38, s22, s30
	s_cselect_b32 s42, s24, s62
	s_cselect_b32 s43, s25, s63
	s_add_u32 s40, s38, 0x80
	s_addc_u32 s41, s39, 0
	ds_read_b128 v[178:181], v164
	ds_read_b128 v[182:185], v164 offset:1024
	ds_read_b128 v[186:189], v164 offset:2048
	ds_read_b128 v[190:193], v164 offset:3072
	ds_read_b128 v[194:197], v164 offset:4096
	ds_read_b128 v[198:201], v164 offset:5120
	ds_read_b128 v[202:205], v164 offset:6144
	ds_read_b128 v[206:209], v164 offset:7168
	s_mov_b32 m0, s58
	s_nop 0
	global_load_lds_dwordx4 v158, s[26:27]
	s_add_u32 s66, s26, 0x20000
	s_mov_b32 m0, s59
	s_addc_u32 s67, s27, 0
	global_load_lds_dwordx4 v158, s[66:67]
	s_waitcnt vmcnt(8) lgkmcnt(0)
	s_barrier
	v_mfma_f32_16x16x32_bf16 v[132:135], v[112:115], v[178:181], 0
	v_mfma_f32_16x16x32_bf16 v[128:131], v[140:143], v[178:181], 0
	v_mfma_f32_16x16x32_bf16 v[124:127], v[112:115], v[186:189], 0
	v_mfma_f32_16x16x32_bf16 v[120:123], v[140:143], v[186:189], 0
	v_mfma_f32_16x16x32_bf16 v[108:111], v[112:115], v[194:197], 0
	v_mfma_f32_16x16x32_bf16 v[104:107], v[140:143], v[194:197], 0
	v_mfma_f32_16x16x32_bf16 v[100:103], v[112:115], v[202:205], 0
	v_mfma_f32_16x16x32_bf16 v[96:99], v[140:143], v[202:205], 0
	v_mfma_f32_16x16x32_bf16 v[132:135], v[116:119], v[182:185], v[132:135]
	v_mfma_f32_16x16x32_bf16 v[128:131], v[144:147], v[182:185], v[128:131]
	v_mfma_f32_16x16x32_bf16 v[124:127], v[116:119], v[190:193], v[124:127]
	v_mfma_f32_16x16x32_bf16 v[120:123], v[144:147], v[190:193], v[120:123]
	v_mfma_f32_16x16x32_bf16 v[108:111], v[116:119], v[198:201], v[108:111]
	v_mfma_f32_16x16x32_bf16 v[104:107], v[144:147], v[198:201], v[104:107]
	v_mfma_f32_16x16x32_bf16 v[100:103], v[116:119], v[206:209], v[100:103]
	v_mfma_f32_16x16x32_bf16 v[96:99], v[144:147], v[206:209], v[96:99]
	v_mfma_f32_16x16x32_bf16 v[60:63], v[148:151], v[178:181], 0
	v_mfma_f32_16x16x32_bf16 v[56:59], v[168:171], v[178:181], 0
	v_mfma_f32_16x16x32_bf16 v[52:55], v[148:151], v[186:189], 0
	v_mfma_f32_16x16x32_bf16 v[48:51], v[168:171], v[186:189], 0
	v_mfma_f32_16x16x32_bf16 v[44:47], v[148:151], v[194:197], 0
	v_mfma_f32_16x16x32_bf16 v[40:43], v[168:171], v[194:197], 0
	v_mfma_f32_16x16x32_bf16 v[36:39], v[148:151], v[202:205], 0
	v_mfma_f32_16x16x32_bf16 v[32:35], v[168:171], v[202:205], 0
	v_mfma_f32_16x16x32_bf16 v[60:63], v[152:155], v[182:185], v[60:63]
	v_mfma_f32_16x16x32_bf16 v[56:59], v[172:175], v[182:185], v[56:59]
	v_mfma_f32_16x16x32_bf16 v[52:55], v[152:155], v[190:193], v[52:55]
	v_mfma_f32_16x16x32_bf16 v[48:51], v[172:175], v[190:193], v[48:51]
	v_mfma_f32_16x16x32_bf16 v[44:47], v[152:155], v[198:201], v[44:47]
	v_mfma_f32_16x16x32_bf16 v[40:43], v[172:175], v[198:201], v[40:43]
	v_mfma_f32_16x16x32_bf16 v[36:39], v[152:155], v[206:209], v[36:39]
	v_mfma_f32_16x16x32_bf16 v[32:35], v[172:175], v[206:209], v[32:35]
	s_add_i32 s65, s65, 2
	s_add_u32 s26, s26, 0x100
	s_addc_u32 s27, s27, 0
	s_add_u32 s62, s62, 0x100
	s_addc_u32 s63, s63, 0
	s_barrier
	s_add_u32 s66, s42, 0x20000
	ds_read_b128 v[178:181], v164 offset:16384
	ds_read_b128 v[182:185], v164 offset:17408
	ds_read_b128 v[186:189], v164 offset:18432
	ds_read_b128 v[190:193], v164 offset:19456
	ds_read_b128 v[194:197], v164 offset:20480
	ds_read_b128 v[198:201], v164 offset:21504
	ds_read_b128 v[202:205], v164 offset:22528
	ds_read_b128 v[206:209], v164 offset:23552
	s_mov_b32 m0, s35
	s_nop 0
	global_load_lds_dwordx4 v159, s[42:43]
	s_mov_b32 m0, s36
	s_addc_u32 s67, s43, 0
	global_load_lds_dwordx4 v159, s[66:67]
	s_add_u32 s66, s42, 0x40000
	s_mov_b32 m0, s37
	s_addc_u32 s67, s43, 0
	global_load_lds_dwordx4 v159, s[66:67]
	s_add_u32 s66, s42, 0x60000
	s_mov_b32 m0, s44
	s_addc_u32 s67, s43, 0
	global_load_lds_dwordx4 v159, s[66:67]
	s_mov_b32 m0, s34
	s_nop 0
	global_load_lds_dwordx4 v158, s[38:39]
	s_add_u32 s66, s38, 0x20000
	s_mov_b32 m0, s45
	s_addc_u32 s67, s39, 0
	global_load_lds_dwordx4 v158, s[66:67]
	s_waitcnt vmcnt(8) lgkmcnt(0)
	s_barrier
	v_mfma_f32_16x16x32_bf16 v[92:95], v[112:115], v[178:181], 0
	v_mfma_f32_16x16x32_bf16 v[88:91], v[140:143], v[178:181], 0
	v_mfma_f32_16x16x32_bf16 v[84:87], v[112:115], v[186:189], 0
	v_mfma_f32_16x16x32_bf16 v[80:83], v[140:143], v[186:189], 0
	v_mfma_f32_16x16x32_bf16 v[76:79], v[112:115], v[194:197], 0
	v_mfma_f32_16x16x32_bf16 v[72:75], v[140:143], v[194:197], 0
	v_mfma_f32_16x16x32_bf16 v[68:71], v[112:115], v[202:205], 0
	v_mfma_f32_16x16x32_bf16 v[64:67], v[140:143], v[202:205], 0
	v_mfma_f32_16x16x32_bf16 v[92:95], v[116:119], v[182:185], v[92:95]
	v_mfma_f32_16x16x32_bf16 v[88:91], v[144:147], v[182:185], v[88:91]
	v_mfma_f32_16x16x32_bf16 v[84:87], v[116:119], v[190:193], v[84:87]
	v_mfma_f32_16x16x32_bf16 v[80:83], v[144:147], v[190:193], v[80:83]
	v_mfma_f32_16x16x32_bf16 v[76:79], v[116:119], v[198:201], v[76:79]
	v_mfma_f32_16x16x32_bf16 v[72:75], v[144:147], v[198:201], v[72:75]
	v_mfma_f32_16x16x32_bf16 v[68:71], v[116:119], v[206:209], v[68:71]
	v_mfma_f32_16x16x32_bf16 v[64:67], v[144:147], v[206:209], v[64:67]
	v_mfma_f32_16x16x32_bf16 v[28:31], v[148:151], v[178:181], 0
	v_mfma_f32_16x16x32_bf16 v[24:27], v[168:171], v[178:181], 0
	v_mfma_f32_16x16x32_bf16 v[20:23], v[148:151], v[186:189], 0
	v_mfma_f32_16x16x32_bf16 v[16:19], v[168:171], v[186:189], 0
	v_mfma_f32_16x16x32_bf16 v[12:15], v[148:151], v[194:197], 0
	v_mfma_f32_16x16x32_bf16 v[8:11], v[168:171], v[194:197], 0
	v_mfma_f32_16x16x32_bf16 v[4:7], v[148:151], v[202:205], 0
	v_mfma_f32_16x16x32_bf16 v[0:3], v[168:171], v[202:205], 0
	v_mfma_f32_16x16x32_bf16 v[28:31], v[152:155], v[182:185], v[28:31]
	v_mfma_f32_16x16x32_bf16 v[24:27], v[172:175], v[182:185], v[24:27]
	v_mfma_f32_16x16x32_bf16 v[20:23], v[152:155], v[190:193], v[20:23]
	v_mfma_f32_16x16x32_bf16 v[16:19], v[172:175], v[190:193], v[16:19]
	v_mfma_f32_16x16x32_bf16 v[12:15], v[152:155], v[198:201], v[12:15]
	v_mfma_f32_16x16x32_bf16 v[8:11], v[172:175], v[198:201], v[8:11]
	v_mfma_f32_16x16x32_bf16 v[4:7], v[152:155], v[206:209], v[4:7]
	v_mfma_f32_16x16x32_bf16 v[0:3], v[172:175], v[206:209], v[0:3]
	s_barrier
	s_branch .Lpeel_mid_28770
; #define PG8_STAGE(bufoff, gbase, voff, p64) do { _Pragma("unroll") for (int _i = 0; _i < 2; ++_i) { \
;         const char* _gb = (const char*)(gbase) + (size_t)_i * (p64); const unsigned _la = ldsbase + (unsigned)(bufoff) + (unsigned)_i * 8192u; \
;         asm volatile("s_mov_b32 m0, %0\n\ts_nop 0\n\tglobal_load_lds_dwordx4 %1, %2" :: "s"(_la), "v"(voff), "s"(_gb) : "memory"); } } while (0)
; #define PG8_LDA(dst, b, h) do { _Pragma("unroll") for (int m = 0; m < 4; ++m) _Pragma("unroll") for (int k = 0; k < 2; ++k) dst[m][k] = *(const LAS bf16x8*)(lds + PG8_SA(b, h) + aoff + m * 2048 + k * 1024); } while (0)
; #define PG8_LDB(dst, b, h) do { _Pragma("unroll") for (int n = 0; n < 2; ++n) _Pragma("unroll") for (int k = 0; k < 2; ++k) dst[n][k] = *(const LAS bf16x8*)(lds + PG8_SB(b, h) + boff + n * 2048 + k * 1024); } while (0)
; #define PG8_MMA(ai, bj, At, Bt) do { __builtin_amdgcn_s_setprio(1); _Pragma("unroll") for (int m = 0; m < 4; ++m) _Pragma("unroll") for (int n = 0; n < 2; ++n) _Pragma("unroll") for (int k = 0; k < 2; ++k) \
;         acc[ai][bj][m][n] = __builtin_amdgcn_mfma_f32_16x16x32_bf16(Bt[n][k], At[m][k], acc[ai][bj][m][n], 0, 0, 0); __builtin_amdgcn_s_setprio(0); } while (0)
; #define PG8_WAIT_V(n) asm volatile("s_waitcnt vmcnt(" #n ")" ::: "memory")
; #define PG8_WAIT_L(n) asm volatile("s_waitcnt lgkmcnt(" #n ")" ::: "memory")
; #define PG8_BAR __builtin_amdgcn_s_barrier()
; #define PG8_SCHED __builtin_amdgcn_sched_barrier(0)
; template <class Epi, class Sched>
; __device__ __forceinline__ void gemm_phase(LAS unsigned char* lds, const Sched& S, const Epi& E) {
;     ...
;             PG8_LDB(B0, 0, 0); PG8_LDB(B1, 0, 1); PG8_SCHED; PG8_LDA(At, 0, 0); PG8_STAGE(PG8_SA(1, 1), a1 + hA, voffA, hA / 2);
;             PG8_WAIT_V(8); PG8_WAIT_L(0); PG8_BAR; PG8_MMA(0, 0, At, B0); PG8_MMA(0, 1, At, B1); PG8_BAR; PG8_SCHED;
;             PG8_LDA(At, 0, 1); PG8_STAGE(PG8_SB(0, 0), b2, vB2, hB2 / 2); PG8_STAGE(PG8_SB(0, 1), b2 + hB2, vB2, hB2 / 2); PG8_STAGE(PG8_SA(0, 0), a2, vA2, hA2 / 2);
;             PG8_WAIT_V(8); PG8_WAIT_L(0); PG8_BAR; PG8_MMA(1, 0, At, B0); PG8_MMA(1, 1, At, B1); PG8_BAR; PG8_SCHED;
.LBB0_981:
	ds_read_b128 v[112:115], v162
	ds_read_b128 v[116:119], v162 offset:1024
	ds_read_b128 v[140:143], v162 offset:2048
	ds_read_b128 v[144:147], v162 offset:3072
	ds_read_b128 v[148:151], v163
	ds_read_b128 v[152:155], v163 offset:1024
	ds_read_b128 v[168:171], v163 offset:2048
	ds_read_b128 v[172:175], v163 offset:3072
	s_add_u32 s30, s26, 0xfffc0080
	s_addc_u32 s38, s27, -1
	s_cmp_eq_u32 s65, 12
	s_cselect_b32 s39, s23, s38
	s_cselect_b32 s38, s22, s30
	s_cselect_b32 s42, s24, s62
	s_cselect_b32 s43, s25, s63
	s_add_u32 s40, s38, 0x80
	s_addc_u32 s41, s39, 0
	ds_read_b128 v[178:181], v164
	ds_read_b128 v[182:185], v164 offset:1024
	ds_read_b128 v[186:189], v164 offset:2048
	ds_read_b128 v[190:193], v164 offset:3072
	ds_read_b128 v[194:197], v164 offset:4096
	ds_read_b128 v[198:201], v164 offset:5120
	ds_read_b128 v[202:205], v164 offset:6144
	ds_read_b128 v[206:209], v164 offset:7168
	s_mov_b32 m0, s58
	s_nop 0
	global_load_lds_dwordx4 v158, s[26:27]
	s_add_u32 s66, s26, 0x20000
	s_mov_b32 m0, s59
	s_addc_u32 s67, s27, 0
	global_load_lds_dwordx4 v158, s[66:67]
	s_waitcnt vmcnt(8) lgkmcnt(0)
	s_barrier
	v_mfma_f32_16x16x32_bf16 v[132:135], v[112:115], v[178:181], v[132:135]
	v_mfma_f32_16x16x32_bf16 v[128:131], v[140:143], v[178:181], v[128:131]
	v_mfma_f32_16x16x32_bf16 v[124:127], v[112:115], v[186:189], v[124:127]
	v_mfma_f32_16x16x32_bf16 v[120:123], v[140:143], v[186:189], v[120:123]
	v_mfma_f32_16x16x32_bf16 v[108:111], v[112:115], v[194:197], v[108:111]
	v_mfma_f32_16x16x32_bf16 v[104:107], v[140:143], v[194:197], v[104:107]
	v_mfma_f32_16x16x32_bf16 v[100:103], v[112:115], v[202:205], v[100:103]
	v_mfma_f32_16x16x32_bf16 v[96:99], v[140:143], v[202:205], v[96:99]
	v_mfma_f32_16x16x32_bf16 v[132:135], v[116:119], v[182:185], v[132:135]
	v_mfma_f32_16x16x32_bf16 v[128:131], v[144:147], v[182:185], v[128:131]
	v_mfma_f32_16x16x32_bf16 v[124:127], v[116:119], v[190:193], v[124:127]
	v_mfma_f32_16x16x32_bf16 v[120:123], v[144:147], v[190:193], v[120:123]
	v_mfma_f32_16x16x32_bf16 v[108:111], v[116:119], v[198:201], v[108:111]
	v_mfma_f32_16x16x32_bf16 v[104:107], v[144:147], v[198:201], v[104:107]
	v_mfma_f32_16x16x32_bf16 v[100:103], v[116:119], v[206:209], v[100:103]
	v_mfma_f32_16x16x32_bf16 v[96:99], v[144:147], v[206:209], v[96:99]
	v_mfma_f32_16x16x32_bf16 v[60:63], v[148:151], v[178:181], v[60:63]
	v_mfma_f32_16x16x32_bf16 v[56:59], v[168:171], v[178:181], v[56:59]
	v_mfma_f32_16x16x32_bf16 v[52:55], v[148:151], v[186:189], v[52:55]
	v_mfma_f32_16x16x32_bf16 v[48:51], v[168:171], v[186:189], v[48:51]
	v_mfma_f32_16x16x32_bf16 v[44:47], v[148:151], v[194:197], v[44:47]
	v_mfma_f32_16x16x32_bf16 v[40:43], v[168:171], v[194:197], v[40:43]
	v_mfma_f32_16x16x32_bf16 v[36:39], v[148:151], v[202:205], v[36:39]
	v_mfma_f32_16x16x32_bf16 v[32:35], v[168:171], v[202:205], v[32:35]
	v_mfma_f32_16x16x32_bf16 v[60:63], v[152:155], v[182:185], v[60:63]
	v_mfma_f32_16x16x32_bf16 v[56:59], v[172:175], v[182:185], v[56:59]
	v_mfma_f32_16x16x32_bf16 v[52:55], v[152:155], v[190:193], v[52:55]
	v_mfma_f32_16x16x32_bf16 v[48:51], v[172:175], v[190:193], v[48:51]
	v_mfma_f32_16x16x32_bf16 v[44:47], v[152:155], v[198:201], v[44:47]
	v_mfma_f32_16x16x32_bf16 v[40:43], v[172:175], v[198:201], v[40:43]
	v_mfma_f32_16x16x32_bf16 v[36:39], v[152:155], v[206:209], v[36:39]
	v_mfma_f32_16x16x32_bf16 v[32:35], v[172:175], v[206:209], v[32:35]
	s_add_i32 s65, s65, 2
	s_add_u32 s26, s26, 0x100
	s_addc_u32 s27, s27, 0
	s_add_u32 s62, s62, 0x100
	s_addc_u32 s63, s63, 0
	s_barrier
	s_add_u32 s66, s42, 0x20000
	ds_read_b128 v[178:181], v164 offset:16384
	ds_read_b128 v[182:185], v164 offset:17408
	ds_read_b128 v[186:189], v164 offset:18432
	ds_read_b128 v[190:193], v164 offset:19456
	ds_read_b128 v[194:197], v164 offset:20480
	ds_read_b128 v[198:201], v164 offset:21504
	ds_read_b128 v[202:205], v164 offset:22528
	ds_read_b128 v[206:209], v164 offset:23552
	s_mov_b32 m0, s35
	s_nop 0
	global_load_lds_dwordx4 v159, s[42:43]
	s_mov_b32 m0, s36
	s_addc_u32 s67, s43, 0
	global_load_lds_dwordx4 v159, s[66:67]
	s_add_u32 s66, s42, 0x40000
	s_mov_b32 m0, s37
	s_addc_u32 s67, s43, 0
	global_load_lds_dwordx4 v159, s[66:67]
	s_add_u32 s66, s42, 0x60000
	s_mov_b32 m0, s44
	s_addc_u32 s67, s43, 0
	global_load_lds_dwordx4 v159, s[66:67]
	s_mov_b32 m0, s34
	s_nop 0
	global_load_lds_dwordx4 v158, s[38:39]
	s_add_u32 s66, s38, 0x20000
	s_mov_b32 m0, s45
	s_addc_u32 s67, s39, 0
	global_load_lds_dwordx4 v158, s[66:67]
	s_waitcnt vmcnt(8) lgkmcnt(0)
	s_barrier
	v_mfma_f32_16x16x32_bf16 v[92:95], v[112:115], v[178:181], v[92:95]
	v_mfma_f32_16x16x32_bf16 v[88:91], v[140:143], v[178:181], v[88:91]
	v_mfma_f32_16x16x32_bf16 v[84:87], v[112:115], v[186:189], v[84:87]
	v_mfma_f32_16x16x32_bf16 v[80:83], v[140:143], v[186:189], v[80:83]
	v_mfma_f32_16x16x32_bf16 v[76:79], v[112:115], v[194:197], v[76:79]
	v_mfma_f32_16x16x32_bf16 v[72:75], v[140:143], v[194:197], v[72:75]
	v_mfma_f32_16x16x32_bf16 v[68:71], v[112:115], v[202:205], v[68:71]
	v_mfma_f32_16x16x32_bf16 v[64:67], v[140:143], v[202:205], v[64:67]
	v_mfma_f32_16x16x32_bf16 v[92:95], v[116:119], v[182:185], v[92:95]
	v_mfma_f32_16x16x32_bf16 v[88:91], v[144:147], v[182:185], v[88:91]
	v_mfma_f32_16x16x32_bf16 v[84:87], v[116:119], v[190:193], v[84:87]
	v_mfma_f32_16x16x32_bf16 v[80:83], v[144:147], v[190:193], v[80:83]
	v_mfma_f32_16x16x32_bf16 v[76:79], v[116:119], v[198:201], v[76:79]
	v_mfma_f32_16x16x32_bf16 v[72:75], v[144:147], v[198:201], v[72:75]
	v_mfma_f32_16x16x32_bf16 v[68:71], v[116:119], v[206:209], v[68:71]
	v_mfma_f32_16x16x32_bf16 v[64:67], v[144:147], v[206:209], v[64:67]
	v_mfma_f32_16x16x32_bf16 v[28:31], v[148:151], v[178:181], v[28:31]
	v_mfma_f32_16x16x32_bf16 v[24:27], v[168:171], v[178:181], v[24:27]
	v_mfma_f32_16x16x32_bf16 v[20:23], v[148:151], v[186:189], v[20:23]
	v_mfma_f32_16x16x32_bf16 v[16:19], v[168:171], v[186:189], v[16:19]
	v_mfma_f32_16x16x32_bf16 v[12:15], v[148:151], v[194:197], v[12:15]
	v_mfma_f32_16x16x32_bf16 v[8:11], v[168:171], v[194:197], v[8:11]
	v_mfma_f32_16x16x32_bf16 v[4:7], v[148:151], v[202:205], v[4:7]
	v_mfma_f32_16x16x32_bf16 v[0:3], v[168:171], v[202:205], v[0:3]
	v_mfma_f32_16x16x32_bf16 v[28:31], v[152:155], v[182:185], v[28:31]
	v_mfma_f32_16x16x32_bf16 v[24:27], v[172:175], v[182:185], v[24:27]
	v_mfma_f32_16x16x32_bf16 v[20:23], v[152:155], v[190:193], v[20:23]
	v_mfma_f32_16x16x32_bf16 v[16:19], v[172:175], v[190:193], v[16:19]
	v_mfma_f32_16x16x32_bf16 v[12:15], v[152:155], v[198:201], v[12:15]
	v_mfma_f32_16x16x32_bf16 v[8:11], v[172:175], v[198:201], v[8:11]
	v_mfma_f32_16x16x32_bf16 v[4:7], v[152:155], v[206:209], v[4:7]
	v_mfma_f32_16x16x32_bf16 v[0:3], v[172:175], v[206:209], v[0:3]
	s_barrier
; #define PG8_STAGE(bufoff, gbase, voff, p64) do { _Pragma("unroll") for (int _i = 0; _i < 2; ++_i) { \
;         const char* _gb = (const char*)(gbase) + (size_t)_i * (p64); const unsigned _la = ldsbase + (unsigned)(bufoff) + (unsigned)_i * 8192u; \
;         asm volatile("s_mov_b32 m0, %0\n\ts_nop 0\n\tglobal_load_lds_dwordx4 %1, %2" :: "s"(_la), "v"(voff), "s"(_gb) : "memory"); } } while (0)
; #define PG8_LDA(dst, b, h) do { _Pragma("unroll") for (int m = 0; m < 4; ++m) _Pragma("unroll") for (int k = 0; k < 2; ++k) dst[m][k] = *(const LAS bf16x8*)(lds + PG8_SA(b, h) + aoff + m * 2048 + k * 1024); } while (0)
; #define PG8_LDB(dst, b, h) do { _Pragma("unroll") for (int n = 0; n < 2; ++n) _Pragma("unroll") for (int k = 0; k < 2; ++k) dst[n][k] = *(const LAS bf16x8*)(lds + PG8_SB(b, h) + boff + n * 2048 + k * 1024); } while (0)
; #define PG8_MMA(ai, bj, At, Bt) do { __builtin_amdgcn_s_setprio(1); _Pragma("unroll") for (int m = 0; m < 4; ++m) _Pragma("unroll") for (int n = 0; n < 2; ++n) _Pragma("unroll") for (int k = 0; k < 2; ++k) \
;         acc[ai][bj][m][n] = __builtin_amdgcn_mfma_f32_16x16x32_bf16(Bt[n][k], At[m][k], acc[ai][bj][m][n], 0, 0, 0); __builtin_amdgcn_s_setprio(0); } while (0)
; #define PG8_WAIT_V(n) asm volatile("s_waitcnt vmcnt(" #n ")" ::: "memory")
; #define PG8_WAIT_L(n) asm volatile("s_waitcnt lgkmcnt(" #n ")" ::: "memory")
; #define PG8_BAR __builtin_amdgcn_s_barrier()
; #define PG8_SCHED __builtin_amdgcn_sched_barrier(0)
; template <class Epi, class Sched>
; __device__ __forceinline__ void gemm_phase(LAS unsigned char* lds, const Sched& S, const Epi& E) {
;     ...
;             PG8_LDB(B0, 1, 0); PG8_LDB(B1, 1, 1); PG8_SCHED; PG8_LDA(At, 1, 0); PG8_STAGE(PG8_SA(0, 1), a2 + hA2, vA2, hA2 / 2);
;             PG8_WAIT_V(8); PG8_WAIT_L(0); PG8_BAR; PG8_MMA(0, 0, At, B0); PG8_MMA(0, 1, At, B1); PG8_BAR; PG8_SCHED;
;             PG8_LDA(At, 1, 1); PG8_STAGE(PG8_SB(1, 0), b3, vB2, hB2 / 2); PG8_STAGE(PG8_SB(1, 1), b3 + hB2, vB2, hB2 / 2); PG8_STAGE(PG8_SA(1, 0), a3, vA2, hA2 / 2);
;             PG8_WAIT_V(8); PG8_WAIT_L(0); PG8_BAR; PG8_MMA(1, 0, At, B0); PG8_MMA(1, 1, At, B1); PG8_BAR; PG8_SCHED;
.Lpeel_mid_28770:
	ds_read_b128 v[112:115], v165
	ds_read_b128 v[116:119], v165 offset:1024
	ds_read_b128 v[140:143], v165 offset:2048
	ds_read_b128 v[144:147], v165 offset:3072
	ds_read_b128 v[148:151], v166
	ds_read_b128 v[152:155], v166 offset:1024
	ds_read_b128 v[168:171], v166 offset:2048
	ds_read_b128 v[172:175], v166 offset:3072
	ds_read_b128 v[178:181], v164 offset:32768
	ds_read_b128 v[182:185], v164 offset:33792
	ds_read_b128 v[186:189], v164 offset:34816
	ds_read_b128 v[190:193], v164 offset:35840
	ds_read_b128 v[194:197], v164 offset:36864
	ds_read_b128 v[198:201], v164 offset:37888
	ds_read_b128 v[202:205], v164 offset:38912
	ds_read_b128 v[206:209], v164 offset:39936
	s_add_u32 s66, s38, 0x40000
	s_mov_b32 m0, s46
	s_addc_u32 s67, s39, 0
	global_load_lds_dwordx4 v158, s[66:67]
	s_add_u32 s66, s38, 0x60000
	s_mov_b32 m0, s47
	s_addc_u32 s67, s39, 0
	global_load_lds_dwordx4 v158, s[66:67]
	s_waitcnt vmcnt(8) lgkmcnt(0)
	s_barrier
	v_mfma_f32_16x16x32_bf16 v[132:135], v[112:115], v[178:181], v[132:135]
	v_mfma_f32_16x16x32_bf16 v[128:131], v[140:143], v[178:181], v[128:131]
	v_mfma_f32_16x16x32_bf16 v[124:127], v[112:115], v[186:189], v[124:127]
	v_mfma_f32_16x16x32_bf16 v[120:123], v[140:143], v[186:189], v[120:123]
	v_mfma_f32_16x16x32_bf16 v[108:111], v[112:115], v[194:197], v[108:111]
	v_mfma_f32_16x16x32_bf16 v[104:107], v[140:143], v[194:197], v[104:107]
	v_mfma_f32_16x16x32_bf16 v[100:103], v[112:115], v[202:205], v[100:103]
	v_mfma_f32_16x16x32_bf16 v[96:99], v[140:143], v[202:205], v[96:99]
	v_mfma_f32_16x16x32_bf16 v[132:135], v[116:119], v[182:185], v[132:135]
	v_mfma_f32_16x16x32_bf16 v[128:131], v[144:147], v[182:185], v[128:131]
	v_mfma_f32_16x16x32_bf16 v[124:127], v[116:119], v[190:193], v[124:127]
	v_mfma_f32_16x16x32_bf16 v[120:123], v[144:147], v[190:193], v[120:123]
	v_mfma_f32_16x16x32_bf16 v[108:111], v[116:119], v[198:201], v[108:111]
	v_mfma_f32_16x16x32_bf16 v[104:107], v[144:147], v[198:201], v[104:107]
	v_mfma_f32_16x16x32_bf16 v[100:103], v[116:119], v[206:209], v[100:103]
	v_mfma_f32_16x16x32_bf16 v[96:99], v[144:147], v[206:209], v[96:99]
	v_mfma_f32_16x16x32_bf16 v[60:63], v[148:151], v[178:181], v[60:63]
	v_mfma_f32_16x16x32_bf16 v[56:59], v[168:171], v[178:181], v[56:59]
	v_mfma_f32_16x16x32_bf16 v[52:55], v[148:151], v[186:189], v[52:55]
	v_mfma_f32_16x16x32_bf16 v[48:51], v[168:171], v[186:189], v[48:51]
	v_mfma_f32_16x16x32_bf16 v[44:47], v[148:151], v[194:197], v[44:47]
	v_mfma_f32_16x16x32_bf16 v[40:43], v[168:171], v[194:197], v[40:43]
	v_mfma_f32_16x16x32_bf16 v[36:39], v[148:151], v[202:205], v[36:39]
	v_mfma_f32_16x16x32_bf16 v[32:35], v[168:171], v[202:205], v[32:35]
	v_mfma_f32_16x16x32_bf16 v[60:63], v[152:155], v[182:185], v[60:63]
	v_mfma_f32_16x16x32_bf16 v[56:59], v[172:175], v[182:185], v[56:59]
	v_mfma_f32_16x16x32_bf16 v[52:55], v[152:155], v[190:193], v[52:55]
	v_mfma_f32_16x16x32_bf16 v[48:51], v[172:175], v[190:193], v[48:51]
	v_mfma_f32_16x16x32_bf16 v[44:47], v[152:155], v[198:201], v[44:47]
	v_mfma_f32_16x16x32_bf16 v[40:43], v[172:175], v[198:201], v[40:43]
	v_mfma_f32_16x16x32_bf16 v[36:39], v[152:155], v[206:209], v[36:39]
	v_mfma_f32_16x16x32_bf16 v[32:35], v[172:175], v[206:209], v[32:35]
	s_barrier
	s_add_u32 s66, s42, 0x80
	s_addc_u32 s67, s43, 0
	ds_read_b128 v[178:181], v164 offset:49152
	ds_read_b128 v[182:185], v164 offset:50176
	ds_read_b128 v[186:189], v164 offset:51200
	ds_read_b128 v[190:193], v164 offset:52224
	ds_read_b128 v[194:197], v164 offset:53248
	ds_read_b128 v[198:201], v164 offset:54272
	ds_read_b128 v[202:205], v164 offset:55296
	ds_read_b128 v[206:209], v164 offset:56320
	s_mov_b32 m0, s52
	s_nop 0
	global_load_lds_dwordx4 v159, s[66:67]
	s_add_u32 s66, s42, 0x20080
	s_mov_b32 m0, s53
	s_addc_u32 s67, s43, 0
	global_load_lds_dwordx4 v159, s[66:67]
	s_add_u32 s66, s42, 0x40080
	s_mov_b32 m0, s56
	s_addc_u32 s67, s43, 0
	global_load_lds_dwordx4 v159, s[66:67]
	s_add_u32 s42, s42, 0x60080
	s_mov_b32 m0, s57
	s_addc_u32 s43, s43, 0
	global_load_lds_dwordx4 v159, s[42:43]
	s_mov_b32 m0, s54
	s_nop 0
	global_load_lds_dwordx4 v158, s[40:41]
	s_add_u32 s38, s38, 0x20080
	s_mov_b32 m0, s55
	s_addc_u32 s39, s39, 0
	global_load_lds_dwordx4 v158, s[38:39]
	s_waitcnt vmcnt(8) lgkmcnt(0)
	s_barrier
	v_mfma_f32_16x16x32_bf16 v[92:95], v[112:115], v[178:181], v[92:95]
	v_mfma_f32_16x16x32_bf16 v[88:91], v[140:143], v[178:181], v[88:91]
	v_mfma_f32_16x16x32_bf16 v[84:87], v[112:115], v[186:189], v[84:87]
	v_mfma_f32_16x16x32_bf16 v[80:83], v[140:143], v[186:189], v[80:83]
	v_mfma_f32_16x16x32_bf16 v[76:79], v[112:115], v[194:197], v[76:79]
	v_mfma_f32_16x16x32_bf16 v[72:75], v[140:143], v[194:197], v[72:75]
	v_mfma_f32_16x16x32_bf16 v[68:71], v[112:115], v[202:205], v[68:71]
	v_mfma_f32_16x16x32_bf16 v[64:67], v[140:143], v[202:205], v[64:67]
	v_mfma_f32_16x16x32_bf16 v[92:95], v[116:119], v[182:185], v[92:95]
	v_mfma_f32_16x16x32_bf16 v[88:91], v[144:147], v[182:185], v[88:91]
	v_mfma_f32_16x16x32_bf16 v[84:87], v[116:119], v[190:193], v[84:87]
	v_mfma_f32_16x16x32_bf16 v[80:83], v[144:147], v[190:193], v[80:83]
	v_mfma_f32_16x16x32_bf16 v[76:79], v[116:119], v[198:201], v[76:79]
	v_mfma_f32_16x16x32_bf16 v[72:75], v[144:147], v[198:201], v[72:75]
	v_mfma_f32_16x16x32_bf16 v[68:71], v[116:119], v[206:209], v[68:71]
	v_mfma_f32_16x16x32_bf16 v[64:67], v[144:147], v[206:209], v[64:67]
	v_mfma_f32_16x16x32_bf16 v[28:31], v[148:151], v[178:181], v[28:31]
	v_mfma_f32_16x16x32_bf16 v[24:27], v[168:171], v[178:181], v[24:27]
	v_mfma_f32_16x16x32_bf16 v[20:23], v[148:151], v[186:189], v[20:23]
	v_mfma_f32_16x16x32_bf16 v[16:19], v[168:171], v[186:189], v[16:19]
	v_mfma_f32_16x16x32_bf16 v[12:15], v[148:151], v[194:197], v[12:15]
	v_mfma_f32_16x16x32_bf16 v[8:11], v[168:171], v[194:197], v[8:11]
	v_mfma_f32_16x16x32_bf16 v[4:7], v[148:151], v[202:205], v[4:7]
	v_mfma_f32_16x16x32_bf16 v[0:3], v[168:171], v[202:205], v[0:3]
	v_mfma_f32_16x16x32_bf16 v[28:31], v[152:155], v[182:185], v[28:31]
	v_mfma_f32_16x16x32_bf16 v[24:27], v[172:175], v[182:185], v[24:27]
	v_mfma_f32_16x16x32_bf16 v[20:23], v[152:155], v[190:193], v[20:23]
	v_mfma_f32_16x16x32_bf16 v[16:19], v[172:175], v[190:193], v[16:19]
	v_mfma_f32_16x16x32_bf16 v[12:15], v[152:155], v[198:201], v[12:15]
	v_mfma_f32_16x16x32_bf16 v[8:11], v[172:175], v[198:201], v[8:11]
	v_mfma_f32_16x16x32_bf16 v[4:7], v[152:155], v[206:209], v[4:7]
	v_mfma_f32_16x16x32_bf16 v[0:3], v[172:175], v[206:209], v[0:3]
	s_barrier
	s_cmp_gt_u32 s65, 13
	s_cbranch_scc0 .LBB0_981
	s_and_b64 vcc, exec, s[14:15]
	s_cbranch_vccz .LBB0_984
	s_barrier

; #define PG8_STAGE(bufoff, gbase, voff, p64) do { _Pragma("unroll") for (int _i = 0; _i < 2; ++_i) { \
;         const char* _gb = (const char*)(gbase) + (size_t)_i * (p64); const unsigned _la = ldsbase + (unsigned)(bufoff) + (unsigned)_i * 8192u; \
;         asm volatile("s_mov_b32 m0, %0\n\ts_nop 0\n\tglobal_load_lds_dwordx4 %1, %2" :: "s"(_la), "v"(voff), "s"(_gb) : "memory"); } } while (0)
; #define PG8_LDA(dst, b, h) do { _Pragma("unroll") for (int m = 0; m < 4; ++m) _Pragma("unroll") for (int k = 0; k < 2; ++k) dst[m][k] = *(const LAS bf16x8*)(lds + PG8_SA(b, h) + aoff + m * 2048 + k * 1024); } while (0)
; #define PG8_LDB(dst, b, h) do { _Pragma("unroll") for (int n = 0; n < 2; ++n) _Pragma("unroll") for (int k = 0; k < 2; ++k) dst[n][k] = *(const LAS bf16x8*)(lds + PG8_SB(b, h) + boff + n * 2048 + k * 1024); } while (0)
; #define PG8_MMA(ai, bj, At, Bt) do { __builtin_amdgcn_s_setprio(1); _Pragma("unroll") for (int m = 0; m < 4; ++m) _Pragma("unroll") for (int n = 0; n < 2; ++n) _Pragma("unroll") for (int k = 0; k < 2; ++k) \
;         acc[ai][bj][m][n] = __builtin_amdgcn_mfma_f32_16x16x32_bf16(Bt[n][k], At[m][k], acc[ai][bj][m][n], 0, 0, 0); __builtin_amdgcn_s_setprio(0); } while (0)
; #define PG8_WAIT_V(n) asm volatile("s_waitcnt vmcnt(" #n ")" ::: "memory")
; #define PG8_BAR __builtin_amdgcn_s_barrier()
; template <class Epi, class Sched>
; __device__ __forceinline__ void gemm_phase(LAS unsigned char* lds, const Sched& S, const Epi& E) {
;     ...
;             const bool last = (t == nt - 2);
;             const char* a1 = cA + (size_t)(t + 1) * kstep;
;             const char* a2 = last ? nA : cA + (size_t)(t + 2) * kstep; const char* b2 = last ? nB : cB + (size_t)(t + 2) * kstep;
;             const char* a3 = a2 + kstep; const char* b3 = b2 + kstep;
;             const unsigned vA2 = voffA, vB2 = voffB, hA2 = hA, hB2 = hB;
;             PG8_LDB(B0, 0, 0); PG8_LDB(B1, 0, 1); PG8_SCHED; PG8_LDA(At, 0, 0); PG8_STAGE(PG8_SA(1, 1), a1 + hA, voffA, hA / 2);
;             PG8_WAIT_V(8); PG8_WAIT_L(0); PG8_BAR; PG8_MMA(0, 0, At, B0); PG8_MMA(0, 1, At, B1); PG8_BAR; PG8_SCHED;
;             PG8_LDA(At, 0, 1); PG8_STAGE(PG8_SB(0, 0), b2, vB2, hB2 / 2); PG8_STAGE(PG8_SB(0, 1), b2 + hB2, vB2, hB2 / 2); PG8_STAGE(PG8_SA(0, 0), a2, vA2, hA2 / 2);
;             PG8_WAIT_V(8); PG8_WAIT_L(0); PG8_BAR; PG8_MMA(1, 0, At, B0); PG8_MMA(1, 1, At, B1); PG8_BAR; PG8_SCHED;
.LBB0_1010:
	s_add_u32 s26, s26, 0x40080
	s_addc_u32 s27, s27, 0
	s_add_u32 s61, s38, 0x100
	s_addc_u32 s62, s39, 0
	s_mov_b32 s63, -2
	ds_read_b128 v[144:147], v138
	ds_read_b128 v[148:151], v138 offset:1024
	ds_read_b128 v[152:155], v138 offset:2048
	ds_read_b128 v[156:159], v138 offset:3072
	ds_read_b128 v[160:163], v139
	ds_read_b128 v[164:167], v139 offset:1024
	ds_read_b128 v[168:171], v139 offset:2048
	ds_read_b128 v[172:175], v139 offset:3072
	s_add_u32 s30, s26, 0xfffc0080
	s_addc_u32 s38, s27, -1
	s_cmp_eq_u32 s63, 12
	s_cselect_b32 s39, s23, s38
	s_cselect_b32 s38, s22, s30
	s_cselect_b32 s42, s24, s61
	s_cselect_b32 s43, s25, s62
	s_add_u32 s40, s38, 0x80
	s_addc_u32 s41, s39, 0
	ds_read_b128 v[178:181], v140
	ds_read_b128 v[182:185], v140 offset:1024
	ds_read_b128 v[186:189], v140 offset:2048
	ds_read_b128 v[190:193], v140 offset:3072
	ds_read_b128 v[194:197], v140 offset:4096
	ds_read_b128 v[198:201], v140 offset:5120
	ds_read_b128 v[202:205], v140 offset:6144
	ds_read_b128 v[206:209], v140 offset:7168
	s_mov_b32 m0, s57
	s_nop 0
	global_load_lds_dwordx4 v134, s[26:27]
	s_add_u32 s66, s26, 0x20000
	s_mov_b32 m0, s58
	s_addc_u32 s67, s27, 0
	global_load_lds_dwordx4 v134, s[66:67]
	s_waitcnt vmcnt(8) lgkmcnt(0)
	s_barrier
	v_mfma_f32_16x16x32_bf16 v[120:123], v[144:147], v[178:181], 0
	v_mfma_f32_16x16x32_bf16 v[116:119], v[152:155], v[178:181], 0
	v_mfma_f32_16x16x32_bf16 v[104:107], v[144:147], v[186:189], 0
	v_mfma_f32_16x16x32_bf16 v[100:103], v[152:155], v[186:189], 0
	v_mfma_f32_16x16x32_bf16 v[88:91], v[144:147], v[194:197], 0
	v_mfma_f32_16x16x32_bf16 v[84:87], v[152:155], v[194:197], 0
	v_mfma_f32_16x16x32_bf16 v[72:75], v[144:147], v[202:205], 0
	v_mfma_f32_16x16x32_bf16 v[68:71], v[152:155], v[202:205], 0
	v_mfma_f32_16x16x32_bf16 v[120:123], v[148:151], v[182:185], v[120:123]
	v_mfma_f32_16x16x32_bf16 v[116:119], v[156:159], v[182:185], v[116:119]
	v_mfma_f32_16x16x32_bf16 v[104:107], v[148:151], v[190:193], v[104:107]
	v_mfma_f32_16x16x32_bf16 v[100:103], v[156:159], v[190:193], v[100:103]
	v_mfma_f32_16x16x32_bf16 v[88:91], v[148:151], v[198:201], v[88:91]
	v_mfma_f32_16x16x32_bf16 v[84:87], v[156:159], v[198:201], v[84:87]
	v_mfma_f32_16x16x32_bf16 v[72:75], v[148:151], v[206:209], v[72:75]
	v_mfma_f32_16x16x32_bf16 v[68:71], v[156:159], v[206:209], v[68:71]
	v_mfma_f32_16x16x32_bf16 v[124:127], v[160:163], v[178:181], 0
	v_mfma_f32_16x16x32_bf16 v[112:115], v[168:171], v[178:181], 0
	v_mfma_f32_16x16x32_bf16 v[108:111], v[160:163], v[186:189], 0
	v_mfma_f32_16x16x32_bf16 v[96:99], v[168:171], v[186:189], 0
	v_mfma_f32_16x16x32_bf16 v[92:95], v[160:163], v[194:197], 0
	v_mfma_f32_16x16x32_bf16 v[80:83], v[168:171], v[194:197], 0
	v_mfma_f32_16x16x32_bf16 v[76:79], v[160:163], v[202:205], 0
	v_mfma_f32_16x16x32_bf16 v[64:67], v[168:171], v[202:205], 0
	v_mfma_f32_16x16x32_bf16 v[124:127], v[164:167], v[182:185], v[124:127]
	v_mfma_f32_16x16x32_bf16 v[112:115], v[172:175], v[182:185], v[112:115]
	v_mfma_f32_16x16x32_bf16 v[108:111], v[164:167], v[190:193], v[108:111]
	v_mfma_f32_16x16x32_bf16 v[96:99], v[172:175], v[190:193], v[96:99]
	v_mfma_f32_16x16x32_bf16 v[92:95], v[164:167], v[198:201], v[92:95]
	v_mfma_f32_16x16x32_bf16 v[80:83], v[172:175], v[198:201], v[80:83]
	v_mfma_f32_16x16x32_bf16 v[76:79], v[164:167], v[206:209], v[76:79]
	v_mfma_f32_16x16x32_bf16 v[64:67], v[172:175], v[206:209], v[64:67]
	s_add_i32 s63, s63, 2
	s_add_u32 s26, s26, 0x100
	s_addc_u32 s27, s27, 0
	s_add_u32 s61, s61, 0x100
	s_addc_u32 s62, s62, 0
	s_barrier
	s_add_u32 s66, s42, 0x20000
	ds_read_b128 v[178:181], v140 offset:16384
	ds_read_b128 v[182:185], v140 offset:17408
	ds_read_b128 v[186:189], v140 offset:18432
	ds_read_b128 v[190:193], v140 offset:19456
	ds_read_b128 v[194:197], v140 offset:20480
	ds_read_b128 v[198:201], v140 offset:21504
	ds_read_b128 v[202:205], v140 offset:22528
	ds_read_b128 v[206:209], v140 offset:23552
	s_mov_b32 m0, s35
	s_nop 0
	global_load_lds_dwordx4 v135, s[42:43]
	s_mov_b32 m0, s36
	s_addc_u32 s67, s43, 0
	global_load_lds_dwordx4 v135, s[66:67]
	s_add_u32 s66, s42, 0x40000
	s_mov_b32 m0, s37
	s_addc_u32 s67, s43, 0
	global_load_lds_dwordx4 v135, s[66:67]
	s_add_u32 s66, s42, 0x60000
	s_mov_b32 m0, s44
	s_addc_u32 s67, s43, 0
	global_load_lds_dwordx4 v135, s[66:67]
	s_mov_b32 m0, s34
	s_nop 0
	global_load_lds_dwordx4 v134, s[38:39]
	s_add_u32 s66, s38, 0x20000
	s_mov_b32 m0, s45
	s_addc_u32 s67, s39, 0
	global_load_lds_dwordx4 v134, s[66:67]
	s_waitcnt vmcnt(8) lgkmcnt(0)
	s_barrier
	v_mfma_f32_16x16x32_bf16 v[56:59], v[144:147], v[178:181], 0
	v_mfma_f32_16x16x32_bf16 v[52:55], v[152:155], v[178:181], 0
	v_mfma_f32_16x16x32_bf16 v[40:43], v[144:147], v[186:189], 0
	v_mfma_f32_16x16x32_bf16 v[36:39], v[152:155], v[186:189], 0
	v_mfma_f32_16x16x32_bf16 v[24:27], v[144:147], v[194:197], 0
	v_mfma_f32_16x16x32_bf16 v[20:23], v[152:155], v[194:197], 0
	v_mfma_f32_16x16x32_bf16 v[8:11], v[144:147], v[202:205], 0
	v_mfma_f32_16x16x32_bf16 v[4:7], v[152:155], v[202:205], 0
	v_mfma_f32_16x16x32_bf16 v[56:59], v[148:151], v[182:185], v[56:59]
	v_mfma_f32_16x16x32_bf16 v[52:55], v[156:159], v[182:185], v[52:55]
	v_mfma_f32_16x16x32_bf16 v[40:43], v[148:151], v[190:193], v[40:43]
	v_mfma_f32_16x16x32_bf16 v[36:39], v[156:159], v[190:193], v[36:39]
	v_mfma_f32_16x16x32_bf16 v[24:27], v[148:151], v[198:201], v[24:27]
	v_mfma_f32_16x16x32_bf16 v[20:23], v[156:159], v[198:201], v[20:23]
	v_mfma_f32_16x16x32_bf16 v[8:11], v[148:151], v[206:209], v[8:11]
	v_mfma_f32_16x16x32_bf16 v[4:7], v[156:159], v[206:209], v[4:7]
	v_mfma_f32_16x16x32_bf16 v[60:63], v[160:163], v[178:181], 0
	v_mfma_f32_16x16x32_bf16 v[48:51], v[168:171], v[178:181], 0
	v_mfma_f32_16x16x32_bf16 v[44:47], v[160:163], v[186:189], 0
	v_mfma_f32_16x16x32_bf16 v[32:35], v[168:171], v[186:189], 0
	v_mfma_f32_16x16x32_bf16 v[28:31], v[160:163], v[194:197], 0
	v_mfma_f32_16x16x32_bf16 v[16:19], v[168:171], v[194:197], 0
	v_mfma_f32_16x16x32_bf16 v[12:15], v[160:163], v[202:205], 0
	v_mfma_f32_16x16x32_bf16 v[0:3], v[168:171], v[202:205], 0
	v_mfma_f32_16x16x32_bf16 v[60:63], v[164:167], v[182:185], v[60:63]
	v_mfma_f32_16x16x32_bf16 v[48:51], v[172:175], v[182:185], v[48:51]
	v_mfma_f32_16x16x32_bf16 v[44:47], v[164:167], v[190:193], v[44:47]
	v_mfma_f32_16x16x32_bf16 v[32:35], v[172:175], v[190:193], v[32:35]
	v_mfma_f32_16x16x32_bf16 v[28:31], v[164:167], v[198:201], v[28:31]
	v_mfma_f32_16x16x32_bf16 v[16:19], v[172:175], v[198:201], v[16:19]
	v_mfma_f32_16x16x32_bf16 v[12:15], v[164:167], v[206:209], v[12:15]
	v_mfma_f32_16x16x32_bf16 v[0:3], v[172:175], v[206:209], v[0:3]
	s_barrier
	s_branch .Lpeel_mid_30674
; #define PG8_STAGE(bufoff, gbase, voff, p64) do { _Pragma("unroll") for (int _i = 0; _i < 2; ++_i) { \
;         const char* _gb = (const char*)(gbase) + (size_t)_i * (p64); const unsigned _la = ldsbase + (unsigned)(bufoff) + (unsigned)_i * 8192u; \
;         asm volatile("s_mov_b32 m0, %0\n\ts_nop 0\n\tglobal_load_lds_dwordx4 %1, %2" :: "s"(_la), "v"(voff), "s"(_gb) : "memory"); } } while (0)
; #define PG8_LDA(dst, b, h) do { _Pragma("unroll") for (int m = 0; m < 4; ++m) _Pragma("unroll") for (int k = 0; k < 2; ++k) dst[m][k] = *(const LAS bf16x8*)(lds + PG8_SA(b, h) + aoff + m * 2048 + k * 1024); } while (0)
; #define PG8_LDB(dst, b, h) do { _Pragma("unroll") for (int n = 0; n < 2; ++n) _Pragma("unroll") for (int k = 0; k < 2; ++k) dst[n][k] = *(const LAS bf16x8*)(lds + PG8_SB(b, h) + boff + n * 2048 + k * 1024); } while (0)
; #define PG8_MMA(ai, bj, At, Bt) do { __builtin_amdgcn_s_setprio(1); _Pragma("unroll") for (int m = 0; m < 4; ++m) _Pragma("unroll") for (int n = 0; n < 2; ++n) _Pragma("unroll") for (int k = 0; k < 2; ++k) \
;         acc[ai][bj][m][n] = __builtin_amdgcn_mfma_f32_16x16x32_bf16(Bt[n][k], At[m][k], acc[ai][bj][m][n], 0, 0, 0); __builtin_amdgcn_s_setprio(0); } while (0)
; #define PG8_WAIT_V(n) asm volatile("s_waitcnt vmcnt(" #n ")" ::: "memory")
; #define PG8_BAR __builtin_amdgcn_s_barrier()
; template <class Epi, class Sched>
; __device__ __forceinline__ void gemm_phase(LAS unsigned char* lds, const Sched& S, const Epi& E) {
;     ...
;             const bool last = (t == nt - 2);
;             const char* a1 = cA + (size_t)(t + 1) * kstep;
;             const char* a2 = last ? nA : cA + (size_t)(t + 2) * kstep; const char* b2 = last ? nB : cB + (size_t)(t + 2) * kstep;
;             const char* a3 = a2 + kstep; const char* b3 = b2 + kstep;
;             const unsigned vA2 = voffA, vB2 = voffB, hA2 = hA, hB2 = hB;
;             PG8_LDB(B0, 0, 0); PG8_LDB(B1, 0, 1); PG8_SCHED; PG8_LDA(At, 0, 0); PG8_STAGE(PG8_SA(1, 1), a1 + hA, voffA, hA / 2);
;             PG8_WAIT_V(8); PG8_WAIT_L(0); PG8_BAR; PG8_MMA(0, 0, At, B0); PG8_MMA(0, 1, At, B1); PG8_BAR; PG8_SCHED;
;             PG8_LDA(At, 0, 1); PG8_STAGE(PG8_SB(0, 0), b2, vB2, hB2 / 2); PG8_STAGE(PG8_SB(0, 1), b2 + hB2, vB2, hB2 / 2); PG8_STAGE(PG8_SA(0, 0), a2, vA2, hA2 / 2);
;             PG8_WAIT_V(8); PG8_WAIT_L(0); PG8_BAR; PG8_MMA(1, 0, At, B0); PG8_MMA(1, 1, At, B1); PG8_BAR; PG8_SCHED;
.LBB0_1011:
	ds_read_b128 v[144:147], v138
	ds_read_b128 v[148:151], v138 offset:1024
	ds_read_b128 v[152:155], v138 offset:2048
	ds_read_b128 v[156:159], v138 offset:3072
	ds_read_b128 v[160:163], v139
	ds_read_b128 v[164:167], v139 offset:1024
	ds_read_b128 v[168:171], v139 offset:2048
	ds_read_b128 v[172:175], v139 offset:3072
	s_add_u32 s30, s26, 0xfffc0080
	s_addc_u32 s38, s27, -1
	s_cmp_eq_u32 s63, 12
	s_cselect_b32 s39, s23, s38
	s_cselect_b32 s38, s22, s30
	s_cselect_b32 s42, s24, s61
	s_cselect_b32 s43, s25, s62
	s_add_u32 s40, s38, 0x80
	s_addc_u32 s41, s39, 0
	ds_read_b128 v[178:181], v140
	ds_read_b128 v[182:185], v140 offset:1024
	ds_read_b128 v[186:189], v140 offset:2048
	ds_read_b128 v[190:193], v140 offset:3072
	ds_read_b128 v[194:197], v140 offset:4096
	ds_read_b128 v[198:201], v140 offset:5120
	ds_read_b128 v[202:205], v140 offset:6144
	ds_read_b128 v[206:209], v140 offset:7168
	s_mov_b32 m0, s57
	s_nop 0
	global_load_lds_dwordx4 v134, s[26:27]
	s_add_u32 s66, s26, 0x20000
	s_mov_b32 m0, s58
	s_addc_u32 s67, s27, 0
	global_load_lds_dwordx4 v134, s[66:67]
	s_waitcnt vmcnt(8) lgkmcnt(0)
	s_barrier
	v_mfma_f32_16x16x32_bf16 v[120:123], v[144:147], v[178:181], v[120:123]
	v_mfma_f32_16x16x32_bf16 v[116:119], v[152:155], v[178:181], v[116:119]
	v_mfma_f32_16x16x32_bf16 v[104:107], v[144:147], v[186:189], v[104:107]
	v_mfma_f32_16x16x32_bf16 v[100:103], v[152:155], v[186:189], v[100:103]
	v_mfma_f32_16x16x32_bf16 v[88:91], v[144:147], v[194:197], v[88:91]
	v_mfma_f32_16x16x32_bf16 v[84:87], v[152:155], v[194:197], v[84:87]
	v_mfma_f32_16x16x32_bf16 v[72:75], v[144:147], v[202:205], v[72:75]
	v_mfma_f32_16x16x32_bf16 v[68:71], v[152:155], v[202:205], v[68:71]
	v_mfma_f32_16x16x32_bf16 v[120:123], v[148:151], v[182:185], v[120:123]
	v_mfma_f32_16x16x32_bf16 v[116:119], v[156:159], v[182:185], v[116:119]
	v_mfma_f32_16x16x32_bf16 v[104:107], v[148:151], v[190:193], v[104:107]
	v_mfma_f32_16x16x32_bf16 v[100:103], v[156:159], v[190:193], v[100:103]
	v_mfma_f32_16x16x32_bf16 v[88:91], v[148:151], v[198:201], v[88:91]
	v_mfma_f32_16x16x32_bf16 v[84:87], v[156:159], v[198:201], v[84:87]
	v_mfma_f32_16x16x32_bf16 v[72:75], v[148:151], v[206:209], v[72:75]
	v_mfma_f32_16x16x32_bf16 v[68:71], v[156:159], v[206:209], v[68:71]
	v_mfma_f32_16x16x32_bf16 v[124:127], v[160:163], v[178:181], v[124:127]
	v_mfma_f32_16x16x32_bf16 v[112:115], v[168:171], v[178:181], v[112:115]
	v_mfma_f32_16x16x32_bf16 v[108:111], v[160:163], v[186:189], v[108:111]
	v_mfma_f32_16x16x32_bf16 v[96:99], v[168:171], v[186:189], v[96:99]
	v_mfma_f32_16x16x32_bf16 v[92:95], v[160:163], v[194:197], v[92:95]
	v_mfma_f32_16x16x32_bf16 v[80:83], v[168:171], v[194:197], v[80:83]
	v_mfma_f32_16x16x32_bf16 v[76:79], v[160:163], v[202:205], v[76:79]
	v_mfma_f32_16x16x32_bf16 v[64:67], v[168:171], v[202:205], v[64:67]
	v_mfma_f32_16x16x32_bf16 v[124:127], v[164:167], v[182:185], v[124:127]
	v_mfma_f32_16x16x32_bf16 v[112:115], v[172:175], v[182:185], v[112:115]
	v_mfma_f32_16x16x32_bf16 v[108:111], v[164:167], v[190:193], v[108:111]
	v_mfma_f32_16x16x32_bf16 v[96:99], v[172:175], v[190:193], v[96:99]
	v_mfma_f32_16x16x32_bf16 v[92:95], v[164:167], v[198:201], v[92:95]
	v_mfma_f32_16x16x32_bf16 v[80:83], v[172:175], v[198:201], v[80:83]
	v_mfma_f32_16x16x32_bf16 v[76:79], v[164:167], v[206:209], v[76:79]
	v_mfma_f32_16x16x32_bf16 v[64:67], v[172:175], v[206:209], v[64:67]
	s_add_i32 s63, s63, 2
	s_add_u32 s26, s26, 0x100
	s_addc_u32 s27, s27, 0
	s_add_u32 s61, s61, 0x100
	s_addc_u32 s62, s62, 0
	s_barrier
	s_add_u32 s66, s42, 0x20000
	ds_read_b128 v[178:181], v140 offset:16384
	ds_read_b128 v[182:185], v140 offset:17408
	ds_read_b128 v[186:189], v140 offset:18432
	ds_read_b128 v[190:193], v140 offset:19456
	ds_read_b128 v[194:197], v140 offset:20480
	ds_read_b128 v[198:201], v140 offset:21504
	ds_read_b128 v[202:205], v140 offset:22528
	ds_read_b128 v[206:209], v140 offset:23552
	s_mov_b32 m0, s35
	s_nop 0
	global_load_lds_dwordx4 v135, s[42:43]
	s_mov_b32 m0, s36
	s_addc_u32 s67, s43, 0
	global_load_lds_dwordx4 v135, s[66:67]
	s_add_u32 s66, s42, 0x40000
	s_mov_b32 m0, s37
	s_addc_u32 s67, s43, 0
	global_load_lds_dwordx4 v135, s[66:67]
	s_add_u32 s66, s42, 0x60000
	s_mov_b32 m0, s44
	s_addc_u32 s67, s43, 0
	global_load_lds_dwordx4 v135, s[66:67]
	s_mov_b32 m0, s34
	s_nop 0
	global_load_lds_dwordx4 v134, s[38:39]
	s_add_u32 s66, s38, 0x20000
	s_mov_b32 m0, s45
	s_addc_u32 s67, s39, 0
	global_load_lds_dwordx4 v134, s[66:67]
	s_waitcnt vmcnt(8) lgkmcnt(0)
	s_barrier
	v_mfma_f32_16x16x32_bf16 v[56:59], v[144:147], v[178:181], v[56:59]
	v_mfma_f32_16x16x32_bf16 v[52:55], v[152:155], v[178:181], v[52:55]
	v_mfma_f32_16x16x32_bf16 v[40:43], v[144:147], v[186:189], v[40:43]
	v_mfma_f32_16x16x32_bf16 v[36:39], v[152:155], v[186:189], v[36:39]
	v_mfma_f32_16x16x32_bf16 v[24:27], v[144:147], v[194:197], v[24:27]
	v_mfma_f32_16x16x32_bf16 v[20:23], v[152:155], v[194:197], v[20:23]
	v_mfma_f32_16x16x32_bf16 v[8:11], v[144:147], v[202:205], v[8:11]
	v_mfma_f32_16x16x32_bf16 v[4:7], v[152:155], v[202:205], v[4:7]
	v_mfma_f32_16x16x32_bf16 v[56:59], v[148:151], v[182:185], v[56:59]
	v_mfma_f32_16x16x32_bf16 v[52:55], v[156:159], v[182:185], v[52:55]
	v_mfma_f32_16x16x32_bf16 v[40:43], v[148:151], v[190:193], v[40:43]
	v_mfma_f32_16x16x32_bf16 v[36:39], v[156:159], v[190:193], v[36:39]
	v_mfma_f32_16x16x32_bf16 v[24:27], v[148:151], v[198:201], v[24:27]
	v_mfma_f32_16x16x32_bf16 v[20:23], v[156:159], v[198:201], v[20:23]
	v_mfma_f32_16x16x32_bf16 v[8:11], v[148:151], v[206:209], v[8:11]
	v_mfma_f32_16x16x32_bf16 v[4:7], v[156:159], v[206:209], v[4:7]
	v_mfma_f32_16x16x32_bf16 v[60:63], v[160:163], v[178:181], v[60:63]
	v_mfma_f32_16x16x32_bf16 v[48:51], v[168:171], v[178:181], v[48:51]
	v_mfma_f32_16x16x32_bf16 v[44:47], v[160:163], v[186:189], v[44:47]
	v_mfma_f32_16x16x32_bf16 v[32:35], v[168:171], v[186:189], v[32:35]
	v_mfma_f32_16x16x32_bf16 v[28:31], v[160:163], v[194:197], v[28:31]
	v_mfma_f32_16x16x32_bf16 v[16:19], v[168:171], v[194:197], v[16:19]
	v_mfma_f32_16x16x32_bf16 v[12:15], v[160:163], v[202:205], v[12:15]
	v_mfma_f32_16x16x32_bf16 v[0:3], v[168:171], v[202:205], v[0:3]
	v_mfma_f32_16x16x32_bf16 v[60:63], v[164:167], v[182:185], v[60:63]
	v_mfma_f32_16x16x32_bf16 v[48:51], v[172:175], v[182:185], v[48:51]
	v_mfma_f32_16x16x32_bf16 v[44:47], v[164:167], v[190:193], v[44:47]
	v_mfma_f32_16x16x32_bf16 v[32:35], v[172:175], v[190:193], v[32:35]
	v_mfma_f32_16x16x32_bf16 v[28:31], v[164:167], v[198:201], v[28:31]
	v_mfma_f32_16x16x32_bf16 v[16:19], v[172:175], v[198:201], v[16:19]
	v_mfma_f32_16x16x32_bf16 v[12:15], v[164:167], v[206:209], v[12:15]
	v_mfma_f32_16x16x32_bf16 v[0:3], v[172:175], v[206:209], v[0:3]
	s_barrier
; #define PG8_STAGE(bufoff, gbase, voff, p64) do { _Pragma("unroll") for (int _i = 0; _i < 2; ++_i) { \
;         const char* _gb = (const char*)(gbase) + (size_t)_i * (p64); const unsigned _la = ldsbase + (unsigned)(bufoff) + (unsigned)_i * 8192u; \
;         asm volatile("s_mov_b32 m0, %0\n\ts_nop 0\n\tglobal_load_lds_dwordx4 %1, %2" :: "s"(_la), "v"(voff), "s"(_gb) : "memory"); } } while (0)
; #define PG8_LDA(dst, b, h) do { _Pragma("unroll") for (int m = 0; m < 4; ++m) _Pragma("unroll") for (int k = 0; k < 2; ++k) dst[m][k] = *(const LAS bf16x8*)(lds + PG8_SA(b, h) + aoff + m * 2048 + k * 1024); } while (0)
; #define PG8_LDB(dst, b, h) do { _Pragma("unroll") for (int n = 0; n < 2; ++n) _Pragma("unroll") for (int k = 0; k < 2; ++k) dst[n][k] = *(const LAS bf16x8*)(lds + PG8_SB(b, h) + boff + n * 2048 + k * 1024); } while (0)
; #define PG8_MMA(ai, bj, At, Bt) do { __builtin_amdgcn_s_setprio(1); _Pragma("unroll") for (int m = 0; m < 4; ++m) _Pragma("unroll") for (int n = 0; n < 2; ++n) _Pragma("unroll") for (int k = 0; k < 2; ++k) \
;         acc[ai][bj][m][n] = __builtin_amdgcn_mfma_f32_16x16x32_bf16(Bt[n][k], At[m][k], acc[ai][bj][m][n], 0, 0, 0); __builtin_amdgcn_s_setprio(0); } while (0)
; #define PG8_WAIT_V(n) asm volatile("s_waitcnt vmcnt(" #n ")" ::: "memory")
; #define PG8_WAIT_L(n) asm volatile("s_waitcnt lgkmcnt(" #n ")" ::: "memory")
; #define PG8_BAR __builtin_amdgcn_s_barrier()
; #define PG8_SCHED __builtin_amdgcn_sched_barrier(0)
; template <class Epi, class Sched>
; __device__ __forceinline__ void gemm_phase(LAS unsigned char* lds, const Sched& S, const Epi& E) {
;     ...
;             PG8_LDB(B0, 1, 0); PG8_LDB(B1, 1, 1); PG8_SCHED; PG8_LDA(At, 1, 0); PG8_STAGE(PG8_SA(0, 1), a2 + hA2, vA2, hA2 / 2);
;             PG8_WAIT_V(8); PG8_WAIT_L(0); PG8_BAR; PG8_MMA(0, 0, At, B0); PG8_MMA(0, 1, At, B1); PG8_BAR; PG8_SCHED;
;             PG8_LDA(At, 1, 1); PG8_STAGE(PG8_SB(1, 0), b3, vB2, hB2 / 2); PG8_STAGE(PG8_SB(1, 1), b3 + hB2, vB2, hB2 / 2); PG8_STAGE(PG8_SA(1, 0), a3, vA2, hA2 / 2);
;             PG8_WAIT_V(8); PG8_WAIT_L(0); PG8_BAR; PG8_MMA(1, 0, At, B0); PG8_MMA(1, 1, At, B1); PG8_BAR; PG8_SCHED;
.Lpeel_mid_30674:
	ds_read_b128 v[144:147], v141
	ds_read_b128 v[148:151], v141 offset:1024
	ds_read_b128 v[152:155], v141 offset:2048
	ds_read_b128 v[156:159], v141 offset:3072
	ds_read_b128 v[160:163], v142
	ds_read_b128 v[164:167], v142 offset:1024
	ds_read_b128 v[168:171], v142 offset:2048
	ds_read_b128 v[172:175], v142 offset:3072
	ds_read_b128 v[178:181], v140 offset:32768
	ds_read_b128 v[182:185], v140 offset:33792
	ds_read_b128 v[186:189], v140 offset:34816
	ds_read_b128 v[190:193], v140 offset:35840
	ds_read_b128 v[194:197], v140 offset:36864
	ds_read_b128 v[198:201], v140 offset:37888
	ds_read_b128 v[202:205], v140 offset:38912
	ds_read_b128 v[206:209], v140 offset:39936
	s_add_u32 s66, s38, 0x40000
	s_mov_b32 m0, s46
	s_addc_u32 s67, s39, 0
	global_load_lds_dwordx4 v134, s[66:67]
	s_add_u32 s66, s38, 0x60000
	s_mov_b32 m0, s47
	s_addc_u32 s67, s39, 0
	global_load_lds_dwordx4 v134, s[66:67]
	s_waitcnt vmcnt(8) lgkmcnt(0)
	s_barrier
	v_mfma_f32_16x16x32_bf16 v[120:123], v[144:147], v[178:181], v[120:123]
	v_mfma_f32_16x16x32_bf16 v[116:119], v[152:155], v[178:181], v[116:119]
	v_mfma_f32_16x16x32_bf16 v[104:107], v[144:147], v[186:189], v[104:107]
	v_mfma_f32_16x16x32_bf16 v[100:103], v[152:155], v[186:189], v[100:103]
	v_mfma_f32_16x16x32_bf16 v[88:91], v[144:147], v[194:197], v[88:91]
	v_mfma_f32_16x16x32_bf16 v[84:87], v[152:155], v[194:197], v[84:87]
	v_mfma_f32_16x16x32_bf16 v[72:75], v[144:147], v[202:205], v[72:75]
	v_mfma_f32_16x16x32_bf16 v[68:71], v[152:155], v[202:205], v[68:71]
	v_mfma_f32_16x16x32_bf16 v[120:123], v[148:151], v[182:185], v[120:123]
	v_mfma_f32_16x16x32_bf16 v[116:119], v[156:159], v[182:185], v[116:119]
	v_mfma_f32_16x16x32_bf16 v[104:107], v[148:151], v[190:193], v[104:107]
	v_mfma_f32_16x16x32_bf16 v[100:103], v[156:159], v[190:193], v[100:103]
	v_mfma_f32_16x16x32_bf16 v[88:91], v[148:151], v[198:201], v[88:91]
	v_mfma_f32_16x16x32_bf16 v[84:87], v[156:159], v[198:201], v[84:87]
	v_mfma_f32_16x16x32_bf16 v[72:75], v[148:151], v[206:209], v[72:75]
	v_mfma_f32_16x16x32_bf16 v[68:71], v[156:159], v[206:209], v[68:71]
	v_mfma_f32_16x16x32_bf16 v[124:127], v[160:163], v[178:181], v[124:127]
	v_mfma_f32_16x16x32_bf16 v[112:115], v[168:171], v[178:181], v[112:115]
	v_mfma_f32_16x16x32_bf16 v[108:111], v[160:163], v[186:189], v[108:111]
	v_mfma_f32_16x16x32_bf16 v[96:99], v[168:171], v[186:189], v[96:99]
	v_mfma_f32_16x16x32_bf16 v[92:95], v[160:163], v[194:197], v[92:95]
	v_mfma_f32_16x16x32_bf16 v[80:83], v[168:171], v[194:197], v[80:83]
	v_mfma_f32_16x16x32_bf16 v[76:79], v[160:163], v[202:205], v[76:79]
	v_mfma_f32_16x16x32_bf16 v[64:67], v[168:171], v[202:205], v[64:67]
	v_mfma_f32_16x16x32_bf16 v[124:127], v[164:167], v[182:185], v[124:127]
	v_mfma_f32_16x16x32_bf16 v[112:115], v[172:175], v[182:185], v[112:115]
	v_mfma_f32_16x16x32_bf16 v[108:111], v[164:167], v[190:193], v[108:111]
	v_mfma_f32_16x16x32_bf16 v[96:99], v[172:175], v[190:193], v[96:99]
	v_mfma_f32_16x16x32_bf16 v[92:95], v[164:167], v[198:201], v[92:95]
	v_mfma_f32_16x16x32_bf16 v[80:83], v[172:175], v[198:201], v[80:83]
	v_mfma_f32_16x16x32_bf16 v[76:79], v[164:167], v[206:209], v[76:79]
	v_mfma_f32_16x16x32_bf16 v[64:67], v[172:175], v[206:209], v[64:67]
	s_barrier
	s_add_u32 s66, s42, 0x80
	s_addc_u32 s67, s43, 0
	ds_read_b128 v[178:181], v140 offset:49152
	ds_read_b128 v[182:185], v140 offset:50176
	ds_read_b128 v[186:189], v140 offset:51200
	ds_read_b128 v[190:193], v140 offset:52224
	ds_read_b128 v[194:197], v140 offset:53248
	ds_read_b128 v[198:201], v140 offset:54272
	ds_read_b128 v[202:205], v140 offset:55296
	ds_read_b128 v[206:209], v140 offset:56320
	s_mov_b32 m0, s51
	s_nop 0
	global_load_lds_dwordx4 v135, s[66:67]
	s_add_u32 s66, s42, 0x20080
	s_mov_b32 m0, s52
	s_addc_u32 s67, s43, 0
	global_load_lds_dwordx4 v135, s[66:67]
	s_add_u32 s66, s42, 0x40080
	s_mov_b32 m0, s55
	s_addc_u32 s67, s43, 0
	global_load_lds_dwordx4 v135, s[66:67]
	s_add_u32 s42, s42, 0x60080
	s_mov_b32 m0, s56
	s_addc_u32 s43, s43, 0
	global_load_lds_dwordx4 v135, s[42:43]
	s_mov_b32 m0, s53
	s_nop 0
	global_load_lds_dwordx4 v134, s[40:41]
	s_add_u32 s38, s38, 0x20080
	s_mov_b32 m0, s54
	s_addc_u32 s39, s39, 0
	global_load_lds_dwordx4 v134, s[38:39]
	s_waitcnt vmcnt(8) lgkmcnt(0)
	s_barrier
	v_mfma_f32_16x16x32_bf16 v[56:59], v[144:147], v[178:181], v[56:59]
	v_mfma_f32_16x16x32_bf16 v[52:55], v[152:155], v[178:181], v[52:55]
	v_mfma_f32_16x16x32_bf16 v[40:43], v[144:147], v[186:189], v[40:43]
	v_mfma_f32_16x16x32_bf16 v[36:39], v[152:155], v[186:189], v[36:39]
	v_mfma_f32_16x16x32_bf16 v[24:27], v[144:147], v[194:197], v[24:27]
	v_mfma_f32_16x16x32_bf16 v[20:23], v[152:155], v[194:197], v[20:23]
	v_mfma_f32_16x16x32_bf16 v[8:11], v[144:147], v[202:205], v[8:11]
	v_mfma_f32_16x16x32_bf16 v[4:7], v[152:155], v[202:205], v[4:7]
	v_mfma_f32_16x16x32_bf16 v[56:59], v[148:151], v[182:185], v[56:59]
	v_mfma_f32_16x16x32_bf16 v[52:55], v[156:159], v[182:185], v[52:55]
	v_mfma_f32_16x16x32_bf16 v[40:43], v[148:151], v[190:193], v[40:43]
	v_mfma_f32_16x16x32_bf16 v[36:39], v[156:159], v[190:193], v[36:39]
	v_mfma_f32_16x16x32_bf16 v[24:27], v[148:151], v[198:201], v[24:27]
	v_mfma_f32_16x16x32_bf16 v[20:23], v[156:159], v[198:201], v[20:23]
	v_mfma_f32_16x16x32_bf16 v[8:11], v[148:151], v[206:209], v[8:11]
	v_mfma_f32_16x16x32_bf16 v[4:7], v[156:159], v[206:209], v[4:7]
	v_mfma_f32_16x16x32_bf16 v[60:63], v[160:163], v[178:181], v[60:63]
	v_mfma_f32_16x16x32_bf16 v[48:51], v[168:171], v[178:181], v[48:51]
	v_mfma_f32_16x16x32_bf16 v[44:47], v[160:163], v[186:189], v[44:47]
	v_mfma_f32_16x16x32_bf16 v[32:35], v[168:171], v[186:189], v[32:35]
	v_mfma_f32_16x16x32_bf16 v[28:31], v[160:163], v[194:197], v[28:31]
	v_mfma_f32_16x16x32_bf16 v[16:19], v[168:171], v[194:197], v[16:19]
	v_mfma_f32_16x16x32_bf16 v[12:15], v[160:163], v[202:205], v[12:15]
	v_mfma_f32_16x16x32_bf16 v[0:3], v[168:171], v[202:205], v[0:3]
	v_mfma_f32_16x16x32_bf16 v[60:63], v[164:167], v[182:185], v[60:63]
	v_mfma_f32_16x16x32_bf16 v[48:51], v[172:175], v[182:185], v[48:51]
	v_mfma_f32_16x16x32_bf16 v[44:47], v[164:167], v[190:193], v[44:47]
	v_mfma_f32_16x16x32_bf16 v[32:35], v[172:175], v[190:193], v[32:35]
	v_mfma_f32_16x16x32_bf16 v[28:31], v[164:167], v[198:201], v[28:31]
	v_mfma_f32_16x16x32_bf16 v[16:19], v[172:175], v[198:201], v[16:19]
	v_mfma_f32_16x16x32_bf16 v[12:15], v[164:167], v[206:209], v[12:15]
	v_mfma_f32_16x16x32_bf16 v[0:3], v[172:175], v[206:209], v[0:3]
	s_barrier
	s_cmp_gt_u32 s63, 13
	s_cbranch_scc0 .LBB0_1011
	s_and_b64 vcc, exec, s[14:15]
	s_cbranch_vccz .LBB0_1014
	s_barrier

; #define PG8_STAGE(bufoff, gbase, voff, p64) do { _Pragma("unroll") for (int _i = 0; _i < 2; ++_i) { \
;         const char* _gb = (const char*)(gbase) + (size_t)_i * (p64); const unsigned _la = ldsbase + (unsigned)(bufoff) + (unsigned)_i * 8192u; \
;         asm volatile("s_mov_b32 m0, %0\n\ts_nop 0\n\tglobal_load_lds_dwordx4 %1, %2" :: "s"(_la), "v"(voff), "s"(_gb) : "memory"); } } while (0)
; #define PG8_LDA(dst, b, h) do { _Pragma("unroll") for (int m = 0; m < 4; ++m) _Pragma("unroll") for (int k = 0; k < 2; ++k) dst[m][k] = *(const LAS bf16x8*)(lds + PG8_SA(b, h) + aoff + m * 2048 + k * 1024); } while (0)
; #define PG8_LDB(dst, b, h) do { _Pragma("unroll") for (int n = 0; n < 2; ++n) _Pragma("unroll") for (int k = 0; k < 2; ++k) dst[n][k] = *(const LAS bf16x8*)(lds + PG8_SB(b, h) + boff + n * 2048 + k * 1024); } while (0)
; #define PG8_MMA(ai, bj, At, Bt) do { __builtin_amdgcn_s_setprio(1); _Pragma("unroll") for (int m = 0; m < 4; ++m) _Pragma("unroll") for (int n = 0; n < 2; ++n) _Pragma("unroll") for (int k = 0; k < 2; ++k) \
;         acc[ai][bj][m][n] = __builtin_amdgcn_mfma_f32_16x16x32_bf16(Bt[n][k], At[m][k], acc[ai][bj][m][n], 0, 0, 0); __builtin_amdgcn_s_setprio(0); } while (0)
; #define PG8_WAIT_V(n) asm volatile("s_waitcnt vmcnt(" #n ")" ::: "memory")
; #define PG8_BAR __builtin_amdgcn_s_barrier()
; template <class Epi, class Sched>
; __device__ __forceinline__ void gemm_phase(LAS unsigned char* lds, const Sched& S, const Epi& E) {
;     ...
;             const bool last = (t == nt - 2);
;             const char* a1 = cA + (size_t)(t + 1) * kstep;
;             const char* a2 = last ? nA : cA + (size_t)(t + 2) * kstep; const char* b2 = last ? nB : cB + (size_t)(t + 2) * kstep;
;             const char* a3 = a2 + kstep; const char* b3 = b2 + kstep;
;             const unsigned vA2 = voffA, vB2 = voffB, hA2 = hA, hB2 = hB;
;             PG8_LDB(B0, 0, 0); PG8_LDB(B1, 0, 1); PG8_SCHED; PG8_LDA(At, 0, 0); PG8_STAGE(PG8_SA(1, 1), a1 + hA, voffA, hA / 2);
;             PG8_WAIT_V(8); PG8_WAIT_L(0); PG8_BAR; PG8_MMA(0, 0, At, B0); PG8_MMA(0, 1, At, B1); PG8_BAR; PG8_SCHED;
;             PG8_LDA(At, 0, 1); PG8_STAGE(PG8_SB(0, 0), b2, vB2, hB2 / 2); PG8_STAGE(PG8_SB(0, 1), b2 + hB2, vB2, hB2 / 2); PG8_STAGE(PG8_SA(0, 0), a2, vA2, hA2 / 2);
;             PG8_WAIT_V(8); PG8_WAIT_L(0); PG8_BAR; PG8_MMA(1, 0, At, B0); PG8_MMA(1, 1, At, B1); PG8_BAR; PG8_SCHED;
.LBB0_1088:
	s_add_u32 s38, s38, 0x80080
	s_addc_u32 s39, s39, 0
	s_add_u32 s60, s40, 0x100
	s_addc_u32 s61, s41, 0
	s_mov_b32 s62, -2
	ds_read_b128 v[144:147], v138
	ds_read_b128 v[148:151], v138 offset:1024
	ds_read_b128 v[152:155], v138 offset:2048
	ds_read_b128 v[156:159], v138 offset:3072
	ds_read_b128 v[160:163], v139
	ds_read_b128 v[164:167], v139 offset:1024
	ds_read_b128 v[168:171], v139 offset:2048
	ds_read_b128 v[172:175], v139 offset:3072
	s_add_u32 s30, s38, 0xfff80080
	s_addc_u32 s40, s39, -1
	s_cmp_eq_u32 s62, 28
	s_cselect_b32 s41, s25, s40
	s_cselect_b32 s40, s24, s30
	s_cselect_b32 s44, s26, s60
	s_cselect_b32 s45, s27, s61
	s_add_u32 s42, s40, 0x80
	s_addc_u32 s43, s41, 0
	ds_read_b128 v[178:181], v140
	ds_read_b128 v[182:185], v140 offset:1024
	ds_read_b128 v[186:189], v140 offset:2048
	ds_read_b128 v[190:193], v140 offset:3072
	ds_read_b128 v[194:197], v140 offset:4096
	ds_read_b128 v[198:201], v140 offset:5120
	ds_read_b128 v[202:205], v140 offset:6144
	ds_read_b128 v[206:209], v140 offset:7168
	s_mov_b32 m0, s56
	s_nop 0
	global_load_lds_dwordx4 v134, s[38:39]
	s_add_u32 s66, s38, 0x40000
	s_mov_b32 m0, s57
	s_addc_u32 s67, s39, 0
	global_load_lds_dwordx4 v134, s[66:67]
	s_waitcnt vmcnt(8) lgkmcnt(0)
	s_barrier
	v_mfma_f32_16x16x32_bf16 v[124:127], v[144:147], v[178:181], 0
	v_mfma_f32_16x16x32_bf16 v[120:123], v[152:155], v[178:181], 0
	v_mfma_f32_16x16x32_bf16 v[116:119], v[144:147], v[186:189], 0
	v_mfma_f32_16x16x32_bf16 v[108:111], v[152:155], v[186:189], 0
	v_mfma_f32_16x16x32_bf16 v[100:103], v[144:147], v[194:197], 0
	v_mfma_f32_16x16x32_bf16 v[92:95], v[152:155], v[194:197], 0
	v_mfma_f32_16x16x32_bf16 v[84:87], v[144:147], v[202:205], 0
	v_mfma_f32_16x16x32_bf16 v[76:79], v[152:155], v[202:205], 0
	v_mfma_f32_16x16x32_bf16 v[124:127], v[148:151], v[182:185], v[124:127]
	v_mfma_f32_16x16x32_bf16 v[120:123], v[156:159], v[182:185], v[120:123]
	v_mfma_f32_16x16x32_bf16 v[116:119], v[148:151], v[190:193], v[116:119]
	v_mfma_f32_16x16x32_bf16 v[108:111], v[156:159], v[190:193], v[108:111]
	v_mfma_f32_16x16x32_bf16 v[100:103], v[148:151], v[198:201], v[100:103]
	v_mfma_f32_16x16x32_bf16 v[92:95], v[156:159], v[198:201], v[92:95]
	v_mfma_f32_16x16x32_bf16 v[84:87], v[148:151], v[206:209], v[84:87]
	v_mfma_f32_16x16x32_bf16 v[76:79], v[156:159], v[206:209], v[76:79]
	v_mfma_f32_16x16x32_bf16 v[112:115], v[160:163], v[178:181], 0
	v_mfma_f32_16x16x32_bf16 v[104:107], v[168:171], v[178:181], 0
	v_mfma_f32_16x16x32_bf16 v[96:99], v[160:163], v[186:189], 0
	v_mfma_f32_16x16x32_bf16 v[88:91], v[168:171], v[186:189], 0
	v_mfma_f32_16x16x32_bf16 v[80:83], v[160:163], v[194:197], 0
	v_mfma_f32_16x16x32_bf16 v[72:75], v[168:171], v[194:197], 0
	v_mfma_f32_16x16x32_bf16 v[68:71], v[160:163], v[202:205], 0
	v_mfma_f32_16x16x32_bf16 v[64:67], v[168:171], v[202:205], 0
	v_mfma_f32_16x16x32_bf16 v[112:115], v[164:167], v[182:185], v[112:115]
	v_mfma_f32_16x16x32_bf16 v[104:107], v[172:175], v[182:185], v[104:107]
	v_mfma_f32_16x16x32_bf16 v[96:99], v[164:167], v[190:193], v[96:99]
	v_mfma_f32_16x16x32_bf16 v[88:91], v[172:175], v[190:193], v[88:91]
	v_mfma_f32_16x16x32_bf16 v[80:83], v[164:167], v[198:201], v[80:83]
	v_mfma_f32_16x16x32_bf16 v[72:75], v[172:175], v[198:201], v[72:75]
	v_mfma_f32_16x16x32_bf16 v[68:71], v[164:167], v[206:209], v[68:71]
	v_mfma_f32_16x16x32_bf16 v[64:67], v[172:175], v[206:209], v[64:67]
	s_add_i32 s62, s62, 2
	s_add_u32 s38, s38, 0x100
	s_addc_u32 s39, s39, 0
	s_add_u32 s60, s60, 0x100
	s_addc_u32 s61, s61, 0
	s_barrier
	s_add_u32 s66, s44, 0x40000
	ds_read_b128 v[178:181], v140 offset:16384
	ds_read_b128 v[182:185], v140 offset:17408
	ds_read_b128 v[186:189], v140 offset:18432
	ds_read_b128 v[190:193], v140 offset:19456
	ds_read_b128 v[194:197], v140 offset:20480
	ds_read_b128 v[198:201], v140 offset:21504
	ds_read_b128 v[202:205], v140 offset:22528
	ds_read_b128 v[206:209], v140 offset:23552
	s_mov_b32 m0, s33
	s_nop 0
	global_load_lds_dwordx4 v135, s[44:45]
	s_mov_b32 m0, s34
	s_addc_u32 s67, s45, 0
	global_load_lds_dwordx4 v135, s[66:67]
	s_add_u32 s66, s44, 0x80000
	s_mov_b32 m0, s35
	s_addc_u32 s67, s45, 0
	global_load_lds_dwordx4 v135, s[66:67]
	s_add_u32 s66, s44, 0xc0000
	s_mov_b32 m0, s36
	s_addc_u32 s67, s45, 0
	global_load_lds_dwordx4 v135, s[66:67]
	s_mov_b32 m0, s31
	s_nop 0
	global_load_lds_dwordx4 v134, s[40:41]
	s_add_u32 s66, s40, 0x40000
	s_mov_b32 m0, s37
	s_addc_u32 s67, s41, 0
	global_load_lds_dwordx4 v134, s[66:67]
	s_waitcnt vmcnt(8) lgkmcnt(0)
	s_barrier
	v_mfma_f32_16x16x32_bf16 v[60:63], v[144:147], v[178:181], 0
	v_mfma_f32_16x16x32_bf16 v[56:59], v[152:155], v[178:181], 0
	v_mfma_f32_16x16x32_bf16 v[52:55], v[144:147], v[186:189], 0
	v_mfma_f32_16x16x32_bf16 v[44:47], v[152:155], v[186:189], 0
	v_mfma_f32_16x16x32_bf16 v[36:39], v[144:147], v[194:197], 0
	v_mfma_f32_16x16x32_bf16 v[28:31], v[152:155], v[194:197], 0
	v_mfma_f32_16x16x32_bf16 v[20:23], v[144:147], v[202:205], 0
	v_mfma_f32_16x16x32_bf16 v[12:15], v[152:155], v[202:205], 0
	v_mfma_f32_16x16x32_bf16 v[60:63], v[148:151], v[182:185], v[60:63]
	v_mfma_f32_16x16x32_bf16 v[56:59], v[156:159], v[182:185], v[56:59]
	v_mfma_f32_16x16x32_bf16 v[52:55], v[148:151], v[190:193], v[52:55]
	v_mfma_f32_16x16x32_bf16 v[44:47], v[156:159], v[190:193], v[44:47]
	v_mfma_f32_16x16x32_bf16 v[36:39], v[148:151], v[198:201], v[36:39]
	v_mfma_f32_16x16x32_bf16 v[28:31], v[156:159], v[198:201], v[28:31]
	v_mfma_f32_16x16x32_bf16 v[20:23], v[148:151], v[206:209], v[20:23]
	v_mfma_f32_16x16x32_bf16 v[12:15], v[156:159], v[206:209], v[12:15]
	v_mfma_f32_16x16x32_bf16 v[48:51], v[160:163], v[178:181], 0
	v_mfma_f32_16x16x32_bf16 v[40:43], v[168:171], v[178:181], 0
	v_mfma_f32_16x16x32_bf16 v[32:35], v[160:163], v[186:189], 0
	v_mfma_f32_16x16x32_bf16 v[24:27], v[168:171], v[186:189], 0
	v_mfma_f32_16x16x32_bf16 v[16:19], v[160:163], v[194:197], 0
	v_mfma_f32_16x16x32_bf16 v[8:11], v[168:171], v[194:197], 0
	v_mfma_f32_16x16x32_bf16 v[4:7], v[160:163], v[202:205], 0
	v_mfma_f32_16x16x32_bf16 v[0:3], v[168:171], v[202:205], 0
	v_mfma_f32_16x16x32_bf16 v[48:51], v[164:167], v[182:185], v[48:51]
	v_mfma_f32_16x16x32_bf16 v[40:43], v[172:175], v[182:185], v[40:43]
	v_mfma_f32_16x16x32_bf16 v[32:35], v[164:167], v[190:193], v[32:35]
	v_mfma_f32_16x16x32_bf16 v[24:27], v[172:175], v[190:193], v[24:27]
	v_mfma_f32_16x16x32_bf16 v[16:19], v[164:167], v[198:201], v[16:19]
	v_mfma_f32_16x16x32_bf16 v[8:11], v[172:175], v[198:201], v[8:11]
	v_mfma_f32_16x16x32_bf16 v[4:7], v[164:167], v[206:209], v[4:7]
	v_mfma_f32_16x16x32_bf16 v[0:3], v[172:175], v[206:209], v[0:3]
	s_barrier
	s_branch .Lpeel_mid_32521
; #define PG8_STAGE(bufoff, gbase, voff, p64) do { _Pragma("unroll") for (int _i = 0; _i < 2; ++_i) { \
;         const char* _gb = (const char*)(gbase) + (size_t)_i * (p64); const unsigned _la = ldsbase + (unsigned)(bufoff) + (unsigned)_i * 8192u; \
;         asm volatile("s_mov_b32 m0, %0\n\ts_nop 0\n\tglobal_load_lds_dwordx4 %1, %2" :: "s"(_la), "v"(voff), "s"(_gb) : "memory"); } } while (0)
; #define PG8_LDA(dst, b, h) do { _Pragma("unroll") for (int m = 0; m < 4; ++m) _Pragma("unroll") for (int k = 0; k < 2; ++k) dst[m][k] = *(const LAS bf16x8*)(lds + PG8_SA(b, h) + aoff + m * 2048 + k * 1024); } while (0)
; #define PG8_LDB(dst, b, h) do { _Pragma("unroll") for (int n = 0; n < 2; ++n) _Pragma("unroll") for (int k = 0; k < 2; ++k) dst[n][k] = *(const LAS bf16x8*)(lds + PG8_SB(b, h) + boff + n * 2048 + k * 1024); } while (0)
; #define PG8_MMA(ai, bj, At, Bt) do { __builtin_amdgcn_s_setprio(1); _Pragma("unroll") for (int m = 0; m < 4; ++m) _Pragma("unroll") for (int n = 0; n < 2; ++n) _Pragma("unroll") for (int k = 0; k < 2; ++k) \
;         acc[ai][bj][m][n] = __builtin_amdgcn_mfma_f32_16x16x32_bf16(Bt[n][k], At[m][k], acc[ai][bj][m][n], 0, 0, 0); __builtin_amdgcn_s_setprio(0); } while (0)
; #define PG8_WAIT_V(n) asm volatile("s_waitcnt vmcnt(" #n ")" ::: "memory")
; #define PG8_BAR __builtin_amdgcn_s_barrier()
; template <class Epi, class Sched>
; __device__ __forceinline__ void gemm_phase(LAS unsigned char* lds, const Sched& S, const Epi& E) {
;     ...
;             const bool last = (t == nt - 2);
;             const char* a1 = cA + (size_t)(t + 1) * kstep;
;             const char* a2 = last ? nA : cA + (size_t)(t + 2) * kstep; const char* b2 = last ? nB : cB + (size_t)(t + 2) * kstep;
;             const char* a3 = a2 + kstep; const char* b3 = b2 + kstep;
;             const unsigned vA2 = voffA, vB2 = voffB, hA2 = hA, hB2 = hB;
;             PG8_LDB(B0, 0, 0); PG8_LDB(B1, 0, 1); PG8_SCHED; PG8_LDA(At, 0, 0); PG8_STAGE(PG8_SA(1, 1), a1 + hA, voffA, hA / 2);
;             PG8_WAIT_V(8); PG8_WAIT_L(0); PG8_BAR; PG8_MMA(0, 0, At, B0); PG8_MMA(0, 1, At, B1); PG8_BAR; PG8_SCHED;
;             PG8_LDA(At, 0, 1); PG8_STAGE(PG8_SB(0, 0), b2, vB2, hB2 / 2); PG8_STAGE(PG8_SB(0, 1), b2 + hB2, vB2, hB2 / 2); PG8_STAGE(PG8_SA(0, 0), a2, vA2, hA2 / 2);
;             PG8_WAIT_V(8); PG8_WAIT_L(0); PG8_BAR; PG8_MMA(1, 0, At, B0); PG8_MMA(1, 1, At, B1); PG8_BAR; PG8_SCHED;
.LBB0_1089:
	ds_read_b128 v[144:147], v138
	ds_read_b128 v[148:151], v138 offset:1024
	ds_read_b128 v[152:155], v138 offset:2048
	ds_read_b128 v[156:159], v138 offset:3072
	ds_read_b128 v[160:163], v139
	ds_read_b128 v[164:167], v139 offset:1024
	ds_read_b128 v[168:171], v139 offset:2048
	ds_read_b128 v[172:175], v139 offset:3072
	s_add_u32 s30, s38, 0xfff80080
	s_addc_u32 s40, s39, -1
	s_cmp_eq_u32 s62, 28
	s_cselect_b32 s41, s25, s40
	s_cselect_b32 s40, s24, s30
	s_cselect_b32 s44, s26, s60
	s_cselect_b32 s45, s27, s61
	s_add_u32 s42, s40, 0x80
	s_addc_u32 s43, s41, 0
	ds_read_b128 v[178:181], v140
	ds_read_b128 v[182:185], v140 offset:1024
	ds_read_b128 v[186:189], v140 offset:2048
	ds_read_b128 v[190:193], v140 offset:3072
	ds_read_b128 v[194:197], v140 offset:4096
	ds_read_b128 v[198:201], v140 offset:5120
	ds_read_b128 v[202:205], v140 offset:6144
	ds_read_b128 v[206:209], v140 offset:7168
	s_mov_b32 m0, s56
	s_nop 0
	global_load_lds_dwordx4 v134, s[38:39]
	s_add_u32 s66, s38, 0x40000
	s_mov_b32 m0, s57
	s_addc_u32 s67, s39, 0
	global_load_lds_dwordx4 v134, s[66:67]
	s_waitcnt vmcnt(8) lgkmcnt(0)
	s_barrier
	v_mfma_f32_16x16x32_bf16 v[124:127], v[144:147], v[178:181], v[124:127]
	v_mfma_f32_16x16x32_bf16 v[120:123], v[152:155], v[178:181], v[120:123]
	v_mfma_f32_16x16x32_bf16 v[116:119], v[144:147], v[186:189], v[116:119]
	v_mfma_f32_16x16x32_bf16 v[108:111], v[152:155], v[186:189], v[108:111]
	v_mfma_f32_16x16x32_bf16 v[100:103], v[144:147], v[194:197], v[100:103]
	v_mfma_f32_16x16x32_bf16 v[92:95], v[152:155], v[194:197], v[92:95]
	v_mfma_f32_16x16x32_bf16 v[84:87], v[144:147], v[202:205], v[84:87]
	v_mfma_f32_16x16x32_bf16 v[76:79], v[152:155], v[202:205], v[76:79]
	v_mfma_f32_16x16x32_bf16 v[124:127], v[148:151], v[182:185], v[124:127]
	v_mfma_f32_16x16x32_bf16 v[120:123], v[156:159], v[182:185], v[120:123]
	v_mfma_f32_16x16x32_bf16 v[116:119], v[148:151], v[190:193], v[116:119]
	v_mfma_f32_16x16x32_bf16 v[108:111], v[156:159], v[190:193], v[108:111]
	v_mfma_f32_16x16x32_bf16 v[100:103], v[148:151], v[198:201], v[100:103]
	v_mfma_f32_16x16x32_bf16 v[92:95], v[156:159], v[198:201], v[92:95]
	v_mfma_f32_16x16x32_bf16 v[84:87], v[148:151], v[206:209], v[84:87]
	v_mfma_f32_16x16x32_bf16 v[76:79], v[156:159], v[206:209], v[76:79]
	v_mfma_f32_16x16x32_bf16 v[112:115], v[160:163], v[178:181], v[112:115]
	v_mfma_f32_16x16x32_bf16 v[104:107], v[168:171], v[178:181], v[104:107]
	v_mfma_f32_16x16x32_bf16 v[96:99], v[160:163], v[186:189], v[96:99]
	v_mfma_f32_16x16x32_bf16 v[88:91], v[168:171], v[186:189], v[88:91]
	v_mfma_f32_16x16x32_bf16 v[80:83], v[160:163], v[194:197], v[80:83]
	v_mfma_f32_16x16x32_bf16 v[72:75], v[168:171], v[194:197], v[72:75]
	v_mfma_f32_16x16x32_bf16 v[68:71], v[160:163], v[202:205], v[68:71]
	v_mfma_f32_16x16x32_bf16 v[64:67], v[168:171], v[202:205], v[64:67]
	v_mfma_f32_16x16x32_bf16 v[112:115], v[164:167], v[182:185], v[112:115]
	v_mfma_f32_16x16x32_bf16 v[104:107], v[172:175], v[182:185], v[104:107]
	v_mfma_f32_16x16x32_bf16 v[96:99], v[164:167], v[190:193], v[96:99]
	v_mfma_f32_16x16x32_bf16 v[88:91], v[172:175], v[190:193], v[88:91]
	v_mfma_f32_16x16x32_bf16 v[80:83], v[164:167], v[198:201], v[80:83]
	v_mfma_f32_16x16x32_bf16 v[72:75], v[172:175], v[198:201], v[72:75]
	v_mfma_f32_16x16x32_bf16 v[68:71], v[164:167], v[206:209], v[68:71]
	v_mfma_f32_16x16x32_bf16 v[64:67], v[172:175], v[206:209], v[64:67]
	s_add_i32 s62, s62, 2
	s_add_u32 s38, s38, 0x100
	s_addc_u32 s39, s39, 0
	s_add_u32 s60, s60, 0x100
	s_addc_u32 s61, s61, 0
	s_barrier
	s_add_u32 s66, s44, 0x40000
	ds_read_b128 v[178:181], v140 offset:16384
	ds_read_b128 v[182:185], v140 offset:17408
	ds_read_b128 v[186:189], v140 offset:18432
	ds_read_b128 v[190:193], v140 offset:19456
	ds_read_b128 v[194:197], v140 offset:20480
	ds_read_b128 v[198:201], v140 offset:21504
	ds_read_b128 v[202:205], v140 offset:22528
	ds_read_b128 v[206:209], v140 offset:23552
	s_mov_b32 m0, s33
	s_nop 0
	global_load_lds_dwordx4 v135, s[44:45]
	s_mov_b32 m0, s34
	s_addc_u32 s67, s45, 0
	global_load_lds_dwordx4 v135, s[66:67]
	s_add_u32 s66, s44, 0x80000
	s_mov_b32 m0, s35
	s_addc_u32 s67, s45, 0
	global_load_lds_dwordx4 v135, s[66:67]
	s_add_u32 s66, s44, 0xc0000
	s_mov_b32 m0, s36
	s_addc_u32 s67, s45, 0
	global_load_lds_dwordx4 v135, s[66:67]
	s_mov_b32 m0, s31
	s_nop 0
	global_load_lds_dwordx4 v134, s[40:41]
	s_add_u32 s66, s40, 0x40000
	s_mov_b32 m0, s37
	s_addc_u32 s67, s41, 0
	global_load_lds_dwordx4 v134, s[66:67]
	s_waitcnt vmcnt(8) lgkmcnt(0)
	s_barrier
	v_mfma_f32_16x16x32_bf16 v[60:63], v[144:147], v[178:181], v[60:63]
	v_mfma_f32_16x16x32_bf16 v[56:59], v[152:155], v[178:181], v[56:59]
	v_mfma_f32_16x16x32_bf16 v[52:55], v[144:147], v[186:189], v[52:55]
	v_mfma_f32_16x16x32_bf16 v[44:47], v[152:155], v[186:189], v[44:47]
	v_mfma_f32_16x16x32_bf16 v[36:39], v[144:147], v[194:197], v[36:39]
	v_mfma_f32_16x16x32_bf16 v[28:31], v[152:155], v[194:197], v[28:31]
	v_mfma_f32_16x16x32_bf16 v[20:23], v[144:147], v[202:205], v[20:23]
	v_mfma_f32_16x16x32_bf16 v[12:15], v[152:155], v[202:205], v[12:15]
	v_mfma_f32_16x16x32_bf16 v[60:63], v[148:151], v[182:185], v[60:63]
	v_mfma_f32_16x16x32_bf16 v[56:59], v[156:159], v[182:185], v[56:59]
	v_mfma_f32_16x16x32_bf16 v[52:55], v[148:151], v[190:193], v[52:55]
	v_mfma_f32_16x16x32_bf16 v[44:47], v[156:159], v[190:193], v[44:47]
	v_mfma_f32_16x16x32_bf16 v[36:39], v[148:151], v[198:201], v[36:39]
	v_mfma_f32_16x16x32_bf16 v[28:31], v[156:159], v[198:201], v[28:31]
	v_mfma_f32_16x16x32_bf16 v[20:23], v[148:151], v[206:209], v[20:23]
	v_mfma_f32_16x16x32_bf16 v[12:15], v[156:159], v[206:209], v[12:15]
	v_mfma_f32_16x16x32_bf16 v[48:51], v[160:163], v[178:181], v[48:51]
	v_mfma_f32_16x16x32_bf16 v[40:43], v[168:171], v[178:181], v[40:43]
	v_mfma_f32_16x16x32_bf16 v[32:35], v[160:163], v[186:189], v[32:35]
	v_mfma_f32_16x16x32_bf16 v[24:27], v[168:171], v[186:189], v[24:27]
	v_mfma_f32_16x16x32_bf16 v[16:19], v[160:163], v[194:197], v[16:19]
	v_mfma_f32_16x16x32_bf16 v[8:11], v[168:171], v[194:197], v[8:11]
	v_mfma_f32_16x16x32_bf16 v[4:7], v[160:163], v[202:205], v[4:7]
	v_mfma_f32_16x16x32_bf16 v[0:3], v[168:171], v[202:205], v[0:3]
	v_mfma_f32_16x16x32_bf16 v[48:51], v[164:167], v[182:185], v[48:51]
	v_mfma_f32_16x16x32_bf16 v[40:43], v[172:175], v[182:185], v[40:43]
	v_mfma_f32_16x16x32_bf16 v[32:35], v[164:167], v[190:193], v[32:35]
	v_mfma_f32_16x16x32_bf16 v[24:27], v[172:175], v[190:193], v[24:27]
	v_mfma_f32_16x16x32_bf16 v[16:19], v[164:167], v[198:201], v[16:19]
	v_mfma_f32_16x16x32_bf16 v[8:11], v[172:175], v[198:201], v[8:11]
	v_mfma_f32_16x16x32_bf16 v[4:7], v[164:167], v[206:209], v[4:7]
	v_mfma_f32_16x16x32_bf16 v[0:3], v[172:175], v[206:209], v[0:3]
	s_barrier
; #define PG8_STAGE(bufoff, gbase, voff, p64) do { _Pragma("unroll") for (int _i = 0; _i < 2; ++_i) { \
;         const char* _gb = (const char*)(gbase) + (size_t)_i * (p64); const unsigned _la = ldsbase + (unsigned)(bufoff) + (unsigned)_i * 8192u; \
;         asm volatile("s_mov_b32 m0, %0\n\ts_nop 0\n\tglobal_load_lds_dwordx4 %1, %2" :: "s"(_la), "v"(voff), "s"(_gb) : "memory"); } } while (0)
; #define PG8_LDA(dst, b, h) do { _Pragma("unroll") for (int m = 0; m < 4; ++m) _Pragma("unroll") for (int k = 0; k < 2; ++k) dst[m][k] = *(const LAS bf16x8*)(lds + PG8_SA(b, h) + aoff + m * 2048 + k * 1024); } while (0)
; #define PG8_LDB(dst, b, h) do { _Pragma("unroll") for (int n = 0; n < 2; ++n) _Pragma("unroll") for (int k = 0; k < 2; ++k) dst[n][k] = *(const LAS bf16x8*)(lds + PG8_SB(b, h) + boff + n * 2048 + k * 1024); } while (0)
; #define PG8_MMA(ai, bj, At, Bt) do { __builtin_amdgcn_s_setprio(1); _Pragma("unroll") for (int m = 0; m < 4; ++m) _Pragma("unroll") for (int n = 0; n < 2; ++n) _Pragma("unroll") for (int k = 0; k < 2; ++k) \
;         acc[ai][bj][m][n] = __builtin_amdgcn_mfma_f32_16x16x32_bf16(Bt[n][k], At[m][k], acc[ai][bj][m][n], 0, 0, 0); __builtin_amdgcn_s_setprio(0); } while (0)
; #define PG8_WAIT_V(n) asm volatile("s_waitcnt vmcnt(" #n ")" ::: "memory")
; #define PG8_WAIT_L(n) asm volatile("s_waitcnt lgkmcnt(" #n ")" ::: "memory")
; #define PG8_BAR __builtin_amdgcn_s_barrier()
; #define PG8_SCHED __builtin_amdgcn_sched_barrier(0)
; template <class Epi, class Sched>
; __device__ __forceinline__ void gemm_phase(LAS unsigned char* lds, const Sched& S, const Epi& E) {
;     ...
;             PG8_LDB(B0, 1, 0); PG8_LDB(B1, 1, 1); PG8_SCHED; PG8_LDA(At, 1, 0); PG8_STAGE(PG8_SA(0, 1), a2 + hA2, vA2, hA2 / 2);
;             PG8_WAIT_V(8); PG8_WAIT_L(0); PG8_BAR; PG8_MMA(0, 0, At, B0); PG8_MMA(0, 1, At, B1); PG8_BAR; PG8_SCHED;
;             PG8_LDA(At, 1, 1); PG8_STAGE(PG8_SB(1, 0), b3, vB2, hB2 / 2); PG8_STAGE(PG8_SB(1, 1), b3 + hB2, vB2, hB2 / 2); PG8_STAGE(PG8_SA(1, 0), a3, vA2, hA2 / 2);
;             PG8_WAIT_V(8); PG8_WAIT_L(0); PG8_BAR; PG8_MMA(1, 0, At, B0); PG8_MMA(1, 1, At, B1); PG8_BAR; PG8_SCHED;
.Lpeel_mid_32521:
	ds_read_b128 v[144:147], v141
	ds_read_b128 v[148:151], v141 offset:1024
	ds_read_b128 v[152:155], v141 offset:2048
	ds_read_b128 v[156:159], v141 offset:3072
	ds_read_b128 v[160:163], v142
	ds_read_b128 v[164:167], v142 offset:1024
	ds_read_b128 v[168:171], v142 offset:2048
	ds_read_b128 v[172:175], v142 offset:3072
	ds_read_b128 v[178:181], v140 offset:32768
	ds_read_b128 v[182:185], v140 offset:33792
	ds_read_b128 v[186:189], v140 offset:34816
	ds_read_b128 v[190:193], v140 offset:35840
	ds_read_b128 v[194:197], v140 offset:36864
	ds_read_b128 v[198:201], v140 offset:37888
	ds_read_b128 v[202:205], v140 offset:38912
	ds_read_b128 v[206:209], v140 offset:39936
	s_add_u32 s66, s40, 0x80000
	s_mov_b32 m0, s46
	s_addc_u32 s67, s41, 0
	global_load_lds_dwordx4 v134, s[66:67]
	s_add_u32 s66, s40, 0xc0000
	s_mov_b32 m0, s47
	s_addc_u32 s67, s41, 0
	global_load_lds_dwordx4 v134, s[66:67]
	s_waitcnt vmcnt(8) lgkmcnt(0)
	s_barrier
	v_mfma_f32_16x16x32_bf16 v[124:127], v[144:147], v[178:181], v[124:127]
	v_mfma_f32_16x16x32_bf16 v[120:123], v[152:155], v[178:181], v[120:123]
	v_mfma_f32_16x16x32_bf16 v[116:119], v[144:147], v[186:189], v[116:119]
	v_mfma_f32_16x16x32_bf16 v[108:111], v[152:155], v[186:189], v[108:111]
	v_mfma_f32_16x16x32_bf16 v[100:103], v[144:147], v[194:197], v[100:103]
	v_mfma_f32_16x16x32_bf16 v[92:95], v[152:155], v[194:197], v[92:95]
	v_mfma_f32_16x16x32_bf16 v[84:87], v[144:147], v[202:205], v[84:87]
	v_mfma_f32_16x16x32_bf16 v[76:79], v[152:155], v[202:205], v[76:79]
	v_mfma_f32_16x16x32_bf16 v[124:127], v[148:151], v[182:185], v[124:127]
	v_mfma_f32_16x16x32_bf16 v[120:123], v[156:159], v[182:185], v[120:123]
	v_mfma_f32_16x16x32_bf16 v[116:119], v[148:151], v[190:193], v[116:119]
	v_mfma_f32_16x16x32_bf16 v[108:111], v[156:159], v[190:193], v[108:111]
	v_mfma_f32_16x16x32_bf16 v[100:103], v[148:151], v[198:201], v[100:103]
	v_mfma_f32_16x16x32_bf16 v[92:95], v[156:159], v[198:201], v[92:95]
	v_mfma_f32_16x16x32_bf16 v[84:87], v[148:151], v[206:209], v[84:87]
	v_mfma_f32_16x16x32_bf16 v[76:79], v[156:159], v[206:209], v[76:79]
	v_mfma_f32_16x16x32_bf16 v[112:115], v[160:163], v[178:181], v[112:115]
	v_mfma_f32_16x16x32_bf16 v[104:107], v[168:171], v[178:181], v[104:107]
	v_mfma_f32_16x16x32_bf16 v[96:99], v[160:163], v[186:189], v[96:99]
	v_mfma_f32_16x16x32_bf16 v[88:91], v[168:171], v[186:189], v[88:91]
	v_mfma_f32_16x16x32_bf16 v[80:83], v[160:163], v[194:197], v[80:83]
	v_mfma_f32_16x16x32_bf16 v[72:75], v[168:171], v[194:197], v[72:75]
	v_mfma_f32_16x16x32_bf16 v[68:71], v[160:163], v[202:205], v[68:71]
	v_mfma_f32_16x16x32_bf16 v[64:67], v[168:171], v[202:205], v[64:67]
	v_mfma_f32_16x16x32_bf16 v[112:115], v[164:167], v[182:185], v[112:115]
	v_mfma_f32_16x16x32_bf16 v[104:107], v[172:175], v[182:185], v[104:107]
	v_mfma_f32_16x16x32_bf16 v[96:99], v[164:167], v[190:193], v[96:99]
	v_mfma_f32_16x16x32_bf16 v[88:91], v[172:175], v[190:193], v[88:91]
	v_mfma_f32_16x16x32_bf16 v[80:83], v[164:167], v[198:201], v[80:83]
	v_mfma_f32_16x16x32_bf16 v[72:75], v[172:175], v[198:201], v[72:75]
	v_mfma_f32_16x16x32_bf16 v[68:71], v[164:167], v[206:209], v[68:71]
	v_mfma_f32_16x16x32_bf16 v[64:67], v[172:175], v[206:209], v[64:67]
	s_barrier
	s_add_u32 s66, s44, 0x80
	s_addc_u32 s67, s45, 0
	ds_read_b128 v[178:181], v140 offset:49152
	ds_read_b128 v[182:185], v140 offset:50176
	ds_read_b128 v[186:189], v140 offset:51200
	ds_read_b128 v[190:193], v140 offset:52224
	ds_read_b128 v[194:197], v140 offset:53248
	ds_read_b128 v[198:201], v140 offset:54272
	ds_read_b128 v[202:205], v140 offset:55296
	ds_read_b128 v[206:209], v140 offset:56320
	s_mov_b32 m0, s50
	s_nop 0
	global_load_lds_dwordx4 v135, s[66:67]
	s_add_u32 s66, s44, 0x40080
	s_mov_b32 m0, s51
	s_addc_u32 s67, s45, 0
	global_load_lds_dwordx4 v135, s[66:67]
	s_add_u32 s66, s44, 0x80080
	s_mov_b32 m0, s54
	s_addc_u32 s67, s45, 0
	global_load_lds_dwordx4 v135, s[66:67]
	s_add_u32 s44, s44, 0xc0080
	s_mov_b32 m0, s55
	s_addc_u32 s45, s45, 0
	global_load_lds_dwordx4 v135, s[44:45]
	s_mov_b32 m0, s52
	s_nop 0
	global_load_lds_dwordx4 v134, s[42:43]
	s_add_u32 s40, s40, 0x40080
	s_mov_b32 m0, s53
	s_addc_u32 s41, s41, 0
	global_load_lds_dwordx4 v134, s[40:41]
	s_waitcnt vmcnt(8) lgkmcnt(0)
	s_barrier
	v_mfma_f32_16x16x32_bf16 v[60:63], v[144:147], v[178:181], v[60:63]
	v_mfma_f32_16x16x32_bf16 v[56:59], v[152:155], v[178:181], v[56:59]
	v_mfma_f32_16x16x32_bf16 v[52:55], v[144:147], v[186:189], v[52:55]
	v_mfma_f32_16x16x32_bf16 v[44:47], v[152:155], v[186:189], v[44:47]
	v_mfma_f32_16x16x32_bf16 v[36:39], v[144:147], v[194:197], v[36:39]
	v_mfma_f32_16x16x32_bf16 v[28:31], v[152:155], v[194:197], v[28:31]
	v_mfma_f32_16x16x32_bf16 v[20:23], v[144:147], v[202:205], v[20:23]
	v_mfma_f32_16x16x32_bf16 v[12:15], v[152:155], v[202:205], v[12:15]
	v_mfma_f32_16x16x32_bf16 v[60:63], v[148:151], v[182:185], v[60:63]
	v_mfma_f32_16x16x32_bf16 v[56:59], v[156:159], v[182:185], v[56:59]
	v_mfma_f32_16x16x32_bf16 v[52:55], v[148:151], v[190:193], v[52:55]
	v_mfma_f32_16x16x32_bf16 v[44:47], v[156:159], v[190:193], v[44:47]
	v_mfma_f32_16x16x32_bf16 v[36:39], v[148:151], v[198:201], v[36:39]
	v_mfma_f32_16x16x32_bf16 v[28:31], v[156:159], v[198:201], v[28:31]
	v_mfma_f32_16x16x32_bf16 v[20:23], v[148:151], v[206:209], v[20:23]
	v_mfma_f32_16x16x32_bf16 v[12:15], v[156:159], v[206:209], v[12:15]
	v_mfma_f32_16x16x32_bf16 v[48:51], v[160:163], v[178:181], v[48:51]
	v_mfma_f32_16x16x32_bf16 v[40:43], v[168:171], v[178:181], v[40:43]
	v_mfma_f32_16x16x32_bf16 v[32:35], v[160:163], v[186:189], v[32:35]
	v_mfma_f32_16x16x32_bf16 v[24:27], v[168:171], v[186:189], v[24:27]
	v_mfma_f32_16x16x32_bf16 v[16:19], v[160:163], v[194:197], v[16:19]
	v_mfma_f32_16x16x32_bf16 v[8:11], v[168:171], v[194:197], v[8:11]
	v_mfma_f32_16x16x32_bf16 v[4:7], v[160:163], v[202:205], v[4:7]
	v_mfma_f32_16x16x32_bf16 v[0:3], v[168:171], v[202:205], v[0:3]
	v_mfma_f32_16x16x32_bf16 v[48:51], v[164:167], v[182:185], v[48:51]
	v_mfma_f32_16x16x32_bf16 v[40:43], v[172:175], v[182:185], v[40:43]
	v_mfma_f32_16x16x32_bf16 v[32:35], v[164:167], v[190:193], v[32:35]
	v_mfma_f32_16x16x32_bf16 v[24:27], v[172:175], v[190:193], v[24:27]
	v_mfma_f32_16x16x32_bf16 v[16:19], v[164:167], v[198:201], v[16:19]
	v_mfma_f32_16x16x32_bf16 v[8:11], v[172:175], v[198:201], v[8:11]
	v_mfma_f32_16x16x32_bf16 v[4:7], v[164:167], v[206:209], v[4:7]
	v_mfma_f32_16x16x32_bf16 v[0:3], v[172:175], v[206:209], v[0:3]
	s_barrier
	s_cmp_gt_u32 s62, 29
	s_cbranch_scc0 .LBB0_1089
	s_and_b64 vcc, exec, s[18:19]
	s_cbranch_vccz .LBB0_1092
	s_barrier

; #define PG8_STAGE(bufoff, gbase, voff, p64) do { _Pragma("unroll") for (int _i = 0; _i < 2; ++_i) { \
;         const char* _gb = (const char*)(gbase) + (size_t)_i * (p64); const unsigned _la = ldsbase + (unsigned)(bufoff) + (unsigned)_i * 8192u; \
;         asm volatile("s_mov_b32 m0, %0\n\ts_nop 0\n\tglobal_load_lds_dwordx4 %1, %2" :: "s"(_la), "v"(voff), "s"(_gb) : "memory"); } } while (0)
; #define PG8_LDA(dst, b, h) do { _Pragma("unroll") for (int m = 0; m < 4; ++m) _Pragma("unroll") for (int k = 0; k < 2; ++k) dst[m][k] = *(const LAS bf16x8*)(lds + PG8_SA(b, h) + aoff + m * 2048 + k * 1024); } while (0)
; #define PG8_LDB(dst, b, h) do { _Pragma("unroll") for (int n = 0; n < 2; ++n) _Pragma("unroll") for (int k = 0; k < 2; ++k) dst[n][k] = *(const LAS bf16x8*)(lds + PG8_SB(b, h) + boff + n * 2048 + k * 1024); } while (0)
; #define PG8_MMA(ai, bj, At, Bt) do { __builtin_amdgcn_s_setprio(1); _Pragma("unroll") for (int m = 0; m < 4; ++m) _Pragma("unroll") for (int n = 0; n < 2; ++n) _Pragma("unroll") for (int k = 0; k < 2; ++k) \
;         acc[ai][bj][m][n] = __builtin_amdgcn_mfma_f32_16x16x32_bf16(Bt[n][k], At[m][k], acc[ai][bj][m][n], 0, 0, 0); __builtin_amdgcn_s_setprio(0); } while (0)
; #define PG8_WAIT_V(n) asm volatile("s_waitcnt vmcnt(" #n ")" ::: "memory")
; #define PG8_BAR __builtin_amdgcn_s_barrier()
; template <class Epi, class Sched>
; __device__ __forceinline__ void gemm_phase(LAS unsigned char* lds, const Sched& S, const Epi& E) {
;     ...
;             const bool last = (t == nt - 2);
;             const char* a1 = cA + (size_t)(t + 1) * kstep;
;             const char* a2 = last ? nA : cA + (size_t)(t + 2) * kstep; const char* b2 = last ? nB : cB + (size_t)(t + 2) * kstep;
;             const char* a3 = a2 + kstep; const char* b3 = b2 + kstep;
;             const unsigned vA2 = voffA, vB2 = voffB, hA2 = hA, hB2 = hB;
;             PG8_LDB(B0, 0, 0); PG8_LDB(B1, 0, 1); PG8_SCHED; PG8_LDA(At, 0, 0); PG8_STAGE(PG8_SA(1, 1), a1 + hA, voffA, hA / 2);
;             PG8_WAIT_V(8); PG8_WAIT_L(0); PG8_BAR; PG8_MMA(0, 0, At, B0); PG8_MMA(0, 1, At, B1); PG8_BAR; PG8_SCHED;
;             PG8_LDA(At, 0, 1); PG8_STAGE(PG8_SB(0, 0), b2, vB2, hB2 / 2); PG8_STAGE(PG8_SB(0, 1), b2 + hB2, vB2, hB2 / 2); PG8_STAGE(PG8_SA(0, 0), a2, vA2, hA2 / 2);
;             PG8_WAIT_V(8); PG8_WAIT_L(0); PG8_BAR; PG8_MMA(1, 0, At, B0); PG8_MMA(1, 1, At, B1); PG8_BAR; PG8_SCHED;
.LBB0_1191:
	s_add_u32 s24, s24, 0x40080
	s_addc_u32 s25, s25, 0
	s_add_u32 s58, s26, 0x100
	s_addc_u32 s59, s27, 0
	s_mov_b32 s60, -2
	ds_read_b128 v[144:147], v138
	ds_read_b128 v[148:151], v138 offset:1024
	ds_read_b128 v[152:155], v138 offset:2048
	ds_read_b128 v[156:159], v138 offset:3072
	ds_read_b128 v[160:163], v139
	ds_read_b128 v[164:167], v139 offset:1024
	ds_read_b128 v[168:171], v139 offset:2048
	ds_read_b128 v[172:175], v139 offset:3072
	s_add_u32 s26, s24, 0xfffc0080
	s_addc_u32 s27, s25, -1
	s_cmp_eq_u32 s60, 12
	s_cselect_b32 s26, s20, s26
	s_cselect_b32 s27, s21, s27
	s_cselect_b32 s40, s22, s58
	s_cselect_b32 s41, s23, s59
	s_add_u32 s38, s26, 0x80
	s_addc_u32 s39, s27, 0
	ds_read_b128 v[178:181], v140
	ds_read_b128 v[182:185], v140 offset:1024
	ds_read_b128 v[186:189], v140 offset:2048
	ds_read_b128 v[190:193], v140 offset:3072
	ds_read_b128 v[194:197], v140 offset:4096
	ds_read_b128 v[198:201], v140 offset:5120
	ds_read_b128 v[202:205], v140 offset:6144
	ds_read_b128 v[206:209], v140 offset:7168
	s_mov_b32 m0, s54
	s_nop 0
	global_load_lds_dwordx4 v134, s[24:25]
	s_add_u32 s62, s24, 0x20000
	s_mov_b32 m0, s55
	s_addc_u32 s63, s25, 0
	global_load_lds_dwordx4 v134, s[62:63]
	s_waitcnt vmcnt(8) lgkmcnt(0)
	s_barrier
	v_mfma_f32_16x16x32_bf16 v[124:127], v[144:147], v[178:181], 0
	v_mfma_f32_16x16x32_bf16 v[120:123], v[152:155], v[178:181], 0
	v_mfma_f32_16x16x32_bf16 v[116:119], v[144:147], v[186:189], 0
	v_mfma_f32_16x16x32_bf16 v[108:111], v[152:155], v[186:189], 0
	v_mfma_f32_16x16x32_bf16 v[100:103], v[144:147], v[194:197], 0
	v_mfma_f32_16x16x32_bf16 v[92:95], v[152:155], v[194:197], 0
	v_mfma_f32_16x16x32_bf16 v[84:87], v[144:147], v[202:205], 0
	v_mfma_f32_16x16x32_bf16 v[76:79], v[152:155], v[202:205], 0
	v_mfma_f32_16x16x32_bf16 v[124:127], v[148:151], v[182:185], v[124:127]
	v_mfma_f32_16x16x32_bf16 v[120:123], v[156:159], v[182:185], v[120:123]
	v_mfma_f32_16x16x32_bf16 v[116:119], v[148:151], v[190:193], v[116:119]
	v_mfma_f32_16x16x32_bf16 v[108:111], v[156:159], v[190:193], v[108:111]
	v_mfma_f32_16x16x32_bf16 v[100:103], v[148:151], v[198:201], v[100:103]
	v_mfma_f32_16x16x32_bf16 v[92:95], v[156:159], v[198:201], v[92:95]
	v_mfma_f32_16x16x32_bf16 v[84:87], v[148:151], v[206:209], v[84:87]
	v_mfma_f32_16x16x32_bf16 v[76:79], v[156:159], v[206:209], v[76:79]
	v_mfma_f32_16x16x32_bf16 v[112:115], v[160:163], v[178:181], 0
	v_mfma_f32_16x16x32_bf16 v[104:107], v[168:171], v[178:181], 0
	v_mfma_f32_16x16x32_bf16 v[96:99], v[160:163], v[186:189], 0
	v_mfma_f32_16x16x32_bf16 v[88:91], v[168:171], v[186:189], 0
	v_mfma_f32_16x16x32_bf16 v[80:83], v[160:163], v[194:197], 0
	v_mfma_f32_16x16x32_bf16 v[72:75], v[168:171], v[194:197], 0
	v_mfma_f32_16x16x32_bf16 v[68:71], v[160:163], v[202:205], 0
	v_mfma_f32_16x16x32_bf16 v[64:67], v[168:171], v[202:205], 0
	v_mfma_f32_16x16x32_bf16 v[112:115], v[164:167], v[182:185], v[112:115]
	v_mfma_f32_16x16x32_bf16 v[104:107], v[172:175], v[182:185], v[104:107]
	v_mfma_f32_16x16x32_bf16 v[96:99], v[164:167], v[190:193], v[96:99]
	v_mfma_f32_16x16x32_bf16 v[88:91], v[172:175], v[190:193], v[88:91]
	v_mfma_f32_16x16x32_bf16 v[80:83], v[164:167], v[198:201], v[80:83]
	v_mfma_f32_16x16x32_bf16 v[72:75], v[172:175], v[198:201], v[72:75]
	v_mfma_f32_16x16x32_bf16 v[68:71], v[164:167], v[206:209], v[68:71]
	v_mfma_f32_16x16x32_bf16 v[64:67], v[172:175], v[206:209], v[64:67]
	s_add_i32 s60, s60, 2
	s_add_u32 s24, s24, 0x100
	s_addc_u32 s25, s25, 0
	s_add_u32 s58, s58, 0x100
	s_addc_u32 s59, s59, 0
	s_barrier
	s_add_u32 s62, s40, 0x20000
	ds_read_b128 v[178:181], v140 offset:16384
	ds_read_b128 v[182:185], v140 offset:17408
	ds_read_b128 v[186:189], v140 offset:18432
	ds_read_b128 v[190:193], v140 offset:19456
	ds_read_b128 v[194:197], v140 offset:20480
	ds_read_b128 v[198:201], v140 offset:21504
	ds_read_b128 v[202:205], v140 offset:22528
	ds_read_b128 v[206:209], v140 offset:23552
	s_mov_b32 m0, s35
	s_nop 0
	global_load_lds_dwordx4 v135, s[40:41]
	s_mov_b32 m0, s36
	s_addc_u32 s63, s41, 0
	global_load_lds_dwordx4 v135, s[62:63]
	s_add_u32 s62, s40, 0x40000
	s_mov_b32 m0, s37
	s_addc_u32 s63, s41, 0
	global_load_lds_dwordx4 v135, s[62:63]
	s_add_u32 s62, s40, 0x60000
	s_mov_b32 m0, s42
	s_addc_u32 s63, s41, 0
	global_load_lds_dwordx4 v135, s[62:63]
	s_mov_b32 m0, s34
	s_nop 0
	global_load_lds_dwordx4 v134, s[26:27]
	s_add_u32 s62, s26, 0x20000
	s_mov_b32 m0, s43
	s_addc_u32 s63, s27, 0
	global_load_lds_dwordx4 v134, s[62:63]
	s_waitcnt vmcnt(8) lgkmcnt(0)
	s_barrier
	v_mfma_f32_16x16x32_bf16 v[60:63], v[144:147], v[178:181], 0
	v_mfma_f32_16x16x32_bf16 v[56:59], v[152:155], v[178:181], 0
	v_mfma_f32_16x16x32_bf16 v[52:55], v[144:147], v[186:189], 0
	v_mfma_f32_16x16x32_bf16 v[44:47], v[152:155], v[186:189], 0
	v_mfma_f32_16x16x32_bf16 v[36:39], v[144:147], v[194:197], 0
	v_mfma_f32_16x16x32_bf16 v[28:31], v[152:155], v[194:197], 0
	v_mfma_f32_16x16x32_bf16 v[20:23], v[144:147], v[202:205], 0
	v_mfma_f32_16x16x32_bf16 v[12:15], v[152:155], v[202:205], 0
	v_mfma_f32_16x16x32_bf16 v[60:63], v[148:151], v[182:185], v[60:63]
	v_mfma_f32_16x16x32_bf16 v[56:59], v[156:159], v[182:185], v[56:59]
	v_mfma_f32_16x16x32_bf16 v[52:55], v[148:151], v[190:193], v[52:55]
	v_mfma_f32_16x16x32_bf16 v[44:47], v[156:159], v[190:193], v[44:47]
	v_mfma_f32_16x16x32_bf16 v[36:39], v[148:151], v[198:201], v[36:39]
	v_mfma_f32_16x16x32_bf16 v[28:31], v[156:159], v[198:201], v[28:31]
	v_mfma_f32_16x16x32_bf16 v[20:23], v[148:151], v[206:209], v[20:23]
	v_mfma_f32_16x16x32_bf16 v[12:15], v[156:159], v[206:209], v[12:15]
	v_mfma_f32_16x16x32_bf16 v[48:51], v[160:163], v[178:181], 0
	v_mfma_f32_16x16x32_bf16 v[40:43], v[168:171], v[178:181], 0
	v_mfma_f32_16x16x32_bf16 v[32:35], v[160:163], v[186:189], 0
	v_mfma_f32_16x16x32_bf16 v[24:27], v[168:171], v[186:189], 0
	v_mfma_f32_16x16x32_bf16 v[16:19], v[160:163], v[194:197], 0
	v_mfma_f32_16x16x32_bf16 v[8:11], v[168:171], v[194:197], 0
	v_mfma_f32_16x16x32_bf16 v[4:7], v[160:163], v[202:205], 0
	v_mfma_f32_16x16x32_bf16 v[0:3], v[168:171], v[202:205], 0
	v_mfma_f32_16x16x32_bf16 v[48:51], v[164:167], v[182:185], v[48:51]
	v_mfma_f32_16x16x32_bf16 v[40:43], v[172:175], v[182:185], v[40:43]
	v_mfma_f32_16x16x32_bf16 v[32:35], v[164:167], v[190:193], v[32:35]
	v_mfma_f32_16x16x32_bf16 v[24:27], v[172:175], v[190:193], v[24:27]
	v_mfma_f32_16x16x32_bf16 v[16:19], v[164:167], v[198:201], v[16:19]
	v_mfma_f32_16x16x32_bf16 v[8:11], v[172:175], v[198:201], v[8:11]
	v_mfma_f32_16x16x32_bf16 v[4:7], v[164:167], v[206:209], v[4:7]
	v_mfma_f32_16x16x32_bf16 v[0:3], v[172:175], v[206:209], v[0:3]
	s_barrier
	s_branch .Lpeel_mid_36225
; #define PG8_STAGE(bufoff, gbase, voff, p64) do { _Pragma("unroll") for (int _i = 0; _i < 2; ++_i) { \
;         const char* _gb = (const char*)(gbase) + (size_t)_i * (p64); const unsigned _la = ldsbase + (unsigned)(bufoff) + (unsigned)_i * 8192u; \
;         asm volatile("s_mov_b32 m0, %0\n\ts_nop 0\n\tglobal_load_lds_dwordx4 %1, %2" :: "s"(_la), "v"(voff), "s"(_gb) : "memory"); } } while (0)
; #define PG8_LDA(dst, b, h) do { _Pragma("unroll") for (int m = 0; m < 4; ++m) _Pragma("unroll") for (int k = 0; k < 2; ++k) dst[m][k] = *(const LAS bf16x8*)(lds + PG8_SA(b, h) + aoff + m * 2048 + k * 1024); } while (0)
; #define PG8_LDB(dst, b, h) do { _Pragma("unroll") for (int n = 0; n < 2; ++n) _Pragma("unroll") for (int k = 0; k < 2; ++k) dst[n][k] = *(const LAS bf16x8*)(lds + PG8_SB(b, h) + boff + n * 2048 + k * 1024); } while (0)
; #define PG8_MMA(ai, bj, At, Bt) do { __builtin_amdgcn_s_setprio(1); _Pragma("unroll") for (int m = 0; m < 4; ++m) _Pragma("unroll") for (int n = 0; n < 2; ++n) _Pragma("unroll") for (int k = 0; k < 2; ++k) \
;         acc[ai][bj][m][n] = __builtin_amdgcn_mfma_f32_16x16x32_bf16(Bt[n][k], At[m][k], acc[ai][bj][m][n], 0, 0, 0); __builtin_amdgcn_s_setprio(0); } while (0)
; #define PG8_WAIT_V(n) asm volatile("s_waitcnt vmcnt(" #n ")" ::: "memory")
; #define PG8_BAR __builtin_amdgcn_s_barrier()
; template <class Epi, class Sched>
; __device__ __forceinline__ void gemm_phase(LAS unsigned char* lds, const Sched& S, const Epi& E) {
;     ...
;             const bool last = (t == nt - 2);
;             const char* a1 = cA + (size_t)(t + 1) * kstep;
;             const char* a2 = last ? nA : cA + (size_t)(t + 2) * kstep; const char* b2 = last ? nB : cB + (size_t)(t + 2) * kstep;
;             const char* a3 = a2 + kstep; const char* b3 = b2 + kstep;
;             const unsigned vA2 = voffA, vB2 = voffB, hA2 = hA, hB2 = hB;
;             PG8_LDB(B0, 0, 0); PG8_LDB(B1, 0, 1); PG8_SCHED; PG8_LDA(At, 0, 0); PG8_STAGE(PG8_SA(1, 1), a1 + hA, voffA, hA / 2);
;             PG8_WAIT_V(8); PG8_WAIT_L(0); PG8_BAR; PG8_MMA(0, 0, At, B0); PG8_MMA(0, 1, At, B1); PG8_BAR; PG8_SCHED;
;             PG8_LDA(At, 0, 1); PG8_STAGE(PG8_SB(0, 0), b2, vB2, hB2 / 2); PG8_STAGE(PG8_SB(0, 1), b2 + hB2, vB2, hB2 / 2); PG8_STAGE(PG8_SA(0, 0), a2, vA2, hA2 / 2);
;             PG8_WAIT_V(8); PG8_WAIT_L(0); PG8_BAR; PG8_MMA(1, 0, At, B0); PG8_MMA(1, 1, At, B1); PG8_BAR; PG8_SCHED;
.LBB0_1192:
	ds_read_b128 v[144:147], v138
	ds_read_b128 v[148:151], v138 offset:1024
	ds_read_b128 v[152:155], v138 offset:2048
	ds_read_b128 v[156:159], v138 offset:3072
	ds_read_b128 v[160:163], v139
	ds_read_b128 v[164:167], v139 offset:1024
	ds_read_b128 v[168:171], v139 offset:2048
	ds_read_b128 v[172:175], v139 offset:3072
	s_add_u32 s26, s24, 0xfffc0080
	s_addc_u32 s27, s25, -1
	s_cmp_eq_u32 s60, 12
	s_cselect_b32 s26, s20, s26
	s_cselect_b32 s27, s21, s27
	s_cselect_b32 s40, s22, s58
	s_cselect_b32 s41, s23, s59
	s_add_u32 s38, s26, 0x80
	s_addc_u32 s39, s27, 0
	ds_read_b128 v[178:181], v140
	ds_read_b128 v[182:185], v140 offset:1024
	ds_read_b128 v[186:189], v140 offset:2048
	ds_read_b128 v[190:193], v140 offset:3072
	ds_read_b128 v[194:197], v140 offset:4096
	ds_read_b128 v[198:201], v140 offset:5120
	ds_read_b128 v[202:205], v140 offset:6144
	ds_read_b128 v[206:209], v140 offset:7168
	s_mov_b32 m0, s54
	s_nop 0
	global_load_lds_dwordx4 v134, s[24:25]
	s_add_u32 s62, s24, 0x20000
	s_mov_b32 m0, s55
	s_addc_u32 s63, s25, 0
	global_load_lds_dwordx4 v134, s[62:63]
	s_waitcnt vmcnt(8) lgkmcnt(0)
	s_barrier
	v_mfma_f32_16x16x32_bf16 v[124:127], v[144:147], v[178:181], v[124:127]
	v_mfma_f32_16x16x32_bf16 v[120:123], v[152:155], v[178:181], v[120:123]
	v_mfma_f32_16x16x32_bf16 v[116:119], v[144:147], v[186:189], v[116:119]
	v_mfma_f32_16x16x32_bf16 v[108:111], v[152:155], v[186:189], v[108:111]
	v_mfma_f32_16x16x32_bf16 v[100:103], v[144:147], v[194:197], v[100:103]
	v_mfma_f32_16x16x32_bf16 v[92:95], v[152:155], v[194:197], v[92:95]
	v_mfma_f32_16x16x32_bf16 v[84:87], v[144:147], v[202:205], v[84:87]
	v_mfma_f32_16x16x32_bf16 v[76:79], v[152:155], v[202:205], v[76:79]
	v_mfma_f32_16x16x32_bf16 v[124:127], v[148:151], v[182:185], v[124:127]
	v_mfma_f32_16x16x32_bf16 v[120:123], v[156:159], v[182:185], v[120:123]
	v_mfma_f32_16x16x32_bf16 v[116:119], v[148:151], v[190:193], v[116:119]
	v_mfma_f32_16x16x32_bf16 v[108:111], v[156:159], v[190:193], v[108:111]
	v_mfma_f32_16x16x32_bf16 v[100:103], v[148:151], v[198:201], v[100:103]
	v_mfma_f32_16x16x32_bf16 v[92:95], v[156:159], v[198:201], v[92:95]
	v_mfma_f32_16x16x32_bf16 v[84:87], v[148:151], v[206:209], v[84:87]
	v_mfma_f32_16x16x32_bf16 v[76:79], v[156:159], v[206:209], v[76:79]
	v_mfma_f32_16x16x32_bf16 v[112:115], v[160:163], v[178:181], v[112:115]
	v_mfma_f32_16x16x32_bf16 v[104:107], v[168:171], v[178:181], v[104:107]
	v_mfma_f32_16x16x32_bf16 v[96:99], v[160:163], v[186:189], v[96:99]
	v_mfma_f32_16x16x32_bf16 v[88:91], v[168:171], v[186:189], v[88:91]
	v_mfma_f32_16x16x32_bf16 v[80:83], v[160:163], v[194:197], v[80:83]
	v_mfma_f32_16x16x32_bf16 v[72:75], v[168:171], v[194:197], v[72:75]
	v_mfma_f32_16x16x32_bf16 v[68:71], v[160:163], v[202:205], v[68:71]
	v_mfma_f32_16x16x32_bf16 v[64:67], v[168:171], v[202:205], v[64:67]
	v_mfma_f32_16x16x32_bf16 v[112:115], v[164:167], v[182:185], v[112:115]
	v_mfma_f32_16x16x32_bf16 v[104:107], v[172:175], v[182:185], v[104:107]
	v_mfma_f32_16x16x32_bf16 v[96:99], v[164:167], v[190:193], v[96:99]
	v_mfma_f32_16x16x32_bf16 v[88:91], v[172:175], v[190:193], v[88:91]
	v_mfma_f32_16x16x32_bf16 v[80:83], v[164:167], v[198:201], v[80:83]
	v_mfma_f32_16x16x32_bf16 v[72:75], v[172:175], v[198:201], v[72:75]
	v_mfma_f32_16x16x32_bf16 v[68:71], v[164:167], v[206:209], v[68:71]
	v_mfma_f32_16x16x32_bf16 v[64:67], v[172:175], v[206:209], v[64:67]
	s_add_i32 s60, s60, 2
	s_add_u32 s24, s24, 0x100
	s_addc_u32 s25, s25, 0
	s_add_u32 s58, s58, 0x100
	s_addc_u32 s59, s59, 0
	s_barrier
	s_add_u32 s62, s40, 0x20000
	ds_read_b128 v[178:181], v140 offset:16384
	ds_read_b128 v[182:185], v140 offset:17408
	ds_read_b128 v[186:189], v140 offset:18432
	ds_read_b128 v[190:193], v140 offset:19456
	ds_read_b128 v[194:197], v140 offset:20480
	ds_read_b128 v[198:201], v140 offset:21504
	ds_read_b128 v[202:205], v140 offset:22528
	ds_read_b128 v[206:209], v140 offset:23552
	s_mov_b32 m0, s35
	s_nop 0
	global_load_lds_dwordx4 v135, s[40:41]
	s_mov_b32 m0, s36
	s_addc_u32 s63, s41, 0
	global_load_lds_dwordx4 v135, s[62:63]
	s_add_u32 s62, s40, 0x40000
	s_mov_b32 m0, s37
	s_addc_u32 s63, s41, 0
	global_load_lds_dwordx4 v135, s[62:63]
	s_add_u32 s62, s40, 0x60000
	s_mov_b32 m0, s42
	s_addc_u32 s63, s41, 0
	global_load_lds_dwordx4 v135, s[62:63]
	s_mov_b32 m0, s34
	s_nop 0
	global_load_lds_dwordx4 v134, s[26:27]
	s_add_u32 s62, s26, 0x20000
	s_mov_b32 m0, s43
	s_addc_u32 s63, s27, 0
	global_load_lds_dwordx4 v134, s[62:63]
	s_waitcnt vmcnt(8) lgkmcnt(0)
	s_barrier
	v_mfma_f32_16x16x32_bf16 v[60:63], v[144:147], v[178:181], v[60:63]
	v_mfma_f32_16x16x32_bf16 v[56:59], v[152:155], v[178:181], v[56:59]
	v_mfma_f32_16x16x32_bf16 v[52:55], v[144:147], v[186:189], v[52:55]
	v_mfma_f32_16x16x32_bf16 v[44:47], v[152:155], v[186:189], v[44:47]
	v_mfma_f32_16x16x32_bf16 v[36:39], v[144:147], v[194:197], v[36:39]
	v_mfma_f32_16x16x32_bf16 v[28:31], v[152:155], v[194:197], v[28:31]
	v_mfma_f32_16x16x32_bf16 v[20:23], v[144:147], v[202:205], v[20:23]
	v_mfma_f32_16x16x32_bf16 v[12:15], v[152:155], v[202:205], v[12:15]
	v_mfma_f32_16x16x32_bf16 v[60:63], v[148:151], v[182:185], v[60:63]
	v_mfma_f32_16x16x32_bf16 v[56:59], v[156:159], v[182:185], v[56:59]
	v_mfma_f32_16x16x32_bf16 v[52:55], v[148:151], v[190:193], v[52:55]
	v_mfma_f32_16x16x32_bf16 v[44:47], v[156:159], v[190:193], v[44:47]
	v_mfma_f32_16x16x32_bf16 v[36:39], v[148:151], v[198:201], v[36:39]
	v_mfma_f32_16x16x32_bf16 v[28:31], v[156:159], v[198:201], v[28:31]
	v_mfma_f32_16x16x32_bf16 v[20:23], v[148:151], v[206:209], v[20:23]
	v_mfma_f32_16x16x32_bf16 v[12:15], v[156:159], v[206:209], v[12:15]
	v_mfma_f32_16x16x32_bf16 v[48:51], v[160:163], v[178:181], v[48:51]
	v_mfma_f32_16x16x32_bf16 v[40:43], v[168:171], v[178:181], v[40:43]
	v_mfma_f32_16x16x32_bf16 v[32:35], v[160:163], v[186:189], v[32:35]
	v_mfma_f32_16x16x32_bf16 v[24:27], v[168:171], v[186:189], v[24:27]
	v_mfma_f32_16x16x32_bf16 v[16:19], v[160:163], v[194:197], v[16:19]
	v_mfma_f32_16x16x32_bf16 v[8:11], v[168:171], v[194:197], v[8:11]
	v_mfma_f32_16x16x32_bf16 v[4:7], v[160:163], v[202:205], v[4:7]
	v_mfma_f32_16x16x32_bf16 v[0:3], v[168:171], v[202:205], v[0:3]
	v_mfma_f32_16x16x32_bf16 v[48:51], v[164:167], v[182:185], v[48:51]
	v_mfma_f32_16x16x32_bf16 v[40:43], v[172:175], v[182:185], v[40:43]
	v_mfma_f32_16x16x32_bf16 v[32:35], v[164:167], v[190:193], v[32:35]
	v_mfma_f32_16x16x32_bf16 v[24:27], v[172:175], v[190:193], v[24:27]
	v_mfma_f32_16x16x32_bf16 v[16:19], v[164:167], v[198:201], v[16:19]
	v_mfma_f32_16x16x32_bf16 v[8:11], v[172:175], v[198:201], v[8:11]
	v_mfma_f32_16x16x32_bf16 v[4:7], v[164:167], v[206:209], v[4:7]
	v_mfma_f32_16x16x32_bf16 v[0:3], v[172:175], v[206:209], v[0:3]
	s_barrier
; #define PG8_STAGE(bufoff, gbase, voff, p64) do { _Pragma("unroll") for (int _i = 0; _i < 2; ++_i) { \
;         const char* _gb = (const char*)(gbase) + (size_t)_i * (p64); const unsigned _la = ldsbase + (unsigned)(bufoff) + (unsigned)_i * 8192u; \
;         asm volatile("s_mov_b32 m0, %0\n\ts_nop 0\n\tglobal_load_lds_dwordx4 %1, %2" :: "s"(_la), "v"(voff), "s"(_gb) : "memory"); } } while (0)
; #define PG8_LDA(dst, b, h) do { _Pragma("unroll") for (int m = 0; m < 4; ++m) _Pragma("unroll") for (int k = 0; k < 2; ++k) dst[m][k] = *(const LAS bf16x8*)(lds + PG8_SA(b, h) + aoff + m * 2048 + k * 1024); } while (0)
; #define PG8_LDB(dst, b, h) do { _Pragma("unroll") for (int n = 0; n < 2; ++n) _Pragma("unroll") for (int k = 0; k < 2; ++k) dst[n][k] = *(const LAS bf16x8*)(lds + PG8_SB(b, h) + boff + n * 2048 + k * 1024); } while (0)
; #define PG8_MMA(ai, bj, At, Bt) do { __builtin_amdgcn_s_setprio(1); _Pragma("unroll") for (int m = 0; m < 4; ++m) _Pragma("unroll") for (int n = 0; n < 2; ++n) _Pragma("unroll") for (int k = 0; k < 2; ++k) \
;         acc[ai][bj][m][n] = __builtin_amdgcn_mfma_f32_16x16x32_bf16(Bt[n][k], At[m][k], acc[ai][bj][m][n], 0, 0, 0); __builtin_amdgcn_s_setprio(0); } while (0)
; #define PG8_WAIT_V(n) asm volatile("s_waitcnt vmcnt(" #n ")" ::: "memory")
; #define PG8_WAIT_L(n) asm volatile("s_waitcnt lgkmcnt(" #n ")" ::: "memory")
; #define PG8_BAR __builtin_amdgcn_s_barrier()
; #define PG8_SCHED __builtin_amdgcn_sched_barrier(0)
; template <class Epi, class Sched>
; __device__ __forceinline__ void gemm_phase(LAS unsigned char* lds, const Sched& S, const Epi& E) {
;     ...
;             PG8_LDB(B0, 1, 0); PG8_LDB(B1, 1, 1); PG8_SCHED; PG8_LDA(At, 1, 0); PG8_STAGE(PG8_SA(0, 1), a2 + hA2, vA2, hA2 / 2);
;             PG8_WAIT_V(8); PG8_WAIT_L(0); PG8_BAR; PG8_MMA(0, 0, At, B0); PG8_MMA(0, 1, At, B1); PG8_BAR; PG8_SCHED;
;             PG8_LDA(At, 1, 1); PG8_STAGE(PG8_SB(1, 0), b3, vB2, hB2 / 2); PG8_STAGE(PG8_SB(1, 1), b3 + hB2, vB2, hB2 / 2); PG8_STAGE(PG8_SA(1, 0), a3, vA2, hA2 / 2);
;             PG8_WAIT_V(8); PG8_WAIT_L(0); PG8_BAR; PG8_MMA(1, 0, At, B0); PG8_MMA(1, 1, At, B1); PG8_BAR; PG8_SCHED;
.Lpeel_mid_36225:
	ds_read_b128 v[144:147], v141
	ds_read_b128 v[148:151], v141 offset:1024
	ds_read_b128 v[152:155], v141 offset:2048
	ds_read_b128 v[156:159], v141 offset:3072
	ds_read_b128 v[160:163], v142
	ds_read_b128 v[164:167], v142 offset:1024
	ds_read_b128 v[168:171], v142 offset:2048
	ds_read_b128 v[172:175], v142 offset:3072
	ds_read_b128 v[178:181], v140 offset:32768
	ds_read_b128 v[182:185], v140 offset:33792
	ds_read_b128 v[186:189], v140 offset:34816
	ds_read_b128 v[190:193], v140 offset:35840
	ds_read_b128 v[194:197], v140 offset:36864
	ds_read_b128 v[198:201], v140 offset:37888
	ds_read_b128 v[202:205], v140 offset:38912
	ds_read_b128 v[206:209], v140 offset:39936
	s_add_u32 s62, s26, 0x40000
	s_mov_b32 m0, s44
	s_addc_u32 s63, s27, 0
	global_load_lds_dwordx4 v134, s[62:63]
	s_add_u32 s62, s26, 0x60000
	s_mov_b32 m0, s45
	s_addc_u32 s63, s27, 0
	global_load_lds_dwordx4 v134, s[62:63]
	s_waitcnt vmcnt(8) lgkmcnt(0)
	s_barrier
	v_mfma_f32_16x16x32_bf16 v[124:127], v[144:147], v[178:181], v[124:127]
	v_mfma_f32_16x16x32_bf16 v[120:123], v[152:155], v[178:181], v[120:123]
	v_mfma_f32_16x16x32_bf16 v[116:119], v[144:147], v[186:189], v[116:119]
	v_mfma_f32_16x16x32_bf16 v[108:111], v[152:155], v[186:189], v[108:111]
	v_mfma_f32_16x16x32_bf16 v[100:103], v[144:147], v[194:197], v[100:103]
	v_mfma_f32_16x16x32_bf16 v[92:95], v[152:155], v[194:197], v[92:95]
	v_mfma_f32_16x16x32_bf16 v[84:87], v[144:147], v[202:205], v[84:87]
	v_mfma_f32_16x16x32_bf16 v[76:79], v[152:155], v[202:205], v[76:79]
	v_mfma_f32_16x16x32_bf16 v[124:127], v[148:151], v[182:185], v[124:127]
	v_mfma_f32_16x16x32_bf16 v[120:123], v[156:159], v[182:185], v[120:123]
	v_mfma_f32_16x16x32_bf16 v[116:119], v[148:151], v[190:193], v[116:119]
	v_mfma_f32_16x16x32_bf16 v[108:111], v[156:159], v[190:193], v[108:111]
	v_mfma_f32_16x16x32_bf16 v[100:103], v[148:151], v[198:201], v[100:103]
	v_mfma_f32_16x16x32_bf16 v[92:95], v[156:159], v[198:201], v[92:95]
	v_mfma_f32_16x16x32_bf16 v[84:87], v[148:151], v[206:209], v[84:87]
	v_mfma_f32_16x16x32_bf16 v[76:79], v[156:159], v[206:209], v[76:79]
	v_mfma_f32_16x16x32_bf16 v[112:115], v[160:163], v[178:181], v[112:115]
	v_mfma_f32_16x16x32_bf16 v[104:107], v[168:171], v[178:181], v[104:107]
	v_mfma_f32_16x16x32_bf16 v[96:99], v[160:163], v[186:189], v[96:99]
	v_mfma_f32_16x16x32_bf16 v[88:91], v[168:171], v[186:189], v[88:91]
	v_mfma_f32_16x16x32_bf16 v[80:83], v[160:163], v[194:197], v[80:83]
	v_mfma_f32_16x16x32_bf16 v[72:75], v[168:171], v[194:197], v[72:75]
	v_mfma_f32_16x16x32_bf16 v[68:71], v[160:163], v[202:205], v[68:71]
	v_mfma_f32_16x16x32_bf16 v[64:67], v[168:171], v[202:205], v[64:67]
	v_mfma_f32_16x16x32_bf16 v[112:115], v[164:167], v[182:185], v[112:115]
	v_mfma_f32_16x16x32_bf16 v[104:107], v[172:175], v[182:185], v[104:107]
	v_mfma_f32_16x16x32_bf16 v[96:99], v[164:167], v[190:193], v[96:99]
	v_mfma_f32_16x16x32_bf16 v[88:91], v[172:175], v[190:193], v[88:91]
	v_mfma_f32_16x16x32_bf16 v[80:83], v[164:167], v[198:201], v[80:83]
	v_mfma_f32_16x16x32_bf16 v[72:75], v[172:175], v[198:201], v[72:75]
	v_mfma_f32_16x16x32_bf16 v[68:71], v[164:167], v[206:209], v[68:71]
	v_mfma_f32_16x16x32_bf16 v[64:67], v[172:175], v[206:209], v[64:67]
	s_barrier
	s_add_u32 s62, s40, 0x80
	s_addc_u32 s63, s41, 0
	ds_read_b128 v[178:181], v140 offset:49152
	ds_read_b128 v[182:185], v140 offset:50176
	ds_read_b128 v[186:189], v140 offset:51200
	ds_read_b128 v[190:193], v140 offset:52224
	ds_read_b128 v[194:197], v140 offset:53248
	ds_read_b128 v[198:201], v140 offset:54272
	ds_read_b128 v[202:205], v140 offset:55296
	ds_read_b128 v[206:209], v140 offset:56320
	s_mov_b32 m0, s48
	s_nop 0
	global_load_lds_dwordx4 v135, s[62:63]
	s_add_u32 s62, s40, 0x20080
	s_mov_b32 m0, s49
	s_addc_u32 s63, s41, 0
	global_load_lds_dwordx4 v135, s[62:63]
	s_add_u32 s62, s40, 0x40080
	s_mov_b32 m0, s52
	s_addc_u32 s63, s41, 0
	global_load_lds_dwordx4 v135, s[62:63]
	s_add_u32 s40, s40, 0x60080
	s_mov_b32 m0, s53
	s_addc_u32 s41, s41, 0
	global_load_lds_dwordx4 v135, s[40:41]
	s_mov_b32 m0, s50
	s_nop 0
	global_load_lds_dwordx4 v134, s[38:39]
	s_add_u32 s26, s26, 0x20080
	s_mov_b32 m0, s51
	s_addc_u32 s27, s27, 0
	global_load_lds_dwordx4 v134, s[26:27]
	s_waitcnt vmcnt(8) lgkmcnt(0)
	s_barrier
	v_mfma_f32_16x16x32_bf16 v[60:63], v[144:147], v[178:181], v[60:63]
	v_mfma_f32_16x16x32_bf16 v[56:59], v[152:155], v[178:181], v[56:59]
	v_mfma_f32_16x16x32_bf16 v[52:55], v[144:147], v[186:189], v[52:55]
	v_mfma_f32_16x16x32_bf16 v[44:47], v[152:155], v[186:189], v[44:47]
	v_mfma_f32_16x16x32_bf16 v[36:39], v[144:147], v[194:197], v[36:39]
	v_mfma_f32_16x16x32_bf16 v[28:31], v[152:155], v[194:197], v[28:31]
	v_mfma_f32_16x16x32_bf16 v[20:23], v[144:147], v[202:205], v[20:23]
	v_mfma_f32_16x16x32_bf16 v[12:15], v[152:155], v[202:205], v[12:15]
	v_mfma_f32_16x16x32_bf16 v[60:63], v[148:151], v[182:185], v[60:63]
	v_mfma_f32_16x16x32_bf16 v[56:59], v[156:159], v[182:185], v[56:59]
	v_mfma_f32_16x16x32_bf16 v[52:55], v[148:151], v[190:193], v[52:55]
	v_mfma_f32_16x16x32_bf16 v[44:47], v[156:159], v[190:193], v[44:47]
	v_mfma_f32_16x16x32_bf16 v[36:39], v[148:151], v[198:201], v[36:39]
	v_mfma_f32_16x16x32_bf16 v[28:31], v[156:159], v[198:201], v[28:31]
	v_mfma_f32_16x16x32_bf16 v[20:23], v[148:151], v[206:209], v[20:23]
	v_mfma_f32_16x16x32_bf16 v[12:15], v[156:159], v[206:209], v[12:15]
	v_mfma_f32_16x16x32_bf16 v[48:51], v[160:163], v[178:181], v[48:51]
	v_mfma_f32_16x16x32_bf16 v[40:43], v[168:171], v[178:181], v[40:43]
	v_mfma_f32_16x16x32_bf16 v[32:35], v[160:163], v[186:189], v[32:35]
	v_mfma_f32_16x16x32_bf16 v[24:27], v[168:171], v[186:189], v[24:27]
	v_mfma_f32_16x16x32_bf16 v[16:19], v[160:163], v[194:197], v[16:19]
	v_mfma_f32_16x16x32_bf16 v[8:11], v[168:171], v[194:197], v[8:11]
	v_mfma_f32_16x16x32_bf16 v[4:7], v[160:163], v[202:205], v[4:7]
	v_mfma_f32_16x16x32_bf16 v[0:3], v[168:171], v[202:205], v[0:3]
	v_mfma_f32_16x16x32_bf16 v[48:51], v[164:167], v[182:185], v[48:51]
	v_mfma_f32_16x16x32_bf16 v[40:43], v[172:175], v[182:185], v[40:43]
	v_mfma_f32_16x16x32_bf16 v[32:35], v[164:167], v[190:193], v[32:35]
	v_mfma_f32_16x16x32_bf16 v[24:27], v[172:175], v[190:193], v[24:27]
	v_mfma_f32_16x16x32_bf16 v[16:19], v[164:167], v[198:201], v[16:19]
	v_mfma_f32_16x16x32_bf16 v[8:11], v[172:175], v[198:201], v[8:11]
	v_mfma_f32_16x16x32_bf16 v[4:7], v[164:167], v[206:209], v[4:7]
	v_mfma_f32_16x16x32_bf16 v[0:3], v[172:175], v[206:209], v[0:3]
	s_barrier
	s_cmp_gt_u32 s60, 13
	s_cbranch_scc0 .LBB0_1192
	s_and_b64 vcc, exec, s[14:15]
	s_cbranch_vccz .LBB0_1195
	s_barrier

; #define PG8_STAGE(bufoff, gbase, voff, p64) do { _Pragma("unroll") for (int _i = 0; _i < 2; ++_i) { \
;         const char* _gb = (const char*)(gbase) + (size_t)_i * (p64); const unsigned _la = ldsbase + (unsigned)(bufoff) + (unsigned)_i * 8192u; \
;         asm volatile("s_mov_b32 m0, %0\n\ts_nop 0\n\tglobal_load_lds_dwordx4 %1, %2" :: "s"(_la), "v"(voff), "s"(_gb) : "memory"); } } while (0)
; #define PG8_LDA(dst, b, h) do { _Pragma("unroll") for (int m = 0; m < 4; ++m) _Pragma("unroll") for (int k = 0; k < 2; ++k) dst[m][k] = *(const LAS bf16x8*)(lds + PG8_SA(b, h) + aoff + m * 2048 + k * 1024); } while (0)
; #define PG8_LDB(dst, b, h) do { _Pragma("unroll") for (int n = 0; n < 2; ++n) _Pragma("unroll") for (int k = 0; k < 2; ++k) dst[n][k] = *(const LAS bf16x8*)(lds + PG8_SB(b, h) + boff + n * 2048 + k * 1024); } while (0)
; #define PG8_MMA(ai, bj, At, Bt) do { __builtin_amdgcn_s_setprio(1); _Pragma("unroll") for (int m = 0; m < 4; ++m) _Pragma("unroll") for (int n = 0; n < 2; ++n) _Pragma("unroll") for (int k = 0; k < 2; ++k) \
;         acc[ai][bj][m][n] = __builtin_amdgcn_mfma_f32_16x16x32_bf16(Bt[n][k], At[m][k], acc[ai][bj][m][n], 0, 0, 0); __builtin_amdgcn_s_setprio(0); } while (0)
; #define PG8_WAIT_V(n) asm volatile("s_waitcnt vmcnt(" #n ")" ::: "memory")
; #define PG8_BAR __builtin_amdgcn_s_barrier()
; template <class Epi, class Sched>
; __device__ __forceinline__ void gemm_phase(LAS unsigned char* lds, const Sched& S, const Epi& E) {
;     ...
;             const bool last = (t == nt - 2);
;             const char* a1 = cA + (size_t)(t + 1) * kstep;
;             const char* a2 = last ? nA : cA + (size_t)(t + 2) * kstep; const char* b2 = last ? nB : cB + (size_t)(t + 2) * kstep;
;             const char* a3 = a2 + kstep; const char* b3 = b2 + kstep;
;             const unsigned vA2 = voffA, vB2 = voffB, hA2 = hA, hB2 = hB;
;             PG8_LDB(B0, 0, 0); PG8_LDB(B1, 0, 1); PG8_SCHED; PG8_LDA(At, 0, 0); PG8_STAGE(PG8_SA(1, 1), a1 + hA, voffA, hA / 2);
;             PG8_WAIT_V(8); PG8_WAIT_L(0); PG8_BAR; PG8_MMA(0, 0, At, B0); PG8_MMA(0, 1, At, B1); PG8_BAR; PG8_SCHED;
;             PG8_LDA(At, 0, 1); PG8_STAGE(PG8_SB(0, 0), b2, vB2, hB2 / 2); PG8_STAGE(PG8_SB(0, 1), b2 + hB2, vB2, hB2 / 2); PG8_STAGE(PG8_SA(0, 0), a2, vA2, hA2 / 2);
;             PG8_WAIT_V(8); PG8_WAIT_L(0); PG8_BAR; PG8_MMA(1, 0, At, B0); PG8_MMA(1, 1, At, B1); PG8_BAR; PG8_SCHED;
.LBB0_1273:
	s_add_u32 s38, s38, 0x40080
	s_addc_u32 s39, s39, 0
	s_add_u32 s61, s40, 0x100
	s_addc_u32 s62, s41, 0
	s_mov_b32 s63, -2
	s_waitcnt vmcnt(3)
	s_waitcnt vmcnt(1)
	s_waitcnt vmcnt(0)
	ds_read_b128 v[128:131], v156
	ds_read_b128 v[132:135], v156 offset:1024
	ds_read_b128 v[140:143], v156 offset:2048
	ds_read_b128 v[144:147], v156 offset:3072
	ds_read_b128 v[148:151], v157
	ds_read_b128 v[162:165], v157 offset:1024
	ds_read_b128 v[166:169], v157 offset:2048
	ds_read_b128 v[170:173], v157 offset:3072
	s_add_u32 s30, s38, 0xfffc0080
	s_addc_u32 s40, s39, -1
	s_cmp_eq_u32 s63, 12
	s_cselect_b32 s41, s25, s40
	s_cselect_b32 s40, s24, s30
	s_cselect_b32 s44, s26, s61
	s_cselect_b32 s45, s27, s62
	s_add_u32 s42, s40, 0x80
	s_addc_u32 s43, s41, 0
	ds_read_b128 v[178:181], v158
	ds_read_b128 v[182:185], v158 offset:1024
	ds_read_b128 v[186:189], v158 offset:2048
	ds_read_b128 v[190:193], v158 offset:3072
	ds_read_b128 v[194:197], v158 offset:4096
	ds_read_b128 v[198:201], v158 offset:5120
	ds_read_b128 v[202:205], v158 offset:6144
	ds_read_b128 v[206:209], v158 offset:7168
	s_mov_b32 m0, s57
	s_nop 0
	global_load_lds_dwordx4 v152, s[38:39]
	s_add_u32 s66, s38, 0x20000
	s_mov_b32 m0, s58
	s_addc_u32 s67, s39, 0
	global_load_lds_dwordx4 v152, s[66:67]
	s_waitcnt vmcnt(8) lgkmcnt(0)
	s_barrier
	v_mfma_f32_16x16x32_bf16 v[124:127], v[128:131], v[178:181], 0
	v_mfma_f32_16x16x32_bf16 v[116:119], v[140:143], v[178:181], 0
	v_mfma_f32_16x16x32_bf16 v[108:111], v[128:131], v[186:189], 0
	v_mfma_f32_16x16x32_bf16 v[100:103], v[140:143], v[186:189], 0
	v_mfma_f32_16x16x32_bf16 v[92:95], v[128:131], v[194:197], 0
	v_mfma_f32_16x16x32_bf16 v[84:87], v[140:143], v[194:197], 0
	v_mfma_f32_16x16x32_bf16 v[76:79], v[128:131], v[202:205], 0
	v_mfma_f32_16x16x32_bf16 v[68:71], v[140:143], v[202:205], 0
	v_mfma_f32_16x16x32_bf16 v[124:127], v[132:135], v[182:185], v[124:127]
	v_mfma_f32_16x16x32_bf16 v[116:119], v[144:147], v[182:185], v[116:119]
	v_mfma_f32_16x16x32_bf16 v[108:111], v[132:135], v[190:193], v[108:111]
	v_mfma_f32_16x16x32_bf16 v[100:103], v[144:147], v[190:193], v[100:103]
	v_mfma_f32_16x16x32_bf16 v[92:95], v[132:135], v[198:201], v[92:95]
	v_mfma_f32_16x16x32_bf16 v[84:87], v[144:147], v[198:201], v[84:87]
	v_mfma_f32_16x16x32_bf16 v[76:79], v[132:135], v[206:209], v[76:79]
	v_mfma_f32_16x16x32_bf16 v[68:71], v[144:147], v[206:209], v[68:71]
	v_mfma_f32_16x16x32_bf16 v[120:123], v[148:151], v[178:181], 0
	v_mfma_f32_16x16x32_bf16 v[112:115], v[166:169], v[178:181], 0
	v_mfma_f32_16x16x32_bf16 v[104:107], v[148:151], v[186:189], 0
	v_mfma_f32_16x16x32_bf16 v[96:99], v[166:169], v[186:189], 0
	v_mfma_f32_16x16x32_bf16 v[88:91], v[148:151], v[194:197], 0
	v_mfma_f32_16x16x32_bf16 v[80:83], v[166:169], v[194:197], 0
	v_mfma_f32_16x16x32_bf16 v[72:75], v[148:151], v[202:205], 0
	v_mfma_f32_16x16x32_bf16 v[64:67], v[166:169], v[202:205], 0
	v_mfma_f32_16x16x32_bf16 v[120:123], v[162:165], v[182:185], v[120:123]
	v_mfma_f32_16x16x32_bf16 v[112:115], v[170:173], v[182:185], v[112:115]
	v_mfma_f32_16x16x32_bf16 v[104:107], v[162:165], v[190:193], v[104:107]
	v_mfma_f32_16x16x32_bf16 v[96:99], v[170:173], v[190:193], v[96:99]
	v_mfma_f32_16x16x32_bf16 v[88:91], v[162:165], v[198:201], v[88:91]
	v_mfma_f32_16x16x32_bf16 v[80:83], v[170:173], v[198:201], v[80:83]
	v_mfma_f32_16x16x32_bf16 v[72:75], v[162:165], v[206:209], v[72:75]
	v_mfma_f32_16x16x32_bf16 v[64:67], v[170:173], v[206:209], v[64:67]
	s_add_i32 s63, s63, 2
	s_add_u32 s38, s38, 0x100
	s_addc_u32 s39, s39, 0
	s_add_u32 s61, s61, 0x100
	s_addc_u32 s62, s62, 0
	s_barrier
	s_add_u32 s66, s44, 0x20000
	ds_read_b128 v[178:181], v158 offset:16384
	ds_read_b128 v[182:185], v158 offset:17408
	ds_read_b128 v[186:189], v158 offset:18432
	ds_read_b128 v[190:193], v158 offset:19456
	ds_read_b128 v[194:197], v158 offset:20480
	ds_read_b128 v[198:201], v158 offset:21504
	ds_read_b128 v[202:205], v158 offset:22528
	ds_read_b128 v[206:209], v158 offset:23552
	s_mov_b32 m0, s35
	s_nop 0
	global_load_lds_dwordx4 v153, s[44:45]
	s_mov_b32 m0, s36
	s_addc_u32 s67, s45, 0
	global_load_lds_dwordx4 v153, s[66:67]
	s_add_u32 s66, s44, 0x40000
	s_mov_b32 m0, s37
	s_addc_u32 s67, s45, 0
	global_load_lds_dwordx4 v153, s[66:67]
	s_add_u32 s66, s44, 0x60000
	s_mov_b32 m0, s46
	s_addc_u32 s67, s45, 0
	global_load_lds_dwordx4 v153, s[66:67]
	s_mov_b32 m0, s34
	s_nop 0
	global_load_lds_dwordx4 v152, s[40:41]
	s_add_u32 s66, s40, 0x20000
	s_mov_b32 m0, s47
	s_addc_u32 s67, s41, 0
	global_load_lds_dwordx4 v152, s[66:67]
	s_waitcnt vmcnt(8) lgkmcnt(0)
	s_barrier
	v_mfma_f32_16x16x32_bf16 v[60:63], v[128:131], v[178:181], 0
	v_mfma_f32_16x16x32_bf16 v[52:55], v[140:143], v[178:181], 0
	v_mfma_f32_16x16x32_bf16 v[44:47], v[128:131], v[186:189], 0
	v_mfma_f32_16x16x32_bf16 v[36:39], v[140:143], v[186:189], 0
	v_mfma_f32_16x16x32_bf16 v[28:31], v[128:131], v[194:197], 0
	v_mfma_f32_16x16x32_bf16 v[20:23], v[140:143], v[194:197], 0
	v_mfma_f32_16x16x32_bf16 v[12:15], v[128:131], v[202:205], 0
	v_mfma_f32_16x16x32_bf16 v[4:7], v[140:143], v[202:205], 0
	v_mfma_f32_16x16x32_bf16 v[60:63], v[132:135], v[182:185], v[60:63]
	v_mfma_f32_16x16x32_bf16 v[52:55], v[144:147], v[182:185], v[52:55]
	v_mfma_f32_16x16x32_bf16 v[44:47], v[132:135], v[190:193], v[44:47]
	v_mfma_f32_16x16x32_bf16 v[36:39], v[144:147], v[190:193], v[36:39]
	v_mfma_f32_16x16x32_bf16 v[28:31], v[132:135], v[198:201], v[28:31]
	v_mfma_f32_16x16x32_bf16 v[20:23], v[144:147], v[198:201], v[20:23]
	v_mfma_f32_16x16x32_bf16 v[12:15], v[132:135], v[206:209], v[12:15]
	v_mfma_f32_16x16x32_bf16 v[4:7], v[144:147], v[206:209], v[4:7]
	v_mfma_f32_16x16x32_bf16 v[56:59], v[148:151], v[178:181], 0
	v_mfma_f32_16x16x32_bf16 v[48:51], v[166:169], v[178:181], 0
	v_mfma_f32_16x16x32_bf16 v[40:43], v[148:151], v[186:189], 0
	v_mfma_f32_16x16x32_bf16 v[32:35], v[166:169], v[186:189], 0
	v_mfma_f32_16x16x32_bf16 v[24:27], v[148:151], v[194:197], 0
	v_mfma_f32_16x16x32_bf16 v[16:19], v[166:169], v[194:197], 0
	v_mfma_f32_16x16x32_bf16 v[8:11], v[148:151], v[202:205], 0
	v_mfma_f32_16x16x32_bf16 v[0:3], v[166:169], v[202:205], 0
	v_mfma_f32_16x16x32_bf16 v[56:59], v[162:165], v[182:185], v[56:59]
	v_mfma_f32_16x16x32_bf16 v[48:51], v[170:173], v[182:185], v[48:51]
	v_mfma_f32_16x16x32_bf16 v[40:43], v[162:165], v[190:193], v[40:43]
	v_mfma_f32_16x16x32_bf16 v[32:35], v[170:173], v[190:193], v[32:35]
	v_mfma_f32_16x16x32_bf16 v[24:27], v[162:165], v[198:201], v[24:27]
	v_mfma_f32_16x16x32_bf16 v[16:19], v[170:173], v[198:201], v[16:19]
	v_mfma_f32_16x16x32_bf16 v[8:11], v[162:165], v[206:209], v[8:11]
	v_mfma_f32_16x16x32_bf16 v[0:3], v[170:173], v[206:209], v[0:3]
	s_barrier
	s_branch .Lpeel_mid_37910
; #define PG8_STAGE(bufoff, gbase, voff, p64) do { _Pragma("unroll") for (int _i = 0; _i < 2; ++_i) { \
;         const char* _gb = (const char*)(gbase) + (size_t)_i * (p64); const unsigned _la = ldsbase + (unsigned)(bufoff) + (unsigned)_i * 8192u; \
;         asm volatile("s_mov_b32 m0, %0\n\ts_nop 0\n\tglobal_load_lds_dwordx4 %1, %2" :: "s"(_la), "v"(voff), "s"(_gb) : "memory"); } } while (0)
; #define PG8_LDA(dst, b, h) do { _Pragma("unroll") for (int m = 0; m < 4; ++m) _Pragma("unroll") for (int k = 0; k < 2; ++k) dst[m][k] = *(const LAS bf16x8*)(lds + PG8_SA(b, h) + aoff + m * 2048 + k * 1024); } while (0)
; #define PG8_LDB(dst, b, h) do { _Pragma("unroll") for (int n = 0; n < 2; ++n) _Pragma("unroll") for (int k = 0; k < 2; ++k) dst[n][k] = *(const LAS bf16x8*)(lds + PG8_SB(b, h) + boff + n * 2048 + k * 1024); } while (0)
; #define PG8_MMA(ai, bj, At, Bt) do { __builtin_amdgcn_s_setprio(1); _Pragma("unroll") for (int m = 0; m < 4; ++m) _Pragma("unroll") for (int n = 0; n < 2; ++n) _Pragma("unroll") for (int k = 0; k < 2; ++k) \
;         acc[ai][bj][m][n] = __builtin_amdgcn_mfma_f32_16x16x32_bf16(Bt[n][k], At[m][k], acc[ai][bj][m][n], 0, 0, 0); __builtin_amdgcn_s_setprio(0); } while (0)
; #define PG8_WAIT_V(n) asm volatile("s_waitcnt vmcnt(" #n ")" ::: "memory")
; #define PG8_BAR __builtin_amdgcn_s_barrier()
; template <class Epi, class Sched>
; __device__ __forceinline__ void gemm_phase(LAS unsigned char* lds, const Sched& S, const Epi& E) {
;     ...
;             const bool last = (t == nt - 2);
;             const char* a1 = cA + (size_t)(t + 1) * kstep;
;             const char* a2 = last ? nA : cA + (size_t)(t + 2) * kstep; const char* b2 = last ? nB : cB + (size_t)(t + 2) * kstep;
;             const char* a3 = a2 + kstep; const char* b3 = b2 + kstep;
;             const unsigned vA2 = voffA, vB2 = voffB, hA2 = hA, hB2 = hB;
;             PG8_LDB(B0, 0, 0); PG8_LDB(B1, 0, 1); PG8_SCHED; PG8_LDA(At, 0, 0); PG8_STAGE(PG8_SA(1, 1), a1 + hA, voffA, hA / 2);
;             PG8_WAIT_V(8); PG8_WAIT_L(0); PG8_BAR; PG8_MMA(0, 0, At, B0); PG8_MMA(0, 1, At, B1); PG8_BAR; PG8_SCHED;
;             PG8_LDA(At, 0, 1); PG8_STAGE(PG8_SB(0, 0), b2, vB2, hB2 / 2); PG8_STAGE(PG8_SB(0, 1), b2 + hB2, vB2, hB2 / 2); PG8_STAGE(PG8_SA(0, 0), a2, vA2, hA2 / 2);
;             PG8_WAIT_V(8); PG8_WAIT_L(0); PG8_BAR; PG8_MMA(1, 0, At, B0); PG8_MMA(1, 1, At, B1); PG8_BAR; PG8_SCHED;
.LBB0_1274:
	ds_read_b128 v[128:131], v156
	ds_read_b128 v[132:135], v156 offset:1024
	ds_read_b128 v[140:143], v156 offset:2048
	ds_read_b128 v[144:147], v156 offset:3072
	ds_read_b128 v[148:151], v157
	ds_read_b128 v[162:165], v157 offset:1024
	ds_read_b128 v[166:169], v157 offset:2048
	ds_read_b128 v[170:173], v157 offset:3072
	s_add_u32 s30, s38, 0xfffc0080
	s_addc_u32 s40, s39, -1
	s_cmp_eq_u32 s63, 12
	s_cselect_b32 s41, s25, s40
	s_cselect_b32 s40, s24, s30
	s_cselect_b32 s44, s26, s61
	s_cselect_b32 s45, s27, s62
	s_add_u32 s42, s40, 0x80
	s_addc_u32 s43, s41, 0
	ds_read_b128 v[178:181], v158
	ds_read_b128 v[182:185], v158 offset:1024
	ds_read_b128 v[186:189], v158 offset:2048
	ds_read_b128 v[190:193], v158 offset:3072
	ds_read_b128 v[194:197], v158 offset:4096
	ds_read_b128 v[198:201], v158 offset:5120
	ds_read_b128 v[202:205], v158 offset:6144
	ds_read_b128 v[206:209], v158 offset:7168
	s_mov_b32 m0, s57
	s_nop 0
	global_load_lds_dwordx4 v152, s[38:39]
	s_add_u32 s66, s38, 0x20000
	s_mov_b32 m0, s58
	s_addc_u32 s67, s39, 0
	global_load_lds_dwordx4 v152, s[66:67]
	s_waitcnt vmcnt(8) lgkmcnt(0)
	s_barrier
	v_mfma_f32_16x16x32_bf16 v[124:127], v[128:131], v[178:181], v[124:127]
	v_mfma_f32_16x16x32_bf16 v[116:119], v[140:143], v[178:181], v[116:119]
	v_mfma_f32_16x16x32_bf16 v[108:111], v[128:131], v[186:189], v[108:111]
	v_mfma_f32_16x16x32_bf16 v[100:103], v[140:143], v[186:189], v[100:103]
	v_mfma_f32_16x16x32_bf16 v[92:95], v[128:131], v[194:197], v[92:95]
	v_mfma_f32_16x16x32_bf16 v[84:87], v[140:143], v[194:197], v[84:87]
	v_mfma_f32_16x16x32_bf16 v[76:79], v[128:131], v[202:205], v[76:79]
	v_mfma_f32_16x16x32_bf16 v[68:71], v[140:143], v[202:205], v[68:71]
	v_mfma_f32_16x16x32_bf16 v[124:127], v[132:135], v[182:185], v[124:127]
	v_mfma_f32_16x16x32_bf16 v[116:119], v[144:147], v[182:185], v[116:119]
	v_mfma_f32_16x16x32_bf16 v[108:111], v[132:135], v[190:193], v[108:111]
	v_mfma_f32_16x16x32_bf16 v[100:103], v[144:147], v[190:193], v[100:103]
	v_mfma_f32_16x16x32_bf16 v[92:95], v[132:135], v[198:201], v[92:95]
	v_mfma_f32_16x16x32_bf16 v[84:87], v[144:147], v[198:201], v[84:87]
	v_mfma_f32_16x16x32_bf16 v[76:79], v[132:135], v[206:209], v[76:79]
	v_mfma_f32_16x16x32_bf16 v[68:71], v[144:147], v[206:209], v[68:71]
	v_mfma_f32_16x16x32_bf16 v[120:123], v[148:151], v[178:181], v[120:123]
	v_mfma_f32_16x16x32_bf16 v[112:115], v[166:169], v[178:181], v[112:115]
	v_mfma_f32_16x16x32_bf16 v[104:107], v[148:151], v[186:189], v[104:107]
	v_mfma_f32_16x16x32_bf16 v[96:99], v[166:169], v[186:189], v[96:99]
	v_mfma_f32_16x16x32_bf16 v[88:91], v[148:151], v[194:197], v[88:91]
	v_mfma_f32_16x16x32_bf16 v[80:83], v[166:169], v[194:197], v[80:83]
	v_mfma_f32_16x16x32_bf16 v[72:75], v[148:151], v[202:205], v[72:75]
	v_mfma_f32_16x16x32_bf16 v[64:67], v[166:169], v[202:205], v[64:67]
	v_mfma_f32_16x16x32_bf16 v[120:123], v[162:165], v[182:185], v[120:123]
	v_mfma_f32_16x16x32_bf16 v[112:115], v[170:173], v[182:185], v[112:115]
	v_mfma_f32_16x16x32_bf16 v[104:107], v[162:165], v[190:193], v[104:107]
	v_mfma_f32_16x16x32_bf16 v[96:99], v[170:173], v[190:193], v[96:99]
	v_mfma_f32_16x16x32_bf16 v[88:91], v[162:165], v[198:201], v[88:91]
	v_mfma_f32_16x16x32_bf16 v[80:83], v[170:173], v[198:201], v[80:83]
	v_mfma_f32_16x16x32_bf16 v[72:75], v[162:165], v[206:209], v[72:75]
	v_mfma_f32_16x16x32_bf16 v[64:67], v[170:173], v[206:209], v[64:67]
	s_add_i32 s63, s63, 2
	s_add_u32 s38, s38, 0x100
	s_addc_u32 s39, s39, 0
	s_add_u32 s61, s61, 0x100
	s_addc_u32 s62, s62, 0
	s_barrier
	s_add_u32 s66, s44, 0x20000
	ds_read_b128 v[178:181], v158 offset:16384
	ds_read_b128 v[182:185], v158 offset:17408
	ds_read_b128 v[186:189], v158 offset:18432
	ds_read_b128 v[190:193], v158 offset:19456
	ds_read_b128 v[194:197], v158 offset:20480
	ds_read_b128 v[198:201], v158 offset:21504
	ds_read_b128 v[202:205], v158 offset:22528
	ds_read_b128 v[206:209], v158 offset:23552
	s_mov_b32 m0, s35
	s_nop 0
	global_load_lds_dwordx4 v153, s[44:45]
	s_mov_b32 m0, s36
	s_addc_u32 s67, s45, 0
	global_load_lds_dwordx4 v153, s[66:67]
	s_add_u32 s66, s44, 0x40000
	s_mov_b32 m0, s37
	s_addc_u32 s67, s45, 0
	global_load_lds_dwordx4 v153, s[66:67]
	s_add_u32 s66, s44, 0x60000
	s_mov_b32 m0, s46
	s_addc_u32 s67, s45, 0
	global_load_lds_dwordx4 v153, s[66:67]
	s_mov_b32 m0, s34
	s_nop 0
	global_load_lds_dwordx4 v152, s[40:41]
	s_add_u32 s66, s40, 0x20000
	s_mov_b32 m0, s47
	s_addc_u32 s67, s41, 0
	global_load_lds_dwordx4 v152, s[66:67]
	s_waitcnt vmcnt(8) lgkmcnt(0)
	s_barrier
	v_mfma_f32_16x16x32_bf16 v[60:63], v[128:131], v[178:181], v[60:63]
	v_mfma_f32_16x16x32_bf16 v[52:55], v[140:143], v[178:181], v[52:55]
	v_mfma_f32_16x16x32_bf16 v[44:47], v[128:131], v[186:189], v[44:47]
	v_mfma_f32_16x16x32_bf16 v[36:39], v[140:143], v[186:189], v[36:39]
	v_mfma_f32_16x16x32_bf16 v[28:31], v[128:131], v[194:197], v[28:31]
	v_mfma_f32_16x16x32_bf16 v[20:23], v[140:143], v[194:197], v[20:23]
	v_mfma_f32_16x16x32_bf16 v[12:15], v[128:131], v[202:205], v[12:15]
	v_mfma_f32_16x16x32_bf16 v[4:7], v[140:143], v[202:205], v[4:7]
	v_mfma_f32_16x16x32_bf16 v[60:63], v[132:135], v[182:185], v[60:63]
	v_mfma_f32_16x16x32_bf16 v[52:55], v[144:147], v[182:185], v[52:55]
	v_mfma_f32_16x16x32_bf16 v[44:47], v[132:135], v[190:193], v[44:47]
	v_mfma_f32_16x16x32_bf16 v[36:39], v[144:147], v[190:193], v[36:39]
	v_mfma_f32_16x16x32_bf16 v[28:31], v[132:135], v[198:201], v[28:31]
	v_mfma_f32_16x16x32_bf16 v[20:23], v[144:147], v[198:201], v[20:23]
	v_mfma_f32_16x16x32_bf16 v[12:15], v[132:135], v[206:209], v[12:15]
	v_mfma_f32_16x16x32_bf16 v[4:7], v[144:147], v[206:209], v[4:7]
	v_mfma_f32_16x16x32_bf16 v[56:59], v[148:151], v[178:181], v[56:59]
	v_mfma_f32_16x16x32_bf16 v[48:51], v[166:169], v[178:181], v[48:51]
	v_mfma_f32_16x16x32_bf16 v[40:43], v[148:151], v[186:189], v[40:43]
	v_mfma_f32_16x16x32_bf16 v[32:35], v[166:169], v[186:189], v[32:35]
	v_mfma_f32_16x16x32_bf16 v[24:27], v[148:151], v[194:197], v[24:27]
	v_mfma_f32_16x16x32_bf16 v[16:19], v[166:169], v[194:197], v[16:19]
	v_mfma_f32_16x16x32_bf16 v[8:11], v[148:151], v[202:205], v[8:11]
	v_mfma_f32_16x16x32_bf16 v[0:3], v[166:169], v[202:205], v[0:3]
	v_mfma_f32_16x16x32_bf16 v[56:59], v[162:165], v[182:185], v[56:59]
	v_mfma_f32_16x16x32_bf16 v[48:51], v[170:173], v[182:185], v[48:51]
	v_mfma_f32_16x16x32_bf16 v[40:43], v[162:165], v[190:193], v[40:43]
	v_mfma_f32_16x16x32_bf16 v[32:35], v[170:173], v[190:193], v[32:35]
	v_mfma_f32_16x16x32_bf16 v[24:27], v[162:165], v[198:201], v[24:27]
	v_mfma_f32_16x16x32_bf16 v[16:19], v[170:173], v[198:201], v[16:19]
	v_mfma_f32_16x16x32_bf16 v[8:11], v[162:165], v[206:209], v[8:11]
	v_mfma_f32_16x16x32_bf16 v[0:3], v[170:173], v[206:209], v[0:3]
	s_barrier
; #define PG8_STAGE(bufoff, gbase, voff, p64) do { _Pragma("unroll") for (int _i = 0; _i < 2; ++_i) { \
;         const char* _gb = (const char*)(gbase) + (size_t)_i * (p64); const unsigned _la = ldsbase + (unsigned)(bufoff) + (unsigned)_i * 8192u; \
;         asm volatile("s_mov_b32 m0, %0\n\ts_nop 0\n\tglobal_load_lds_dwordx4 %1, %2" :: "s"(_la), "v"(voff), "s"(_gb) : "memory"); } } while (0)
; #define PG8_LDA(dst, b, h) do { _Pragma("unroll") for (int m = 0; m < 4; ++m) _Pragma("unroll") for (int k = 0; k < 2; ++k) dst[m][k] = *(const LAS bf16x8*)(lds + PG8_SA(b, h) + aoff + m * 2048 + k * 1024); } while (0)
; #define PG8_LDB(dst, b, h) do { _Pragma("unroll") for (int n = 0; n < 2; ++n) _Pragma("unroll") for (int k = 0; k < 2; ++k) dst[n][k] = *(const LAS bf16x8*)(lds + PG8_SB(b, h) + boff + n * 2048 + k * 1024); } while (0)
; #define PG8_MMA(ai, bj, At, Bt) do { __builtin_amdgcn_s_setprio(1); _Pragma("unroll") for (int m = 0; m < 4; ++m) _Pragma("unroll") for (int n = 0; n < 2; ++n) _Pragma("unroll") for (int k = 0; k < 2; ++k) \
;         acc[ai][bj][m][n] = __builtin_amdgcn_mfma_f32_16x16x32_bf16(Bt[n][k], At[m][k], acc[ai][bj][m][n], 0, 0, 0); __builtin_amdgcn_s_setprio(0); } while (0)
; #define PG8_WAIT_V(n) asm volatile("s_waitcnt vmcnt(" #n ")" ::: "memory")
; #define PG8_WAIT_L(n) asm volatile("s_waitcnt lgkmcnt(" #n ")" ::: "memory")
; #define PG8_BAR __builtin_amdgcn_s_barrier()
; #define PG8_SCHED __builtin_amdgcn_sched_barrier(0)
; template <class Epi, class Sched>
; __device__ __forceinline__ void gemm_phase(LAS unsigned char* lds, const Sched& S, const Epi& E) {
;     ...
;             PG8_LDB(B0, 1, 0); PG8_LDB(B1, 1, 1); PG8_SCHED; PG8_LDA(At, 1, 0); PG8_STAGE(PG8_SA(0, 1), a2 + hA2, vA2, hA2 / 2);
;             PG8_WAIT_V(8); PG8_WAIT_L(0); PG8_BAR; PG8_MMA(0, 0, At, B0); PG8_MMA(0, 1, At, B1); PG8_BAR; PG8_SCHED;
;             PG8_LDA(At, 1, 1); PG8_STAGE(PG8_SB(1, 0), b3, vB2, hB2 / 2); PG8_STAGE(PG8_SB(1, 1), b3 + hB2, vB2, hB2 / 2); PG8_STAGE(PG8_SA(1, 0), a3, vA2, hA2 / 2);
;             PG8_WAIT_V(8); PG8_WAIT_L(0); PG8_BAR; PG8_MMA(1, 0, At, B0); PG8_MMA(1, 1, At, B1); PG8_BAR; PG8_SCHED;
.Lpeel_mid_37910:
	ds_read_b128 v[128:131], v159
	ds_read_b128 v[132:135], v159 offset:1024
	ds_read_b128 v[140:143], v159 offset:2048
	ds_read_b128 v[144:147], v159 offset:3072
	ds_read_b128 v[148:151], v160
	ds_read_b128 v[162:165], v160 offset:1024
	ds_read_b128 v[166:169], v160 offset:2048
	ds_read_b128 v[170:173], v160 offset:3072
	ds_read_b128 v[178:181], v158 offset:32768
	ds_read_b128 v[182:185], v158 offset:33792
	ds_read_b128 v[186:189], v158 offset:34816
	ds_read_b128 v[190:193], v158 offset:35840
	ds_read_b128 v[194:197], v158 offset:36864
	ds_read_b128 v[198:201], v158 offset:37888
	ds_read_b128 v[202:205], v158 offset:38912
	ds_read_b128 v[206:209], v158 offset:39936
	s_add_u32 s66, s40, 0x40000
	s_mov_b32 m0, s48
	s_addc_u32 s67, s41, 0
	global_load_lds_dwordx4 v152, s[66:67]
	s_add_u32 s66, s40, 0x60000
	s_mov_b32 m0, s49
	s_addc_u32 s67, s41, 0
	global_load_lds_dwordx4 v152, s[66:67]
	s_waitcnt vmcnt(8) lgkmcnt(0)
	s_barrier
	v_mfma_f32_16x16x32_bf16 v[124:127], v[128:131], v[178:181], v[124:127]
	v_mfma_f32_16x16x32_bf16 v[116:119], v[140:143], v[178:181], v[116:119]
	v_mfma_f32_16x16x32_bf16 v[108:111], v[128:131], v[186:189], v[108:111]
	v_mfma_f32_16x16x32_bf16 v[100:103], v[140:143], v[186:189], v[100:103]
	v_mfma_f32_16x16x32_bf16 v[92:95], v[128:131], v[194:197], v[92:95]
	v_mfma_f32_16x16x32_bf16 v[84:87], v[140:143], v[194:197], v[84:87]
	v_mfma_f32_16x16x32_bf16 v[76:79], v[128:131], v[202:205], v[76:79]
	v_mfma_f32_16x16x32_bf16 v[68:71], v[140:143], v[202:205], v[68:71]
	v_mfma_f32_16x16x32_bf16 v[124:127], v[132:135], v[182:185], v[124:127]
	v_mfma_f32_16x16x32_bf16 v[116:119], v[144:147], v[182:185], v[116:119]
	v_mfma_f32_16x16x32_bf16 v[108:111], v[132:135], v[190:193], v[108:111]
	v_mfma_f32_16x16x32_bf16 v[100:103], v[144:147], v[190:193], v[100:103]
	v_mfma_f32_16x16x32_bf16 v[92:95], v[132:135], v[198:201], v[92:95]
	v_mfma_f32_16x16x32_bf16 v[84:87], v[144:147], v[198:201], v[84:87]
	v_mfma_f32_16x16x32_bf16 v[76:79], v[132:135], v[206:209], v[76:79]
	v_mfma_f32_16x16x32_bf16 v[68:71], v[144:147], v[206:209], v[68:71]
	v_mfma_f32_16x16x32_bf16 v[120:123], v[148:151], v[178:181], v[120:123]
	v_mfma_f32_16x16x32_bf16 v[112:115], v[166:169], v[178:181], v[112:115]
	v_mfma_f32_16x16x32_bf16 v[104:107], v[148:151], v[186:189], v[104:107]
	v_mfma_f32_16x16x32_bf16 v[96:99], v[166:169], v[186:189], v[96:99]
	v_mfma_f32_16x16x32_bf16 v[88:91], v[148:151], v[194:197], v[88:91]
	v_mfma_f32_16x16x32_bf16 v[80:83], v[166:169], v[194:197], v[80:83]
	v_mfma_f32_16x16x32_bf16 v[72:75], v[148:151], v[202:205], v[72:75]
	v_mfma_f32_16x16x32_bf16 v[64:67], v[166:169], v[202:205], v[64:67]
	v_mfma_f32_16x16x32_bf16 v[120:123], v[162:165], v[182:185], v[120:123]
	v_mfma_f32_16x16x32_bf16 v[112:115], v[170:173], v[182:185], v[112:115]
	v_mfma_f32_16x16x32_bf16 v[104:107], v[162:165], v[190:193], v[104:107]
	v_mfma_f32_16x16x32_bf16 v[96:99], v[170:173], v[190:193], v[96:99]
	v_mfma_f32_16x16x32_bf16 v[88:91], v[162:165], v[198:201], v[88:91]
	v_mfma_f32_16x16x32_bf16 v[80:83], v[170:173], v[198:201], v[80:83]
	v_mfma_f32_16x16x32_bf16 v[72:75], v[162:165], v[206:209], v[72:75]
	v_mfma_f32_16x16x32_bf16 v[64:67], v[170:173], v[206:209], v[64:67]
	s_barrier
	s_add_u32 s66, s44, 0x80
	s_addc_u32 s67, s45, 0
	ds_read_b128 v[178:181], v158 offset:49152
	ds_read_b128 v[182:185], v158 offset:50176
	ds_read_b128 v[186:189], v158 offset:51200
	ds_read_b128 v[190:193], v158 offset:52224
	ds_read_b128 v[194:197], v158 offset:53248
	ds_read_b128 v[198:201], v158 offset:54272
	ds_read_b128 v[202:205], v158 offset:55296
	ds_read_b128 v[206:209], v158 offset:56320
	s_mov_b32 m0, s51
	s_nop 0
	global_load_lds_dwordx4 v153, s[66:67]
	s_add_u32 s66, s44, 0x20080
	s_mov_b32 m0, s52
	s_addc_u32 s67, s45, 0
	global_load_lds_dwordx4 v153, s[66:67]
	s_add_u32 s66, s44, 0x40080
	s_mov_b32 m0, s55
	s_addc_u32 s67, s45, 0
	global_load_lds_dwordx4 v153, s[66:67]
	s_add_u32 s44, s44, 0x60080
	s_mov_b32 m0, s56
	s_addc_u32 s45, s45, 0
	global_load_lds_dwordx4 v153, s[44:45]
	s_mov_b32 m0, s53
	s_nop 0
	global_load_lds_dwordx4 v152, s[42:43]
	s_add_u32 s40, s40, 0x20080
	s_mov_b32 m0, s54
	s_addc_u32 s41, s41, 0
	global_load_lds_dwordx4 v152, s[40:41]
	s_waitcnt vmcnt(8) lgkmcnt(0)
	s_barrier
	v_mfma_f32_16x16x32_bf16 v[60:63], v[128:131], v[178:181], v[60:63]
	v_mfma_f32_16x16x32_bf16 v[52:55], v[140:143], v[178:181], v[52:55]
	v_mfma_f32_16x16x32_bf16 v[44:47], v[128:131], v[186:189], v[44:47]
	v_mfma_f32_16x16x32_bf16 v[36:39], v[140:143], v[186:189], v[36:39]
	v_mfma_f32_16x16x32_bf16 v[28:31], v[128:131], v[194:197], v[28:31]
	v_mfma_f32_16x16x32_bf16 v[20:23], v[140:143], v[194:197], v[20:23]
	v_mfma_f32_16x16x32_bf16 v[12:15], v[128:131], v[202:205], v[12:15]
	v_mfma_f32_16x16x32_bf16 v[4:7], v[140:143], v[202:205], v[4:7]
	v_mfma_f32_16x16x32_bf16 v[60:63], v[132:135], v[182:185], v[60:63]
	v_mfma_f32_16x16x32_bf16 v[52:55], v[144:147], v[182:185], v[52:55]
	v_mfma_f32_16x16x32_bf16 v[44:47], v[132:135], v[190:193], v[44:47]
	v_mfma_f32_16x16x32_bf16 v[36:39], v[144:147], v[190:193], v[36:39]
	v_mfma_f32_16x16x32_bf16 v[28:31], v[132:135], v[198:201], v[28:31]
	v_mfma_f32_16x16x32_bf16 v[20:23], v[144:147], v[198:201], v[20:23]
	v_mfma_f32_16x16x32_bf16 v[12:15], v[132:135], v[206:209], v[12:15]
	v_mfma_f32_16x16x32_bf16 v[4:7], v[144:147], v[206:209], v[4:7]
	v_mfma_f32_16x16x32_bf16 v[56:59], v[148:151], v[178:181], v[56:59]
	v_mfma_f32_16x16x32_bf16 v[48:51], v[166:169], v[178:181], v[48:51]
	v_mfma_f32_16x16x32_bf16 v[40:43], v[148:151], v[186:189], v[40:43]
	v_mfma_f32_16x16x32_bf16 v[32:35], v[166:169], v[186:189], v[32:35]
	v_mfma_f32_16x16x32_bf16 v[24:27], v[148:151], v[194:197], v[24:27]
	v_mfma_f32_16x16x32_bf16 v[16:19], v[166:169], v[194:197], v[16:19]
	v_mfma_f32_16x16x32_bf16 v[8:11], v[148:151], v[202:205], v[8:11]
	v_mfma_f32_16x16x32_bf16 v[0:3], v[166:169], v[202:205], v[0:3]
	v_mfma_f32_16x16x32_bf16 v[56:59], v[162:165], v[182:185], v[56:59]
	v_mfma_f32_16x16x32_bf16 v[48:51], v[170:173], v[182:185], v[48:51]
	v_mfma_f32_16x16x32_bf16 v[40:43], v[162:165], v[190:193], v[40:43]
	v_mfma_f32_16x16x32_bf16 v[32:35], v[170:173], v[190:193], v[32:35]
	v_mfma_f32_16x16x32_bf16 v[24:27], v[162:165], v[198:201], v[24:27]
	v_mfma_f32_16x16x32_bf16 v[16:19], v[170:173], v[198:201], v[16:19]
	v_mfma_f32_16x16x32_bf16 v[8:11], v[162:165], v[206:209], v[8:11]
	v_mfma_f32_16x16x32_bf16 v[0:3], v[170:173], v[206:209], v[0:3]
	s_barrier
	s_cmp_gt_u32 s63, 13
	s_cbranch_scc0 .LBB0_1274
	s_and_b64 vcc, exec, s[18:19]
	s_cbranch_vccz .LBB0_1277
	s_barrier

; #define PG8_STAGE(bufoff, gbase, voff, p64) do { _Pragma("unroll") for (int _i = 0; _i < 2; ++_i) { \
;         const char* _gb = (const char*)(gbase) + (size_t)_i * (p64); const unsigned _la = ldsbase + (unsigned)(bufoff) + (unsigned)_i * 8192u; \
;         asm volatile("s_mov_b32 m0, %0\n\ts_nop 0\n\tglobal_load_lds_dwordx4 %1, %2" :: "s"(_la), "v"(voff), "s"(_gb) : "memory"); } } while (0)
; #define PG8_LDA(dst, b, h) do { _Pragma("unroll") for (int m = 0; m < 4; ++m) _Pragma("unroll") for (int k = 0; k < 2; ++k) dst[m][k] = *(const LAS bf16x8*)(lds + PG8_SA(b, h) + aoff + m * 2048 + k * 1024); } while (0)
; #define PG8_LDB(dst, b, h) do { _Pragma("unroll") for (int n = 0; n < 2; ++n) _Pragma("unroll") for (int k = 0; k < 2; ++k) dst[n][k] = *(const LAS bf16x8*)(lds + PG8_SB(b, h) + boff + n * 2048 + k * 1024); } while (0)
; #define PG8_MMA(ai, bj, At, Bt) do { __builtin_amdgcn_s_setprio(1); _Pragma("unroll") for (int m = 0; m < 4; ++m) _Pragma("unroll") for (int n = 0; n < 2; ++n) _Pragma("unroll") for (int k = 0; k < 2; ++k) \
;         acc[ai][bj][m][n] = __builtin_amdgcn_mfma_f32_16x16x32_bf16(Bt[n][k], At[m][k], acc[ai][bj][m][n], 0, 0, 0); __builtin_amdgcn_s_setprio(0); } while (0)
; #define PG8_WAIT_V(n) asm volatile("s_waitcnt vmcnt(" #n ")" ::: "memory")
; #define PG8_BAR __builtin_amdgcn_s_barrier()
; template <class Epi, class Sched>
; __device__ __forceinline__ void gemm_phase(LAS unsigned char* lds, const Sched& S, const Epi& E) {
;     ...
;             const bool last = (t == nt - 2);
;             const char* a1 = cA + (size_t)(t + 1) * kstep;
;             const char* a2 = last ? nA : cA + (size_t)(t + 2) * kstep; const char* b2 = last ? nB : cB + (size_t)(t + 2) * kstep;
;             const char* a3 = a2 + kstep; const char* b3 = b2 + kstep;
;             const unsigned vA2 = voffA, vB2 = voffB, hA2 = hA, hB2 = hB;
;             PG8_LDB(B0, 0, 0); PG8_LDB(B1, 0, 1); PG8_SCHED; PG8_LDA(At, 0, 0); PG8_STAGE(PG8_SA(1, 1), a1 + hA, voffA, hA / 2);
;             PG8_WAIT_V(8); PG8_WAIT_L(0); PG8_BAR; PG8_MMA(0, 0, At, B0); PG8_MMA(0, 1, At, B1); PG8_BAR; PG8_SCHED;
;             PG8_LDA(At, 0, 1); PG8_STAGE(PG8_SB(0, 0), b2, vB2, hB2 / 2); PG8_STAGE(PG8_SB(0, 1), b2 + hB2, vB2, hB2 / 2); PG8_STAGE(PG8_SA(0, 0), a2, vA2, hA2 / 2);
;             PG8_WAIT_V(8); PG8_WAIT_L(0); PG8_BAR; PG8_MMA(1, 0, At, B0); PG8_MMA(1, 1, At, B1); PG8_BAR; PG8_SCHED;
.LBB0_1351:
	s_add_u32 s22, s22, 0x40080
	s_addc_u32 s23, s23, 0
	s_add_u32 s59, s24, 0x100
	s_addc_u32 s60, s25, 0
	s_mov_b32 s61, -2
	s_waitcnt vmcnt(3)
	s_waitcnt vmcnt(2)
	s_waitcnt vmcnt(1)
	s_waitcnt vmcnt(0)
	ds_read_b128 v[128:131], v174
	ds_read_b128 v[132:135], v174 offset:1024
	ds_read_b128 v[136:139], v174 offset:2048
	ds_read_b128 v[144:147], v174 offset:3072
	ds_read_b128 v[148:151], v175
	ds_read_b128 v[152:155], v175 offset:1024
	ds_read_b128 v[156:159], v175 offset:2048
	ds_read_b128 v[160:163], v175 offset:3072
	s_add_u32 s24, s22, 0xfffc0080
	s_addc_u32 s25, s23, -1
	s_cmp_eq_u32 s61, 12
	s_cselect_b32 s24, s18, s24
	s_cselect_b32 s25, s19, s25
	s_cselect_b32 s38, s20, s59
	s_cselect_b32 s39, s21, s60
	s_add_u32 s26, s24, 0x80
	s_addc_u32 s27, s25, 0
	ds_read_b128 v[164:167], v177
	ds_read_b128 v[180:183], v177 offset:1024
	ds_read_b128 v[184:187], v177 offset:2048
	ds_read_b128 v[188:191], v177 offset:3072
	ds_read_b128 v[192:195], v177 offset:4096
	ds_read_b128 v[196:199], v177 offset:5120
	ds_read_b128 v[200:203], v177 offset:6144
	ds_read_b128 v[204:207], v177 offset:7168
	s_mov_b32 m0, s54
	s_nop 0
	global_load_lds_dwordx4 v170, s[22:23]
	s_add_u32 s62, s22, 0x20000
	s_mov_b32 m0, s55
	s_addc_u32 s63, s23, 0
	global_load_lds_dwordx4 v170, s[62:63]
	s_waitcnt vmcnt(8) lgkmcnt(0)
	s_barrier
	v_mfma_f32_16x16x32_bf16 v[84:87], v[128:131], v[164:167], 0
	v_mfma_f32_16x16x32_bf16 v[76:79], v[136:139], v[164:167], 0
	v_mfma_f32_16x16x32_bf16 v[124:127], v[128:131], v[184:187], 0
	v_mfma_f32_16x16x32_bf16 v[120:123], v[136:139], v[184:187], 0
	v_mfma_f32_16x16x32_bf16 v[116:119], v[128:131], v[192:195], 0
	v_mfma_f32_16x16x32_bf16 v[112:115], v[136:139], v[192:195], 0
	v_mfma_f32_16x16x32_bf16 v[108:111], v[128:131], v[200:203], 0
	v_mfma_f32_16x16x32_bf16 v[104:107], v[136:139], v[200:203], 0
	v_mfma_f32_16x16x32_bf16 v[84:87], v[132:135], v[180:183], v[84:87]
	v_mfma_f32_16x16x32_bf16 v[76:79], v[144:147], v[180:183], v[76:79]
	v_mfma_f32_16x16x32_bf16 v[124:127], v[132:135], v[188:191], v[124:127]
	v_mfma_f32_16x16x32_bf16 v[120:123], v[144:147], v[188:191], v[120:123]
	v_mfma_f32_16x16x32_bf16 v[116:119], v[132:135], v[196:199], v[116:119]
	v_mfma_f32_16x16x32_bf16 v[112:115], v[144:147], v[196:199], v[112:115]
	v_mfma_f32_16x16x32_bf16 v[108:111], v[132:135], v[204:207], v[108:111]
	v_mfma_f32_16x16x32_bf16 v[104:107], v[144:147], v[204:207], v[104:107]
	v_mfma_f32_16x16x32_bf16 v[60:63], v[148:151], v[164:167], 0
	v_mfma_f32_16x16x32_bf16 v[56:59], v[156:159], v[164:167], 0
	v_mfma_f32_16x16x32_bf16 v[52:55], v[148:151], v[184:187], 0
	v_mfma_f32_16x16x32_bf16 v[48:51], v[156:159], v[184:187], 0
	v_mfma_f32_16x16x32_bf16 v[44:47], v[148:151], v[192:195], 0
	v_mfma_f32_16x16x32_bf16 v[40:43], v[156:159], v[192:195], 0
	v_mfma_f32_16x16x32_bf16 v[36:39], v[148:151], v[200:203], 0
	v_mfma_f32_16x16x32_bf16 v[32:35], v[156:159], v[200:203], 0
	v_mfma_f32_16x16x32_bf16 v[60:63], v[152:155], v[180:183], v[60:63]
	v_mfma_f32_16x16x32_bf16 v[56:59], v[160:163], v[180:183], v[56:59]
	v_mfma_f32_16x16x32_bf16 v[52:55], v[152:155], v[188:191], v[52:55]
	v_mfma_f32_16x16x32_bf16 v[48:51], v[160:163], v[188:191], v[48:51]
	v_mfma_f32_16x16x32_bf16 v[44:47], v[152:155], v[196:199], v[44:47]
	v_mfma_f32_16x16x32_bf16 v[40:43], v[160:163], v[196:199], v[40:43]
	v_mfma_f32_16x16x32_bf16 v[36:39], v[152:155], v[204:207], v[36:39]
	v_mfma_f32_16x16x32_bf16 v[32:35], v[160:163], v[204:207], v[32:35]
	s_add_i32 s61, s61, 2
	s_add_u32 s22, s22, 0x100
	s_addc_u32 s23, s23, 0
	s_add_u32 s59, s59, 0x100
	s_addc_u32 s60, s60, 0
	s_barrier
	s_add_u32 s62, s38, 0x20000
	ds_read_b128 v[164:167], v177 offset:16384
	ds_read_b128 v[180:183], v177 offset:17408
	ds_read_b128 v[184:187], v177 offset:18432
	ds_read_b128 v[188:191], v177 offset:19456
	ds_read_b128 v[192:195], v177 offset:20480
	ds_read_b128 v[196:199], v177 offset:21504
	ds_read_b128 v[200:203], v177 offset:22528
	ds_read_b128 v[204:207], v177 offset:23552
	s_mov_b32 m0, s35
	s_nop 0
	global_load_lds_dwordx4 v171, s[38:39]
	s_mov_b32 m0, s36
	s_addc_u32 s63, s39, 0
	global_load_lds_dwordx4 v171, s[62:63]
	s_add_u32 s62, s38, 0x40000
	s_mov_b32 m0, s37
	s_addc_u32 s63, s39, 0
	global_load_lds_dwordx4 v171, s[62:63]
	s_add_u32 s62, s38, 0x60000
	s_mov_b32 m0, s40
	s_addc_u32 s63, s39, 0
	global_load_lds_dwordx4 v171, s[62:63]
	s_mov_b32 m0, s34
	s_nop 0
	global_load_lds_dwordx4 v170, s[24:25]
	s_add_u32 s62, s24, 0x20000
	s_mov_b32 m0, s41
	s_addc_u32 s63, s25, 0
	global_load_lds_dwordx4 v170, s[62:63]
	s_waitcnt vmcnt(8) lgkmcnt(0)
	s_barrier
	v_mfma_f32_16x16x32_bf16 v[100:103], v[128:131], v[164:167], 0
	v_mfma_f32_16x16x32_bf16 v[96:99], v[136:139], v[164:167], 0
	v_mfma_f32_16x16x32_bf16 v[92:95], v[128:131], v[184:187], 0
	v_mfma_f32_16x16x32_bf16 v[88:91], v[136:139], v[184:187], 0
	v_mfma_f32_16x16x32_bf16 v[80:83], v[128:131], v[192:195], 0
	v_mfma_f32_16x16x32_bf16 v[72:75], v[136:139], v[192:195], 0
	v_mfma_f32_16x16x32_bf16 v[68:71], v[128:131], v[200:203], 0
	v_mfma_f32_16x16x32_bf16 v[64:67], v[136:139], v[200:203], 0
	v_mfma_f32_16x16x32_bf16 v[100:103], v[132:135], v[180:183], v[100:103]
	v_mfma_f32_16x16x32_bf16 v[96:99], v[144:147], v[180:183], v[96:99]
	v_mfma_f32_16x16x32_bf16 v[92:95], v[132:135], v[188:191], v[92:95]
	v_mfma_f32_16x16x32_bf16 v[88:91], v[144:147], v[188:191], v[88:91]
	v_mfma_f32_16x16x32_bf16 v[80:83], v[132:135], v[196:199], v[80:83]
	v_mfma_f32_16x16x32_bf16 v[72:75], v[144:147], v[196:199], v[72:75]
	v_mfma_f32_16x16x32_bf16 v[68:71], v[132:135], v[204:207], v[68:71]
	v_mfma_f32_16x16x32_bf16 v[64:67], v[144:147], v[204:207], v[64:67]
	v_mfma_f32_16x16x32_bf16 v[28:31], v[148:151], v[164:167], 0
	v_mfma_f32_16x16x32_bf16 v[24:27], v[156:159], v[164:167], 0
	v_mfma_f32_16x16x32_bf16 v[20:23], v[148:151], v[184:187], 0
	v_mfma_f32_16x16x32_bf16 v[16:19], v[156:159], v[184:187], 0
	v_mfma_f32_16x16x32_bf16 v[12:15], v[148:151], v[192:195], 0
	v_mfma_f32_16x16x32_bf16 v[8:11], v[156:159], v[192:195], 0
	v_mfma_f32_16x16x32_bf16 v[4:7], v[148:151], v[200:203], 0
	v_mfma_f32_16x16x32_bf16 v[0:3], v[156:159], v[200:203], 0
	v_mfma_f32_16x16x32_bf16 v[28:31], v[152:155], v[180:183], v[28:31]
	v_mfma_f32_16x16x32_bf16 v[24:27], v[160:163], v[180:183], v[24:27]
	v_mfma_f32_16x16x32_bf16 v[20:23], v[152:155], v[188:191], v[20:23]
	v_mfma_f32_16x16x32_bf16 v[16:19], v[160:163], v[188:191], v[16:19]
	v_mfma_f32_16x16x32_bf16 v[12:15], v[152:155], v[196:199], v[12:15]
	v_mfma_f32_16x16x32_bf16 v[8:11], v[160:163], v[196:199], v[8:11]
	v_mfma_f32_16x16x32_bf16 v[4:7], v[152:155], v[204:207], v[4:7]
	v_mfma_f32_16x16x32_bf16 v[0:3], v[160:163], v[204:207], v[0:3]
	s_barrier
	s_branch .Lpeel_mid_40254
; #define PG8_STAGE(bufoff, gbase, voff, p64) do { _Pragma("unroll") for (int _i = 0; _i < 2; ++_i) { \
;         const char* _gb = (const char*)(gbase) + (size_t)_i * (p64); const unsigned _la = ldsbase + (unsigned)(bufoff) + (unsigned)_i * 8192u; \
;         asm volatile("s_mov_b32 m0, %0\n\ts_nop 0\n\tglobal_load_lds_dwordx4 %1, %2" :: "s"(_la), "v"(voff), "s"(_gb) : "memory"); } } while (0)
; #define PG8_LDA(dst, b, h) do { _Pragma("unroll") for (int m = 0; m < 4; ++m) _Pragma("unroll") for (int k = 0; k < 2; ++k) dst[m][k] = *(const LAS bf16x8*)(lds + PG8_SA(b, h) + aoff + m * 2048 + k * 1024); } while (0)
; #define PG8_LDB(dst, b, h) do { _Pragma("unroll") for (int n = 0; n < 2; ++n) _Pragma("unroll") for (int k = 0; k < 2; ++k) dst[n][k] = *(const LAS bf16x8*)(lds + PG8_SB(b, h) + boff + n * 2048 + k * 1024); } while (0)
; #define PG8_MMA(ai, bj, At, Bt) do { __builtin_amdgcn_s_setprio(1); _Pragma("unroll") for (int m = 0; m < 4; ++m) _Pragma("unroll") for (int n = 0; n < 2; ++n) _Pragma("unroll") for (int k = 0; k < 2; ++k) \
;         acc[ai][bj][m][n] = __builtin_amdgcn_mfma_f32_16x16x32_bf16(Bt[n][k], At[m][k], acc[ai][bj][m][n], 0, 0, 0); __builtin_amdgcn_s_setprio(0); } while (0)
; #define PG8_WAIT_V(n) asm volatile("s_waitcnt vmcnt(" #n ")" ::: "memory")
; #define PG8_BAR __builtin_amdgcn_s_barrier()
; template <class Epi, class Sched>
; __device__ __forceinline__ void gemm_phase(LAS unsigned char* lds, const Sched& S, const Epi& E) {
;     ...
;             const bool last = (t == nt - 2);
;             const char* a1 = cA + (size_t)(t + 1) * kstep;
;             const char* a2 = last ? nA : cA + (size_t)(t + 2) * kstep; const char* b2 = last ? nB : cB + (size_t)(t + 2) * kstep;
;             const char* a3 = a2 + kstep; const char* b3 = b2 + kstep;
;             const unsigned vA2 = voffA, vB2 = voffB, hA2 = hA, hB2 = hB;
;             PG8_LDB(B0, 0, 0); PG8_LDB(B1, 0, 1); PG8_SCHED; PG8_LDA(At, 0, 0); PG8_STAGE(PG8_SA(1, 1), a1 + hA, voffA, hA / 2);
;             PG8_WAIT_V(8); PG8_WAIT_L(0); PG8_BAR; PG8_MMA(0, 0, At, B0); PG8_MMA(0, 1, At, B1); PG8_BAR; PG8_SCHED;
;             PG8_LDA(At, 0, 1); PG8_STAGE(PG8_SB(0, 0), b2, vB2, hB2 / 2); PG8_STAGE(PG8_SB(0, 1), b2 + hB2, vB2, hB2 / 2); PG8_STAGE(PG8_SA(0, 0), a2, vA2, hA2 / 2);
;             PG8_WAIT_V(8); PG8_WAIT_L(0); PG8_BAR; PG8_MMA(1, 0, At, B0); PG8_MMA(1, 1, At, B1); PG8_BAR; PG8_SCHED;
.LBB0_1352:
	ds_read_b128 v[128:131], v174
	ds_read_b128 v[132:135], v174 offset:1024
	ds_read_b128 v[136:139], v174 offset:2048
	ds_read_b128 v[144:147], v174 offset:3072
	ds_read_b128 v[148:151], v175
	ds_read_b128 v[152:155], v175 offset:1024
	ds_read_b128 v[156:159], v175 offset:2048
	ds_read_b128 v[160:163], v175 offset:3072
	s_add_u32 s24, s22, 0xfffc0080
	s_addc_u32 s25, s23, -1
	s_cmp_eq_u32 s61, 12
	s_cselect_b32 s24, s18, s24
	s_cselect_b32 s25, s19, s25
	s_cselect_b32 s38, s20, s59
	s_cselect_b32 s39, s21, s60
	s_add_u32 s26, s24, 0x80
	s_addc_u32 s27, s25, 0
	ds_read_b128 v[164:167], v177
	ds_read_b128 v[180:183], v177 offset:1024
	ds_read_b128 v[184:187], v177 offset:2048
	ds_read_b128 v[188:191], v177 offset:3072
	ds_read_b128 v[192:195], v177 offset:4096
	ds_read_b128 v[196:199], v177 offset:5120
	ds_read_b128 v[200:203], v177 offset:6144
	ds_read_b128 v[204:207], v177 offset:7168
	s_mov_b32 m0, s54
	s_nop 0
	global_load_lds_dwordx4 v170, s[22:23]
	s_add_u32 s62, s22, 0x20000
	s_mov_b32 m0, s55
	s_addc_u32 s63, s23, 0
	global_load_lds_dwordx4 v170, s[62:63]
	s_waitcnt vmcnt(8) lgkmcnt(0)
	s_barrier
	v_mfma_f32_16x16x32_bf16 v[84:87], v[128:131], v[164:167], v[84:87]
	v_mfma_f32_16x16x32_bf16 v[76:79], v[136:139], v[164:167], v[76:79]
	v_mfma_f32_16x16x32_bf16 v[124:127], v[128:131], v[184:187], v[124:127]
	v_mfma_f32_16x16x32_bf16 v[120:123], v[136:139], v[184:187], v[120:123]
	v_mfma_f32_16x16x32_bf16 v[116:119], v[128:131], v[192:195], v[116:119]
	v_mfma_f32_16x16x32_bf16 v[112:115], v[136:139], v[192:195], v[112:115]
	v_mfma_f32_16x16x32_bf16 v[108:111], v[128:131], v[200:203], v[108:111]
	v_mfma_f32_16x16x32_bf16 v[104:107], v[136:139], v[200:203], v[104:107]
	v_mfma_f32_16x16x32_bf16 v[84:87], v[132:135], v[180:183], v[84:87]
	v_mfma_f32_16x16x32_bf16 v[76:79], v[144:147], v[180:183], v[76:79]
	v_mfma_f32_16x16x32_bf16 v[124:127], v[132:135], v[188:191], v[124:127]
	v_mfma_f32_16x16x32_bf16 v[120:123], v[144:147], v[188:191], v[120:123]
	v_mfma_f32_16x16x32_bf16 v[116:119], v[132:135], v[196:199], v[116:119]
	v_mfma_f32_16x16x32_bf16 v[112:115], v[144:147], v[196:199], v[112:115]
	v_mfma_f32_16x16x32_bf16 v[108:111], v[132:135], v[204:207], v[108:111]
	v_mfma_f32_16x16x32_bf16 v[104:107], v[144:147], v[204:207], v[104:107]
	v_mfma_f32_16x16x32_bf16 v[60:63], v[148:151], v[164:167], v[60:63]
	v_mfma_f32_16x16x32_bf16 v[56:59], v[156:159], v[164:167], v[56:59]
	v_mfma_f32_16x16x32_bf16 v[52:55], v[148:151], v[184:187], v[52:55]
	v_mfma_f32_16x16x32_bf16 v[48:51], v[156:159], v[184:187], v[48:51]
	v_mfma_f32_16x16x32_bf16 v[44:47], v[148:151], v[192:195], v[44:47]
	v_mfma_f32_16x16x32_bf16 v[40:43], v[156:159], v[192:195], v[40:43]
	v_mfma_f32_16x16x32_bf16 v[36:39], v[148:151], v[200:203], v[36:39]
	v_mfma_f32_16x16x32_bf16 v[32:35], v[156:159], v[200:203], v[32:35]
	v_mfma_f32_16x16x32_bf16 v[60:63], v[152:155], v[180:183], v[60:63]
	v_mfma_f32_16x16x32_bf16 v[56:59], v[160:163], v[180:183], v[56:59]
	v_mfma_f32_16x16x32_bf16 v[52:55], v[152:155], v[188:191], v[52:55]
	v_mfma_f32_16x16x32_bf16 v[48:51], v[160:163], v[188:191], v[48:51]
	v_mfma_f32_16x16x32_bf16 v[44:47], v[152:155], v[196:199], v[44:47]
	v_mfma_f32_16x16x32_bf16 v[40:43], v[160:163], v[196:199], v[40:43]
	v_mfma_f32_16x16x32_bf16 v[36:39], v[152:155], v[204:207], v[36:39]
	v_mfma_f32_16x16x32_bf16 v[32:35], v[160:163], v[204:207], v[32:35]
	s_add_i32 s61, s61, 2
	s_add_u32 s22, s22, 0x100
	s_addc_u32 s23, s23, 0
	s_add_u32 s59, s59, 0x100
	s_addc_u32 s60, s60, 0
	s_barrier
	s_add_u32 s62, s38, 0x20000
	ds_read_b128 v[164:167], v177 offset:16384
	ds_read_b128 v[180:183], v177 offset:17408
	ds_read_b128 v[184:187], v177 offset:18432
	ds_read_b128 v[188:191], v177 offset:19456
	ds_read_b128 v[192:195], v177 offset:20480
	ds_read_b128 v[196:199], v177 offset:21504
	ds_read_b128 v[200:203], v177 offset:22528
	ds_read_b128 v[204:207], v177 offset:23552
	s_mov_b32 m0, s35
	s_nop 0
	global_load_lds_dwordx4 v171, s[38:39]
	s_mov_b32 m0, s36
	s_addc_u32 s63, s39, 0
	global_load_lds_dwordx4 v171, s[62:63]
	s_add_u32 s62, s38, 0x40000
	s_mov_b32 m0, s37
	s_addc_u32 s63, s39, 0
	global_load_lds_dwordx4 v171, s[62:63]
	s_add_u32 s62, s38, 0x60000
	s_mov_b32 m0, s40
	s_addc_u32 s63, s39, 0
	global_load_lds_dwordx4 v171, s[62:63]
	s_mov_b32 m0, s34
	s_nop 0
	global_load_lds_dwordx4 v170, s[24:25]
	s_add_u32 s62, s24, 0x20000
	s_mov_b32 m0, s41
	s_addc_u32 s63, s25, 0
	global_load_lds_dwordx4 v170, s[62:63]
	s_waitcnt vmcnt(8) lgkmcnt(0)
	s_barrier
	v_mfma_f32_16x16x32_bf16 v[100:103], v[128:131], v[164:167], v[100:103]
	v_mfma_f32_16x16x32_bf16 v[96:99], v[136:139], v[164:167], v[96:99]
	v_mfma_f32_16x16x32_bf16 v[92:95], v[128:131], v[184:187], v[92:95]
	v_mfma_f32_16x16x32_bf16 v[88:91], v[136:139], v[184:187], v[88:91]
	v_mfma_f32_16x16x32_bf16 v[80:83], v[128:131], v[192:195], v[80:83]
	v_mfma_f32_16x16x32_bf16 v[72:75], v[136:139], v[192:195], v[72:75]
	v_mfma_f32_16x16x32_bf16 v[68:71], v[128:131], v[200:203], v[68:71]
	v_mfma_f32_16x16x32_bf16 v[64:67], v[136:139], v[200:203], v[64:67]
	v_mfma_f32_16x16x32_bf16 v[100:103], v[132:135], v[180:183], v[100:103]
	v_mfma_f32_16x16x32_bf16 v[96:99], v[144:147], v[180:183], v[96:99]
	v_mfma_f32_16x16x32_bf16 v[92:95], v[132:135], v[188:191], v[92:95]
	v_mfma_f32_16x16x32_bf16 v[88:91], v[144:147], v[188:191], v[88:91]
	v_mfma_f32_16x16x32_bf16 v[80:83], v[132:135], v[196:199], v[80:83]
	v_mfma_f32_16x16x32_bf16 v[72:75], v[144:147], v[196:199], v[72:75]
	v_mfma_f32_16x16x32_bf16 v[68:71], v[132:135], v[204:207], v[68:71]
	v_mfma_f32_16x16x32_bf16 v[64:67], v[144:147], v[204:207], v[64:67]
	v_mfma_f32_16x16x32_bf16 v[28:31], v[148:151], v[164:167], v[28:31]
	v_mfma_f32_16x16x32_bf16 v[24:27], v[156:159], v[164:167], v[24:27]
	v_mfma_f32_16x16x32_bf16 v[20:23], v[148:151], v[184:187], v[20:23]
	v_mfma_f32_16x16x32_bf16 v[16:19], v[156:159], v[184:187], v[16:19]
	v_mfma_f32_16x16x32_bf16 v[12:15], v[148:151], v[192:195], v[12:15]
	v_mfma_f32_16x16x32_bf16 v[8:11], v[156:159], v[192:195], v[8:11]
	v_mfma_f32_16x16x32_bf16 v[4:7], v[148:151], v[200:203], v[4:7]
	v_mfma_f32_16x16x32_bf16 v[0:3], v[156:159], v[200:203], v[0:3]
	v_mfma_f32_16x16x32_bf16 v[28:31], v[152:155], v[180:183], v[28:31]
	v_mfma_f32_16x16x32_bf16 v[24:27], v[160:163], v[180:183], v[24:27]
	v_mfma_f32_16x16x32_bf16 v[20:23], v[152:155], v[188:191], v[20:23]
	v_mfma_f32_16x16x32_bf16 v[16:19], v[160:163], v[188:191], v[16:19]
	v_mfma_f32_16x16x32_bf16 v[12:15], v[152:155], v[196:199], v[12:15]
	v_mfma_f32_16x16x32_bf16 v[8:11], v[160:163], v[196:199], v[8:11]
	v_mfma_f32_16x16x32_bf16 v[4:7], v[152:155], v[204:207], v[4:7]
	v_mfma_f32_16x16x32_bf16 v[0:3], v[160:163], v[204:207], v[0:3]
	s_barrier
; #define PG8_STAGE(bufoff, gbase, voff, p64) do { _Pragma("unroll") for (int _i = 0; _i < 2; ++_i) { \
;         const char* _gb = (const char*)(gbase) + (size_t)_i * (p64); const unsigned _la = ldsbase + (unsigned)(bufoff) + (unsigned)_i * 8192u; \
;         asm volatile("s_mov_b32 m0, %0\n\ts_nop 0\n\tglobal_load_lds_dwordx4 %1, %2" :: "s"(_la), "v"(voff), "s"(_gb) : "memory"); } } while (0)
; #define PG8_LDA(dst, b, h) do { _Pragma("unroll") for (int m = 0; m < 4; ++m) _Pragma("unroll") for (int k = 0; k < 2; ++k) dst[m][k] = *(const LAS bf16x8*)(lds + PG8_SA(b, h) + aoff + m * 2048 + k * 1024); } while (0)
; #define PG8_LDB(dst, b, h) do { _Pragma("unroll") for (int n = 0; n < 2; ++n) _Pragma("unroll") for (int k = 0; k < 2; ++k) dst[n][k] = *(const LAS bf16x8*)(lds + PG8_SB(b, h) + boff + n * 2048 + k * 1024); } while (0)
; #define PG8_MMA(ai, bj, At, Bt) do { __builtin_amdgcn_s_setprio(1); _Pragma("unroll") for (int m = 0; m < 4; ++m) _Pragma("unroll") for (int n = 0; n < 2; ++n) _Pragma("unroll") for (int k = 0; k < 2; ++k) \
;         acc[ai][bj][m][n] = __builtin_amdgcn_mfma_f32_16x16x32_bf16(Bt[n][k], At[m][k], acc[ai][bj][m][n], 0, 0, 0); __builtin_amdgcn_s_setprio(0); } while (0)
; #define PG8_WAIT_V(n) asm volatile("s_waitcnt vmcnt(" #n ")" ::: "memory")
; #define PG8_WAIT_L(n) asm volatile("s_waitcnt lgkmcnt(" #n ")" ::: "memory")
; #define PG8_BAR __builtin_amdgcn_s_barrier()
; #define PG8_SCHED __builtin_amdgcn_sched_barrier(0)
; template <class Epi, class Sched>
; __device__ __forceinline__ void gemm_phase(LAS unsigned char* lds, const Sched& S, const Epi& E) {
;     ...
;             PG8_LDB(B0, 1, 0); PG8_LDB(B1, 1, 1); PG8_SCHED; PG8_LDA(At, 1, 0); PG8_STAGE(PG8_SA(0, 1), a2 + hA2, vA2, hA2 / 2);
;             PG8_WAIT_V(8); PG8_WAIT_L(0); PG8_BAR; PG8_MMA(0, 0, At, B0); PG8_MMA(0, 1, At, B1); PG8_BAR; PG8_SCHED;
;             PG8_LDA(At, 1, 1); PG8_STAGE(PG8_SB(1, 0), b3, vB2, hB2 / 2); PG8_STAGE(PG8_SB(1, 1), b3 + hB2, vB2, hB2 / 2); PG8_STAGE(PG8_SA(1, 0), a3, vA2, hA2 / 2);
;             PG8_WAIT_V(8); PG8_WAIT_L(0); PG8_BAR; PG8_MMA(1, 0, At, B0); PG8_MMA(1, 1, At, B1); PG8_BAR; PG8_SCHED;
.Lpeel_mid_40254:
	ds_read_b128 v[128:131], v178
	ds_read_b128 v[132:135], v178 offset:1024
	ds_read_b128 v[136:139], v178 offset:2048
	ds_read_b128 v[144:147], v178 offset:3072
	ds_read_b128 v[148:151], v179
	ds_read_b128 v[152:155], v179 offset:1024
	ds_read_b128 v[156:159], v179 offset:2048
	ds_read_b128 v[160:163], v179 offset:3072
	ds_read_b128 v[164:167], v177 offset:32768
	ds_read_b128 v[180:183], v177 offset:33792
	ds_read_b128 v[184:187], v177 offset:34816
	ds_read_b128 v[188:191], v177 offset:35840
	ds_read_b128 v[192:195], v177 offset:36864
	ds_read_b128 v[196:199], v177 offset:37888
	ds_read_b128 v[200:203], v177 offset:38912
	ds_read_b128 v[204:207], v177 offset:39936
	s_add_u32 s62, s24, 0x40000
	s_mov_b32 m0, s42
	s_addc_u32 s63, s25, 0
	global_load_lds_dwordx4 v170, s[62:63]
	s_add_u32 s62, s24, 0x60000
	s_mov_b32 m0, s43
	s_addc_u32 s63, s25, 0
	global_load_lds_dwordx4 v170, s[62:63]
	s_waitcnt vmcnt(8) lgkmcnt(0)
	s_barrier
	v_mfma_f32_16x16x32_bf16 v[84:87], v[128:131], v[164:167], v[84:87]
	v_mfma_f32_16x16x32_bf16 v[76:79], v[136:139], v[164:167], v[76:79]
	v_mfma_f32_16x16x32_bf16 v[124:127], v[128:131], v[184:187], v[124:127]
	v_mfma_f32_16x16x32_bf16 v[120:123], v[136:139], v[184:187], v[120:123]
	v_mfma_f32_16x16x32_bf16 v[116:119], v[128:131], v[192:195], v[116:119]
	v_mfma_f32_16x16x32_bf16 v[112:115], v[136:139], v[192:195], v[112:115]
	v_mfma_f32_16x16x32_bf16 v[108:111], v[128:131], v[200:203], v[108:111]
	v_mfma_f32_16x16x32_bf16 v[104:107], v[136:139], v[200:203], v[104:107]
	v_mfma_f32_16x16x32_bf16 v[84:87], v[132:135], v[180:183], v[84:87]
	v_mfma_f32_16x16x32_bf16 v[76:79], v[144:147], v[180:183], v[76:79]
	v_mfma_f32_16x16x32_bf16 v[124:127], v[132:135], v[188:191], v[124:127]
	v_mfma_f32_16x16x32_bf16 v[120:123], v[144:147], v[188:191], v[120:123]
	v_mfma_f32_16x16x32_bf16 v[116:119], v[132:135], v[196:199], v[116:119]
	v_mfma_f32_16x16x32_bf16 v[112:115], v[144:147], v[196:199], v[112:115]
	v_mfma_f32_16x16x32_bf16 v[108:111], v[132:135], v[204:207], v[108:111]
	v_mfma_f32_16x16x32_bf16 v[104:107], v[144:147], v[204:207], v[104:107]
	v_mfma_f32_16x16x32_bf16 v[60:63], v[148:151], v[164:167], v[60:63]
	v_mfma_f32_16x16x32_bf16 v[56:59], v[156:159], v[164:167], v[56:59]
	v_mfma_f32_16x16x32_bf16 v[52:55], v[148:151], v[184:187], v[52:55]
	v_mfma_f32_16x16x32_bf16 v[48:51], v[156:159], v[184:187], v[48:51]
	v_mfma_f32_16x16x32_bf16 v[44:47], v[148:151], v[192:195], v[44:47]
	v_mfma_f32_16x16x32_bf16 v[40:43], v[156:159], v[192:195], v[40:43]
	v_mfma_f32_16x16x32_bf16 v[36:39], v[148:151], v[200:203], v[36:39]
	v_mfma_f32_16x16x32_bf16 v[32:35], v[156:159], v[200:203], v[32:35]
	v_mfma_f32_16x16x32_bf16 v[60:63], v[152:155], v[180:183], v[60:63]
	v_mfma_f32_16x16x32_bf16 v[56:59], v[160:163], v[180:183], v[56:59]
	v_mfma_f32_16x16x32_bf16 v[52:55], v[152:155], v[188:191], v[52:55]
	v_mfma_f32_16x16x32_bf16 v[48:51], v[160:163], v[188:191], v[48:51]
	v_mfma_f32_16x16x32_bf16 v[44:47], v[152:155], v[196:199], v[44:47]
	v_mfma_f32_16x16x32_bf16 v[40:43], v[160:163], v[196:199], v[40:43]
	v_mfma_f32_16x16x32_bf16 v[36:39], v[152:155], v[204:207], v[36:39]
	v_mfma_f32_16x16x32_bf16 v[32:35], v[160:163], v[204:207], v[32:35]
	s_barrier
	s_add_u32 s62, s38, 0x80
	s_addc_u32 s63, s39, 0
	ds_read_b128 v[164:167], v177 offset:49152
	ds_read_b128 v[180:183], v177 offset:50176
	ds_read_b128 v[184:187], v177 offset:51200
	ds_read_b128 v[188:191], v177 offset:52224
	ds_read_b128 v[192:195], v177 offset:53248
	ds_read_b128 v[196:199], v177 offset:54272
	ds_read_b128 v[200:203], v177 offset:55296
	ds_read_b128 v[204:207], v177 offset:56320
	s_mov_b32 m0, s48
	s_nop 0
	global_load_lds_dwordx4 v171, s[62:63]
	s_add_u32 s62, s38, 0x20080
	s_mov_b32 m0, s49
	s_addc_u32 s63, s39, 0
	global_load_lds_dwordx4 v171, s[62:63]
	s_add_u32 s62, s38, 0x40080
	s_mov_b32 m0, s52
	s_addc_u32 s63, s39, 0
	global_load_lds_dwordx4 v171, s[62:63]
	s_add_u32 s38, s38, 0x60080
	s_mov_b32 m0, s53
	s_addc_u32 s39, s39, 0
	global_load_lds_dwordx4 v171, s[38:39]
	s_mov_b32 m0, s50
	s_nop 0
	global_load_lds_dwordx4 v170, s[26:27]
	s_add_u32 s24, s24, 0x20080
	s_mov_b32 m0, s51
	s_addc_u32 s25, s25, 0
	global_load_lds_dwordx4 v170, s[24:25]
	s_waitcnt vmcnt(8) lgkmcnt(0)
	s_barrier
	v_mfma_f32_16x16x32_bf16 v[100:103], v[128:131], v[164:167], v[100:103]
	v_mfma_f32_16x16x32_bf16 v[96:99], v[136:139], v[164:167], v[96:99]
	v_mfma_f32_16x16x32_bf16 v[92:95], v[128:131], v[184:187], v[92:95]
	v_mfma_f32_16x16x32_bf16 v[88:91], v[136:139], v[184:187], v[88:91]
	v_mfma_f32_16x16x32_bf16 v[80:83], v[128:131], v[192:195], v[80:83]
	v_mfma_f32_16x16x32_bf16 v[72:75], v[136:139], v[192:195], v[72:75]
	v_mfma_f32_16x16x32_bf16 v[68:71], v[128:131], v[200:203], v[68:71]
	v_mfma_f32_16x16x32_bf16 v[64:67], v[136:139], v[200:203], v[64:67]
	v_mfma_f32_16x16x32_bf16 v[100:103], v[132:135], v[180:183], v[100:103]
	v_mfma_f32_16x16x32_bf16 v[96:99], v[144:147], v[180:183], v[96:99]
	v_mfma_f32_16x16x32_bf16 v[92:95], v[132:135], v[188:191], v[92:95]
	v_mfma_f32_16x16x32_bf16 v[88:91], v[144:147], v[188:191], v[88:91]
	v_mfma_f32_16x16x32_bf16 v[80:83], v[132:135], v[196:199], v[80:83]
	v_mfma_f32_16x16x32_bf16 v[72:75], v[144:147], v[196:199], v[72:75]
	v_mfma_f32_16x16x32_bf16 v[68:71], v[132:135], v[204:207], v[68:71]
	v_mfma_f32_16x16x32_bf16 v[64:67], v[144:147], v[204:207], v[64:67]
	v_mfma_f32_16x16x32_bf16 v[28:31], v[148:151], v[164:167], v[28:31]
	v_mfma_f32_16x16x32_bf16 v[24:27], v[156:159], v[164:167], v[24:27]
	v_mfma_f32_16x16x32_bf16 v[20:23], v[148:151], v[184:187], v[20:23]
	v_mfma_f32_16x16x32_bf16 v[16:19], v[156:159], v[184:187], v[16:19]
	v_mfma_f32_16x16x32_bf16 v[12:15], v[148:151], v[192:195], v[12:15]
	v_mfma_f32_16x16x32_bf16 v[8:11], v[156:159], v[192:195], v[8:11]
	v_mfma_f32_16x16x32_bf16 v[4:7], v[148:151], v[200:203], v[4:7]
	v_mfma_f32_16x16x32_bf16 v[0:3], v[156:159], v[200:203], v[0:3]
	v_mfma_f32_16x16x32_bf16 v[28:31], v[152:155], v[180:183], v[28:31]
	v_mfma_f32_16x16x32_bf16 v[24:27], v[160:163], v[180:183], v[24:27]
	v_mfma_f32_16x16x32_bf16 v[20:23], v[152:155], v[188:191], v[20:23]
	v_mfma_f32_16x16x32_bf16 v[16:19], v[160:163], v[188:191], v[16:19]
	v_mfma_f32_16x16x32_bf16 v[12:15], v[152:155], v[196:199], v[12:15]
	v_mfma_f32_16x16x32_bf16 v[8:11], v[160:163], v[196:199], v[8:11]
	v_mfma_f32_16x16x32_bf16 v[4:7], v[152:155], v[204:207], v[4:7]
	v_mfma_f32_16x16x32_bf16 v[0:3], v[160:163], v[204:207], v[0:3]
	s_barrier
	s_cmp_gt_u32 s61, 13
	s_cbranch_scc0 .LBB0_1352
	s_and_b64 vcc, exec, s[12:13]
	s_cbranch_vccz .LBB0_1355
	s_barrier

; #define PG8_STAGE(bufoff, gbase, voff, p64) do { _Pragma("unroll") for (int _i = 0; _i < 2; ++_i) { \
;         const char* _gb = (const char*)(gbase) + (size_t)_i * (p64); const unsigned _la = ldsbase + (unsigned)(bufoff) + (unsigned)_i * 8192u; \
;         asm volatile("s_mov_b32 m0, %0\n\ts_nop 0\n\tglobal_load_lds_dwordx4 %1, %2" :: "s"(_la), "v"(voff), "s"(_gb) : "memory"); } } while (0)
; #define PG8_LDA(dst, b, h) do { _Pragma("unroll") for (int m = 0; m < 4; ++m) _Pragma("unroll") for (int k = 0; k < 2; ++k) dst[m][k] = *(const LAS bf16x8*)(lds + PG8_SA(b, h) + aoff + m * 2048 + k * 1024); } while (0)
; #define PG8_LDB(dst, b, h) do { _Pragma("unroll") for (int n = 0; n < 2; ++n) _Pragma("unroll") for (int k = 0; k < 2; ++k) dst[n][k] = *(const LAS bf16x8*)(lds + PG8_SB(b, h) + boff + n * 2048 + k * 1024); } while (0)
; #define PG8_MMA(ai, bj, At, Bt) do { __builtin_amdgcn_s_setprio(1); _Pragma("unroll") for (int m = 0; m < 4; ++m) _Pragma("unroll") for (int n = 0; n < 2; ++n) _Pragma("unroll") for (int k = 0; k < 2; ++k) \
;         acc[ai][bj][m][n] = __builtin_amdgcn_mfma_f32_16x16x32_bf16(Bt[n][k], At[m][k], acc[ai][bj][m][n], 0, 0, 0); __builtin_amdgcn_s_setprio(0); } while (0)
; #define PG8_WAIT_V(n) asm volatile("s_waitcnt vmcnt(" #n ")" ::: "memory")
; #define PG8_BAR __builtin_amdgcn_s_barrier()
; template <class Epi, class Sched>
; __device__ __forceinline__ void gemm_phase(LAS unsigned char* lds, const Sched& S, const Epi& E) {
;     ...
;             const bool last = (t == nt - 2);
;             const char* a1 = cA + (size_t)(t + 1) * kstep;
;             const char* a2 = last ? nA : cA + (size_t)(t + 2) * kstep; const char* b2 = last ? nB : cB + (size_t)(t + 2) * kstep;
;             const char* a3 = a2 + kstep; const char* b3 = b2 + kstep;
;             const unsigned vA2 = voffA, vB2 = voffB, hA2 = hA, hB2 = hB;
;             PG8_LDB(B0, 0, 0); PG8_LDB(B1, 0, 1); PG8_SCHED; PG8_LDA(At, 0, 0); PG8_STAGE(PG8_SA(1, 1), a1 + hA, voffA, hA / 2);
;             PG8_WAIT_V(8); PG8_WAIT_L(0); PG8_BAR; PG8_MMA(0, 0, At, B0); PG8_MMA(0, 1, At, B1); PG8_BAR; PG8_SCHED;
;             PG8_LDA(At, 0, 1); PG8_STAGE(PG8_SB(0, 0), b2, vB2, hB2 / 2); PG8_STAGE(PG8_SB(0, 1), b2 + hB2, vB2, hB2 / 2); PG8_STAGE(PG8_SA(0, 0), a2, vA2, hA2 / 2);
;             PG8_WAIT_V(8); PG8_WAIT_L(0); PG8_BAR; PG8_MMA(1, 0, At, B0); PG8_MMA(1, 1, At, B1); PG8_BAR; PG8_SCHED;
.LBB0_1484:
	s_add_u32 s24, s24, 0x40080
	s_addc_u32 s25, s25, 0
	s_add_u32 s59, s26, 0x100
	s_addc_u32 s60, s27, 0
	s_mov_b32 s61, -2
	ds_read_b128 v[144:147], v138
	ds_read_b128 v[148:151], v138 offset:1024
	ds_read_b128 v[152:155], v138 offset:2048
	ds_read_b128 v[156:159], v138 offset:3072
	ds_read_b128 v[160:163], v139
	ds_read_b128 v[164:167], v139 offset:1024
	ds_read_b128 v[168:171], v139 offset:2048
	ds_read_b128 v[172:175], v139 offset:3072
	s_add_u32 s26, s24, 0xfffc0080
	s_addc_u32 s27, s25, -1
	s_cmp_eq_u32 s61, 12
	s_cselect_b32 s26, s20, s26
	s_cselect_b32 s27, s21, s27
	s_cselect_b32 s40, s22, s59
	s_cselect_b32 s41, s23, s60
	s_add_u32 s38, s26, 0x80
	s_addc_u32 s39, s27, 0
	ds_read_b128 v[178:181], v140
	ds_read_b128 v[182:185], v140 offset:1024
	ds_read_b128 v[186:189], v140 offset:2048
	ds_read_b128 v[190:193], v140 offset:3072
	ds_read_b128 v[194:197], v140 offset:4096
	ds_read_b128 v[198:201], v140 offset:5120
	ds_read_b128 v[202:205], v140 offset:6144
	ds_read_b128 v[206:209], v140 offset:7168
	s_mov_b32 m0, s54
	s_nop 0
	global_load_lds_dwordx4 v134, s[24:25]
	s_add_u32 s62, s24, 0x20000
	s_mov_b32 m0, s55
	s_addc_u32 s63, s25, 0
	global_load_lds_dwordx4 v134, s[62:63]
	s_waitcnt vmcnt(8) lgkmcnt(0)
	s_barrier
	v_mfma_f32_16x16x32_bf16 v[124:127], v[144:147], v[178:181], 0
	v_mfma_f32_16x16x32_bf16 v[120:123], v[152:155], v[178:181], 0
	v_mfma_f32_16x16x32_bf16 v[108:111], v[144:147], v[186:189], 0
	v_mfma_f32_16x16x32_bf16 v[104:107], v[152:155], v[186:189], 0
	v_mfma_f32_16x16x32_bf16 v[92:95], v[144:147], v[194:197], 0
	v_mfma_f32_16x16x32_bf16 v[88:91], v[152:155], v[194:197], 0
	v_mfma_f32_16x16x32_bf16 v[76:79], v[144:147], v[202:205], 0
	v_mfma_f32_16x16x32_bf16 v[72:75], v[152:155], v[202:205], 0
	v_mfma_f32_16x16x32_bf16 v[124:127], v[148:151], v[182:185], v[124:127]
	v_mfma_f32_16x16x32_bf16 v[120:123], v[156:159], v[182:185], v[120:123]
	v_mfma_f32_16x16x32_bf16 v[108:111], v[148:151], v[190:193], v[108:111]
	v_mfma_f32_16x16x32_bf16 v[104:107], v[156:159], v[190:193], v[104:107]
	v_mfma_f32_16x16x32_bf16 v[92:95], v[148:151], v[198:201], v[92:95]
	v_mfma_f32_16x16x32_bf16 v[88:91], v[156:159], v[198:201], v[88:91]
	v_mfma_f32_16x16x32_bf16 v[76:79], v[148:151], v[206:209], v[76:79]
	v_mfma_f32_16x16x32_bf16 v[72:75], v[156:159], v[206:209], v[72:75]
	v_mfma_f32_16x16x32_bf16 v[116:119], v[160:163], v[178:181], 0
	v_mfma_f32_16x16x32_bf16 v[112:115], v[168:171], v[178:181], 0
	v_mfma_f32_16x16x32_bf16 v[100:103], v[160:163], v[186:189], 0
	v_mfma_f32_16x16x32_bf16 v[96:99], v[168:171], v[186:189], 0
	v_mfma_f32_16x16x32_bf16 v[84:87], v[160:163], v[194:197], 0
	v_mfma_f32_16x16x32_bf16 v[80:83], v[168:171], v[194:197], 0
	v_mfma_f32_16x16x32_bf16 v[68:71], v[160:163], v[202:205], 0
	v_mfma_f32_16x16x32_bf16 v[64:67], v[168:171], v[202:205], 0
	v_mfma_f32_16x16x32_bf16 v[116:119], v[164:167], v[182:185], v[116:119]
	v_mfma_f32_16x16x32_bf16 v[112:115], v[172:175], v[182:185], v[112:115]
	v_mfma_f32_16x16x32_bf16 v[100:103], v[164:167], v[190:193], v[100:103]
	v_mfma_f32_16x16x32_bf16 v[96:99], v[172:175], v[190:193], v[96:99]
	v_mfma_f32_16x16x32_bf16 v[84:87], v[164:167], v[198:201], v[84:87]
	v_mfma_f32_16x16x32_bf16 v[80:83], v[172:175], v[198:201], v[80:83]
	v_mfma_f32_16x16x32_bf16 v[68:71], v[164:167], v[206:209], v[68:71]
	v_mfma_f32_16x16x32_bf16 v[64:67], v[172:175], v[206:209], v[64:67]
	s_add_i32 s61, s61, 2
	s_add_u32 s24, s24, 0x100
	s_addc_u32 s25, s25, 0
	s_add_u32 s59, s59, 0x100
	s_addc_u32 s60, s60, 0
	s_barrier
	s_add_u32 s62, s40, 0x20000
	ds_read_b128 v[178:181], v140 offset:16384
	ds_read_b128 v[182:185], v140 offset:17408
	ds_read_b128 v[186:189], v140 offset:18432
	ds_read_b128 v[190:193], v140 offset:19456
	ds_read_b128 v[194:197], v140 offset:20480
	ds_read_b128 v[198:201], v140 offset:21504
	ds_read_b128 v[202:205], v140 offset:22528
	ds_read_b128 v[206:209], v140 offset:23552
	s_mov_b32 m0, s36
	s_nop 0
	global_load_lds_dwordx4 v135, s[40:41]
	s_mov_b32 m0, s37
	s_addc_u32 s63, s41, 0
	global_load_lds_dwordx4 v135, s[62:63]
	s_add_u32 s62, s40, 0x40000
	s_mov_b32 m0, s42
	s_addc_u32 s63, s41, 0
	global_load_lds_dwordx4 v135, s[62:63]
	s_add_u32 s62, s40, 0x60000
	s_mov_b32 m0, s43
	s_addc_u32 s63, s41, 0
	global_load_lds_dwordx4 v135, s[62:63]
	s_mov_b32 m0, s34
	s_nop 0
	global_load_lds_dwordx4 v134, s[26:27]
	s_add_u32 s62, s26, 0x20000
	s_mov_b32 m0, s44
	s_addc_u32 s63, s27, 0
	global_load_lds_dwordx4 v134, s[62:63]
	s_waitcnt vmcnt(8) lgkmcnt(0)
	s_barrier
	v_mfma_f32_16x16x32_bf16 v[60:63], v[144:147], v[178:181], 0
	v_mfma_f32_16x16x32_bf16 v[56:59], v[152:155], v[178:181], 0
	v_mfma_f32_16x16x32_bf16 v[44:47], v[144:147], v[186:189], 0
	v_mfma_f32_16x16x32_bf16 v[40:43], v[152:155], v[186:189], 0
	v_mfma_f32_16x16x32_bf16 v[28:31], v[144:147], v[194:197], 0
	v_mfma_f32_16x16x32_bf16 v[24:27], v[152:155], v[194:197], 0
	v_mfma_f32_16x16x32_bf16 v[12:15], v[144:147], v[202:205], 0
	v_mfma_f32_16x16x32_bf16 v[8:11], v[152:155], v[202:205], 0
	v_mfma_f32_16x16x32_bf16 v[60:63], v[148:151], v[182:185], v[60:63]
	v_mfma_f32_16x16x32_bf16 v[56:59], v[156:159], v[182:185], v[56:59]
	v_mfma_f32_16x16x32_bf16 v[44:47], v[148:151], v[190:193], v[44:47]
	v_mfma_f32_16x16x32_bf16 v[40:43], v[156:159], v[190:193], v[40:43]
	v_mfma_f32_16x16x32_bf16 v[28:31], v[148:151], v[198:201], v[28:31]
	v_mfma_f32_16x16x32_bf16 v[24:27], v[156:159], v[198:201], v[24:27]
	v_mfma_f32_16x16x32_bf16 v[12:15], v[148:151], v[206:209], v[12:15]
	v_mfma_f32_16x16x32_bf16 v[8:11], v[156:159], v[206:209], v[8:11]
	v_mfma_f32_16x16x32_bf16 v[52:55], v[160:163], v[178:181], 0
	v_mfma_f32_16x16x32_bf16 v[48:51], v[168:171], v[178:181], 0
	v_mfma_f32_16x16x32_bf16 v[36:39], v[160:163], v[186:189], 0
	v_mfma_f32_16x16x32_bf16 v[32:35], v[168:171], v[186:189], 0
	v_mfma_f32_16x16x32_bf16 v[20:23], v[160:163], v[194:197], 0
	v_mfma_f32_16x16x32_bf16 v[16:19], v[168:171], v[194:197], 0
	v_mfma_f32_16x16x32_bf16 v[4:7], v[160:163], v[202:205], 0
	v_mfma_f32_16x16x32_bf16 v[0:3], v[168:171], v[202:205], 0
	v_mfma_f32_16x16x32_bf16 v[52:55], v[164:167], v[182:185], v[52:55]
	v_mfma_f32_16x16x32_bf16 v[48:51], v[172:175], v[182:185], v[48:51]
	v_mfma_f32_16x16x32_bf16 v[36:39], v[164:167], v[190:193], v[36:39]
	v_mfma_f32_16x16x32_bf16 v[32:35], v[172:175], v[190:193], v[32:35]
	v_mfma_f32_16x16x32_bf16 v[20:23], v[164:167], v[198:201], v[20:23]
	v_mfma_f32_16x16x32_bf16 v[16:19], v[172:175], v[198:201], v[16:19]
	v_mfma_f32_16x16x32_bf16 v[4:7], v[164:167], v[206:209], v[4:7]
	v_mfma_f32_16x16x32_bf16 v[0:3], v[172:175], v[206:209], v[0:3]
	s_barrier
	s_branch .Lpeel_mid_43312
; #define PG8_STAGE(bufoff, gbase, voff, p64) do { _Pragma("unroll") for (int _i = 0; _i < 2; ++_i) { \
;         const char* _gb = (const char*)(gbase) + (size_t)_i * (p64); const unsigned _la = ldsbase + (unsigned)(bufoff) + (unsigned)_i * 8192u; \
;         asm volatile("s_mov_b32 m0, %0\n\ts_nop 0\n\tglobal_load_lds_dwordx4 %1, %2" :: "s"(_la), "v"(voff), "s"(_gb) : "memory"); } } while (0)
; #define PG8_LDA(dst, b, h) do { _Pragma("unroll") for (int m = 0; m < 4; ++m) _Pragma("unroll") for (int k = 0; k < 2; ++k) dst[m][k] = *(const LAS bf16x8*)(lds + PG8_SA(b, h) + aoff + m * 2048 + k * 1024); } while (0)
; #define PG8_LDB(dst, b, h) do { _Pragma("unroll") for (int n = 0; n < 2; ++n) _Pragma("unroll") for (int k = 0; k < 2; ++k) dst[n][k] = *(const LAS bf16x8*)(lds + PG8_SB(b, h) + boff + n * 2048 + k * 1024); } while (0)
; #define PG8_MMA(ai, bj, At, Bt) do { __builtin_amdgcn_s_setprio(1); _Pragma("unroll") for (int m = 0; m < 4; ++m) _Pragma("unroll") for (int n = 0; n < 2; ++n) _Pragma("unroll") for (int k = 0; k < 2; ++k) \
;         acc[ai][bj][m][n] = __builtin_amdgcn_mfma_f32_16x16x32_bf16(Bt[n][k], At[m][k], acc[ai][bj][m][n], 0, 0, 0); __builtin_amdgcn_s_setprio(0); } while (0)
; #define PG8_WAIT_V(n) asm volatile("s_waitcnt vmcnt(" #n ")" ::: "memory")
; #define PG8_BAR __builtin_amdgcn_s_barrier()
; template <class Epi, class Sched>
; __device__ __forceinline__ void gemm_phase(LAS unsigned char* lds, const Sched& S, const Epi& E) {
;     ...
;             const bool last = (t == nt - 2);
;             const char* a1 = cA + (size_t)(t + 1) * kstep;
;             const char* a2 = last ? nA : cA + (size_t)(t + 2) * kstep; const char* b2 = last ? nB : cB + (size_t)(t + 2) * kstep;
;             const char* a3 = a2 + kstep; const char* b3 = b2 + kstep;
;             const unsigned vA2 = voffA, vB2 = voffB, hA2 = hA, hB2 = hB;
;             PG8_LDB(B0, 0, 0); PG8_LDB(B1, 0, 1); PG8_SCHED; PG8_LDA(At, 0, 0); PG8_STAGE(PG8_SA(1, 1), a1 + hA, voffA, hA / 2);
;             PG8_WAIT_V(8); PG8_WAIT_L(0); PG8_BAR; PG8_MMA(0, 0, At, B0); PG8_MMA(0, 1, At, B1); PG8_BAR; PG8_SCHED;
;             PG8_LDA(At, 0, 1); PG8_STAGE(PG8_SB(0, 0), b2, vB2, hB2 / 2); PG8_STAGE(PG8_SB(0, 1), b2 + hB2, vB2, hB2 / 2); PG8_STAGE(PG8_SA(0, 0), a2, vA2, hA2 / 2);
;             PG8_WAIT_V(8); PG8_WAIT_L(0); PG8_BAR; PG8_MMA(1, 0, At, B0); PG8_MMA(1, 1, At, B1); PG8_BAR; PG8_SCHED;
.LBB0_1485:
	ds_read_b128 v[144:147], v138
	ds_read_b128 v[148:151], v138 offset:1024
	ds_read_b128 v[152:155], v138 offset:2048
	ds_read_b128 v[156:159], v138 offset:3072
	ds_read_b128 v[160:163], v139
	ds_read_b128 v[164:167], v139 offset:1024
	ds_read_b128 v[168:171], v139 offset:2048
	ds_read_b128 v[172:175], v139 offset:3072
	s_add_u32 s26, s24, 0xfffc0080
	s_addc_u32 s27, s25, -1
	s_cmp_eq_u32 s61, 12
	s_cselect_b32 s26, s20, s26
	s_cselect_b32 s27, s21, s27
	s_cselect_b32 s40, s22, s59
	s_cselect_b32 s41, s23, s60
	s_add_u32 s38, s26, 0x80
	s_addc_u32 s39, s27, 0
	ds_read_b128 v[178:181], v140
	ds_read_b128 v[182:185], v140 offset:1024
	ds_read_b128 v[186:189], v140 offset:2048
	ds_read_b128 v[190:193], v140 offset:3072
	ds_read_b128 v[194:197], v140 offset:4096
	ds_read_b128 v[198:201], v140 offset:5120
	ds_read_b128 v[202:205], v140 offset:6144
	ds_read_b128 v[206:209], v140 offset:7168
	s_mov_b32 m0, s54
	s_nop 0
	global_load_lds_dwordx4 v134, s[24:25]
	s_add_u32 s62, s24, 0x20000
	s_mov_b32 m0, s55
	s_addc_u32 s63, s25, 0
	global_load_lds_dwordx4 v134, s[62:63]
	s_waitcnt vmcnt(8) lgkmcnt(0)
	s_barrier
	v_mfma_f32_16x16x32_bf16 v[124:127], v[144:147], v[178:181], v[124:127]
	v_mfma_f32_16x16x32_bf16 v[120:123], v[152:155], v[178:181], v[120:123]
	v_mfma_f32_16x16x32_bf16 v[108:111], v[144:147], v[186:189], v[108:111]
	v_mfma_f32_16x16x32_bf16 v[104:107], v[152:155], v[186:189], v[104:107]
	v_mfma_f32_16x16x32_bf16 v[92:95], v[144:147], v[194:197], v[92:95]
	v_mfma_f32_16x16x32_bf16 v[88:91], v[152:155], v[194:197], v[88:91]
	v_mfma_f32_16x16x32_bf16 v[76:79], v[144:147], v[202:205], v[76:79]
	v_mfma_f32_16x16x32_bf16 v[72:75], v[152:155], v[202:205], v[72:75]
	v_mfma_f32_16x16x32_bf16 v[124:127], v[148:151], v[182:185], v[124:127]
	v_mfma_f32_16x16x32_bf16 v[120:123], v[156:159], v[182:185], v[120:123]
	v_mfma_f32_16x16x32_bf16 v[108:111], v[148:151], v[190:193], v[108:111]
	v_mfma_f32_16x16x32_bf16 v[104:107], v[156:159], v[190:193], v[104:107]
	v_mfma_f32_16x16x32_bf16 v[92:95], v[148:151], v[198:201], v[92:95]
	v_mfma_f32_16x16x32_bf16 v[88:91], v[156:159], v[198:201], v[88:91]
	v_mfma_f32_16x16x32_bf16 v[76:79], v[148:151], v[206:209], v[76:79]
	v_mfma_f32_16x16x32_bf16 v[72:75], v[156:159], v[206:209], v[72:75]
	v_mfma_f32_16x16x32_bf16 v[116:119], v[160:163], v[178:181], v[116:119]
	v_mfma_f32_16x16x32_bf16 v[112:115], v[168:171], v[178:181], v[112:115]
	v_mfma_f32_16x16x32_bf16 v[100:103], v[160:163], v[186:189], v[100:103]
	v_mfma_f32_16x16x32_bf16 v[96:99], v[168:171], v[186:189], v[96:99]
	v_mfma_f32_16x16x32_bf16 v[84:87], v[160:163], v[194:197], v[84:87]
	v_mfma_f32_16x16x32_bf16 v[80:83], v[168:171], v[194:197], v[80:83]
	v_mfma_f32_16x16x32_bf16 v[68:71], v[160:163], v[202:205], v[68:71]
	v_mfma_f32_16x16x32_bf16 v[64:67], v[168:171], v[202:205], v[64:67]
	v_mfma_f32_16x16x32_bf16 v[116:119], v[164:167], v[182:185], v[116:119]
	v_mfma_f32_16x16x32_bf16 v[112:115], v[172:175], v[182:185], v[112:115]
	v_mfma_f32_16x16x32_bf16 v[100:103], v[164:167], v[190:193], v[100:103]
	v_mfma_f32_16x16x32_bf16 v[96:99], v[172:175], v[190:193], v[96:99]
	v_mfma_f32_16x16x32_bf16 v[84:87], v[164:167], v[198:201], v[84:87]
	v_mfma_f32_16x16x32_bf16 v[80:83], v[172:175], v[198:201], v[80:83]
	v_mfma_f32_16x16x32_bf16 v[68:71], v[164:167], v[206:209], v[68:71]
	v_mfma_f32_16x16x32_bf16 v[64:67], v[172:175], v[206:209], v[64:67]
	s_add_i32 s61, s61, 2
	s_add_u32 s24, s24, 0x100
	s_addc_u32 s25, s25, 0
	s_add_u32 s59, s59, 0x100
	s_addc_u32 s60, s60, 0
	s_barrier
	s_add_u32 s62, s40, 0x20000
	ds_read_b128 v[178:181], v140 offset:16384
	ds_read_b128 v[182:185], v140 offset:17408
	ds_read_b128 v[186:189], v140 offset:18432
	ds_read_b128 v[190:193], v140 offset:19456
	ds_read_b128 v[194:197], v140 offset:20480
	ds_read_b128 v[198:201], v140 offset:21504
	ds_read_b128 v[202:205], v140 offset:22528
	ds_read_b128 v[206:209], v140 offset:23552
	s_mov_b32 m0, s36
	s_nop 0
	global_load_lds_dwordx4 v135, s[40:41]
	s_mov_b32 m0, s37
	s_addc_u32 s63, s41, 0
	global_load_lds_dwordx4 v135, s[62:63]
	s_add_u32 s62, s40, 0x40000
	s_mov_b32 m0, s42
	s_addc_u32 s63, s41, 0
	global_load_lds_dwordx4 v135, s[62:63]
	s_add_u32 s62, s40, 0x60000
	s_mov_b32 m0, s43
	s_addc_u32 s63, s41, 0
	global_load_lds_dwordx4 v135, s[62:63]
	s_mov_b32 m0, s34
	s_nop 0
	global_load_lds_dwordx4 v134, s[26:27]
	s_add_u32 s62, s26, 0x20000
	s_mov_b32 m0, s44
	s_addc_u32 s63, s27, 0
	global_load_lds_dwordx4 v134, s[62:63]
	s_waitcnt vmcnt(8) lgkmcnt(0)
	s_barrier
	v_mfma_f32_16x16x32_bf16 v[60:63], v[144:147], v[178:181], v[60:63]
	v_mfma_f32_16x16x32_bf16 v[56:59], v[152:155], v[178:181], v[56:59]
	v_mfma_f32_16x16x32_bf16 v[44:47], v[144:147], v[186:189], v[44:47]
	v_mfma_f32_16x16x32_bf16 v[40:43], v[152:155], v[186:189], v[40:43]
	v_mfma_f32_16x16x32_bf16 v[28:31], v[144:147], v[194:197], v[28:31]
	v_mfma_f32_16x16x32_bf16 v[24:27], v[152:155], v[194:197], v[24:27]
	v_mfma_f32_16x16x32_bf16 v[12:15], v[144:147], v[202:205], v[12:15]
	v_mfma_f32_16x16x32_bf16 v[8:11], v[152:155], v[202:205], v[8:11]
	v_mfma_f32_16x16x32_bf16 v[60:63], v[148:151], v[182:185], v[60:63]
	v_mfma_f32_16x16x32_bf16 v[56:59], v[156:159], v[182:185], v[56:59]
	v_mfma_f32_16x16x32_bf16 v[44:47], v[148:151], v[190:193], v[44:47]
	v_mfma_f32_16x16x32_bf16 v[40:43], v[156:159], v[190:193], v[40:43]
	v_mfma_f32_16x16x32_bf16 v[28:31], v[148:151], v[198:201], v[28:31]
	v_mfma_f32_16x16x32_bf16 v[24:27], v[156:159], v[198:201], v[24:27]
	v_mfma_f32_16x16x32_bf16 v[12:15], v[148:151], v[206:209], v[12:15]
	v_mfma_f32_16x16x32_bf16 v[8:11], v[156:159], v[206:209], v[8:11]
	v_mfma_f32_16x16x32_bf16 v[52:55], v[160:163], v[178:181], v[52:55]
	v_mfma_f32_16x16x32_bf16 v[48:51], v[168:171], v[178:181], v[48:51]
	v_mfma_f32_16x16x32_bf16 v[36:39], v[160:163], v[186:189], v[36:39]
	v_mfma_f32_16x16x32_bf16 v[32:35], v[168:171], v[186:189], v[32:35]
	v_mfma_f32_16x16x32_bf16 v[20:23], v[160:163], v[194:197], v[20:23]
	v_mfma_f32_16x16x32_bf16 v[16:19], v[168:171], v[194:197], v[16:19]
	v_mfma_f32_16x16x32_bf16 v[4:7], v[160:163], v[202:205], v[4:7]
	v_mfma_f32_16x16x32_bf16 v[0:3], v[168:171], v[202:205], v[0:3]
	v_mfma_f32_16x16x32_bf16 v[52:55], v[164:167], v[182:185], v[52:55]
	v_mfma_f32_16x16x32_bf16 v[48:51], v[172:175], v[182:185], v[48:51]
	v_mfma_f32_16x16x32_bf16 v[36:39], v[164:167], v[190:193], v[36:39]
	v_mfma_f32_16x16x32_bf16 v[32:35], v[172:175], v[190:193], v[32:35]
	v_mfma_f32_16x16x32_bf16 v[20:23], v[164:167], v[198:201], v[20:23]
	v_mfma_f32_16x16x32_bf16 v[16:19], v[172:175], v[198:201], v[16:19]
	v_mfma_f32_16x16x32_bf16 v[4:7], v[164:167], v[206:209], v[4:7]
	v_mfma_f32_16x16x32_bf16 v[0:3], v[172:175], v[206:209], v[0:3]
	s_barrier
; #define PG8_STAGE(bufoff, gbase, voff, p64) do { _Pragma("unroll") for (int _i = 0; _i < 2; ++_i) { \
;         const char* _gb = (const char*)(gbase) + (size_t)_i * (p64); const unsigned _la = ldsbase + (unsigned)(bufoff) + (unsigned)_i * 8192u; \
;         asm volatile("s_mov_b32 m0, %0\n\ts_nop 0\n\tglobal_load_lds_dwordx4 %1, %2" :: "s"(_la), "v"(voff), "s"(_gb) : "memory"); } } while (0)
; #define PG8_LDA(dst, b, h) do { _Pragma("unroll") for (int m = 0; m < 4; ++m) _Pragma("unroll") for (int k = 0; k < 2; ++k) dst[m][k] = *(const LAS bf16x8*)(lds + PG8_SA(b, h) + aoff + m * 2048 + k * 1024); } while (0)
; #define PG8_LDB(dst, b, h) do { _Pragma("unroll") for (int n = 0; n < 2; ++n) _Pragma("unroll") for (int k = 0; k < 2; ++k) dst[n][k] = *(const LAS bf16x8*)(lds + PG8_SB(b, h) + boff + n * 2048 + k * 1024); } while (0)
; #define PG8_MMA(ai, bj, At, Bt) do { __builtin_amdgcn_s_setprio(1); _Pragma("unroll") for (int m = 0; m < 4; ++m) _Pragma("unroll") for (int n = 0; n < 2; ++n) _Pragma("unroll") for (int k = 0; k < 2; ++k) \
;         acc[ai][bj][m][n] = __builtin_amdgcn_mfma_f32_16x16x32_bf16(Bt[n][k], At[m][k], acc[ai][bj][m][n], 0, 0, 0); __builtin_amdgcn_s_setprio(0); } while (0)
; #define PG8_WAIT_V(n) asm volatile("s_waitcnt vmcnt(" #n ")" ::: "memory")
; #define PG8_WAIT_L(n) asm volatile("s_waitcnt lgkmcnt(" #n ")" ::: "memory")
; #define PG8_BAR __builtin_amdgcn_s_barrier()
; #define PG8_SCHED __builtin_amdgcn_sched_barrier(0)
; template <class Epi, class Sched>
; __device__ __forceinline__ void gemm_phase(LAS unsigned char* lds, const Sched& S, const Epi& E) {
;     ...
;             PG8_LDB(B0, 1, 0); PG8_LDB(B1, 1, 1); PG8_SCHED; PG8_LDA(At, 1, 0); PG8_STAGE(PG8_SA(0, 1), a2 + hA2, vA2, hA2 / 2);
;             PG8_WAIT_V(8); PG8_WAIT_L(0); PG8_BAR; PG8_MMA(0, 0, At, B0); PG8_MMA(0, 1, At, B1); PG8_BAR; PG8_SCHED;
;             PG8_LDA(At, 1, 1); PG8_STAGE(PG8_SB(1, 0), b3, vB2, hB2 / 2); PG8_STAGE(PG8_SB(1, 1), b3 + hB2, vB2, hB2 / 2); PG8_STAGE(PG8_SA(1, 0), a3, vA2, hA2 / 2);
;             PG8_WAIT_V(8); PG8_WAIT_L(0); PG8_BAR; PG8_MMA(1, 0, At, B0); PG8_MMA(1, 1, At, B1); PG8_BAR; PG8_SCHED;
;         }
;         if (wr == 0) PG8_BAR;
.Lpeel_mid_43312:
	ds_read_b128 v[144:147], v141
	ds_read_b128 v[148:151], v141 offset:1024
	ds_read_b128 v[152:155], v141 offset:2048
	ds_read_b128 v[156:159], v141 offset:3072
	ds_read_b128 v[160:163], v142
	ds_read_b128 v[164:167], v142 offset:1024
	ds_read_b128 v[168:171], v142 offset:2048
	ds_read_b128 v[172:175], v142 offset:3072
	ds_read_b128 v[178:181], v140 offset:32768
	ds_read_b128 v[182:185], v140 offset:33792
	ds_read_b128 v[186:189], v140 offset:34816
	ds_read_b128 v[190:193], v140 offset:35840
	ds_read_b128 v[194:197], v140 offset:36864
	ds_read_b128 v[198:201], v140 offset:37888
	ds_read_b128 v[202:205], v140 offset:38912
	ds_read_b128 v[206:209], v140 offset:39936
	s_add_u32 s62, s26, 0x40000
	s_mov_b32 m0, s45
	s_addc_u32 s63, s27, 0
	global_load_lds_dwordx4 v134, s[62:63]
	s_add_u32 s62, s26, 0x60000
	s_mov_b32 m0, s46
	s_addc_u32 s63, s27, 0
	global_load_lds_dwordx4 v134, s[62:63]
	s_waitcnt vmcnt(8) lgkmcnt(0)
	s_barrier
	v_mfma_f32_16x16x32_bf16 v[124:127], v[144:147], v[178:181], v[124:127]
	v_mfma_f32_16x16x32_bf16 v[120:123], v[152:155], v[178:181], v[120:123]
	v_mfma_f32_16x16x32_bf16 v[108:111], v[144:147], v[186:189], v[108:111]
	v_mfma_f32_16x16x32_bf16 v[104:107], v[152:155], v[186:189], v[104:107]
	v_mfma_f32_16x16x32_bf16 v[92:95], v[144:147], v[194:197], v[92:95]
	v_mfma_f32_16x16x32_bf16 v[88:91], v[152:155], v[194:197], v[88:91]
	v_mfma_f32_16x16x32_bf16 v[76:79], v[144:147], v[202:205], v[76:79]
	v_mfma_f32_16x16x32_bf16 v[72:75], v[152:155], v[202:205], v[72:75]
	v_mfma_f32_16x16x32_bf16 v[124:127], v[148:151], v[182:185], v[124:127]
	v_mfma_f32_16x16x32_bf16 v[120:123], v[156:159], v[182:185], v[120:123]
	v_mfma_f32_16x16x32_bf16 v[108:111], v[148:151], v[190:193], v[108:111]
	v_mfma_f32_16x16x32_bf16 v[104:107], v[156:159], v[190:193], v[104:107]
	v_mfma_f32_16x16x32_bf16 v[92:95], v[148:151], v[198:201], v[92:95]
	v_mfma_f32_16x16x32_bf16 v[88:91], v[156:159], v[198:201], v[88:91]
	v_mfma_f32_16x16x32_bf16 v[76:79], v[148:151], v[206:209], v[76:79]
	v_mfma_f32_16x16x32_bf16 v[72:75], v[156:159], v[206:209], v[72:75]
	v_mfma_f32_16x16x32_bf16 v[116:119], v[160:163], v[178:181], v[116:119]
	v_mfma_f32_16x16x32_bf16 v[112:115], v[168:171], v[178:181], v[112:115]
	v_mfma_f32_16x16x32_bf16 v[100:103], v[160:163], v[186:189], v[100:103]
	v_mfma_f32_16x16x32_bf16 v[96:99], v[168:171], v[186:189], v[96:99]
	v_mfma_f32_16x16x32_bf16 v[84:87], v[160:163], v[194:197], v[84:87]
	v_mfma_f32_16x16x32_bf16 v[80:83], v[168:171], v[194:197], v[80:83]
	v_mfma_f32_16x16x32_bf16 v[68:71], v[160:163], v[202:205], v[68:71]
	v_mfma_f32_16x16x32_bf16 v[64:67], v[168:171], v[202:205], v[64:67]
	v_mfma_f32_16x16x32_bf16 v[116:119], v[164:167], v[182:185], v[116:119]
	v_mfma_f32_16x16x32_bf16 v[112:115], v[172:175], v[182:185], v[112:115]
	v_mfma_f32_16x16x32_bf16 v[100:103], v[164:167], v[190:193], v[100:103]
	v_mfma_f32_16x16x32_bf16 v[96:99], v[172:175], v[190:193], v[96:99]
	v_mfma_f32_16x16x32_bf16 v[84:87], v[164:167], v[198:201], v[84:87]
	v_mfma_f32_16x16x32_bf16 v[80:83], v[172:175], v[198:201], v[80:83]
	v_mfma_f32_16x16x32_bf16 v[68:71], v[164:167], v[206:209], v[68:71]
	v_mfma_f32_16x16x32_bf16 v[64:67], v[172:175], v[206:209], v[64:67]
	s_barrier
	s_add_u32 s62, s40, 0x80
	s_addc_u32 s63, s41, 0
	ds_read_b128 v[178:181], v140 offset:49152
	ds_read_b128 v[182:185], v140 offset:50176
	ds_read_b128 v[186:189], v140 offset:51200
	ds_read_b128 v[190:193], v140 offset:52224
	ds_read_b128 v[194:197], v140 offset:53248
	ds_read_b128 v[198:201], v140 offset:54272
	ds_read_b128 v[202:205], v140 offset:55296
	ds_read_b128 v[206:209], v140 offset:56320
	s_mov_b32 m0, s48
	s_nop 0
	global_load_lds_dwordx4 v135, s[62:63]
	s_add_u32 s62, s40, 0x20080
	s_mov_b32 m0, s49
	s_addc_u32 s63, s41, 0
	global_load_lds_dwordx4 v135, s[62:63]
	s_add_u32 s62, s40, 0x40080
	s_mov_b32 m0, s52
	s_addc_u32 s63, s41, 0
	global_load_lds_dwordx4 v135, s[62:63]
	s_add_u32 s40, s40, 0x60080
	s_mov_b32 m0, s53
	s_addc_u32 s41, s41, 0
	global_load_lds_dwordx4 v135, s[40:41]
	s_mov_b32 m0, s50
	s_nop 0
	global_load_lds_dwordx4 v134, s[38:39]
	s_add_u32 s26, s26, 0x20080
	s_mov_b32 m0, s51
	s_addc_u32 s27, s27, 0
	global_load_lds_dwordx4 v134, s[26:27]
	s_waitcnt vmcnt(8) lgkmcnt(0)
	s_barrier
	v_mfma_f32_16x16x32_bf16 v[60:63], v[144:147], v[178:181], v[60:63]
	v_mfma_f32_16x16x32_bf16 v[56:59], v[152:155], v[178:181], v[56:59]
	v_mfma_f32_16x16x32_bf16 v[44:47], v[144:147], v[186:189], v[44:47]
	v_mfma_f32_16x16x32_bf16 v[40:43], v[152:155], v[186:189], v[40:43]
	v_mfma_f32_16x16x32_bf16 v[28:31], v[144:147], v[194:197], v[28:31]
	v_mfma_f32_16x16x32_bf16 v[24:27], v[152:155], v[194:197], v[24:27]
	v_mfma_f32_16x16x32_bf16 v[12:15], v[144:147], v[202:205], v[12:15]
	v_mfma_f32_16x16x32_bf16 v[8:11], v[152:155], v[202:205], v[8:11]
	v_mfma_f32_16x16x32_bf16 v[60:63], v[148:151], v[182:185], v[60:63]
	v_mfma_f32_16x16x32_bf16 v[56:59], v[156:159], v[182:185], v[56:59]
	v_mfma_f32_16x16x32_bf16 v[44:47], v[148:151], v[190:193], v[44:47]
	v_mfma_f32_16x16x32_bf16 v[40:43], v[156:159], v[190:193], v[40:43]
	v_mfma_f32_16x16x32_bf16 v[28:31], v[148:151], v[198:201], v[28:31]
	v_mfma_f32_16x16x32_bf16 v[24:27], v[156:159], v[198:201], v[24:27]
	v_mfma_f32_16x16x32_bf16 v[12:15], v[148:151], v[206:209], v[12:15]
	v_mfma_f32_16x16x32_bf16 v[8:11], v[156:159], v[206:209], v[8:11]
	v_mfma_f32_16x16x32_bf16 v[52:55], v[160:163], v[178:181], v[52:55]
	v_mfma_f32_16x16x32_bf16 v[48:51], v[168:171], v[178:181], v[48:51]
	v_mfma_f32_16x16x32_bf16 v[36:39], v[160:163], v[186:189], v[36:39]
	v_mfma_f32_16x16x32_bf16 v[32:35], v[168:171], v[186:189], v[32:35]
	v_mfma_f32_16x16x32_bf16 v[20:23], v[160:163], v[194:197], v[20:23]
	v_mfma_f32_16x16x32_bf16 v[16:19], v[168:171], v[194:197], v[16:19]
	v_mfma_f32_16x16x32_bf16 v[4:7], v[160:163], v[202:205], v[4:7]
	v_mfma_f32_16x16x32_bf16 v[0:3], v[168:171], v[202:205], v[0:3]
	v_mfma_f32_16x16x32_bf16 v[52:55], v[164:167], v[182:185], v[52:55]
	v_mfma_f32_16x16x32_bf16 v[48:51], v[172:175], v[182:185], v[48:51]
	v_mfma_f32_16x16x32_bf16 v[36:39], v[164:167], v[190:193], v[36:39]
	v_mfma_f32_16x16x32_bf16 v[32:35], v[172:175], v[190:193], v[32:35]
	v_mfma_f32_16x16x32_bf16 v[20:23], v[164:167], v[198:201], v[20:23]
	v_mfma_f32_16x16x32_bf16 v[16:19], v[172:175], v[198:201], v[16:19]
	v_mfma_f32_16x16x32_bf16 v[4:7], v[164:167], v[206:209], v[4:7]
	v_mfma_f32_16x16x32_bf16 v[0:3], v[172:175], v[206:209], v[0:3]
	s_barrier
	s_cmp_gt_u32 s61, 13
	s_cbranch_scc0 .LBB0_1485
	s_and_b64 vcc, exec, s[14:15]
	s_cbranch_vccz .LBB0_1488
	s_barrier

; #define PG8_STAGE(bufoff, gbase, voff, p64) do { _Pragma("unroll") for (int _i = 0; _i < 2; ++_i) { \
;         const char* _gb = (const char*)(gbase) + (size_t)_i * (p64); const unsigned _la = ldsbase + (unsigned)(bufoff) + (unsigned)_i * 8192u; \
;         asm volatile("s_mov_b32 m0, %0\n\ts_nop 0\n\tglobal_load_lds_dwordx4 %1, %2" :: "s"(_la), "v"(voff), "s"(_gb) : "memory"); } } while (0)
; #define PG8_LDA(dst, b, h) do { _Pragma("unroll") for (int m = 0; m < 4; ++m) _Pragma("unroll") for (int k = 0; k < 2; ++k) dst[m][k] = *(const LAS bf16x8*)(lds + PG8_SA(b, h) + aoff + m * 2048 + k * 1024); } while (0)
; #define PG8_LDB(dst, b, h) do { _Pragma("unroll") for (int n = 0; n < 2; ++n) _Pragma("unroll") for (int k = 0; k < 2; ++k) dst[n][k] = *(const LAS bf16x8*)(lds + PG8_SB(b, h) + boff + n * 2048 + k * 1024); } while (0)
; #define PG8_MMA(ai, bj, At, Bt) do { __builtin_amdgcn_s_setprio(1); _Pragma("unroll") for (int m = 0; m < 4; ++m) _Pragma("unroll") for (int n = 0; n < 2; ++n) _Pragma("unroll") for (int k = 0; k < 2; ++k) \
;         acc[ai][bj][m][n] = __builtin_amdgcn_mfma_f32_16x16x32_bf16(Bt[n][k], At[m][k], acc[ai][bj][m][n], 0, 0, 0); __builtin_amdgcn_s_setprio(0); } while (0)
; #define PG8_WAIT_V(n) asm volatile("s_waitcnt vmcnt(" #n ")" ::: "memory")
; template <class Epi, class Sched>
; __device__ __forceinline__ void gemm_phase(LAS unsigned char* lds, const Sched& S, const Epi& E) {
;     ...
;         for (int t = 0; t < nt; t += 2) {
;             const bool last = (t == nt - 2);
;             const char* a1 = cA + (size_t)(t + 1) * kstep;
;             const char* a2 = last ? nA : cA + (size_t)(t + 2) * kstep; const char* b2 = last ? nB : cB + (size_t)(t + 2) * kstep;
;             const char* a3 = a2 + kstep; const char* b3 = b2 + kstep;
;             const unsigned vA2 = voffA, vB2 = voffB, hA2 = hA, hB2 = hB;
;             PG8_LDB(B0, 0, 0); PG8_LDB(B1, 0, 1); PG8_SCHED; PG8_LDA(At, 0, 0); PG8_STAGE(PG8_SA(1, 1), a1 + hA, voffA, hA / 2);
;             PG8_WAIT_V(8); PG8_WAIT_L(0); PG8_BAR; PG8_MMA(0, 0, At, B0); PG8_MMA(0, 1, At, B1); PG8_BAR; PG8_SCHED;
;             PG8_LDA(At, 0, 1); PG8_STAGE(PG8_SB(0, 0), b2, vB2, hB2 / 2); PG8_STAGE(PG8_SB(0, 1), b2 + hB2, vB2, hB2 / 2); PG8_STAGE(PG8_SA(0, 0), a2, vA2, hA2 / 2);
;             PG8_WAIT_V(8); PG8_WAIT_L(0); PG8_BAR; PG8_MMA(1, 0, At, B0); PG8_MMA(1, 1, At, B1); PG8_BAR; PG8_SCHED;
.LBB0_1558:
	s_add_u32 s22, s22, 0xb0080
	s_addc_u32 s23, s23, 0
	s_add_u32 s59, s24, 0x100
	s_addc_u32 s60, s25, 0
	s_mov_b32 s61, -2
	s_waitcnt vmcnt(7)
	s_waitcnt vmcnt(6)
	s_waitcnt vmcnt(3)
	s_waitcnt vmcnt(2)
	s_waitcnt vmcnt(1)
	s_waitcnt vmcnt(0)
	ds_read_b128 v[128:131], v179
	ds_read_b128 v[132:135], v179 offset:1024
	ds_read_b128 v[136:139], v179 offset:2048
	ds_read_b128 v[140:143], v179 offset:3072
	ds_read_b128 v[150:153], v180
	ds_read_b128 v[154:157], v180 offset:1024
	ds_read_b128 v[158:161], v180 offset:2048
	ds_read_b128 v[162:165], v180 offset:3072
	s_add_u32 s24, s22, 0xfff50080
	s_addc_u32 s25, s23, -1
	s_cmp_eq_u32 s61, 40
	s_cselect_b32 s24, s18, s24
	s_cselect_b32 s25, s19, s25
	s_cselect_b32 s38, s20, s59
	s_cselect_b32 s39, s21, s60
	s_add_u32 s26, s24, 0x80
	s_addc_u32 s27, s25, 0
	ds_read_b128 v[166:169], v181
	ds_read_b128 v[170:173], v181 offset:1024
	ds_read_b128 v[184:187], v181 offset:2048
	ds_read_b128 v[188:191], v181 offset:3072
	ds_read_b128 v[192:195], v181 offset:4096
	ds_read_b128 v[196:199], v181 offset:5120
	ds_read_b128 v[200:203], v181 offset:6144
	ds_read_b128 v[204:207], v181 offset:7168
	s_mov_b32 m0, s54
	s_nop 0
	global_load_lds_dwordx4 v144, s[22:23]
	s_add_u32 s62, s22, 0x58000
	s_mov_b32 m0, s55
	s_addc_u32 s63, s23, 0
	global_load_lds_dwordx4 v144, s[62:63]
	s_waitcnt vmcnt(8) lgkmcnt(0)
	s_barrier
	v_mfma_f32_16x16x32_bf16 v[124:127], v[128:131], v[166:169], 0
	v_mfma_f32_16x16x32_bf16 v[120:123], v[136:139], v[166:169], 0
	v_mfma_f32_16x16x32_bf16 v[116:119], v[128:131], v[184:187], 0
	v_mfma_f32_16x16x32_bf16 v[112:115], v[136:139], v[184:187], 0
	v_mfma_f32_16x16x32_bf16 v[108:111], v[128:131], v[192:195], 0
	v_mfma_f32_16x16x32_bf16 v[104:107], v[136:139], v[192:195], 0
	v_mfma_f32_16x16x32_bf16 v[100:103], v[128:131], v[200:203], 0
	v_mfma_f32_16x16x32_bf16 v[96:99], v[136:139], v[200:203], 0
	v_mfma_f32_16x16x32_bf16 v[124:127], v[132:135], v[170:173], v[124:127]
	v_mfma_f32_16x16x32_bf16 v[120:123], v[140:143], v[170:173], v[120:123]
	v_mfma_f32_16x16x32_bf16 v[116:119], v[132:135], v[188:191], v[116:119]
	v_mfma_f32_16x16x32_bf16 v[112:115], v[140:143], v[188:191], v[112:115]
	v_mfma_f32_16x16x32_bf16 v[108:111], v[132:135], v[196:199], v[108:111]
	v_mfma_f32_16x16x32_bf16 v[104:107], v[140:143], v[196:199], v[104:107]
	v_mfma_f32_16x16x32_bf16 v[100:103], v[132:135], v[204:207], v[100:103]
	v_mfma_f32_16x16x32_bf16 v[96:99], v[140:143], v[204:207], v[96:99]
	v_mfma_f32_16x16x32_bf16 v[60:63], v[150:153], v[166:169], 0
	v_mfma_f32_16x16x32_bf16 v[56:59], v[158:161], v[166:169], 0
	v_mfma_f32_16x16x32_bf16 v[52:55], v[150:153], v[184:187], 0
	v_mfma_f32_16x16x32_bf16 v[48:51], v[158:161], v[184:187], 0
	v_mfma_f32_16x16x32_bf16 v[44:47], v[150:153], v[192:195], 0
	v_mfma_f32_16x16x32_bf16 v[40:43], v[158:161], v[192:195], 0
	v_mfma_f32_16x16x32_bf16 v[36:39], v[150:153], v[200:203], 0
	v_mfma_f32_16x16x32_bf16 v[32:35], v[158:161], v[200:203], 0
	v_mfma_f32_16x16x32_bf16 v[60:63], v[154:157], v[170:173], v[60:63]
	v_mfma_f32_16x16x32_bf16 v[56:59], v[162:165], v[170:173], v[56:59]
	v_mfma_f32_16x16x32_bf16 v[52:55], v[154:157], v[188:191], v[52:55]
	v_mfma_f32_16x16x32_bf16 v[48:51], v[162:165], v[188:191], v[48:51]
	v_mfma_f32_16x16x32_bf16 v[44:47], v[154:157], v[196:199], v[44:47]
	v_mfma_f32_16x16x32_bf16 v[40:43], v[162:165], v[196:199], v[40:43]
	v_mfma_f32_16x16x32_bf16 v[36:39], v[154:157], v[204:207], v[36:39]
	v_mfma_f32_16x16x32_bf16 v[32:35], v[162:165], v[204:207], v[32:35]
	s_add_i32 s61, s61, 2
	s_add_u32 s22, s22, 0x100
	s_addc_u32 s23, s23, 0
	s_add_u32 s59, s59, 0x100
	s_addc_u32 s60, s60, 0
	s_barrier
	s_add_u32 s62, s38, 0x58000
	ds_read_b128 v[166:169], v181 offset:16384
	ds_read_b128 v[170:173], v181 offset:17408
	ds_read_b128 v[184:187], v181 offset:18432
	ds_read_b128 v[188:191], v181 offset:19456
	ds_read_b128 v[192:195], v181 offset:20480
	ds_read_b128 v[196:199], v181 offset:21504
	ds_read_b128 v[200:203], v181 offset:22528
	ds_read_b128 v[204:207], v181 offset:23552
	s_mov_b32 m0, s35
	s_nop 0
	global_load_lds_dwordx4 v145, s[38:39]
	s_mov_b32 m0, s36
	s_addc_u32 s63, s39, 0
	global_load_lds_dwordx4 v145, s[62:63]
	s_add_u32 s62, s38, 0xb0000
	s_mov_b32 m0, s37
	s_addc_u32 s63, s39, 0
	global_load_lds_dwordx4 v145, s[62:63]
	s_add_u32 s62, s38, 0x108000
	s_mov_b32 m0, s40
	s_addc_u32 s63, s39, 0
	global_load_lds_dwordx4 v145, s[62:63]
	s_mov_b32 m0, s34
	s_nop 0
	global_load_lds_dwordx4 v144, s[24:25]
	s_add_u32 s62, s24, 0x58000
	s_mov_b32 m0, s41
	s_addc_u32 s63, s25, 0
	global_load_lds_dwordx4 v144, s[62:63]
	s_waitcnt vmcnt(8) lgkmcnt(0)
	s_barrier
	v_mfma_f32_16x16x32_bf16 v[92:95], v[128:131], v[166:169], 0
	v_mfma_f32_16x16x32_bf16 v[88:91], v[136:139], v[166:169], 0
	v_mfma_f32_16x16x32_bf16 v[84:87], v[128:131], v[184:187], 0
	v_mfma_f32_16x16x32_bf16 v[80:83], v[136:139], v[184:187], 0
	v_mfma_f32_16x16x32_bf16 v[76:79], v[128:131], v[192:195], 0
	v_mfma_f32_16x16x32_bf16 v[72:75], v[136:139], v[192:195], 0
	v_mfma_f32_16x16x32_bf16 v[68:71], v[128:131], v[200:203], 0
	v_mfma_f32_16x16x32_bf16 v[64:67], v[136:139], v[200:203], 0
	v_mfma_f32_16x16x32_bf16 v[92:95], v[132:135], v[170:173], v[92:95]
	v_mfma_f32_16x16x32_bf16 v[88:91], v[140:143], v[170:173], v[88:91]
	v_mfma_f32_16x16x32_bf16 v[84:87], v[132:135], v[188:191], v[84:87]
	v_mfma_f32_16x16x32_bf16 v[80:83], v[140:143], v[188:191], v[80:83]
	v_mfma_f32_16x16x32_bf16 v[76:79], v[132:135], v[196:199], v[76:79]
	v_mfma_f32_16x16x32_bf16 v[72:75], v[140:143], v[196:199], v[72:75]
	v_mfma_f32_16x16x32_bf16 v[68:71], v[132:135], v[204:207], v[68:71]
	v_mfma_f32_16x16x32_bf16 v[64:67], v[140:143], v[204:207], v[64:67]
	v_mfma_f32_16x16x32_bf16 v[28:31], v[150:153], v[166:169], 0
	v_mfma_f32_16x16x32_bf16 v[24:27], v[158:161], v[166:169], 0
	v_mfma_f32_16x16x32_bf16 v[20:23], v[150:153], v[184:187], 0
	v_mfma_f32_16x16x32_bf16 v[16:19], v[158:161], v[184:187], 0
	v_mfma_f32_16x16x32_bf16 v[12:15], v[150:153], v[192:195], 0
	v_mfma_f32_16x16x32_bf16 v[8:11], v[158:161], v[192:195], 0
	v_mfma_f32_16x16x32_bf16 v[4:7], v[150:153], v[200:203], 0
	v_mfma_f32_16x16x32_bf16 v[0:3], v[158:161], v[200:203], 0
	v_mfma_f32_16x16x32_bf16 v[28:31], v[154:157], v[170:173], v[28:31]
	v_mfma_f32_16x16x32_bf16 v[24:27], v[162:165], v[170:173], v[24:27]
	v_mfma_f32_16x16x32_bf16 v[20:23], v[154:157], v[188:191], v[20:23]
	v_mfma_f32_16x16x32_bf16 v[16:19], v[162:165], v[188:191], v[16:19]
	v_mfma_f32_16x16x32_bf16 v[12:15], v[154:157], v[196:199], v[12:15]
	v_mfma_f32_16x16x32_bf16 v[8:11], v[162:165], v[196:199], v[8:11]
	v_mfma_f32_16x16x32_bf16 v[4:7], v[154:157], v[204:207], v[4:7]
	v_mfma_f32_16x16x32_bf16 v[0:3], v[162:165], v[204:207], v[0:3]
	s_barrier
	s_branch .Lpeel_mid_45164
; #define PG8_STAGE(bufoff, gbase, voff, p64) do { _Pragma("unroll") for (int _i = 0; _i < 2; ++_i) { \
;         const char* _gb = (const char*)(gbase) + (size_t)_i * (p64); const unsigned _la = ldsbase + (unsigned)(bufoff) + (unsigned)_i * 8192u; \
;         asm volatile("s_mov_b32 m0, %0\n\ts_nop 0\n\tglobal_load_lds_dwordx4 %1, %2" :: "s"(_la), "v"(voff), "s"(_gb) : "memory"); } } while (0)
; #define PG8_LDA(dst, b, h) do { _Pragma("unroll") for (int m = 0; m < 4; ++m) _Pragma("unroll") for (int k = 0; k < 2; ++k) dst[m][k] = *(const LAS bf16x8*)(lds + PG8_SA(b, h) + aoff + m * 2048 + k * 1024); } while (0)
; #define PG8_LDB(dst, b, h) do { _Pragma("unroll") for (int n = 0; n < 2; ++n) _Pragma("unroll") for (int k = 0; k < 2; ++k) dst[n][k] = *(const LAS bf16x8*)(lds + PG8_SB(b, h) + boff + n * 2048 + k * 1024); } while (0)
; #define PG8_MMA(ai, bj, At, Bt) do { __builtin_amdgcn_s_setprio(1); _Pragma("unroll") for (int m = 0; m < 4; ++m) _Pragma("unroll") for (int n = 0; n < 2; ++n) _Pragma("unroll") for (int k = 0; k < 2; ++k) \
;         acc[ai][bj][m][n] = __builtin_amdgcn_mfma_f32_16x16x32_bf16(Bt[n][k], At[m][k], acc[ai][bj][m][n], 0, 0, 0); __builtin_amdgcn_s_setprio(0); } while (0)
; #define PG8_WAIT_V(n) asm volatile("s_waitcnt vmcnt(" #n ")" ::: "memory")
; template <class Epi, class Sched>
; __device__ __forceinline__ void gemm_phase(LAS unsigned char* lds, const Sched& S, const Epi& E) {
;     ...
;         for (int t = 0; t < nt; t += 2) {
;             const bool last = (t == nt - 2);
;             const char* a1 = cA + (size_t)(t + 1) * kstep;
;             const char* a2 = last ? nA : cA + (size_t)(t + 2) * kstep; const char* b2 = last ? nB : cB + (size_t)(t + 2) * kstep;
;             const char* a3 = a2 + kstep; const char* b3 = b2 + kstep;
;             const unsigned vA2 = voffA, vB2 = voffB, hA2 = hA, hB2 = hB;
;             PG8_LDB(B0, 0, 0); PG8_LDB(B1, 0, 1); PG8_SCHED; PG8_LDA(At, 0, 0); PG8_STAGE(PG8_SA(1, 1), a1 + hA, voffA, hA / 2);
;             PG8_WAIT_V(8); PG8_WAIT_L(0); PG8_BAR; PG8_MMA(0, 0, At, B0); PG8_MMA(0, 1, At, B1); PG8_BAR; PG8_SCHED;
;             PG8_LDA(At, 0, 1); PG8_STAGE(PG8_SB(0, 0), b2, vB2, hB2 / 2); PG8_STAGE(PG8_SB(0, 1), b2 + hB2, vB2, hB2 / 2); PG8_STAGE(PG8_SA(0, 0), a2, vA2, hA2 / 2);
;             PG8_WAIT_V(8); PG8_WAIT_L(0); PG8_BAR; PG8_MMA(1, 0, At, B0); PG8_MMA(1, 1, At, B1); PG8_BAR; PG8_SCHED;
.LBB0_1559:
	ds_read_b128 v[128:131], v179
	ds_read_b128 v[132:135], v179 offset:1024
	ds_read_b128 v[136:139], v179 offset:2048
	ds_read_b128 v[140:143], v179 offset:3072
	ds_read_b128 v[150:153], v180
	ds_read_b128 v[154:157], v180 offset:1024
	ds_read_b128 v[158:161], v180 offset:2048
	ds_read_b128 v[162:165], v180 offset:3072
	s_add_u32 s24, s22, 0xfff50080
	s_addc_u32 s25, s23, -1
	s_cmp_eq_u32 s61, 40
	s_cselect_b32 s24, s18, s24
	s_cselect_b32 s25, s19, s25
	s_cselect_b32 s38, s20, s59
	s_cselect_b32 s39, s21, s60
	s_add_u32 s26, s24, 0x80
	s_addc_u32 s27, s25, 0
	ds_read_b128 v[166:169], v181
	ds_read_b128 v[170:173], v181 offset:1024
	ds_read_b128 v[184:187], v181 offset:2048
	ds_read_b128 v[188:191], v181 offset:3072
	ds_read_b128 v[192:195], v181 offset:4096
	ds_read_b128 v[196:199], v181 offset:5120
	ds_read_b128 v[200:203], v181 offset:6144
	ds_read_b128 v[204:207], v181 offset:7168
	s_mov_b32 m0, s54
	s_nop 0
	global_load_lds_dwordx4 v144, s[22:23]
	s_add_u32 s62, s22, 0x58000
	s_mov_b32 m0, s55
	s_addc_u32 s63, s23, 0
	global_load_lds_dwordx4 v144, s[62:63]
	s_waitcnt vmcnt(8) lgkmcnt(0)
	s_barrier
	v_mfma_f32_16x16x32_bf16 v[124:127], v[128:131], v[166:169], v[124:127]
	v_mfma_f32_16x16x32_bf16 v[120:123], v[136:139], v[166:169], v[120:123]
	v_mfma_f32_16x16x32_bf16 v[116:119], v[128:131], v[184:187], v[116:119]
	v_mfma_f32_16x16x32_bf16 v[112:115], v[136:139], v[184:187], v[112:115]
	v_mfma_f32_16x16x32_bf16 v[108:111], v[128:131], v[192:195], v[108:111]
	v_mfma_f32_16x16x32_bf16 v[104:107], v[136:139], v[192:195], v[104:107]
	v_mfma_f32_16x16x32_bf16 v[100:103], v[128:131], v[200:203], v[100:103]
	v_mfma_f32_16x16x32_bf16 v[96:99], v[136:139], v[200:203], v[96:99]
	v_mfma_f32_16x16x32_bf16 v[124:127], v[132:135], v[170:173], v[124:127]
	v_mfma_f32_16x16x32_bf16 v[120:123], v[140:143], v[170:173], v[120:123]
	v_mfma_f32_16x16x32_bf16 v[116:119], v[132:135], v[188:191], v[116:119]
	v_mfma_f32_16x16x32_bf16 v[112:115], v[140:143], v[188:191], v[112:115]
	v_mfma_f32_16x16x32_bf16 v[108:111], v[132:135], v[196:199], v[108:111]
	v_mfma_f32_16x16x32_bf16 v[104:107], v[140:143], v[196:199], v[104:107]
	v_mfma_f32_16x16x32_bf16 v[100:103], v[132:135], v[204:207], v[100:103]
	v_mfma_f32_16x16x32_bf16 v[96:99], v[140:143], v[204:207], v[96:99]
	v_mfma_f32_16x16x32_bf16 v[60:63], v[150:153], v[166:169], v[60:63]
	v_mfma_f32_16x16x32_bf16 v[56:59], v[158:161], v[166:169], v[56:59]
	v_mfma_f32_16x16x32_bf16 v[52:55], v[150:153], v[184:187], v[52:55]
	v_mfma_f32_16x16x32_bf16 v[48:51], v[158:161], v[184:187], v[48:51]
	v_mfma_f32_16x16x32_bf16 v[44:47], v[150:153], v[192:195], v[44:47]
	v_mfma_f32_16x16x32_bf16 v[40:43], v[158:161], v[192:195], v[40:43]
	v_mfma_f32_16x16x32_bf16 v[36:39], v[150:153], v[200:203], v[36:39]
	v_mfma_f32_16x16x32_bf16 v[32:35], v[158:161], v[200:203], v[32:35]
	v_mfma_f32_16x16x32_bf16 v[60:63], v[154:157], v[170:173], v[60:63]
	v_mfma_f32_16x16x32_bf16 v[56:59], v[162:165], v[170:173], v[56:59]
	v_mfma_f32_16x16x32_bf16 v[52:55], v[154:157], v[188:191], v[52:55]
	v_mfma_f32_16x16x32_bf16 v[48:51], v[162:165], v[188:191], v[48:51]
	v_mfma_f32_16x16x32_bf16 v[44:47], v[154:157], v[196:199], v[44:47]
	v_mfma_f32_16x16x32_bf16 v[40:43], v[162:165], v[196:199], v[40:43]
	v_mfma_f32_16x16x32_bf16 v[36:39], v[154:157], v[204:207], v[36:39]
	v_mfma_f32_16x16x32_bf16 v[32:35], v[162:165], v[204:207], v[32:35]
	s_add_i32 s61, s61, 2
	s_add_u32 s22, s22, 0x100
	s_addc_u32 s23, s23, 0
	s_add_u32 s59, s59, 0x100
	s_addc_u32 s60, s60, 0
	s_barrier
	s_add_u32 s62, s38, 0x58000
	ds_read_b128 v[166:169], v181 offset:16384
	ds_read_b128 v[170:173], v181 offset:17408
	ds_read_b128 v[184:187], v181 offset:18432
	ds_read_b128 v[188:191], v181 offset:19456
	ds_read_b128 v[192:195], v181 offset:20480
	ds_read_b128 v[196:199], v181 offset:21504
	ds_read_b128 v[200:203], v181 offset:22528
	ds_read_b128 v[204:207], v181 offset:23552
	s_mov_b32 m0, s35
	s_nop 0
	global_load_lds_dwordx4 v145, s[38:39]
	s_mov_b32 m0, s36
	s_addc_u32 s63, s39, 0
	global_load_lds_dwordx4 v145, s[62:63]
	s_add_u32 s62, s38, 0xb0000
	s_mov_b32 m0, s37
	s_addc_u32 s63, s39, 0
	global_load_lds_dwordx4 v145, s[62:63]
	s_add_u32 s62, s38, 0x108000
	s_mov_b32 m0, s40
	s_addc_u32 s63, s39, 0
	global_load_lds_dwordx4 v145, s[62:63]
	s_mov_b32 m0, s34
	s_nop 0
	global_load_lds_dwordx4 v144, s[24:25]
	s_add_u32 s62, s24, 0x58000
	s_mov_b32 m0, s41
	s_addc_u32 s63, s25, 0
	global_load_lds_dwordx4 v144, s[62:63]
	s_waitcnt vmcnt(8) lgkmcnt(0)
	s_barrier
	v_mfma_f32_16x16x32_bf16 v[92:95], v[128:131], v[166:169], v[92:95]
	v_mfma_f32_16x16x32_bf16 v[88:91], v[136:139], v[166:169], v[88:91]
	v_mfma_f32_16x16x32_bf16 v[84:87], v[128:131], v[184:187], v[84:87]
	v_mfma_f32_16x16x32_bf16 v[80:83], v[136:139], v[184:187], v[80:83]
	v_mfma_f32_16x16x32_bf16 v[76:79], v[128:131], v[192:195], v[76:79]
	v_mfma_f32_16x16x32_bf16 v[72:75], v[136:139], v[192:195], v[72:75]
	v_mfma_f32_16x16x32_bf16 v[68:71], v[128:131], v[200:203], v[68:71]
	v_mfma_f32_16x16x32_bf16 v[64:67], v[136:139], v[200:203], v[64:67]
	v_mfma_f32_16x16x32_bf16 v[92:95], v[132:135], v[170:173], v[92:95]
	v_mfma_f32_16x16x32_bf16 v[88:91], v[140:143], v[170:173], v[88:91]
	v_mfma_f32_16x16x32_bf16 v[84:87], v[132:135], v[188:191], v[84:87]
	v_mfma_f32_16x16x32_bf16 v[80:83], v[140:143], v[188:191], v[80:83]
	v_mfma_f32_16x16x32_bf16 v[76:79], v[132:135], v[196:199], v[76:79]
	v_mfma_f32_16x16x32_bf16 v[72:75], v[140:143], v[196:199], v[72:75]
	v_mfma_f32_16x16x32_bf16 v[68:71], v[132:135], v[204:207], v[68:71]
	v_mfma_f32_16x16x32_bf16 v[64:67], v[140:143], v[204:207], v[64:67]
	v_mfma_f32_16x16x32_bf16 v[28:31], v[150:153], v[166:169], v[28:31]
	v_mfma_f32_16x16x32_bf16 v[24:27], v[158:161], v[166:169], v[24:27]
	v_mfma_f32_16x16x32_bf16 v[20:23], v[150:153], v[184:187], v[20:23]
	v_mfma_f32_16x16x32_bf16 v[16:19], v[158:161], v[184:187], v[16:19]
	v_mfma_f32_16x16x32_bf16 v[12:15], v[150:153], v[192:195], v[12:15]
	v_mfma_f32_16x16x32_bf16 v[8:11], v[158:161], v[192:195], v[8:11]
	v_mfma_f32_16x16x32_bf16 v[4:7], v[150:153], v[200:203], v[4:7]
	v_mfma_f32_16x16x32_bf16 v[0:3], v[158:161], v[200:203], v[0:3]
	v_mfma_f32_16x16x32_bf16 v[28:31], v[154:157], v[170:173], v[28:31]
	v_mfma_f32_16x16x32_bf16 v[24:27], v[162:165], v[170:173], v[24:27]
	v_mfma_f32_16x16x32_bf16 v[20:23], v[154:157], v[188:191], v[20:23]
	v_mfma_f32_16x16x32_bf16 v[16:19], v[162:165], v[188:191], v[16:19]
	v_mfma_f32_16x16x32_bf16 v[12:15], v[154:157], v[196:199], v[12:15]
	v_mfma_f32_16x16x32_bf16 v[8:11], v[162:165], v[196:199], v[8:11]
	v_mfma_f32_16x16x32_bf16 v[4:7], v[154:157], v[204:207], v[4:7]
	v_mfma_f32_16x16x32_bf16 v[0:3], v[162:165], v[204:207], v[0:3]
	s_barrier
; #define PG8_STAGE(bufoff, gbase, voff, p64) do { _Pragma("unroll") for (int _i = 0; _i < 2; ++_i) { \
;         const char* _gb = (const char*)(gbase) + (size_t)_i * (p64); const unsigned _la = ldsbase + (unsigned)(bufoff) + (unsigned)_i * 8192u; \
;         asm volatile("s_mov_b32 m0, %0\n\ts_nop 0\n\tglobal_load_lds_dwordx4 %1, %2" :: "s"(_la), "v"(voff), "s"(_gb) : "memory"); } } while (0)
; #define PG8_LDA(dst, b, h) do { _Pragma("unroll") for (int m = 0; m < 4; ++m) _Pragma("unroll") for (int k = 0; k < 2; ++k) dst[m][k] = *(const LAS bf16x8*)(lds + PG8_SA(b, h) + aoff + m * 2048 + k * 1024); } while (0)
; #define PG8_LDB(dst, b, h) do { _Pragma("unroll") for (int n = 0; n < 2; ++n) _Pragma("unroll") for (int k = 0; k < 2; ++k) dst[n][k] = *(const LAS bf16x8*)(lds + PG8_SB(b, h) + boff + n * 2048 + k * 1024); } while (0)
; #define PG8_MMA(ai, bj, At, Bt) do { __builtin_amdgcn_s_setprio(1); _Pragma("unroll") for (int m = 0; m < 4; ++m) _Pragma("unroll") for (int n = 0; n < 2; ++n) _Pragma("unroll") for (int k = 0; k < 2; ++k) \
;         acc[ai][bj][m][n] = __builtin_amdgcn_mfma_f32_16x16x32_bf16(Bt[n][k], At[m][k], acc[ai][bj][m][n], 0, 0, 0); __builtin_amdgcn_s_setprio(0); } while (0)
; #define PG8_WAIT_V(n) asm volatile("s_waitcnt vmcnt(" #n ")" ::: "memory")
; #define PG8_WAIT_L(n) asm volatile("s_waitcnt lgkmcnt(" #n ")" ::: "memory")
; #define PG8_BAR __builtin_amdgcn_s_barrier()
; #define PG8_SCHED __builtin_amdgcn_sched_barrier(0)
; template <class Epi, class Sched>
; __device__ __forceinline__ void gemm_phase(LAS unsigned char* lds, const Sched& S, const Epi& E) {
;     ...
;             PG8_LDB(B0, 1, 0); PG8_LDB(B1, 1, 1); PG8_SCHED; PG8_LDA(At, 1, 0); PG8_STAGE(PG8_SA(0, 1), a2 + hA2, vA2, hA2 / 2);
;             PG8_WAIT_V(8); PG8_WAIT_L(0); PG8_BAR; PG8_MMA(0, 0, At, B0); PG8_MMA(0, 1, At, B1); PG8_BAR; PG8_SCHED;
;             PG8_LDA(At, 1, 1); PG8_STAGE(PG8_SB(1, 0), b3, vB2, hB2 / 2); PG8_STAGE(PG8_SB(1, 1), b3 + hB2, vB2, hB2 / 2); PG8_STAGE(PG8_SA(1, 0), a3, vA2, hA2 / 2);
;             PG8_WAIT_V(8); PG8_WAIT_L(0); PG8_BAR; PG8_MMA(1, 0, At, B0); PG8_MMA(1, 1, At, B1); PG8_BAR; PG8_SCHED;
;         }
;         if (wr == 0) PG8_BAR;
.Lpeel_mid_45164:
	ds_read_b128 v[128:131], v182
	ds_read_b128 v[132:135], v182 offset:1024
	ds_read_b128 v[136:139], v182 offset:2048
	ds_read_b128 v[140:143], v182 offset:3072
	ds_read_b128 v[150:153], v183
	ds_read_b128 v[154:157], v183 offset:1024
	ds_read_b128 v[158:161], v183 offset:2048
	ds_read_b128 v[162:165], v183 offset:3072
	ds_read_b128 v[166:169], v181 offset:32768
	ds_read_b128 v[170:173], v181 offset:33792
	ds_read_b128 v[184:187], v181 offset:34816
	ds_read_b128 v[188:191], v181 offset:35840
	ds_read_b128 v[192:195], v181 offset:36864
	ds_read_b128 v[196:199], v181 offset:37888
	ds_read_b128 v[200:203], v181 offset:38912
	ds_read_b128 v[204:207], v181 offset:39936
	s_add_u32 s62, s24, 0xb0000
	s_mov_b32 m0, s42
	s_addc_u32 s63, s25, 0
	global_load_lds_dwordx4 v144, s[62:63]
	s_add_u32 s62, s24, 0x108000
	s_mov_b32 m0, s43
	s_addc_u32 s63, s25, 0
	global_load_lds_dwordx4 v144, s[62:63]
	s_waitcnt vmcnt(8) lgkmcnt(0)
	s_barrier
	v_mfma_f32_16x16x32_bf16 v[124:127], v[128:131], v[166:169], v[124:127]
	v_mfma_f32_16x16x32_bf16 v[120:123], v[136:139], v[166:169], v[120:123]
	v_mfma_f32_16x16x32_bf16 v[116:119], v[128:131], v[184:187], v[116:119]
	v_mfma_f32_16x16x32_bf16 v[112:115], v[136:139], v[184:187], v[112:115]
	v_mfma_f32_16x16x32_bf16 v[108:111], v[128:131], v[192:195], v[108:111]
	v_mfma_f32_16x16x32_bf16 v[104:107], v[136:139], v[192:195], v[104:107]
	v_mfma_f32_16x16x32_bf16 v[100:103], v[128:131], v[200:203], v[100:103]
	v_mfma_f32_16x16x32_bf16 v[96:99], v[136:139], v[200:203], v[96:99]
	v_mfma_f32_16x16x32_bf16 v[124:127], v[132:135], v[170:173], v[124:127]
	v_mfma_f32_16x16x32_bf16 v[120:123], v[140:143], v[170:173], v[120:123]
	v_mfma_f32_16x16x32_bf16 v[116:119], v[132:135], v[188:191], v[116:119]
	v_mfma_f32_16x16x32_bf16 v[112:115], v[140:143], v[188:191], v[112:115]
	v_mfma_f32_16x16x32_bf16 v[108:111], v[132:135], v[196:199], v[108:111]
	v_mfma_f32_16x16x32_bf16 v[104:107], v[140:143], v[196:199], v[104:107]
	v_mfma_f32_16x16x32_bf16 v[100:103], v[132:135], v[204:207], v[100:103]
	v_mfma_f32_16x16x32_bf16 v[96:99], v[140:143], v[204:207], v[96:99]
	v_mfma_f32_16x16x32_bf16 v[60:63], v[150:153], v[166:169], v[60:63]
	v_mfma_f32_16x16x32_bf16 v[56:59], v[158:161], v[166:169], v[56:59]
	v_mfma_f32_16x16x32_bf16 v[52:55], v[150:153], v[184:187], v[52:55]
	v_mfma_f32_16x16x32_bf16 v[48:51], v[158:161], v[184:187], v[48:51]
	v_mfma_f32_16x16x32_bf16 v[44:47], v[150:153], v[192:195], v[44:47]
	v_mfma_f32_16x16x32_bf16 v[40:43], v[158:161], v[192:195], v[40:43]
	v_mfma_f32_16x16x32_bf16 v[36:39], v[150:153], v[200:203], v[36:39]
	v_mfma_f32_16x16x32_bf16 v[32:35], v[158:161], v[200:203], v[32:35]
	v_mfma_f32_16x16x32_bf16 v[60:63], v[154:157], v[170:173], v[60:63]
	v_mfma_f32_16x16x32_bf16 v[56:59], v[162:165], v[170:173], v[56:59]
	v_mfma_f32_16x16x32_bf16 v[52:55], v[154:157], v[188:191], v[52:55]
	v_mfma_f32_16x16x32_bf16 v[48:51], v[162:165], v[188:191], v[48:51]
	v_mfma_f32_16x16x32_bf16 v[44:47], v[154:157], v[196:199], v[44:47]
	v_mfma_f32_16x16x32_bf16 v[40:43], v[162:165], v[196:199], v[40:43]
	v_mfma_f32_16x16x32_bf16 v[36:39], v[154:157], v[204:207], v[36:39]
	v_mfma_f32_16x16x32_bf16 v[32:35], v[162:165], v[204:207], v[32:35]
	s_barrier
	s_add_u32 s62, s38, 0x80
	s_addc_u32 s63, s39, 0
	ds_read_b128 v[166:169], v181 offset:49152
	ds_read_b128 v[170:173], v181 offset:50176
	ds_read_b128 v[184:187], v181 offset:51200
	ds_read_b128 v[188:191], v181 offset:52224
	ds_read_b128 v[192:195], v181 offset:53248
	ds_read_b128 v[196:199], v181 offset:54272
	ds_read_b128 v[200:203], v181 offset:55296
	ds_read_b128 v[204:207], v181 offset:56320
	s_mov_b32 m0, s48
	s_nop 0
	global_load_lds_dwordx4 v145, s[62:63]
	s_add_u32 s62, s38, 0x58080
	s_mov_b32 m0, s49
	s_addc_u32 s63, s39, 0
	global_load_lds_dwordx4 v145, s[62:63]
	s_add_u32 s62, s38, 0xb0080
	s_mov_b32 m0, s52
	s_addc_u32 s63, s39, 0
	global_load_lds_dwordx4 v145, s[62:63]
	s_add_u32 s38, s38, 0x108080
	s_mov_b32 m0, s53
	s_addc_u32 s39, s39, 0
	global_load_lds_dwordx4 v145, s[38:39]
	s_mov_b32 m0, s50
	s_nop 0
	global_load_lds_dwordx4 v144, s[26:27]
	s_add_u32 s24, s24, 0x58080
	s_mov_b32 m0, s51
	s_addc_u32 s25, s25, 0
	global_load_lds_dwordx4 v144, s[24:25]
	s_waitcnt vmcnt(8) lgkmcnt(0)
	s_barrier
	v_mfma_f32_16x16x32_bf16 v[92:95], v[128:131], v[166:169], v[92:95]
	v_mfma_f32_16x16x32_bf16 v[88:91], v[136:139], v[166:169], v[88:91]
	v_mfma_f32_16x16x32_bf16 v[84:87], v[128:131], v[184:187], v[84:87]
	v_mfma_f32_16x16x32_bf16 v[80:83], v[136:139], v[184:187], v[80:83]
	v_mfma_f32_16x16x32_bf16 v[76:79], v[128:131], v[192:195], v[76:79]
	v_mfma_f32_16x16x32_bf16 v[72:75], v[136:139], v[192:195], v[72:75]
	v_mfma_f32_16x16x32_bf16 v[68:71], v[128:131], v[200:203], v[68:71]
	v_mfma_f32_16x16x32_bf16 v[64:67], v[136:139], v[200:203], v[64:67]
	v_mfma_f32_16x16x32_bf16 v[92:95], v[132:135], v[170:173], v[92:95]
	v_mfma_f32_16x16x32_bf16 v[88:91], v[140:143], v[170:173], v[88:91]
	v_mfma_f32_16x16x32_bf16 v[84:87], v[132:135], v[188:191], v[84:87]
	v_mfma_f32_16x16x32_bf16 v[80:83], v[140:143], v[188:191], v[80:83]
	v_mfma_f32_16x16x32_bf16 v[76:79], v[132:135], v[196:199], v[76:79]
	v_mfma_f32_16x16x32_bf16 v[72:75], v[140:143], v[196:199], v[72:75]
	v_mfma_f32_16x16x32_bf16 v[68:71], v[132:135], v[204:207], v[68:71]
	v_mfma_f32_16x16x32_bf16 v[64:67], v[140:143], v[204:207], v[64:67]
	v_mfma_f32_16x16x32_bf16 v[28:31], v[150:153], v[166:169], v[28:31]
	v_mfma_f32_16x16x32_bf16 v[24:27], v[158:161], v[166:169], v[24:27]
	v_mfma_f32_16x16x32_bf16 v[20:23], v[150:153], v[184:187], v[20:23]
	v_mfma_f32_16x16x32_bf16 v[16:19], v[158:161], v[184:187], v[16:19]
	v_mfma_f32_16x16x32_bf16 v[12:15], v[150:153], v[192:195], v[12:15]
	v_mfma_f32_16x16x32_bf16 v[8:11], v[158:161], v[192:195], v[8:11]
	v_mfma_f32_16x16x32_bf16 v[4:7], v[150:153], v[200:203], v[4:7]
	v_mfma_f32_16x16x32_bf16 v[0:3], v[158:161], v[200:203], v[0:3]
	v_mfma_f32_16x16x32_bf16 v[28:31], v[154:157], v[170:173], v[28:31]
	v_mfma_f32_16x16x32_bf16 v[24:27], v[162:165], v[170:173], v[24:27]
	v_mfma_f32_16x16x32_bf16 v[20:23], v[154:157], v[188:191], v[20:23]
	v_mfma_f32_16x16x32_bf16 v[16:19], v[162:165], v[188:191], v[16:19]
	v_mfma_f32_16x16x32_bf16 v[12:15], v[154:157], v[196:199], v[12:15]
	v_mfma_f32_16x16x32_bf16 v[8:11], v[162:165], v[196:199], v[8:11]
	v_mfma_f32_16x16x32_bf16 v[4:7], v[154:157], v[204:207], v[4:7]
	v_mfma_f32_16x16x32_bf16 v[0:3], v[162:165], v[204:207], v[0:3]
	s_barrier
	s_cmp_gt_u32 s61, 41
	s_cbranch_scc0 .LBB0_1559
	s_and_b64 vcc, exec, s[12:13]
	s_cbranch_vccz .LBB0_1562
	s_barrier
